# GEMM K-loops: post-MFMA s_barrier moved 6 MFMAs earlier so barrier latency overlaps the tail of the MFMA block (all 18 K-loops)
# baseline (speedup 1.0000x reference)
.LBB0_408:
	ds_read_b128 v[34:37], v196
	ds_read_b128 v[38:41], v196 offset:1024
	ds_read_b128 v[42:45], v196 offset:2048
	ds_read_b128 v[46:49], v196 offset:3072
	ds_read_b128 v[146:149], v197
	ds_read_b128 v[150:153], v197 offset:1024
	ds_read_b128 v[184:187], v197 offset:2048
	ds_read_b128 v[188:191], v197 offset:3072
	s_add_i32 s11, s6, 2
	s_add_u32 s12, s4, 0x80
	s_addc_u32 s7, s5, 0
	s_cmp_eq_u32 s27, s6
	s_cselect_b32 s6, s54, s12
	s_cselect_b32 s7, s55, s7
	s_cselect_b32 s13, s61, s9
	s_cselect_b32 s12, s60, s8
	v_lshl_add_u64 v[192:193], s[4:5], 0, v[174:175]
	s_add_i32 m0, s88, 0xc000
	ds_read_b128 v[200:203], v198
	ds_read_b128 v[204:207], v198 offset:1024
	ds_read_b128 v[208:211], v198 offset:2048
	ds_read_b128 v[212:215], v198 offset:3072
	ds_read_b128 v[216:219], v198 offset:4096
	ds_read_b128 v[220:223], v198 offset:5120
	ds_read_b128 v[224:227], v198 offset:6144
	ds_read_b128 v[228:231], v198 offset:7168
	global_load_lds_dwordx4 v[192:193], off
	v_lshl_add_u64 v[192:193], s[4:5], 0, v[176:177]
	s_add_i32 m0, s88, 0xe000
	s_nop 0
	global_load_lds_dwordx4 v[192:193], off
	s_waitcnt vmcnt(8)
	s_waitcnt lgkmcnt(0)
	s_barrier
	s_setprio 1
	s_waitcnt lgkmcnt(0)
	v_mfma_f32_16x16x32_bf16 v[142:145], v[34:37], v[200:203], v[142:145]
	v_mfma_f32_16x16x32_bf16 v[138:141], v[42:45], v[200:203], v[138:141]
	v_mfma_f32_16x16x32_bf16 v[126:129], v[34:37], v[208:211], v[126:129]
	v_mfma_f32_16x16x32_bf16 v[122:125], v[42:45], v[208:211], v[122:125]
	v_mfma_f32_16x16x32_bf16 v[110:113], v[34:37], v[216:219], v[110:113]
	v_mfma_f32_16x16x32_bf16 v[106:109], v[42:45], v[216:219], v[106:109]
	v_mfma_f32_16x16x32_bf16 v[94:97], v[34:37], v[224:227], v[94:97]
	v_mfma_f32_16x16x32_bf16 v[90:93], v[42:45], v[224:227], v[90:93]
	v_mfma_f32_16x16x32_bf16 v[142:145], v[38:41], v[204:207], v[142:145]
	v_mfma_f32_16x16x32_bf16 v[138:141], v[46:49], v[204:207], v[138:141]
	v_mfma_f32_16x16x32_bf16 v[126:129], v[38:41], v[212:215], v[126:129]
	v_mfma_f32_16x16x32_bf16 v[122:125], v[46:49], v[212:215], v[122:125]
	v_mfma_f32_16x16x32_bf16 v[110:113], v[38:41], v[220:223], v[110:113]
	v_mfma_f32_16x16x32_bf16 v[106:109], v[46:49], v[220:223], v[106:109]
	v_mfma_f32_16x16x32_bf16 v[94:97], v[38:41], v[228:231], v[94:97]
	v_mfma_f32_16x16x32_bf16 v[90:93], v[46:49], v[228:231], v[90:93]
	s_setprio 0
	s_setprio 1
	v_mfma_f32_16x16x32_bf16 v[134:137], v[146:149], v[200:203], v[134:137]
	v_mfma_f32_16x16x32_bf16 v[130:133], v[184:187], v[200:203], v[130:133]
	v_mfma_f32_16x16x32_bf16 v[118:121], v[146:149], v[208:211], v[118:121]
	v_mfma_f32_16x16x32_bf16 v[114:117], v[184:187], v[208:211], v[114:117]
	v_mfma_f32_16x16x32_bf16 v[102:105], v[146:149], v[216:219], v[102:105]
	v_mfma_f32_16x16x32_bf16 v[98:101], v[184:187], v[216:219], v[98:101]
	v_mfma_f32_16x16x32_bf16 v[86:89], v[146:149], v[224:227], v[86:89]
	v_mfma_f32_16x16x32_bf16 v[82:85], v[184:187], v[224:227], v[82:85]
	v_mfma_f32_16x16x32_bf16 v[134:137], v[150:153], v[204:207], v[134:137]
	v_mfma_f32_16x16x32_bf16 v[130:133], v[188:191], v[204:207], v[130:133]
	s_barrier
	v_mfma_f32_16x16x32_bf16 v[118:121], v[150:153], v[212:215], v[118:121]
	v_mfma_f32_16x16x32_bf16 v[114:117], v[188:191], v[212:215], v[114:117]
	v_mfma_f32_16x16x32_bf16 v[102:105], v[150:153], v[220:223], v[102:105]
	v_mfma_f32_16x16x32_bf16 v[98:101], v[188:191], v[220:223], v[98:101]
	v_mfma_f32_16x16x32_bf16 v[86:89], v[150:153], v[228:231], v[86:89]
	v_mfma_f32_16x16x32_bf16 v[82:85], v[188:191], v[228:231], v[82:85]
	s_setprio 0
	s_nop 0
	s_add_i32 s24, s84, s81
	v_lshl_add_u64 v[192:193], s[12:13], 0, v[156:157]
	s_mov_b32 m0, s24
	ds_read_b128 v[200:203], v198 offset:16384
	ds_read_b128 v[204:207], v198 offset:17408
	ds_read_b128 v[208:211], v198 offset:18432
	ds_read_b128 v[212:215], v198 offset:19456
	ds_read_b128 v[216:219], v198 offset:20480
	ds_read_b128 v[220:223], v198 offset:21504
	ds_read_b128 v[224:227], v198 offset:22528
	ds_read_b128 v[228:231], v198 offset:23552
	global_load_lds_dwordx4 v[192:193], off
	s_add_i32 m0, s24, 0x2000
	v_lshl_add_u64 v[232:233], s[12:13], 0, v[160:161]
	s_add_u32 s12, s12, s20
	s_addc_u32 s13, s13, s21
	s_add_i32 s24, s85, s81
	global_load_lds_dwordx4 v[232:233], off
	v_lshl_add_u64 v[234:235], s[12:13], 0, v[156:157]
	s_mov_b32 m0, s24
	v_lshl_add_u64 v[236:237], s[12:13], 0, v[160:161]
	global_load_lds_dwordx4 v[234:235], off
	s_add_i32 m0, s24, 0x2000
	v_lshl_add_u64 v[238:239], s[6:7], 0, v[154:155]
	global_load_lds_dwordx4 v[236:237], off
	s_mov_b32 m0, s88
	v_lshl_add_u64 v[240:241], s[6:7], 0, v[158:159]
	global_load_lds_dwordx4 v[238:239], off
	s_mov_b32 m0, s90
	s_nop 0
	global_load_lds_dwordx4 v[240:241], off
	s_waitcnt vmcnt(8)
	s_waitcnt lgkmcnt(0)
	s_barrier
	s_setprio 1
	s_waitcnt lgkmcnt(0)
	v_mfma_f32_16x16x32_bf16 v[78:81], v[34:37], v[200:203], v[78:81]
	v_mfma_f32_16x16x32_bf16 v[74:77], v[42:45], v[200:203], v[74:77]
	v_mfma_f32_16x16x32_bf16 v[62:65], v[34:37], v[208:211], v[62:65]
	v_mfma_f32_16x16x32_bf16 v[58:61], v[42:45], v[208:211], v[58:61]
	v_mfma_f32_16x16x32_bf16 v[30:33], v[34:37], v[216:219], v[30:33]
	v_mfma_f32_16x16x32_bf16 v[26:29], v[42:45], v[216:219], v[26:29]
	v_mfma_f32_16x16x32_bf16 v[14:17], v[34:37], v[224:227], v[14:17]
	v_mfma_f32_16x16x32_bf16 v[10:13], v[42:45], v[224:227], v[10:13]
	v_mfma_f32_16x16x32_bf16 v[78:81], v[38:41], v[204:207], v[78:81]
	v_mfma_f32_16x16x32_bf16 v[74:77], v[46:49], v[204:207], v[74:77]
	v_mfma_f32_16x16x32_bf16 v[62:65], v[38:41], v[212:215], v[62:65]
	v_mfma_f32_16x16x32_bf16 v[58:61], v[46:49], v[212:215], v[58:61]
	v_mfma_f32_16x16x32_bf16 v[30:33], v[38:41], v[220:223], v[30:33]
	v_mfma_f32_16x16x32_bf16 v[26:29], v[46:49], v[220:223], v[26:29]
	v_mfma_f32_16x16x32_bf16 v[14:17], v[38:41], v[228:231], v[14:17]
	v_mfma_f32_16x16x32_bf16 v[10:13], v[46:49], v[228:231], v[10:13]
	s_setprio 0
	s_setprio 1
	v_mfma_f32_16x16x32_bf16 v[22:25], v[146:149], v[216:219], v[22:25]
	v_mfma_f32_16x16x32_bf16 v[18:21], v[184:187], v[216:219], v[18:21]
	v_mfma_f32_16x16x32_bf16 v[6:9], v[146:149], v[224:227], v[6:9]
	v_mfma_f32_16x16x32_bf16 v[2:5], v[184:187], v[224:227], v[2:5]
	v_mfma_f32_16x16x32_bf16 v[34:37], v[146:149], v[200:203], v[70:73]
	v_mfma_f32_16x16x32_bf16 v[38:41], v[184:187], v[200:203], v[66:69]
	v_mfma_f32_16x16x32_bf16 v[42:45], v[146:149], v[208:211], v[54:57]
	v_mfma_f32_16x16x32_bf16 v[46:49], v[184:187], v[208:211], v[50:53]
	v_mfma_f32_16x16x32_bf16 v[22:25], v[150:153], v[220:223], v[22:25]
	v_mfma_f32_16x16x32_bf16 v[18:21], v[188:191], v[220:223], v[18:21]
	s_barrier
	v_mfma_f32_16x16x32_bf16 v[6:9], v[150:153], v[228:231], v[6:9]
	v_mfma_f32_16x16x32_bf16 v[2:5], v[188:191], v[228:231], v[2:5]
	v_mfma_f32_16x16x32_bf16 v[34:37], v[150:153], v[204:207], v[34:37]
	v_mfma_f32_16x16x32_bf16 v[38:41], v[188:191], v[204:207], v[38:41]
	v_mfma_f32_16x16x32_bf16 v[42:45], v[150:153], v[212:215], v[42:45]
	v_mfma_f32_16x16x32_bf16 v[46:49], v[188:191], v[212:215], v[46:49]
	s_setprio 0
	s_nop 0
	s_add_i32 s12, 0, 0x18000
	s_add_i32 s13, 0, 0x1c000
	v_add_u32_e32 v70, s12, v194
	v_add_u32_e32 v162, s13, v194
	ds_read_b128 v[50:53], v70
	ds_read_b128 v[54:57], v70 offset:1024
	ds_read_b128 v[66:69], v70 offset:2048
	ds_read_b128 v[70:73], v70 offset:3072
	ds_read_b128 v[146:149], v162
	ds_read_b128 v[150:153], v162 offset:1024
	ds_read_b128 v[184:187], v162 offset:2048
	ds_read_b128 v[188:191], v162 offset:3072
	s_add_u32 s6, s6, s20
	s_addc_u32 s7, s7, s21
	s_mov_b32 m0, s91
	v_lshl_add_u64 v[242:243], s[6:7], 0, v[154:155]
	ds_read_b128 v[200:203], v198 offset:32768
	ds_read_b128 v[204:207], v198 offset:33792
	ds_read_b128 v[208:211], v198 offset:34816
	ds_read_b128 v[212:215], v198 offset:35840
	ds_read_b128 v[216:219], v198 offset:36864
	ds_read_b128 v[220:223], v198 offset:37888
	ds_read_b128 v[224:227], v198 offset:38912
	ds_read_b128 v[228:231], v198 offset:39936
	global_load_lds_dwordx4 v[242:243], off
	v_lshl_add_u64 v[242:243], s[6:7], 0, v[158:159]
	s_mov_b32 m0, s95
	s_nop 0
	global_load_lds_dwordx4 v[242:243], off
	s_waitcnt vmcnt(8)
	s_waitcnt lgkmcnt(0)
	s_barrier
	s_setprio 1
	s_waitcnt lgkmcnt(0)
	v_mfma_f32_16x16x32_bf16 v[142:145], v[50:53], v[200:203], v[142:145]
	v_mfma_f32_16x16x32_bf16 v[138:141], v[66:69], v[200:203], v[138:141]
	v_mfma_f32_16x16x32_bf16 v[126:129], v[50:53], v[208:211], v[126:129]
	v_mfma_f32_16x16x32_bf16 v[122:125], v[66:69], v[208:211], v[122:125]
	v_mfma_f32_16x16x32_bf16 v[110:113], v[50:53], v[216:219], v[110:113]
	v_mfma_f32_16x16x32_bf16 v[106:109], v[66:69], v[216:219], v[106:109]
	v_mfma_f32_16x16x32_bf16 v[94:97], v[50:53], v[224:227], v[94:97]
	v_mfma_f32_16x16x32_bf16 v[90:93], v[66:69], v[224:227], v[90:93]
	v_mfma_f32_16x16x32_bf16 v[142:145], v[54:57], v[204:207], v[142:145]
	v_mfma_f32_16x16x32_bf16 v[138:141], v[70:73], v[204:207], v[138:141]
	v_mfma_f32_16x16x32_bf16 v[126:129], v[54:57], v[212:215], v[126:129]
	v_mfma_f32_16x16x32_bf16 v[122:125], v[70:73], v[212:215], v[122:125]
	v_mfma_f32_16x16x32_bf16 v[110:113], v[54:57], v[220:223], v[110:113]
	v_mfma_f32_16x16x32_bf16 v[106:109], v[70:73], v[220:223], v[106:109]
	v_mfma_f32_16x16x32_bf16 v[94:97], v[54:57], v[228:231], v[94:97]
	v_mfma_f32_16x16x32_bf16 v[90:93], v[70:73], v[228:231], v[90:93]
	s_setprio 0
	s_setprio 1
	v_mfma_f32_16x16x32_bf16 v[134:137], v[146:149], v[200:203], v[134:137]
	v_mfma_f32_16x16x32_bf16 v[130:133], v[184:187], v[200:203], v[130:133]
	v_mfma_f32_16x16x32_bf16 v[118:121], v[146:149], v[208:211], v[118:121]
	v_mfma_f32_16x16x32_bf16 v[114:117], v[184:187], v[208:211], v[114:117]
	v_mfma_f32_16x16x32_bf16 v[102:105], v[146:149], v[216:219], v[102:105]
	v_mfma_f32_16x16x32_bf16 v[98:101], v[184:187], v[216:219], v[98:101]
	v_mfma_f32_16x16x32_bf16 v[86:89], v[146:149], v[224:227], v[86:89]
	v_mfma_f32_16x16x32_bf16 v[82:85], v[184:187], v[224:227], v[82:85]
	v_mfma_f32_16x16x32_bf16 v[134:137], v[150:153], v[204:207], v[134:137]
	v_mfma_f32_16x16x32_bf16 v[130:133], v[188:191], v[204:207], v[130:133]
	s_barrier
	v_mfma_f32_16x16x32_bf16 v[118:121], v[150:153], v[212:215], v[118:121]
	v_mfma_f32_16x16x32_bf16 v[114:117], v[188:191], v[212:215], v[114:117]
	v_mfma_f32_16x16x32_bf16 v[102:105], v[150:153], v[220:223], v[102:105]
	v_mfma_f32_16x16x32_bf16 v[98:101], v[188:191], v[220:223], v[98:101]
	v_mfma_f32_16x16x32_bf16 v[86:89], v[150:153], v[228:231], v[86:89]
	v_mfma_f32_16x16x32_bf16 v[82:85], v[188:191], v[228:231], v[82:85]
	s_setprio 0
	s_nop 0
	s_add_i32 s6, s12, s81
	v_lshl_add_u64 v[192:193], v[192:193], 0, s[44:45]
	s_mov_b32 m0, s6
	ds_read_b128 v[200:203], v198 offset:49152
	ds_read_b128 v[204:207], v198 offset:50176
	ds_read_b128 v[208:211], v198 offset:51200
	ds_read_b128 v[212:215], v198 offset:52224
	ds_read_b128 v[216:219], v198 offset:53248
	ds_read_b128 v[220:223], v198 offset:54272
	ds_read_b128 v[224:227], v198 offset:55296
	ds_read_b128 v[228:231], v198 offset:56320
	global_load_lds_dwordx4 v[192:193], off
	v_lshl_add_u64 v[192:193], v[232:233], 0, s[44:45]
	s_add_i32 m0, s6, 0x2000
	s_add_i32 s6, s13, s81
	global_load_lds_dwordx4 v[192:193], off
	v_lshl_add_u64 v[192:193], v[234:235], 0, s[44:45]
	s_mov_b32 m0, s6
	s_nop 0
	global_load_lds_dwordx4 v[192:193], off
	v_lshl_add_u64 v[192:193], v[236:237], 0, s[44:45]
	s_add_i32 m0, s6, 0x2000
	s_nop 0
	global_load_lds_dwordx4 v[192:193], off
	v_lshl_add_u64 v[192:193], v[238:239], 0, s[44:45]
	s_mov_b32 m0, s17
	s_nop 0
	global_load_lds_dwordx4 v[192:193], off
	v_lshl_add_u64 v[192:193], v[240:241], 0, s[44:45]
	s_mov_b32 m0, s94
	s_nop 0
	global_load_lds_dwordx4 v[192:193], off
	s_waitcnt vmcnt(8)
	s_waitcnt lgkmcnt(0)
	s_barrier
	s_setprio 1
	s_waitcnt lgkmcnt(0)
	v_mfma_f32_16x16x32_bf16 v[78:81], v[50:53], v[200:203], v[78:81]
	v_mfma_f32_16x16x32_bf16 v[74:77], v[66:69], v[200:203], v[74:77]
	v_mfma_f32_16x16x32_bf16 v[62:65], v[50:53], v[208:211], v[62:65]
	v_mfma_f32_16x16x32_bf16 v[58:61], v[66:69], v[208:211], v[58:61]
	v_mfma_f32_16x16x32_bf16 v[30:33], v[50:53], v[216:219], v[30:33]
	v_mfma_f32_16x16x32_bf16 v[26:29], v[66:69], v[216:219], v[26:29]
	v_mfma_f32_16x16x32_bf16 v[14:17], v[50:53], v[224:227], v[14:17]
	v_mfma_f32_16x16x32_bf16 v[10:13], v[66:69], v[224:227], v[10:13]
	v_mfma_f32_16x16x32_bf16 v[78:81], v[54:57], v[204:207], v[78:81]
	v_mfma_f32_16x16x32_bf16 v[74:77], v[70:73], v[204:207], v[74:77]
	v_mfma_f32_16x16x32_bf16 v[62:65], v[54:57], v[212:215], v[62:65]
	v_mfma_f32_16x16x32_bf16 v[58:61], v[70:73], v[212:215], v[58:61]
	v_mfma_f32_16x16x32_bf16 v[30:33], v[54:57], v[220:223], v[30:33]
	v_mfma_f32_16x16x32_bf16 v[26:29], v[70:73], v[220:223], v[26:29]
	v_mfma_f32_16x16x32_bf16 v[14:17], v[54:57], v[228:231], v[14:17]
	v_mfma_f32_16x16x32_bf16 v[10:13], v[70:73], v[228:231], v[10:13]
	s_setprio 0
	s_setprio 1
	v_mfma_f32_16x16x32_bf16 v[34:37], v[146:149], v[200:203], v[34:37]
	v_mfma_f32_16x16x32_bf16 v[70:73], v[150:153], v[204:207], v[34:37]
	v_mfma_f32_16x16x32_bf16 v[34:37], v[184:187], v[200:203], v[38:41]
	v_mfma_f32_16x16x32_bf16 v[66:69], v[188:191], v[204:207], v[34:37]
	v_mfma_f32_16x16x32_bf16 v[34:37], v[146:149], v[208:211], v[42:45]
	v_mfma_f32_16x16x32_bf16 v[54:57], v[150:153], v[212:215], v[34:37]
	v_mfma_f32_16x16x32_bf16 v[34:37], v[184:187], v[208:211], v[46:49]
	v_mfma_f32_16x16x32_bf16 v[22:25], v[146:149], v[216:219], v[22:25]
	v_mfma_f32_16x16x32_bf16 v[18:21], v[184:187], v[216:219], v[18:21]
	v_mfma_f32_16x16x32_bf16 v[6:9], v[146:149], v[224:227], v[6:9]
	s_barrier
	v_mfma_f32_16x16x32_bf16 v[2:5], v[184:187], v[224:227], v[2:5]
	v_mfma_f32_16x16x32_bf16 v[50:53], v[188:191], v[212:215], v[34:37]
	v_mfma_f32_16x16x32_bf16 v[22:25], v[150:153], v[220:223], v[22:25]
	v_mfma_f32_16x16x32_bf16 v[18:21], v[188:191], v[220:223], v[18:21]
	v_mfma_f32_16x16x32_bf16 v[6:9], v[150:153], v[228:231], v[6:9]
	v_mfma_f32_16x16x32_bf16 v[2:5], v[188:191], v[228:231], v[2:5]
	s_setprio 0
	s_nop 0
	s_add_u32 s4, s4, 0x100
	s_addc_u32 s5, s5, 0
	s_add_u32 s8, s8, 0x100
	s_addc_u32 s9, s9, 0
	s_cmp_ge_i32 s11, s26
	s_mov_b32 s6, s11
	s_cbranch_scc0 .LBB0_408

.LBB0_895:
	v_add_u32_e32 v158, s84, v227
	v_add_u32_e32 v174, s85, v227
	ds_read_b128 v[146:149], v158
	ds_read_b128 v[150:153], v158 offset:1024
	ds_read_b128 v[154:157], v158 offset:2048
	ds_read_b128 v[158:161], v158 offset:3072
	ds_read_b128 v[162:165], v174
	ds_read_b128 v[166:169], v174 offset:1024
	ds_read_b128 v[170:173], v174 offset:2048
	ds_read_b128 v[174:177], v174 offset:3072
	s_add_i32 s16, s50, 2
	s_add_u32 s17, s46, 0x80
	s_addc_u32 s51, s47, 0
	s_cmp_eq_u32 s81, s50
	s_cselect_b32 s50, s4, s17
	s_cselect_b32 s51, s5, s51
	s_cselect_b32 s55, s45, vcc_hi
	s_cselect_b32 s54, s44, vcc_lo
	v_lshl_add_u64 v[210:211], s[46:47], 0, v[138:139]
	s_add_i32 m0, s63, 0xc000
	ds_read_b128 v[178:181], v229
	ds_read_b128 v[182:185], v229 offset:1024
	ds_read_b128 v[186:189], v229 offset:2048
	ds_read_b128 v[190:193], v229 offset:3072
	ds_read_b128 v[194:197], v229 offset:4096
	ds_read_b128 v[198:201], v229 offset:5120
	ds_read_b128 v[202:205], v229 offset:6144
	ds_read_b128 v[206:209], v229 offset:7168
	global_load_lds_dwordx4 v[210:211], off
	v_lshl_add_u64 v[210:211], s[46:47], 0, v[140:141]
	s_add_i32 m0, s63, 0xe000
	s_nop 0
	global_load_lds_dwordx4 v[210:211], off
	s_waitcnt vmcnt(8)
	s_waitcnt lgkmcnt(0)
	s_barrier
	s_setprio 1
	s_waitcnt lgkmcnt(0)
	v_mfma_i32_16x16x64_i8 v[126:129], v[146:149], v[178:181], v[126:129]
	v_mfma_i32_16x16x64_i8 v[122:125], v[154:157], v[178:181], v[122:125]
	v_mfma_i32_16x16x64_i8 v[118:121], v[146:149], v[186:189], v[118:121]
	v_mfma_i32_16x16x64_i8 v[114:117], v[154:157], v[186:189], v[114:117]
	v_mfma_i32_16x16x64_i8 v[106:109], v[146:149], v[194:197], v[106:109]
	v_mfma_i32_16x16x64_i8 v[98:101], v[154:157], v[194:197], v[98:101]
	v_mfma_i32_16x16x64_i8 v[90:93], v[146:149], v[202:205], v[90:93]
	v_mfma_i32_16x16x64_i8 v[82:85], v[154:157], v[202:205], v[82:85]
	v_mfma_i32_16x16x64_i8 v[126:129], v[150:153], v[182:185], v[126:129]
	v_mfma_i32_16x16x64_i8 v[122:125], v[158:161], v[182:185], v[122:125]
	v_mfma_i32_16x16x64_i8 v[118:121], v[150:153], v[190:193], v[118:121]
	v_mfma_i32_16x16x64_i8 v[114:117], v[158:161], v[190:193], v[114:117]
	v_mfma_i32_16x16x64_i8 v[106:109], v[150:153], v[198:201], v[106:109]
	v_mfma_i32_16x16x64_i8 v[98:101], v[158:161], v[198:201], v[98:101]
	v_mfma_i32_16x16x64_i8 v[90:93], v[150:153], v[206:209], v[90:93]
	v_mfma_i32_16x16x64_i8 v[82:85], v[158:161], v[206:209], v[82:85]
	s_setprio 0
	s_setprio 1
	v_mfma_i32_16x16x64_i8 v[110:113], v[162:165], v[178:181], v[110:113]
	v_mfma_i32_16x16x64_i8 v[102:105], v[170:173], v[178:181], v[102:105]
	v_mfma_i32_16x16x64_i8 v[94:97], v[162:165], v[186:189], v[94:97]
	v_mfma_i32_16x16x64_i8 v[86:89], v[170:173], v[186:189], v[86:89]
	v_mfma_i32_16x16x64_i8 v[78:81], v[162:165], v[194:197], v[78:81]
	v_mfma_i32_16x16x64_i8 v[74:77], v[170:173], v[194:197], v[74:77]
	v_mfma_i32_16x16x64_i8 v[70:73], v[162:165], v[202:205], v[70:73]
	v_mfma_i32_16x16x64_i8 v[66:69], v[170:173], v[202:205], v[66:69]
	v_mfma_i32_16x16x64_i8 v[110:113], v[166:169], v[182:185], v[110:113]
	v_mfma_i32_16x16x64_i8 v[102:105], v[174:177], v[182:185], v[102:105]
	s_barrier
	v_mfma_i32_16x16x64_i8 v[94:97], v[166:169], v[190:193], v[94:97]
	v_mfma_i32_16x16x64_i8 v[86:89], v[174:177], v[190:193], v[86:89]
	v_mfma_i32_16x16x64_i8 v[78:81], v[166:169], v[198:201], v[78:81]
	v_mfma_i32_16x16x64_i8 v[74:77], v[174:177], v[198:201], v[74:77]
	v_mfma_i32_16x16x64_i8 v[70:73], v[166:169], v[206:209], v[70:73]
	v_mfma_i32_16x16x64_i8 v[66:69], v[174:177], v[206:209], v[66:69]
	s_setprio 0
	s_nop 0
	s_add_i32 s17, s84, s62
	v_lshl_add_u64 v[210:211], s[54:55], 0, v[132:133]
	s_mov_b32 m0, s17
	ds_read_b128 v[178:181], v229 offset:16384
	ds_read_b128 v[182:185], v229 offset:17408
	ds_read_b128 v[186:189], v229 offset:18432
	ds_read_b128 v[190:193], v229 offset:19456
	ds_read_b128 v[194:197], v229 offset:20480
	ds_read_b128 v[198:201], v229 offset:21504
	ds_read_b128 v[202:205], v229 offset:22528
	ds_read_b128 v[206:209], v229 offset:23552
	global_load_lds_dwordx4 v[210:211], off
	s_add_i32 m0, s17, 0x2000
	v_lshl_add_u64 v[212:213], s[54:55], 0, v[136:137]
	s_add_u32 s54, s54, s8
	s_addc_u32 s55, s55, s9
	s_add_i32 s17, s85, s62
	global_load_lds_dwordx4 v[212:213], off
	v_lshl_add_u64 v[214:215], s[54:55], 0, v[132:133]
	s_mov_b32 m0, s17
	v_lshl_add_u64 v[216:217], s[54:55], 0, v[136:137]
	global_load_lds_dwordx4 v[214:215], off
	s_add_i32 m0, s17, 0x2000
	v_lshl_add_u64 v[218:219], s[50:51], 0, v[130:131]
	global_load_lds_dwordx4 v[216:217], off
	s_mov_b32 m0, s63
	v_lshl_add_u64 v[220:221], s[50:51], 0, v[134:135]
	global_load_lds_dwordx4 v[218:219], off
	s_mov_b32 m0, s64
	s_nop 0
	global_load_lds_dwordx4 v[220:221], off
	s_waitcnt vmcnt(8)
	s_waitcnt lgkmcnt(0)
	s_barrier
	s_setprio 1
	s_waitcnt lgkmcnt(0)
	v_mfma_i32_16x16x64_i8 v[62:65], v[146:149], v[178:181], v[62:65]
	v_mfma_i32_16x16x64_i8 v[58:61], v[154:157], v[178:181], v[58:61]
	v_mfma_i32_16x16x64_i8 v[54:57], v[146:149], v[186:189], v[54:57]
	v_mfma_i32_16x16x64_i8 v[50:53], v[154:157], v[186:189], v[50:53]
	v_mfma_i32_16x16x64_i8 v[42:45], v[146:149], v[194:197], v[42:45]
	v_mfma_i32_16x16x64_i8 v[34:37], v[154:157], v[194:197], v[34:37]
	v_mfma_i32_16x16x64_i8 v[26:29], v[146:149], v[202:205], v[26:29]
	v_mfma_i32_16x16x64_i8 v[18:21], v[154:157], v[202:205], v[18:21]
	v_mfma_i32_16x16x64_i8 v[62:65], v[150:153], v[182:185], v[62:65]
	v_mfma_i32_16x16x64_i8 v[58:61], v[158:161], v[182:185], v[58:61]
	v_mfma_i32_16x16x64_i8 v[54:57], v[150:153], v[190:193], v[54:57]
	v_mfma_i32_16x16x64_i8 v[50:53], v[158:161], v[190:193], v[50:53]
	v_mfma_i32_16x16x64_i8 v[42:45], v[150:153], v[198:201], v[42:45]
	v_mfma_i32_16x16x64_i8 v[34:37], v[158:161], v[198:201], v[34:37]
	v_mfma_i32_16x16x64_i8 v[26:29], v[150:153], v[206:209], v[26:29]
	v_mfma_i32_16x16x64_i8 v[18:21], v[158:161], v[206:209], v[18:21]
	s_setprio 0
	s_setprio 1
	v_mfma_i32_16x16x64_i8 v[46:49], v[162:165], v[178:181], v[46:49]
	v_mfma_i32_16x16x64_i8 v[38:41], v[170:173], v[178:181], v[38:41]
	v_mfma_i32_16x16x64_i8 v[30:33], v[162:165], v[186:189], v[30:33]
	v_mfma_i32_16x16x64_i8 v[22:25], v[170:173], v[186:189], v[22:25]
	v_mfma_i32_16x16x64_i8 v[14:17], v[162:165], v[194:197], v[14:17]
	v_mfma_i32_16x16x64_i8 v[10:13], v[170:173], v[194:197], v[10:13]
	v_mfma_i32_16x16x64_i8 v[6:9], v[162:165], v[202:205], v[6:9]
	v_mfma_i32_16x16x64_i8 v[2:5], v[170:173], v[202:205], v[2:5]
	v_mfma_i32_16x16x64_i8 v[46:49], v[166:169], v[182:185], v[46:49]
	v_mfma_i32_16x16x64_i8 v[38:41], v[174:177], v[182:185], v[38:41]
	s_barrier
	v_mfma_i32_16x16x64_i8 v[30:33], v[166:169], v[190:193], v[30:33]
	v_mfma_i32_16x16x64_i8 v[22:25], v[174:177], v[190:193], v[22:25]
	v_mfma_i32_16x16x64_i8 v[14:17], v[166:169], v[198:201], v[14:17]
	v_mfma_i32_16x16x64_i8 v[10:13], v[174:177], v[198:201], v[10:13]
	v_mfma_i32_16x16x64_i8 v[6:9], v[166:169], v[206:209], v[6:9]
	v_mfma_i32_16x16x64_i8 v[2:5], v[174:177], v[206:209], v[2:5]
	s_setprio 0
	s_nop 0
	s_add_i32 s17, 0, 0x18000
	s_add_i32 s54, 0, 0x1c000
	v_add_u32_e32 v158, s17, v227
	v_add_u32_e32 v174, s54, v227
	ds_read_b128 v[146:149], v158
	ds_read_b128 v[150:153], v158 offset:1024
	ds_read_b128 v[154:157], v158 offset:2048
	ds_read_b128 v[158:161], v158 offset:3072
	ds_read_b128 v[162:165], v174
	ds_read_b128 v[166:169], v174 offset:1024
	ds_read_b128 v[170:173], v174 offset:2048
	ds_read_b128 v[174:177], v174 offset:3072
	s_add_u32 s50, s50, s8
	s_addc_u32 s51, s51, s9
	s_mov_b32 m0, s65
	v_lshl_add_u64 v[222:223], s[50:51], 0, v[130:131]
	ds_read_b128 v[178:181], v229 offset:32768
	ds_read_b128 v[182:185], v229 offset:33792
	ds_read_b128 v[186:189], v229 offset:34816
	ds_read_b128 v[190:193], v229 offset:35840
	ds_read_b128 v[194:197], v229 offset:36864
	ds_read_b128 v[198:201], v229 offset:37888
	ds_read_b128 v[202:205], v229 offset:38912
	ds_read_b128 v[206:209], v229 offset:39936
	global_load_lds_dwordx4 v[222:223], off
	v_lshl_add_u64 v[222:223], s[50:51], 0, v[134:135]
	s_mov_b32 m0, s86
	s_nop 0
	global_load_lds_dwordx4 v[222:223], off
	s_waitcnt vmcnt(8)
	s_waitcnt lgkmcnt(0)
	s_barrier
	s_setprio 1
	s_waitcnt lgkmcnt(0)
	v_mfma_i32_16x16x64_i8 v[126:129], v[146:149], v[178:181], v[126:129]
	v_mfma_i32_16x16x64_i8 v[122:125], v[154:157], v[178:181], v[122:125]
	v_mfma_i32_16x16x64_i8 v[118:121], v[146:149], v[186:189], v[118:121]
	v_mfma_i32_16x16x64_i8 v[114:117], v[154:157], v[186:189], v[114:117]
	v_mfma_i32_16x16x64_i8 v[106:109], v[146:149], v[194:197], v[106:109]
	v_mfma_i32_16x16x64_i8 v[98:101], v[154:157], v[194:197], v[98:101]
	v_mfma_i32_16x16x64_i8 v[90:93], v[146:149], v[202:205], v[90:93]
	v_mfma_i32_16x16x64_i8 v[82:85], v[154:157], v[202:205], v[82:85]
	v_mfma_i32_16x16x64_i8 v[126:129], v[150:153], v[182:185], v[126:129]
	v_mfma_i32_16x16x64_i8 v[122:125], v[158:161], v[182:185], v[122:125]
	v_mfma_i32_16x16x64_i8 v[118:121], v[150:153], v[190:193], v[118:121]
	v_mfma_i32_16x16x64_i8 v[114:117], v[158:161], v[190:193], v[114:117]
	v_mfma_i32_16x16x64_i8 v[106:109], v[150:153], v[198:201], v[106:109]
	v_mfma_i32_16x16x64_i8 v[98:101], v[158:161], v[198:201], v[98:101]
	v_mfma_i32_16x16x64_i8 v[90:93], v[150:153], v[206:209], v[90:93]
	v_mfma_i32_16x16x64_i8 v[82:85], v[158:161], v[206:209], v[82:85]
	s_setprio 0
	s_setprio 1
	v_mfma_i32_16x16x64_i8 v[110:113], v[162:165], v[178:181], v[110:113]
	v_mfma_i32_16x16x64_i8 v[102:105], v[170:173], v[178:181], v[102:105]
	v_mfma_i32_16x16x64_i8 v[94:97], v[162:165], v[186:189], v[94:97]
	v_mfma_i32_16x16x64_i8 v[86:89], v[170:173], v[186:189], v[86:89]
	v_mfma_i32_16x16x64_i8 v[78:81], v[162:165], v[194:197], v[78:81]
	v_mfma_i32_16x16x64_i8 v[74:77], v[170:173], v[194:197], v[74:77]
	v_mfma_i32_16x16x64_i8 v[70:73], v[162:165], v[202:205], v[70:73]
	v_mfma_i32_16x16x64_i8 v[66:69], v[170:173], v[202:205], v[66:69]
	v_mfma_i32_16x16x64_i8 v[110:113], v[166:169], v[182:185], v[110:113]
	v_mfma_i32_16x16x64_i8 v[102:105], v[174:177], v[182:185], v[102:105]
	s_barrier
	v_mfma_i32_16x16x64_i8 v[94:97], v[166:169], v[190:193], v[94:97]
	v_mfma_i32_16x16x64_i8 v[86:89], v[174:177], v[190:193], v[86:89]
	v_mfma_i32_16x16x64_i8 v[78:81], v[166:169], v[198:201], v[78:81]
	v_mfma_i32_16x16x64_i8 v[74:77], v[174:177], v[198:201], v[74:77]
	v_mfma_i32_16x16x64_i8 v[70:73], v[166:169], v[206:209], v[70:73]
	v_mfma_i32_16x16x64_i8 v[66:69], v[174:177], v[206:209], v[66:69]
	s_setprio 0
	s_nop 0
	s_add_i32 s17, s17, s62
	v_lshl_add_u64 v[210:211], v[210:211], 0, s[36:37]
	s_mov_b32 m0, s17
	ds_read_b128 v[178:181], v229 offset:49152
	ds_read_b128 v[182:185], v229 offset:50176
	ds_read_b128 v[186:189], v229 offset:51200
	ds_read_b128 v[190:193], v229 offset:52224
	ds_read_b128 v[194:197], v229 offset:53248
	ds_read_b128 v[198:201], v229 offset:54272
	ds_read_b128 v[202:205], v229 offset:55296
	ds_read_b128 v[206:209], v229 offset:56320
	global_load_lds_dwordx4 v[210:211], off
	v_lshl_add_u64 v[210:211], v[212:213], 0, s[36:37]
	s_add_i32 m0, s17, 0x2000
	s_add_i32 s17, s54, s62
	global_load_lds_dwordx4 v[210:211], off
	v_lshl_add_u64 v[210:211], v[214:215], 0, s[36:37]
	s_mov_b32 m0, s17
	s_nop 0
	global_load_lds_dwordx4 v[210:211], off
	v_lshl_add_u64 v[210:211], v[216:217], 0, s[36:37]
	s_add_i32 m0, s17, 0x2000
	s_nop 0
	global_load_lds_dwordx4 v[210:211], off
	v_lshl_add_u64 v[210:211], v[218:219], 0, s[36:37]
	s_mov_b32 m0, s95
	s_nop 0
	global_load_lds_dwordx4 v[210:211], off
	v_lshl_add_u64 v[210:211], v[220:221], 0, s[36:37]
	s_mov_b32 m0, s80
	s_nop 0
	global_load_lds_dwordx4 v[210:211], off
	s_waitcnt vmcnt(8)
	s_waitcnt lgkmcnt(0)
	s_barrier
	s_setprio 1
	s_waitcnt lgkmcnt(0)
	v_mfma_i32_16x16x64_i8 v[62:65], v[146:149], v[178:181], v[62:65]
	v_mfma_i32_16x16x64_i8 v[58:61], v[154:157], v[178:181], v[58:61]
	v_mfma_i32_16x16x64_i8 v[54:57], v[146:149], v[186:189], v[54:57]
	v_mfma_i32_16x16x64_i8 v[50:53], v[154:157], v[186:189], v[50:53]
	v_mfma_i32_16x16x64_i8 v[42:45], v[146:149], v[194:197], v[42:45]
	v_mfma_i32_16x16x64_i8 v[34:37], v[154:157], v[194:197], v[34:37]
	v_mfma_i32_16x16x64_i8 v[26:29], v[146:149], v[202:205], v[26:29]
	v_mfma_i32_16x16x64_i8 v[18:21], v[154:157], v[202:205], v[18:21]
	v_mfma_i32_16x16x64_i8 v[62:65], v[150:153], v[182:185], v[62:65]
	v_mfma_i32_16x16x64_i8 v[58:61], v[158:161], v[182:185], v[58:61]
	v_mfma_i32_16x16x64_i8 v[54:57], v[150:153], v[190:193], v[54:57]
	v_mfma_i32_16x16x64_i8 v[50:53], v[158:161], v[190:193], v[50:53]
	v_mfma_i32_16x16x64_i8 v[42:45], v[150:153], v[198:201], v[42:45]
	v_mfma_i32_16x16x64_i8 v[34:37], v[158:161], v[198:201], v[34:37]
	v_mfma_i32_16x16x64_i8 v[26:29], v[150:153], v[206:209], v[26:29]
	v_mfma_i32_16x16x64_i8 v[18:21], v[158:161], v[206:209], v[18:21]
	s_setprio 0
	s_setprio 1
	v_mfma_i32_16x16x64_i8 v[46:49], v[162:165], v[178:181], v[46:49]
	v_mfma_i32_16x16x64_i8 v[38:41], v[170:173], v[178:181], v[38:41]
	v_mfma_i32_16x16x64_i8 v[30:33], v[162:165], v[186:189], v[30:33]
	v_mfma_i32_16x16x64_i8 v[22:25], v[170:173], v[186:189], v[22:25]
	v_mfma_i32_16x16x64_i8 v[14:17], v[162:165], v[194:197], v[14:17]
	v_mfma_i32_16x16x64_i8 v[10:13], v[170:173], v[194:197], v[10:13]
	v_mfma_i32_16x16x64_i8 v[6:9], v[162:165], v[202:205], v[6:9]
	v_mfma_i32_16x16x64_i8 v[2:5], v[170:173], v[202:205], v[2:5]
	v_mfma_i32_16x16x64_i8 v[46:49], v[166:169], v[182:185], v[46:49]
	v_mfma_i32_16x16x64_i8 v[38:41], v[174:177], v[182:185], v[38:41]
	s_barrier
	v_mfma_i32_16x16x64_i8 v[30:33], v[166:169], v[190:193], v[30:33]
	v_mfma_i32_16x16x64_i8 v[22:25], v[174:177], v[190:193], v[22:25]
	v_mfma_i32_16x16x64_i8 v[14:17], v[166:169], v[198:201], v[14:17]
	v_mfma_i32_16x16x64_i8 v[10:13], v[174:177], v[198:201], v[10:13]
	v_mfma_i32_16x16x64_i8 v[6:9], v[166:169], v[206:209], v[6:9]
	v_mfma_i32_16x16x64_i8 v[2:5], v[174:177], v[206:209], v[2:5]
	s_setprio 0
	s_nop 0
	s_add_u32 s46, s46, 0x100
	s_addc_u32 s47, s47, 0
	s_add_u32 vcc_lo, vcc_lo, 0x100
	s_addc_u32 vcc_hi, vcc_hi, 0
	s_cmp_ge_i32 s16, s90
	s_mov_b32 s50, s16
	s_cbranch_scc0 .LBB0_895
	v_cvt_f32_i32_e32 v220, v126
	v_cvt_f32_i32_e32 v221, v127
	v_cvt_f32_i32_e32 v218, v128
	v_cvt_f32_i32_e32 v219, v129
	v_cvt_f32_i32_e32 v224, v122
	v_cvt_f32_i32_e32 v225, v123
	v_cvt_f32_i32_e32 v222, v124
	v_cvt_f32_i32_e32 v223, v125
	v_cvt_f32_i32_e32 v212, v110
	v_cvt_f32_i32_e32 v213, v111
	v_cvt_f32_i32_e32 v210, v112
	v_cvt_f32_i32_e32 v211, v113
	v_cvt_f32_i32_e32 v216, v102
	v_cvt_f32_i32_e32 v217, v103
	v_cvt_f32_i32_e32 v214, v104
	v_cvt_f32_i32_e32 v215, v105
	v_cvt_f32_i32_e32 v204, v118
	v_cvt_f32_i32_e32 v205, v119
	v_cvt_f32_i32_e32 v202, v120
	v_cvt_f32_i32_e32 v203, v121
	v_cvt_f32_i32_e32 v208, v114
	v_cvt_f32_i32_e32 v209, v115
	v_cvt_f32_i32_e32 v206, v116
	v_cvt_f32_i32_e32 v207, v117
	v_cvt_f32_i32_e32 v198, v94
	v_cvt_f32_i32_e32 v199, v95
	v_cvt_f32_i32_e32 v194, v96
	v_cvt_f32_i32_e32 v195, v97
	v_cvt_f32_i32_e32 v200, v86
	v_cvt_f32_i32_e32 v201, v87
	v_cvt_f32_i32_e32 v196, v88
	v_cvt_f32_i32_e32 v197, v89
	v_cvt_f32_i32_e32 v188, v106
	v_cvt_f32_i32_e32 v189, v107
	v_cvt_f32_i32_e32 v186, v108
	v_cvt_f32_i32_e32 v187, v109
	v_cvt_f32_i32_e32 v192, v98
	v_cvt_f32_i32_e32 v193, v99
	v_cvt_f32_i32_e32 v190, v100
	v_cvt_f32_i32_e32 v191, v101
	v_cvt_f32_i32_e32 v182, v78
	v_cvt_f32_i32_e32 v183, v79
	v_cvt_f32_i32_e32 v178, v80
	v_cvt_f32_i32_e32 v179, v81
	v_cvt_f32_i32_e32 v184, v74
	v_cvt_f32_i32_e32 v185, v75
	v_cvt_f32_i32_e32 v180, v76
	v_cvt_f32_i32_e32 v181, v77
	v_cvt_f32_i32_e32 v170, v90
	v_cvt_f32_i32_e32 v171, v91
	v_cvt_f32_i32_e32 v168, v92
	v_cvt_f32_i32_e32 v169, v93
	v_cvt_f32_i32_e32 v174, v82
	v_cvt_f32_i32_e32 v175, v83
	v_cvt_f32_i32_e32 v172, v84
	v_cvt_f32_i32_e32 v173, v85
	v_cvt_f32_i32_e32 v164, v70
	v_cvt_f32_i32_e32 v165, v71
	v_cvt_f32_i32_e32 v160, v72
	v_cvt_f32_i32_e32 v161, v73
	v_cvt_f32_i32_e32 v166, v66
	v_cvt_f32_i32_e32 v167, v67
	v_cvt_f32_i32_e32 v162, v68
	v_cvt_f32_i32_e32 v163, v69
	v_cvt_f32_i32_e32 v154, v62
	v_cvt_f32_i32_e32 v155, v63
	v_cvt_f32_i32_e32 v152, v64
	v_cvt_f32_i32_e32 v153, v65
	v_cvt_f32_i32_e32 v158, v58
	v_cvt_f32_i32_e32 v159, v59
	v_cvt_f32_i32_e32 v156, v60
	v_cvt_f32_i32_e32 v157, v61
	v_cvt_f32_i32_e32 v148, v46
	v_cvt_f32_i32_e32 v149, v47
	v_cvt_f32_i32_e32 v128, v48
	v_cvt_f32_i32_e32 v129, v49
	v_cvt_f32_i32_e32 v150, v38
	v_cvt_f32_i32_e32 v151, v39
	v_cvt_f32_i32_e32 v146, v40
	v_cvt_f32_i32_e32 v147, v41
	v_cvt_f32_i32_e32 v122, v54
	v_cvt_f32_i32_e32 v123, v55
	v_cvt_f32_i32_e32 v120, v56
	v_cvt_f32_i32_e32 v121, v57
	v_cvt_f32_i32_e32 v126, v50
	v_cvt_f32_i32_e32 v127, v51
	v_cvt_f32_i32_e32 v124, v52
	v_cvt_f32_i32_e32 v125, v53
	v_cvt_f32_i32_e32 v114, v30
	v_cvt_f32_i32_e32 v115, v31
	v_cvt_f32_i32_e32 v110, v32
	v_cvt_f32_i32_e32 v111, v33
	v_cvt_f32_i32_e32 v116, v22
	v_cvt_f32_i32_e32 v117, v23
	v_cvt_f32_i32_e32 v112, v24
	v_cvt_f32_i32_e32 v113, v25
	v_cvt_f32_i32_e32 v102, v42
	v_cvt_f32_i32_e32 v103, v43
	v_cvt_f32_i32_e32 v100, v44
	v_cvt_f32_i32_e32 v101, v45
	v_cvt_f32_i32_e32 v106, v34
	v_cvt_f32_i32_e32 v107, v35
	v_cvt_f32_i32_e32 v104, v36
	v_cvt_f32_i32_e32 v105, v37
	v_cvt_f32_i32_e32 v96, v14
	v_cvt_f32_i32_e32 v97, v15
	v_cvt_f32_i32_e32 v92, v16
	v_cvt_f32_i32_e32 v93, v17
	v_cvt_f32_i32_e32 v98, v10
	v_cvt_f32_i32_e32 v99, v11
	v_cvt_f32_i32_e32 v94, v12
	v_cvt_f32_i32_e32 v95, v13
	v_cvt_f32_i32_e32 v52, v26
	v_cvt_f32_i32_e32 v53, v27
	v_cvt_f32_i32_e32 v50, v28
	v_cvt_f32_i32_e32 v51, v29
	v_cvt_f32_i32_e32 v56, v18
	v_cvt_f32_i32_e32 v57, v19
	v_cvt_f32_i32_e32 v54, v20
	v_cvt_f32_i32_e32 v55, v21
	v_cvt_f32_i32_e32 v46, v6
	v_cvt_f32_i32_e32 v47, v7
	v_cvt_f32_i32_e32 v42, v8
	v_cvt_f32_i32_e32 v43, v9
	v_cvt_f32_i32_e32 v48, v2
	v_cvt_f32_i32_e32 v49, v3
	v_cvt_f32_i32_e32 v44, v4
	v_cvt_f32_i32_e32 v45, v5

.LBB0_1087:
	v_add_u32_e32 v138, s80, v188
	ds_read_b128 v[148:151], v138
	ds_read_b128 v[152:155], v138 offset:1024
	ds_read_b128 v[156:159], v138 offset:2048
	ds_read_b128 v[160:163], v138 offset:3072
	v_add_u32_e32 v138, s81, v188
	ds_read_b128 v[164:167], v138
	ds_read_b128 v[168:171], v138 offset:1024
	ds_read_b128 v[172:175], v138 offset:2048
	ds_read_b128 v[176:179], v138 offset:3072
	s_add_i32 s84, s34, 2
	s_add_u32 s85, s30, 0x80
	s_addc_u32 s35, s31, 0
	s_cmp_eq_u32 s64, s34
	s_cselect_b32 s34, s2, s85
	s_cselect_b32 s35, s3, s35
	s_cselect_b32 s87, s29, s39
	s_cselect_b32 s86, s28, s38
	v_lshl_add_u64 v[184:185], s[30:31], 0, v[140:141]
	s_add_i32 m0, s50, 0xc000
	ds_read_b128 v[180:183], v189
	ds_read_b128 v[190:193], v189 offset:1024
	ds_read_b128 v[194:197], v189 offset:2048
	ds_read_b128 v[198:201], v189 offset:3072
	ds_read_b128 v[202:205], v189 offset:4096
	ds_read_b128 v[206:209], v189 offset:5120
	ds_read_b128 v[210:213], v189 offset:6144
	ds_read_b128 v[214:217], v189 offset:7168
	global_load_lds_dwordx4 v[184:185], off
	v_lshl_add_u64 v[184:185], s[30:31], 0, v[142:143]
	s_add_i32 m0, s50, 0xe000
	s_nop 0
	global_load_lds_dwordx4 v[184:185], off
	s_waitcnt vmcnt(8)
	s_waitcnt lgkmcnt(0)
	s_barrier
	s_setprio 1
	s_waitcnt lgkmcnt(0)
	v_mfma_i32_16x16x64_i8 v[126:129], v[148:151], v[180:183], v[126:129]
	v_mfma_i32_16x16x64_i8 v[122:125], v[156:159], v[180:183], v[122:125]
	v_mfma_i32_16x16x64_i8 v[118:121], v[148:151], v[194:197], v[118:121]
	v_mfma_i32_16x16x64_i8 v[114:117], v[156:159], v[194:197], v[114:117]
	v_mfma_i32_16x16x64_i8 v[106:109], v[148:151], v[202:205], v[106:109]
	v_mfma_i32_16x16x64_i8 v[98:101], v[156:159], v[202:205], v[98:101]
	v_mfma_i32_16x16x64_i8 v[90:93], v[148:151], v[210:213], v[90:93]
	v_mfma_i32_16x16x64_i8 v[82:85], v[156:159], v[210:213], v[82:85]
	v_mfma_i32_16x16x64_i8 v[126:129], v[152:155], v[190:193], v[126:129]
	v_mfma_i32_16x16x64_i8 v[122:125], v[160:163], v[190:193], v[122:125]
	v_mfma_i32_16x16x64_i8 v[118:121], v[152:155], v[198:201], v[118:121]
	v_mfma_i32_16x16x64_i8 v[114:117], v[160:163], v[198:201], v[114:117]
	v_mfma_i32_16x16x64_i8 v[106:109], v[152:155], v[206:209], v[106:109]
	v_mfma_i32_16x16x64_i8 v[98:101], v[160:163], v[206:209], v[98:101]
	v_mfma_i32_16x16x64_i8 v[90:93], v[152:155], v[214:217], v[90:93]
	v_mfma_i32_16x16x64_i8 v[82:85], v[160:163], v[214:217], v[82:85]
	s_setprio 0
	s_setprio 1
	v_mfma_i32_16x16x64_i8 v[110:113], v[164:167], v[180:183], v[110:113]
	v_mfma_i32_16x16x64_i8 v[102:105], v[172:175], v[180:183], v[102:105]
	v_mfma_i32_16x16x64_i8 v[94:97], v[164:167], v[194:197], v[94:97]
	v_mfma_i32_16x16x64_i8 v[86:89], v[172:175], v[194:197], v[86:89]
	v_mfma_i32_16x16x64_i8 v[78:81], v[164:167], v[202:205], v[78:81]
	v_mfma_i32_16x16x64_i8 v[74:77], v[172:175], v[202:205], v[74:77]
	v_mfma_i32_16x16x64_i8 v[70:73], v[164:167], v[210:213], v[70:73]
	v_mfma_i32_16x16x64_i8 v[66:69], v[172:175], v[210:213], v[66:69]
	v_mfma_i32_16x16x64_i8 v[110:113], v[168:171], v[190:193], v[110:113]
	v_mfma_i32_16x16x64_i8 v[102:105], v[176:179], v[190:193], v[102:105]
	s_barrier
	v_mfma_i32_16x16x64_i8 v[94:97], v[168:171], v[198:201], v[94:97]
	v_mfma_i32_16x16x64_i8 v[86:89], v[176:179], v[198:201], v[86:89]
	v_mfma_i32_16x16x64_i8 v[78:81], v[168:171], v[206:209], v[78:81]
	v_mfma_i32_16x16x64_i8 v[74:77], v[176:179], v[206:209], v[74:77]
	v_mfma_i32_16x16x64_i8 v[70:73], v[168:171], v[214:217], v[70:73]
	v_mfma_i32_16x16x64_i8 v[66:69], v[176:179], v[214:217], v[66:69]
	s_setprio 0
	s_nop 0
	s_add_i32 s85, s80, s47
	v_lshl_add_u64 v[184:185], s[86:87], 0, v[132:133]
	s_mov_b32 m0, s85
	ds_read_b128 v[180:183], v189 offset:16384
	ds_read_b128 v[190:193], v189 offset:17408
	ds_read_b128 v[194:197], v189 offset:18432
	ds_read_b128 v[198:201], v189 offset:19456
	ds_read_b128 v[202:205], v189 offset:20480
	ds_read_b128 v[206:209], v189 offset:21504
	ds_read_b128 v[210:213], v189 offset:22528
	ds_read_b128 v[214:217], v189 offset:23552
	global_load_lds_dwordx4 v[184:185], off
	s_add_i32 m0, s85, 0x2000
	v_lshl_add_u64 v[218:219], s[86:87], 0, v[136:137]
	s_add_u32 s86, s86, s6
	s_addc_u32 s87, s87, s7
	s_add_i32 s85, s81, s47
	global_load_lds_dwordx4 v[218:219], off
	v_lshl_add_u64 v[220:221], s[86:87], 0, v[132:133]
	s_mov_b32 m0, s85
	v_lshl_add_u64 v[222:223], s[86:87], 0, v[136:137]
	global_load_lds_dwordx4 v[220:221], off
	s_add_i32 m0, s85, 0x2000
	v_lshl_add_u64 v[224:225], s[34:35], 0, v[130:131]
	global_load_lds_dwordx4 v[222:223], off
	s_mov_b32 m0, s50
	v_lshl_add_u64 v[226:227], s[34:35], 0, v[134:135]
	global_load_lds_dwordx4 v[224:225], off
	s_mov_b32 m0, s51
	s_nop 0
	global_load_lds_dwordx4 v[226:227], off
	s_waitcnt vmcnt(8)
	s_waitcnt lgkmcnt(0)
	s_barrier
	s_setprio 1
	s_waitcnt lgkmcnt(0)
	v_mfma_i32_16x16x64_i8 v[62:65], v[148:151], v[180:183], v[62:65]
	v_mfma_i32_16x16x64_i8 v[58:61], v[156:159], v[180:183], v[58:61]
	v_mfma_i32_16x16x64_i8 v[54:57], v[148:151], v[194:197], v[54:57]
	v_mfma_i32_16x16x64_i8 v[50:53], v[156:159], v[194:197], v[50:53]
	v_mfma_i32_16x16x64_i8 v[42:45], v[148:151], v[202:205], v[42:45]
	v_mfma_i32_16x16x64_i8 v[34:37], v[156:159], v[202:205], v[34:37]
	v_mfma_i32_16x16x64_i8 v[26:29], v[148:151], v[210:213], v[26:29]
	v_mfma_i32_16x16x64_i8 v[18:21], v[156:159], v[210:213], v[18:21]
	v_mfma_i32_16x16x64_i8 v[62:65], v[152:155], v[190:193], v[62:65]
	v_mfma_i32_16x16x64_i8 v[58:61], v[160:163], v[190:193], v[58:61]
	v_mfma_i32_16x16x64_i8 v[54:57], v[152:155], v[198:201], v[54:57]
	v_mfma_i32_16x16x64_i8 v[50:53], v[160:163], v[198:201], v[50:53]
	v_mfma_i32_16x16x64_i8 v[42:45], v[152:155], v[206:209], v[42:45]
	v_mfma_i32_16x16x64_i8 v[34:37], v[160:163], v[206:209], v[34:37]
	v_mfma_i32_16x16x64_i8 v[26:29], v[152:155], v[214:217], v[26:29]
	v_mfma_i32_16x16x64_i8 v[18:21], v[160:163], v[214:217], v[18:21]
	s_setprio 0
	s_setprio 1
	v_mfma_i32_16x16x64_i8 v[46:49], v[164:167], v[180:183], v[46:49]
	v_mfma_i32_16x16x64_i8 v[38:41], v[172:175], v[180:183], v[38:41]
	v_mfma_i32_16x16x64_i8 v[30:33], v[164:167], v[194:197], v[30:33]
	v_mfma_i32_16x16x64_i8 v[22:25], v[172:175], v[194:197], v[22:25]
	v_mfma_i32_16x16x64_i8 v[14:17], v[164:167], v[202:205], v[14:17]
	v_mfma_i32_16x16x64_i8 v[10:13], v[172:175], v[202:205], v[10:13]
	v_mfma_i32_16x16x64_i8 v[6:9], v[164:167], v[210:213], v[6:9]
	v_mfma_i32_16x16x64_i8 v[2:5], v[172:175], v[210:213], v[2:5]
	v_mfma_i32_16x16x64_i8 v[46:49], v[168:171], v[190:193], v[46:49]
	v_mfma_i32_16x16x64_i8 v[38:41], v[176:179], v[190:193], v[38:41]
	s_barrier
	v_mfma_i32_16x16x64_i8 v[30:33], v[168:171], v[198:201], v[30:33]
	v_mfma_i32_16x16x64_i8 v[22:25], v[176:179], v[198:201], v[22:25]
	v_mfma_i32_16x16x64_i8 v[14:17], v[168:171], v[206:209], v[14:17]
	v_mfma_i32_16x16x64_i8 v[10:13], v[176:179], v[206:209], v[10:13]
	v_mfma_i32_16x16x64_i8 v[6:9], v[168:171], v[214:217], v[6:9]
	v_mfma_i32_16x16x64_i8 v[2:5], v[176:179], v[214:217], v[2:5]
	s_setprio 0
	s_nop 0
	s_add_i32 s85, 0, 0x18000
	v_add_u32_e32 v138, s85, v188
	s_add_i32 s86, 0, 0x1c000
	ds_read_b128 v[148:151], v138
	ds_read_b128 v[152:155], v138 offset:1024
	ds_read_b128 v[156:159], v138 offset:2048
	ds_read_b128 v[160:163], v138 offset:3072
	v_add_u32_e32 v138, s86, v188
	ds_read_b128 v[164:167], v138
	ds_read_b128 v[168:171], v138 offset:1024
	ds_read_b128 v[172:175], v138 offset:2048
	ds_read_b128 v[176:179], v138 offset:3072
	s_add_u32 s34, s34, s6
	s_addc_u32 s35, s35, s7
	s_mov_b32 m0, s54
	v_lshl_add_u64 v[228:229], s[34:35], 0, v[130:131]
	ds_read_b128 v[180:183], v189 offset:32768
	ds_read_b128 v[190:193], v189 offset:33792
	ds_read_b128 v[194:197], v189 offset:34816
	ds_read_b128 v[198:201], v189 offset:35840
	ds_read_b128 v[202:205], v189 offset:36864
	ds_read_b128 v[206:209], v189 offset:37888
	ds_read_b128 v[210:213], v189 offset:38912
	ds_read_b128 v[214:217], v189 offset:39936
	global_load_lds_dwordx4 v[228:229], off
	v_lshl_add_u64 v[228:229], s[34:35], 0, v[134:135]
	s_mov_b32 m0, s55
	s_nop 0
	global_load_lds_dwordx4 v[228:229], off
	s_waitcnt vmcnt(8)
	s_waitcnt lgkmcnt(0)
	s_barrier
	s_setprio 1
	s_waitcnt lgkmcnt(0)
	v_mfma_i32_16x16x64_i8 v[126:129], v[148:151], v[180:183], v[126:129]
	v_mfma_i32_16x16x64_i8 v[122:125], v[156:159], v[180:183], v[122:125]
	v_mfma_i32_16x16x64_i8 v[118:121], v[148:151], v[194:197], v[118:121]
	v_mfma_i32_16x16x64_i8 v[114:117], v[156:159], v[194:197], v[114:117]
	v_mfma_i32_16x16x64_i8 v[106:109], v[148:151], v[202:205], v[106:109]
	v_mfma_i32_16x16x64_i8 v[98:101], v[156:159], v[202:205], v[98:101]
	v_mfma_i32_16x16x64_i8 v[90:93], v[148:151], v[210:213], v[90:93]
	v_mfma_i32_16x16x64_i8 v[82:85], v[156:159], v[210:213], v[82:85]
	v_mfma_i32_16x16x64_i8 v[126:129], v[152:155], v[190:193], v[126:129]
	v_mfma_i32_16x16x64_i8 v[122:125], v[160:163], v[190:193], v[122:125]
	v_mfma_i32_16x16x64_i8 v[118:121], v[152:155], v[198:201], v[118:121]
	v_mfma_i32_16x16x64_i8 v[114:117], v[160:163], v[198:201], v[114:117]
	v_mfma_i32_16x16x64_i8 v[106:109], v[152:155], v[206:209], v[106:109]
	v_mfma_i32_16x16x64_i8 v[98:101], v[160:163], v[206:209], v[98:101]
	v_mfma_i32_16x16x64_i8 v[90:93], v[152:155], v[214:217], v[90:93]
	v_mfma_i32_16x16x64_i8 v[82:85], v[160:163], v[214:217], v[82:85]
	s_setprio 0
	s_setprio 1
	v_mfma_i32_16x16x64_i8 v[110:113], v[164:167], v[180:183], v[110:113]
	v_mfma_i32_16x16x64_i8 v[102:105], v[172:175], v[180:183], v[102:105]
	v_mfma_i32_16x16x64_i8 v[94:97], v[164:167], v[194:197], v[94:97]
	v_mfma_i32_16x16x64_i8 v[86:89], v[172:175], v[194:197], v[86:89]
	v_mfma_i32_16x16x64_i8 v[78:81], v[164:167], v[202:205], v[78:81]
	v_mfma_i32_16x16x64_i8 v[74:77], v[172:175], v[202:205], v[74:77]
	v_mfma_i32_16x16x64_i8 v[70:73], v[164:167], v[210:213], v[70:73]
	v_mfma_i32_16x16x64_i8 v[66:69], v[172:175], v[210:213], v[66:69]
	v_mfma_i32_16x16x64_i8 v[110:113], v[168:171], v[190:193], v[110:113]
	v_mfma_i32_16x16x64_i8 v[102:105], v[176:179], v[190:193], v[102:105]
	s_barrier
	v_mfma_i32_16x16x64_i8 v[94:97], v[168:171], v[198:201], v[94:97]
	v_mfma_i32_16x16x64_i8 v[86:89], v[176:179], v[198:201], v[86:89]
	v_mfma_i32_16x16x64_i8 v[78:81], v[168:171], v[206:209], v[78:81]
	v_mfma_i32_16x16x64_i8 v[74:77], v[176:179], v[206:209], v[74:77]
	v_mfma_i32_16x16x64_i8 v[70:73], v[168:171], v[214:217], v[70:73]
	v_mfma_i32_16x16x64_i8 v[66:69], v[176:179], v[214:217], v[66:69]
	s_setprio 0
	s_nop 0
	s_add_i32 s34, s85, s47
	v_lshl_add_u64 v[184:185], v[184:185], 0, s[22:23]
	s_mov_b32 m0, s34
	ds_read_b128 v[180:183], v189 offset:49152
	ds_read_b128 v[190:193], v189 offset:50176
	ds_read_b128 v[194:197], v189 offset:51200
	ds_read_b128 v[198:201], v189 offset:52224
	ds_read_b128 v[202:205], v189 offset:53248
	ds_read_b128 v[206:209], v189 offset:54272
	ds_read_b128 v[210:213], v189 offset:55296
	ds_read_b128 v[214:217], v189 offset:56320
	global_load_lds_dwordx4 v[184:185], off
	v_lshl_add_u64 v[184:185], v[218:219], 0, s[22:23]
	s_add_i32 m0, s34, 0x2000
	s_add_i32 s34, s86, s47
	global_load_lds_dwordx4 v[184:185], off
	v_lshl_add_u64 v[184:185], v[220:221], 0, s[22:23]
	s_mov_b32 m0, s34
	s_nop 0
	global_load_lds_dwordx4 v[184:185], off
	v_lshl_add_u64 v[184:185], v[222:223], 0, s[22:23]
	s_add_i32 m0, s34, 0x2000
	s_nop 0
	global_load_lds_dwordx4 v[184:185], off
	v_lshl_add_u64 v[184:185], v[224:225], 0, s[22:23]
	s_mov_b32 m0, s59
	s_nop 0
	global_load_lds_dwordx4 v[184:185], off
	v_lshl_add_u64 v[184:185], v[226:227], 0, s[22:23]
	s_mov_b32 m0, s60
	s_nop 0
	global_load_lds_dwordx4 v[184:185], off
	s_waitcnt vmcnt(8)
	s_waitcnt lgkmcnt(0)
	s_barrier
	s_setprio 1
	s_waitcnt lgkmcnt(0)
	v_mfma_i32_16x16x64_i8 v[62:65], v[148:151], v[180:183], v[62:65]
	v_mfma_i32_16x16x64_i8 v[58:61], v[156:159], v[180:183], v[58:61]
	v_mfma_i32_16x16x64_i8 v[54:57], v[148:151], v[194:197], v[54:57]
	v_mfma_i32_16x16x64_i8 v[50:53], v[156:159], v[194:197], v[50:53]
	v_mfma_i32_16x16x64_i8 v[42:45], v[148:151], v[202:205], v[42:45]
	v_mfma_i32_16x16x64_i8 v[34:37], v[156:159], v[202:205], v[34:37]
	v_mfma_i32_16x16x64_i8 v[26:29], v[148:151], v[210:213], v[26:29]
	v_mfma_i32_16x16x64_i8 v[18:21], v[156:159], v[210:213], v[18:21]
	v_mfma_i32_16x16x64_i8 v[62:65], v[152:155], v[190:193], v[62:65]
	v_mfma_i32_16x16x64_i8 v[58:61], v[160:163], v[190:193], v[58:61]
	v_mfma_i32_16x16x64_i8 v[54:57], v[152:155], v[198:201], v[54:57]
	v_mfma_i32_16x16x64_i8 v[50:53], v[160:163], v[198:201], v[50:53]
	v_mfma_i32_16x16x64_i8 v[42:45], v[152:155], v[206:209], v[42:45]
	v_mfma_i32_16x16x64_i8 v[34:37], v[160:163], v[206:209], v[34:37]
	v_mfma_i32_16x16x64_i8 v[26:29], v[152:155], v[214:217], v[26:29]
	v_mfma_i32_16x16x64_i8 v[18:21], v[160:163], v[214:217], v[18:21]
	s_setprio 0
	s_setprio 1
	v_mfma_i32_16x16x64_i8 v[46:49], v[164:167], v[180:183], v[46:49]
	v_mfma_i32_16x16x64_i8 v[38:41], v[172:175], v[180:183], v[38:41]
	v_mfma_i32_16x16x64_i8 v[30:33], v[164:167], v[194:197], v[30:33]
	v_mfma_i32_16x16x64_i8 v[22:25], v[172:175], v[194:197], v[22:25]
	v_mfma_i32_16x16x64_i8 v[14:17], v[164:167], v[202:205], v[14:17]
	v_mfma_i32_16x16x64_i8 v[10:13], v[172:175], v[202:205], v[10:13]
	v_mfma_i32_16x16x64_i8 v[6:9], v[164:167], v[210:213], v[6:9]
	v_mfma_i32_16x16x64_i8 v[2:5], v[172:175], v[210:213], v[2:5]
	v_mfma_i32_16x16x64_i8 v[46:49], v[168:171], v[190:193], v[46:49]
	v_mfma_i32_16x16x64_i8 v[38:41], v[176:179], v[190:193], v[38:41]
	s_barrier
	v_mfma_i32_16x16x64_i8 v[30:33], v[168:171], v[198:201], v[30:33]
	v_mfma_i32_16x16x64_i8 v[22:25], v[176:179], v[198:201], v[22:25]
	v_mfma_i32_16x16x64_i8 v[14:17], v[168:171], v[206:209], v[14:17]
	v_mfma_i32_16x16x64_i8 v[10:13], v[176:179], v[206:209], v[10:13]
	v_mfma_i32_16x16x64_i8 v[6:9], v[168:171], v[214:217], v[6:9]
	v_mfma_i32_16x16x64_i8 v[2:5], v[176:179], v[214:217], v[2:5]
	s_setprio 0
	s_nop 0
	s_add_u32 s30, s30, 0x100
	s_addc_u32 s31, s31, 0
	s_add_u32 s38, s38, 0x100
	s_addc_u32 s39, s39, 0
	s_cmp_ge_i32 s84, s61
	s_mov_b32 s34, s84
	s_cbranch_scc0 .LBB0_1087
	v_cvt_f32_i32_e32 v172, v126
	v_cvt_f32_i32_e32 v173, v127
	v_cvt_f32_i32_e32 v170, v128
	v_cvt_f32_i32_e32 v171, v129
	v_cvt_f32_i32_e32 v174, v122
	v_cvt_f32_i32_e32 v175, v123
	v_cvt_f32_i32_e32 v176, v124
	v_cvt_f32_i32_e32 v177, v125
	v_cvt_f32_i32_e32 v180, v110
	v_cvt_f32_i32_e32 v181, v111
	v_cvt_f32_i32_e32 v182, v112
	v_cvt_f32_i32_e32 v183, v113
	v_cvt_f32_i32_e32 v178, v102
	v_cvt_f32_i32_e32 v179, v103
	v_cvt_f32_i32_e32 v184, v104
	v_cvt_f32_i32_e32 v185, v105
	v_cvt_f32_i32_e32 v152, v118
	v_cvt_f32_i32_e32 v153, v119
	v_cvt_f32_i32_e32 v154, v120
	v_cvt_f32_i32_e32 v155, v121
	v_cvt_f32_i32_e32 v156, v114
	v_cvt_f32_i32_e32 v157, v115
	v_cvt_f32_i32_e32 v158, v116
	v_cvt_f32_i32_e32 v159, v117
	v_cvt_f32_i32_e32 v160, v94
	v_cvt_f32_i32_e32 v161, v95
	v_cvt_f32_i32_e32 v162, v96
	v_cvt_f32_i32_e32 v163, v97
	v_cvt_f32_i32_e32 v164, v86
	v_cvt_f32_i32_e32 v165, v87
	v_cvt_f32_i32_e32 v166, v88
	v_cvt_f32_i32_e32 v167, v89
	v_cvt_f32_i32_e32 v118, v106
	v_cvt_f32_i32_e32 v119, v107
	v_cvt_f32_i32_e32 v120, v108
	v_cvt_f32_i32_e32 v121, v109
	v_cvt_f32_i32_e32 v122, v98
	v_cvt_f32_i32_e32 v123, v99
	v_cvt_f32_i32_e32 v124, v100
	v_cvt_f32_i32_e32 v125, v101
	v_cvt_f32_i32_e32 v126, v78
	v_cvt_f32_i32_e32 v127, v79
	v_cvt_f32_i32_e32 v128, v80
	v_cvt_f32_i32_e32 v129, v81
	v_cvt_f32_i32_e32 v148, v74
	v_cvt_f32_i32_e32 v149, v75
	v_cvt_f32_i32_e32 v150, v76
	v_cvt_f32_i32_e32 v151, v77
	v_cvt_f32_i32_e32 v102, v90
	v_cvt_f32_i32_e32 v103, v91
	v_cvt_f32_i32_e32 v104, v92
	v_cvt_f32_i32_e32 v105, v93
	v_cvt_f32_i32_e32 v106, v82
	v_cvt_f32_i32_e32 v107, v83
	v_cvt_f32_i32_e32 v108, v84
	v_cvt_f32_i32_e32 v109, v85
	v_cvt_f32_i32_e32 v110, v70
	v_cvt_f32_i32_e32 v111, v71
	v_cvt_f32_i32_e32 v112, v72
	v_cvt_f32_i32_e32 v113, v73
	v_cvt_f32_i32_e32 v114, v66
	v_cvt_f32_i32_e32 v115, v67
	v_cvt_f32_i32_e32 v116, v68
	v_cvt_f32_i32_e32 v117, v69
	v_cvt_f32_i32_e32 v82, v62
	v_cvt_f32_i32_e32 v83, v63
	v_cvt_f32_i32_e32 v84, v64
	v_cvt_f32_i32_e32 v85, v65
	v_cvt_f32_i32_e32 v86, v58
	v_cvt_f32_i32_e32 v87, v59
	v_cvt_f32_i32_e32 v88, v60
	v_cvt_f32_i32_e32 v89, v61
	v_cvt_f32_i32_e32 v92, v46
	v_cvt_f32_i32_e32 v93, v47
	v_cvt_f32_i32_e32 v94, v48
	v_cvt_f32_i32_e32 v95, v49
	v_cvt_f32_i32_e32 v96, v38
	v_cvt_f32_i32_e32 v97, v39
	v_cvt_f32_i32_e32 v98, v40
	v_cvt_f32_i32_e32 v99, v41
	v_cvt_f32_i32_e32 v66, v54
	v_cvt_f32_i32_e32 v67, v55
	v_cvt_f32_i32_e32 v68, v56
	v_cvt_f32_i32_e32 v69, v57
	v_cvt_f32_i32_e32 v70, v50
	v_cvt_f32_i32_e32 v71, v51
	v_cvt_f32_i32_e32 v72, v52
	v_cvt_f32_i32_e32 v73, v53
	v_cvt_f32_i32_e32 v74, v30
	v_cvt_f32_i32_e32 v75, v31
	v_cvt_f32_i32_e32 v76, v32
	v_cvt_f32_i32_e32 v77, v33
	v_cvt_f32_i32_e32 v78, v22
	v_cvt_f32_i32_e32 v79, v23
	v_cvt_f32_i32_e32 v80, v24
	v_cvt_f32_i32_e32 v81, v25
	v_cvt_f32_i32_e32 v50, v42
	v_cvt_f32_i32_e32 v51, v43
	v_cvt_f32_i32_e32 v52, v44
	v_cvt_f32_i32_e32 v53, v45
	v_cvt_f32_i32_e32 v54, v34
	v_cvt_f32_i32_e32 v55, v35
	v_cvt_f32_i32_e32 v56, v36
	v_cvt_f32_i32_e32 v57, v37
	v_cvt_f32_i32_e32 v58, v14
	v_cvt_f32_i32_e32 v59, v15
	v_cvt_f32_i32_e32 v60, v16
	v_cvt_f32_i32_e32 v61, v17
	v_cvt_f32_i32_e32 v62, v10
	v_cvt_f32_i32_e32 v63, v11
	v_cvt_f32_i32_e32 v64, v12
	v_cvt_f32_i32_e32 v65, v13
	v_cvt_f32_i32_e32 v34, v26
	v_cvt_f32_i32_e32 v35, v27
	v_cvt_f32_i32_e32 v36, v28
	v_cvt_f32_i32_e32 v37, v29
	v_cvt_f32_i32_e32 v38, v18
	v_cvt_f32_i32_e32 v39, v19
	v_cvt_f32_i32_e32 v40, v20
	v_cvt_f32_i32_e32 v41, v21
	v_cvt_f32_i32_e32 v42, v6
	v_cvt_f32_i32_e32 v43, v7
	v_cvt_f32_i32_e32 v44, v8
	v_cvt_f32_i32_e32 v45, v9
	v_cvt_f32_i32_e32 v46, v2
	v_cvt_f32_i32_e32 v47, v3
	v_cvt_f32_i32_e32 v48, v4
	v_cvt_f32_i32_e32 v49, v5

.LBB0_1170:
	s_waitcnt lgkmcnt(0)
	ds_read_b128 v[114:117], v209
	ds_read_b128 v[118:121], v209 offset:1024
	ds_read_b128 v[122:125], v209 offset:2048
	ds_read_b128 v[126:129], v209 offset:3072
	ds_read_b128 v[146:149], v210
	ds_read_b128 v[150:153], v210 offset:1024
	ds_read_b128 v[154:157], v210 offset:2048
	ds_read_b128 v[158:161], v210 offset:3072
	s_add_i32 s92, s42, 2
	s_add_u32 s43, s38, 0x4000
	s_addc_u32 s44, s39, 0
	s_cmp_eq_u32 s81, s42
	s_cselect_b32 s45, s5, s44
	s_cselect_b32 s44, s4, s43
	s_cselect_b32 s94, s36, s90
	s_cselect_b32 s95, s37, s91
	s_add_u32 s42, s44, 0x8000
	s_addc_u32 s43, s45, 0
	v_lshl_add_u64 v[218:219], s[38:39], 0, v[170:171]
	s_add_i32 m0, s55, 0xc000
	ds_read_b128 v[178:181], v211
	ds_read_b128 v[182:185], v211 offset:1024
	ds_read_b128 v[186:189], v211 offset:2048
	ds_read_b128 v[190:193], v211 offset:3072
	ds_read_b128 v[194:197], v211 offset:4096
	ds_read_b128 v[198:201], v211 offset:5120
	ds_read_b128 v[202:205], v211 offset:6144
	ds_read_b128 v[214:217], v211 offset:7168
	global_load_lds_dwordx4 v[218:219], off
	v_lshl_add_u64 v[218:219], s[38:39], 0, v[172:173]
	s_add_i32 m0, s55, 0xe000
	s_nop 0
	global_load_lds_dwordx4 v[218:219], off
	s_waitcnt vmcnt(8)
	s_waitcnt lgkmcnt(0)
	s_barrier
	s_setprio 1
	s_waitcnt lgkmcnt(0)
	v_mfma_f32_16x16x32_bf16 v[142:145], v[114:117], v[178:181], v[142:145]
	v_mfma_f32_16x16x32_bf16 v[138:141], v[122:125], v[178:181], v[138:141]
	v_mfma_f32_16x16x32_bf16 v[110:113], v[114:117], v[186:189], v[110:113]
	v_mfma_f32_16x16x32_bf16 v[106:109], v[122:125], v[186:189], v[106:109]
	v_mfma_f32_16x16x32_bf16 v[94:97], v[114:117], v[194:197], v[94:97]
	v_mfma_f32_16x16x32_bf16 v[90:93], v[122:125], v[194:197], v[90:93]
	v_mfma_f32_16x16x32_bf16 v[78:81], v[114:117], v[202:205], v[78:81]
	v_mfma_f32_16x16x32_bf16 v[74:77], v[122:125], v[202:205], v[74:77]
	v_mfma_f32_16x16x32_bf16 v[142:145], v[118:121], v[182:185], v[142:145]
	v_mfma_f32_16x16x32_bf16 v[138:141], v[126:129], v[182:185], v[138:141]
	v_mfma_f32_16x16x32_bf16 v[110:113], v[118:121], v[190:193], v[110:113]
	v_mfma_f32_16x16x32_bf16 v[106:109], v[126:129], v[190:193], v[106:109]
	v_mfma_f32_16x16x32_bf16 v[94:97], v[118:121], v[198:201], v[94:97]
	v_mfma_f32_16x16x32_bf16 v[90:93], v[126:129], v[198:201], v[90:93]
	v_mfma_f32_16x16x32_bf16 v[78:81], v[118:121], v[214:217], v[78:81]
	v_mfma_f32_16x16x32_bf16 v[74:77], v[126:129], v[214:217], v[74:77]
	s_setprio 0
	s_setprio 1
	v_mfma_f32_16x16x32_bf16 v[134:137], v[146:149], v[178:181], v[134:137]
	v_mfma_f32_16x16x32_bf16 v[130:133], v[154:157], v[178:181], v[130:133]
	v_mfma_f32_16x16x32_bf16 v[102:105], v[146:149], v[186:189], v[102:105]
	v_mfma_f32_16x16x32_bf16 v[98:101], v[154:157], v[186:189], v[98:101]
	v_mfma_f32_16x16x32_bf16 v[86:89], v[146:149], v[194:197], v[86:89]
	v_mfma_f32_16x16x32_bf16 v[82:85], v[154:157], v[194:197], v[82:85]
	v_mfma_f32_16x16x32_bf16 v[70:73], v[146:149], v[202:205], v[70:73]
	v_mfma_f32_16x16x32_bf16 v[66:69], v[154:157], v[202:205], v[66:69]
	v_mfma_f32_16x16x32_bf16 v[134:137], v[150:153], v[182:185], v[134:137]
	v_mfma_f32_16x16x32_bf16 v[130:133], v[158:161], v[182:185], v[130:133]
	s_barrier
	v_mfma_f32_16x16x32_bf16 v[102:105], v[150:153], v[190:193], v[102:105]
	v_mfma_f32_16x16x32_bf16 v[98:101], v[158:161], v[190:193], v[98:101]
	v_mfma_f32_16x16x32_bf16 v[86:89], v[150:153], v[198:201], v[86:89]
	v_mfma_f32_16x16x32_bf16 v[82:85], v[158:161], v[198:201], v[82:85]
	v_mfma_f32_16x16x32_bf16 v[70:73], v[150:153], v[214:217], v[70:73]
	v_mfma_f32_16x16x32_bf16 v[66:69], v[158:161], v[214:217], v[66:69]
	s_setprio 0
	s_nop 0
	s_add_i32 s93, s84, s54
	v_lshl_add_u64 v[218:219], s[94:95], 0, v[164:165]
	s_mov_b32 m0, s93
	ds_read_b128 v[178:181], v211 offset:16384
	ds_read_b128 v[182:185], v211 offset:17408
	ds_read_b128 v[186:189], v211 offset:18432
	ds_read_b128 v[190:193], v211 offset:19456
	ds_read_b128 v[194:197], v211 offset:20480
	ds_read_b128 v[198:201], v211 offset:21504
	ds_read_b128 v[202:205], v211 offset:22528
	ds_read_b128 v[214:217], v211 offset:23552
	global_load_lds_dwordx4 v[218:219], off
	s_add_i32 m0, s93, 0x2000
	v_lshl_add_u64 v[220:221], s[94:95], 0, v[168:169]
	s_add_u32 s94, s94, s8
	s_addc_u32 s95, s95, s9
	s_add_i32 s93, s85, s54
	global_load_lds_dwordx4 v[220:221], off
	v_lshl_add_u64 v[222:223], s[94:95], 0, v[164:165]
	s_mov_b32 m0, s93
	v_lshl_add_u64 v[224:225], s[94:95], 0, v[168:169]
	global_load_lds_dwordx4 v[222:223], off
	s_add_i32 m0, s93, 0x2000
	v_lshl_add_u64 v[226:227], s[44:45], 0, v[162:163]
	global_load_lds_dwordx4 v[224:225], off
	s_mov_b32 m0, s55
	s_nop 0
	global_load_lds_dwordx4 v[226:227], off
	v_lshl_add_u64 v[226:227], s[44:45], 0, v[166:167]
	s_mov_b32 m0, s56
	s_nop 0
	global_load_lds_dwordx4 v[226:227], off
	s_waitcnt vmcnt(8)
	s_waitcnt lgkmcnt(0)
	s_barrier
	s_setprio 1
	s_waitcnt lgkmcnt(0)
	v_mfma_f32_16x16x32_bf16 v[62:65], v[114:117], v[178:181], v[62:65]
	v_mfma_f32_16x16x32_bf16 v[58:61], v[122:125], v[178:181], v[58:61]
	v_mfma_f32_16x16x32_bf16 v[46:49], v[114:117], v[186:189], v[46:49]
	v_mfma_f32_16x16x32_bf16 v[42:45], v[122:125], v[186:189], v[42:45]
	v_mfma_f32_16x16x32_bf16 v[30:33], v[114:117], v[194:197], v[30:33]
	v_mfma_f32_16x16x32_bf16 v[26:29], v[122:125], v[194:197], v[26:29]
	v_mfma_f32_16x16x32_bf16 v[14:17], v[114:117], v[202:205], v[14:17]
	v_mfma_f32_16x16x32_bf16 v[10:13], v[122:125], v[202:205], v[10:13]
	v_mfma_f32_16x16x32_bf16 v[62:65], v[118:121], v[182:185], v[62:65]
	v_mfma_f32_16x16x32_bf16 v[58:61], v[126:129], v[182:185], v[58:61]
	v_mfma_f32_16x16x32_bf16 v[46:49], v[118:121], v[190:193], v[46:49]
	v_mfma_f32_16x16x32_bf16 v[42:45], v[126:129], v[190:193], v[42:45]
	v_mfma_f32_16x16x32_bf16 v[30:33], v[118:121], v[198:201], v[30:33]
	v_mfma_f32_16x16x32_bf16 v[26:29], v[126:129], v[198:201], v[26:29]
	v_mfma_f32_16x16x32_bf16 v[14:17], v[118:121], v[214:217], v[14:17]
	v_mfma_f32_16x16x32_bf16 v[10:13], v[126:129], v[214:217], v[10:13]
	s_setprio 0
	s_setprio 1
	v_mfma_f32_16x16x32_bf16 v[54:57], v[146:149], v[178:181], v[54:57]
	v_mfma_f32_16x16x32_bf16 v[50:53], v[154:157], v[178:181], v[50:53]
	v_mfma_f32_16x16x32_bf16 v[38:41], v[146:149], v[186:189], v[38:41]
	v_mfma_f32_16x16x32_bf16 v[34:37], v[154:157], v[186:189], v[34:37]
	v_mfma_f32_16x16x32_bf16 v[22:25], v[146:149], v[194:197], v[22:25]
	v_mfma_f32_16x16x32_bf16 v[18:21], v[154:157], v[194:197], v[18:21]
	v_mfma_f32_16x16x32_bf16 v[6:9], v[146:149], v[202:205], v[6:9]
	v_mfma_f32_16x16x32_bf16 v[2:5], v[154:157], v[202:205], v[2:5]
	v_mfma_f32_16x16x32_bf16 v[54:57], v[150:153], v[182:185], v[54:57]
	v_mfma_f32_16x16x32_bf16 v[50:53], v[158:161], v[182:185], v[50:53]
	s_barrier
	v_mfma_f32_16x16x32_bf16 v[38:41], v[150:153], v[190:193], v[38:41]
	v_mfma_f32_16x16x32_bf16 v[34:37], v[158:161], v[190:193], v[34:37]
	v_mfma_f32_16x16x32_bf16 v[22:25], v[150:153], v[198:201], v[22:25]
	v_mfma_f32_16x16x32_bf16 v[18:21], v[158:161], v[198:201], v[18:21]
	v_mfma_f32_16x16x32_bf16 v[6:9], v[150:153], v[214:217], v[6:9]
	v_mfma_f32_16x16x32_bf16 v[2:5], v[158:161], v[214:217], v[2:5]
	s_setprio 0
	s_nop 0
	s_add_i32 s93, 0, 0x18000
	s_add_i32 s94, 0, 0x1c000
	v_add_u32_e32 v126, s93, v207
	v_add_u32_e32 v158, s94, v207
	ds_read_b128 v[114:117], v126
	ds_read_b128 v[118:121], v126 offset:1024
	ds_read_b128 v[122:125], v126 offset:2048
	ds_read_b128 v[126:129], v126 offset:3072
	ds_read_b128 v[146:149], v158
	ds_read_b128 v[150:153], v158 offset:1024
	ds_read_b128 v[154:157], v158 offset:2048
	ds_read_b128 v[158:161], v158 offset:3072
	s_add_u32 s44, s44, 0x4000
	s_addc_u32 s45, s45, 0
	s_mov_b32 m0, s57
	v_lshl_add_u64 v[226:227], s[44:45], 0, v[162:163]
	ds_read_b128 v[178:181], v211 offset:32768
	ds_read_b128 v[182:185], v211 offset:33792
	ds_read_b128 v[186:189], v211 offset:34816
	ds_read_b128 v[190:193], v211 offset:35840
	ds_read_b128 v[194:197], v211 offset:36864
	ds_read_b128 v[198:201], v211 offset:37888
	ds_read_b128 v[202:205], v211 offset:38912
	ds_read_b128 v[214:217], v211 offset:39936
	global_load_lds_dwordx4 v[226:227], off
	v_lshl_add_u64 v[226:227], s[44:45], 0, v[166:167]
	s_mov_b32 m0, s58
	s_nop 0
	global_load_lds_dwordx4 v[226:227], off
	s_waitcnt vmcnt(8)
	s_waitcnt lgkmcnt(0)
	s_barrier
	s_setprio 1
	s_waitcnt lgkmcnt(0)
	v_mfma_f32_16x16x32_bf16 v[142:145], v[114:117], v[178:181], v[142:145]
	v_mfma_f32_16x16x32_bf16 v[138:141], v[122:125], v[178:181], v[138:141]
	v_mfma_f32_16x16x32_bf16 v[110:113], v[114:117], v[186:189], v[110:113]
	v_mfma_f32_16x16x32_bf16 v[106:109], v[122:125], v[186:189], v[106:109]
	v_mfma_f32_16x16x32_bf16 v[94:97], v[114:117], v[194:197], v[94:97]
	v_mfma_f32_16x16x32_bf16 v[90:93], v[122:125], v[194:197], v[90:93]
	v_mfma_f32_16x16x32_bf16 v[78:81], v[114:117], v[202:205], v[78:81]
	v_mfma_f32_16x16x32_bf16 v[74:77], v[122:125], v[202:205], v[74:77]
	v_mfma_f32_16x16x32_bf16 v[142:145], v[118:121], v[182:185], v[142:145]
	v_mfma_f32_16x16x32_bf16 v[138:141], v[126:129], v[182:185], v[138:141]
	v_mfma_f32_16x16x32_bf16 v[110:113], v[118:121], v[190:193], v[110:113]
	v_mfma_f32_16x16x32_bf16 v[106:109], v[126:129], v[190:193], v[106:109]
	v_mfma_f32_16x16x32_bf16 v[94:97], v[118:121], v[198:201], v[94:97]
	v_mfma_f32_16x16x32_bf16 v[90:93], v[126:129], v[198:201], v[90:93]
	v_mfma_f32_16x16x32_bf16 v[78:81], v[118:121], v[214:217], v[78:81]
	v_mfma_f32_16x16x32_bf16 v[74:77], v[126:129], v[214:217], v[74:77]
	s_setprio 0
	s_setprio 1
	v_mfma_f32_16x16x32_bf16 v[134:137], v[146:149], v[178:181], v[134:137]
	v_mfma_f32_16x16x32_bf16 v[130:133], v[154:157], v[178:181], v[130:133]
	v_mfma_f32_16x16x32_bf16 v[102:105], v[146:149], v[186:189], v[102:105]
	v_mfma_f32_16x16x32_bf16 v[98:101], v[154:157], v[186:189], v[98:101]
	v_mfma_f32_16x16x32_bf16 v[86:89], v[146:149], v[194:197], v[86:89]
	v_mfma_f32_16x16x32_bf16 v[82:85], v[154:157], v[194:197], v[82:85]
	v_mfma_f32_16x16x32_bf16 v[70:73], v[146:149], v[202:205], v[70:73]
	v_mfma_f32_16x16x32_bf16 v[66:69], v[154:157], v[202:205], v[66:69]
	v_mfma_f32_16x16x32_bf16 v[134:137], v[150:153], v[182:185], v[134:137]
	v_mfma_f32_16x16x32_bf16 v[130:133], v[158:161], v[182:185], v[130:133]
	s_barrier
	v_mfma_f32_16x16x32_bf16 v[102:105], v[150:153], v[190:193], v[102:105]
	v_mfma_f32_16x16x32_bf16 v[98:101], v[158:161], v[190:193], v[98:101]
	v_mfma_f32_16x16x32_bf16 v[86:89], v[150:153], v[198:201], v[86:89]
	v_mfma_f32_16x16x32_bf16 v[82:85], v[158:161], v[198:201], v[82:85]
	v_mfma_f32_16x16x32_bf16 v[70:73], v[150:153], v[214:217], v[70:73]
	v_mfma_f32_16x16x32_bf16 v[66:69], v[158:161], v[214:217], v[66:69]
	s_setprio 0
	s_nop 0
	s_add_i32 s44, s93, s54
	v_lshl_add_u64 v[218:219], v[218:219], 0, s[28:29]
	s_mov_b32 m0, s44
	ds_read_b128 v[178:181], v211 offset:49152
	ds_read_b128 v[182:185], v211 offset:50176
	ds_read_b128 v[186:189], v211 offset:51200
	ds_read_b128 v[190:193], v211 offset:52224
	ds_read_b128 v[194:197], v211 offset:53248
	ds_read_b128 v[198:201], v211 offset:54272
	ds_read_b128 v[202:205], v211 offset:55296
	ds_read_b128 v[214:217], v211 offset:56320
	global_load_lds_dwordx4 v[218:219], off
	v_lshl_add_u64 v[218:219], v[220:221], 0, s[28:29]
	s_add_i32 m0, s44, 0x2000
	s_add_i32 s44, s94, s54
	global_load_lds_dwordx4 v[218:219], off
	v_lshl_add_u64 v[218:219], v[222:223], 0, s[28:29]
	s_mov_b32 m0, s44
	s_nop 0
	global_load_lds_dwordx4 v[218:219], off
	v_lshl_add_u64 v[218:219], v[224:225], 0, s[28:29]
	s_add_i32 m0, s44, 0x2000
	s_nop 0
	global_load_lds_dwordx4 v[218:219], off
	v_lshl_add_u64 v[218:219], s[42:43], 0, v[162:163]
	s_mov_b32 m0, s65
	s_nop 0
	global_load_lds_dwordx4 v[218:219], off
	v_lshl_add_u64 v[218:219], s[42:43], 0, v[166:167]
	s_mov_b32 m0, s80
	s_nop 0
	global_load_lds_dwordx4 v[218:219], off
	s_waitcnt vmcnt(8)
	s_waitcnt lgkmcnt(0)
	s_barrier
	s_setprio 1
	s_waitcnt lgkmcnt(0)
	v_mfma_f32_16x16x32_bf16 v[62:65], v[114:117], v[178:181], v[62:65]
	v_mfma_f32_16x16x32_bf16 v[58:61], v[122:125], v[178:181], v[58:61]
	v_mfma_f32_16x16x32_bf16 v[46:49], v[114:117], v[186:189], v[46:49]
	v_mfma_f32_16x16x32_bf16 v[42:45], v[122:125], v[186:189], v[42:45]
	v_mfma_f32_16x16x32_bf16 v[30:33], v[114:117], v[194:197], v[30:33]
	v_mfma_f32_16x16x32_bf16 v[26:29], v[122:125], v[194:197], v[26:29]
	v_mfma_f32_16x16x32_bf16 v[14:17], v[114:117], v[202:205], v[14:17]
	v_mfma_f32_16x16x32_bf16 v[10:13], v[122:125], v[202:205], v[10:13]
	v_mfma_f32_16x16x32_bf16 v[62:65], v[118:121], v[182:185], v[62:65]
	v_mfma_f32_16x16x32_bf16 v[58:61], v[126:129], v[182:185], v[58:61]
	v_mfma_f32_16x16x32_bf16 v[46:49], v[118:121], v[190:193], v[46:49]
	v_mfma_f32_16x16x32_bf16 v[42:45], v[126:129], v[190:193], v[42:45]
	v_mfma_f32_16x16x32_bf16 v[30:33], v[118:121], v[198:201], v[30:33]
	v_mfma_f32_16x16x32_bf16 v[26:29], v[126:129], v[198:201], v[26:29]
	v_mfma_f32_16x16x32_bf16 v[14:17], v[118:121], v[214:217], v[14:17]
	v_mfma_f32_16x16x32_bf16 v[10:13], v[126:129], v[214:217], v[10:13]
	s_setprio 0
	s_setprio 1
	v_mfma_f32_16x16x32_bf16 v[54:57], v[146:149], v[178:181], v[54:57]
	v_mfma_f32_16x16x32_bf16 v[50:53], v[154:157], v[178:181], v[50:53]
	v_mfma_f32_16x16x32_bf16 v[38:41], v[146:149], v[186:189], v[38:41]
	v_mfma_f32_16x16x32_bf16 v[34:37], v[154:157], v[186:189], v[34:37]
	v_mfma_f32_16x16x32_bf16 v[22:25], v[146:149], v[194:197], v[22:25]
	v_mfma_f32_16x16x32_bf16 v[18:21], v[154:157], v[194:197], v[18:21]
	v_mfma_f32_16x16x32_bf16 v[6:9], v[146:149], v[202:205], v[6:9]
	v_mfma_f32_16x16x32_bf16 v[2:5], v[154:157], v[202:205], v[2:5]
	v_mfma_f32_16x16x32_bf16 v[54:57], v[150:153], v[182:185], v[54:57]
	v_mfma_f32_16x16x32_bf16 v[50:53], v[158:161], v[182:185], v[50:53]
	s_barrier
	v_mfma_f32_16x16x32_bf16 v[38:41], v[150:153], v[190:193], v[38:41]
	v_mfma_f32_16x16x32_bf16 v[34:37], v[158:161], v[190:193], v[34:37]
	v_mfma_f32_16x16x32_bf16 v[22:25], v[150:153], v[198:201], v[22:25]
	v_mfma_f32_16x16x32_bf16 v[18:21], v[158:161], v[198:201], v[18:21]
	v_mfma_f32_16x16x32_bf16 v[6:9], v[150:153], v[214:217], v[6:9]
	v_mfma_f32_16x16x32_bf16 v[2:5], v[158:161], v[214:217], v[2:5]
	s_setprio 0
	s_nop 0
	s_add_u32 s90, s90, 0x100
	s_addc_u32 s91, s91, 0
	s_add_u32 s38, s38, 0x10000
	s_addc_u32 s39, s39, 0
	s_cmp_ge_i32 s92, s64
	s_mov_b32 s42, s92
	s_cbranch_scc0 .LBB0_1170

.LBB0_1276:
	ds_read_b128 v[114:117], v171
	ds_read_b128 v[118:121], v171 offset:1024
	ds_read_b128 v[122:125], v171 offset:2048
	ds_read_b128 v[130:133], v171 offset:3072
	ds_read_b128 v[162:165], v172
	ds_read_b128 v[176:179], v172 offset:1024
	ds_read_b128 v[180:183], v172 offset:2048
	ds_read_b128 v[184:187], v172 offset:3072
	s_add_i32 s82, s30, 2
	s_add_u32 s83, s2, 0x80
	s_addc_u32 s31, s3, 0
	s_cmp_eq_u32 s58, s30
	s_cselect_b32 s30, s26, s83
	s_cselect_b32 s31, s27, s31
	s_cselect_b32 s85, s29, s35
	s_cselect_b32 s84, s28, s34
	v_lshl_add_u64 v[220:221], s[2:3], 0, v[154:155]
	s_add_i32 m0, s44, 0xc000
	ds_read_b128 v[188:191], v173
	ds_read_b128 v[192:195], v173 offset:1024
	ds_read_b128 v[196:199], v173 offset:2048
	ds_read_b128 v[200:203], v173 offset:3072
	ds_read_b128 v[204:207], v173 offset:4096
	ds_read_b128 v[208:211], v173 offset:5120
	ds_read_b128 v[212:215], v173 offset:6144
	ds_read_b128 v[216:219], v173 offset:7168
	global_load_lds_dwordx4 v[220:221], off
	v_lshl_add_u64 v[220:221], s[2:3], 0, v[156:157]
	s_add_i32 m0, s44, 0xe000
	s_nop 0
	global_load_lds_dwordx4 v[220:221], off
	s_waitcnt vmcnt(8)
	s_waitcnt lgkmcnt(0)
	s_barrier
	s_setprio 1
	s_waitcnt lgkmcnt(0)
	v_mfma_f32_16x16x32_bf16 v[142:145], v[114:117], v[188:191], v[142:145]
	v_mfma_f32_16x16x32_bf16 v[138:141], v[122:125], v[188:191], v[138:141]
	v_mfma_f32_16x16x32_bf16 v[110:113], v[114:117], v[196:199], v[110:113]
	v_mfma_f32_16x16x32_bf16 v[106:109], v[122:125], v[196:199], v[106:109]
	v_mfma_f32_16x16x32_bf16 v[94:97], v[114:117], v[204:207], v[94:97]
	v_mfma_f32_16x16x32_bf16 v[90:93], v[122:125], v[204:207], v[90:93]
	v_mfma_f32_16x16x32_bf16 v[78:81], v[114:117], v[212:215], v[78:81]
	v_mfma_f32_16x16x32_bf16 v[74:77], v[122:125], v[212:215], v[74:77]
	v_mfma_f32_16x16x32_bf16 v[142:145], v[118:121], v[192:195], v[142:145]
	v_mfma_f32_16x16x32_bf16 v[138:141], v[130:133], v[192:195], v[138:141]
	v_mfma_f32_16x16x32_bf16 v[110:113], v[118:121], v[200:203], v[110:113]
	v_mfma_f32_16x16x32_bf16 v[106:109], v[130:133], v[200:203], v[106:109]
	v_mfma_f32_16x16x32_bf16 v[94:97], v[118:121], v[208:211], v[94:97]
	v_mfma_f32_16x16x32_bf16 v[90:93], v[130:133], v[208:211], v[90:93]
	v_mfma_f32_16x16x32_bf16 v[78:81], v[118:121], v[216:219], v[78:81]
	v_mfma_f32_16x16x32_bf16 v[74:77], v[130:133], v[216:219], v[74:77]
	s_setprio 0
	s_setprio 1
	v_mfma_f32_16x16x32_bf16 v[134:137], v[162:165], v[188:191], v[134:137]
	v_mfma_f32_16x16x32_bf16 v[126:129], v[180:183], v[188:191], v[126:129]
	v_mfma_f32_16x16x32_bf16 v[102:105], v[162:165], v[196:199], v[102:105]
	v_mfma_f32_16x16x32_bf16 v[98:101], v[180:183], v[196:199], v[98:101]
	v_mfma_f32_16x16x32_bf16 v[86:89], v[162:165], v[204:207], v[86:89]
	v_mfma_f32_16x16x32_bf16 v[82:85], v[180:183], v[204:207], v[82:85]
	v_mfma_f32_16x16x32_bf16 v[70:73], v[162:165], v[212:215], v[70:73]
	v_mfma_f32_16x16x32_bf16 v[66:69], v[180:183], v[212:215], v[66:69]
	v_mfma_f32_16x16x32_bf16 v[134:137], v[176:179], v[192:195], v[134:137]
	v_mfma_f32_16x16x32_bf16 v[126:129], v[184:187], v[192:195], v[126:129]
	s_barrier
	v_mfma_f32_16x16x32_bf16 v[102:105], v[176:179], v[200:203], v[102:105]
	v_mfma_f32_16x16x32_bf16 v[98:101], v[184:187], v[200:203], v[98:101]
	v_mfma_f32_16x16x32_bf16 v[86:89], v[176:179], v[208:211], v[86:89]
	v_mfma_f32_16x16x32_bf16 v[82:85], v[184:187], v[208:211], v[82:85]
	v_mfma_f32_16x16x32_bf16 v[70:73], v[176:179], v[216:219], v[70:73]
	v_mfma_f32_16x16x32_bf16 v[66:69], v[184:187], v[216:219], v[66:69]
	s_setprio 0
	s_nop 0
	s_add_i32 s83, s61, s37
	v_lshl_add_u64 v[220:221], s[84:85], 0, v[148:149]
	s_mov_b32 m0, s83
	ds_read_b128 v[188:191], v173 offset:16384
	ds_read_b128 v[192:195], v173 offset:17408
	ds_read_b128 v[196:199], v173 offset:18432
	ds_read_b128 v[200:203], v173 offset:19456
	ds_read_b128 v[204:207], v173 offset:20480
	ds_read_b128 v[208:211], v173 offset:21504
	ds_read_b128 v[212:215], v173 offset:22528
	ds_read_b128 v[216:219], v173 offset:23552
	global_load_lds_dwordx4 v[220:221], off
	s_add_i32 m0, s83, 0x2000
	v_lshl_add_u64 v[222:223], s[84:85], 0, v[152:153]
	s_add_u32 s84, s84, s6
	s_addc_u32 s85, s85, s7
	s_add_i32 s83, s62, s37
	global_load_lds_dwordx4 v[222:223], off
	v_lshl_add_u64 v[224:225], s[84:85], 0, v[148:149]
	s_mov_b32 m0, s83
	v_lshl_add_u64 v[226:227], s[84:85], 0, v[152:153]
	global_load_lds_dwordx4 v[224:225], off
	s_add_i32 m0, s83, 0x2000
	v_lshl_add_u64 v[228:229], s[30:31], 0, v[146:147]
	global_load_lds_dwordx4 v[226:227], off
	s_mov_b32 m0, s44
	v_lshl_add_u64 v[230:231], s[30:31], 0, v[150:151]
	global_load_lds_dwordx4 v[228:229], off
	s_mov_b32 m0, s45
	s_nop 0
	global_load_lds_dwordx4 v[230:231], off
	s_waitcnt vmcnt(8)
	s_waitcnt lgkmcnt(0)
	s_barrier
	s_setprio 1
	s_waitcnt lgkmcnt(0)
	v_mfma_f32_16x16x32_bf16 v[62:65], v[114:117], v[188:191], v[62:65]
	v_mfma_f32_16x16x32_bf16 v[58:61], v[122:125], v[188:191], v[58:61]
	v_mfma_f32_16x16x32_bf16 v[46:49], v[114:117], v[196:199], v[46:49]
	v_mfma_f32_16x16x32_bf16 v[42:45], v[122:125], v[196:199], v[42:45]
	v_mfma_f32_16x16x32_bf16 v[30:33], v[114:117], v[204:207], v[30:33]
	v_mfma_f32_16x16x32_bf16 v[26:29], v[122:125], v[204:207], v[26:29]
	v_mfma_f32_16x16x32_bf16 v[14:17], v[114:117], v[212:215], v[14:17]
	v_mfma_f32_16x16x32_bf16 v[10:13], v[122:125], v[212:215], v[10:13]
	v_mfma_f32_16x16x32_bf16 v[62:65], v[118:121], v[192:195], v[62:65]
	v_mfma_f32_16x16x32_bf16 v[58:61], v[130:133], v[192:195], v[58:61]
	v_mfma_f32_16x16x32_bf16 v[46:49], v[118:121], v[200:203], v[46:49]
	v_mfma_f32_16x16x32_bf16 v[42:45], v[130:133], v[200:203], v[42:45]
	v_mfma_f32_16x16x32_bf16 v[30:33], v[118:121], v[208:211], v[30:33]
	v_mfma_f32_16x16x32_bf16 v[26:29], v[130:133], v[208:211], v[26:29]
	v_mfma_f32_16x16x32_bf16 v[14:17], v[118:121], v[216:219], v[14:17]
	v_mfma_f32_16x16x32_bf16 v[10:13], v[130:133], v[216:219], v[10:13]
	s_setprio 0
	s_setprio 1
	v_mfma_f32_16x16x32_bf16 v[54:57], v[162:165], v[188:191], v[54:57]
	v_mfma_f32_16x16x32_bf16 v[50:53], v[180:183], v[188:191], v[50:53]
	v_mfma_f32_16x16x32_bf16 v[38:41], v[162:165], v[196:199], v[38:41]
	v_mfma_f32_16x16x32_bf16 v[34:37], v[180:183], v[196:199], v[34:37]
	v_mfma_f32_16x16x32_bf16 v[22:25], v[162:165], v[204:207], v[22:25]
	v_mfma_f32_16x16x32_bf16 v[18:21], v[180:183], v[204:207], v[18:21]
	v_mfma_f32_16x16x32_bf16 v[6:9], v[162:165], v[212:215], v[6:9]
	v_mfma_f32_16x16x32_bf16 v[2:5], v[180:183], v[212:215], v[2:5]
	v_mfma_f32_16x16x32_bf16 v[54:57], v[176:179], v[192:195], v[54:57]
	v_mfma_f32_16x16x32_bf16 v[50:53], v[184:187], v[192:195], v[50:53]
	s_barrier
	v_mfma_f32_16x16x32_bf16 v[38:41], v[176:179], v[200:203], v[38:41]
	v_mfma_f32_16x16x32_bf16 v[34:37], v[184:187], v[200:203], v[34:37]
	v_mfma_f32_16x16x32_bf16 v[22:25], v[176:179], v[208:211], v[22:25]
	v_mfma_f32_16x16x32_bf16 v[18:21], v[184:187], v[208:211], v[18:21]
	v_mfma_f32_16x16x32_bf16 v[6:9], v[176:179], v[216:219], v[6:9]
	v_mfma_f32_16x16x32_bf16 v[2:5], v[184:187], v[216:219], v[2:5]
	s_setprio 0
	s_nop 0
	s_add_i32 s83, 0, 0x18000
	s_add_i32 s84, 0, 0x1c000
	v_add_u32_e32 v130, s83, v168
	v_add_u32_e32 v166, s84, v168
	ds_read_b128 v[114:117], v130
	ds_read_b128 v[118:121], v130 offset:1024
	ds_read_b128 v[122:125], v130 offset:2048
	ds_read_b128 v[130:133], v130 offset:3072
	ds_read_b128 v[162:165], v166
	ds_read_b128 v[176:179], v166 offset:1024
	ds_read_b128 v[180:183], v166 offset:2048
	ds_read_b128 v[184:187], v166 offset:3072
	s_add_u32 s30, s30, s6
	s_addc_u32 s31, s31, s7
	s_mov_b32 m0, s46
	v_lshl_add_u64 v[232:233], s[30:31], 0, v[146:147]
	ds_read_b128 v[188:191], v173 offset:32768
	ds_read_b128 v[192:195], v173 offset:33792
	ds_read_b128 v[196:199], v173 offset:34816
	ds_read_b128 v[200:203], v173 offset:35840
	ds_read_b128 v[204:207], v173 offset:36864
	ds_read_b128 v[208:211], v173 offset:37888
	ds_read_b128 v[212:215], v173 offset:38912
	ds_read_b128 v[216:219], v173 offset:39936
	global_load_lds_dwordx4 v[232:233], off
	v_lshl_add_u64 v[232:233], s[30:31], 0, v[150:151]
	s_mov_b32 m0, s47
	s_nop 0
	global_load_lds_dwordx4 v[232:233], off
	s_waitcnt vmcnt(8)
	s_waitcnt lgkmcnt(0)
	s_barrier
	s_setprio 1
	s_waitcnt lgkmcnt(0)
	v_mfma_f32_16x16x32_bf16 v[142:145], v[114:117], v[188:191], v[142:145]
	v_mfma_f32_16x16x32_bf16 v[138:141], v[122:125], v[188:191], v[138:141]
	v_mfma_f32_16x16x32_bf16 v[110:113], v[114:117], v[196:199], v[110:113]
	v_mfma_f32_16x16x32_bf16 v[106:109], v[122:125], v[196:199], v[106:109]
	v_mfma_f32_16x16x32_bf16 v[94:97], v[114:117], v[204:207], v[94:97]
	v_mfma_f32_16x16x32_bf16 v[90:93], v[122:125], v[204:207], v[90:93]
	v_mfma_f32_16x16x32_bf16 v[78:81], v[114:117], v[212:215], v[78:81]
	v_mfma_f32_16x16x32_bf16 v[74:77], v[122:125], v[212:215], v[74:77]
	v_mfma_f32_16x16x32_bf16 v[142:145], v[118:121], v[192:195], v[142:145]
	v_mfma_f32_16x16x32_bf16 v[138:141], v[130:133], v[192:195], v[138:141]
	v_mfma_f32_16x16x32_bf16 v[110:113], v[118:121], v[200:203], v[110:113]
	v_mfma_f32_16x16x32_bf16 v[106:109], v[130:133], v[200:203], v[106:109]
	v_mfma_f32_16x16x32_bf16 v[94:97], v[118:121], v[208:211], v[94:97]
	v_mfma_f32_16x16x32_bf16 v[90:93], v[130:133], v[208:211], v[90:93]
	v_mfma_f32_16x16x32_bf16 v[78:81], v[118:121], v[216:219], v[78:81]
	v_mfma_f32_16x16x32_bf16 v[74:77], v[130:133], v[216:219], v[74:77]
	s_setprio 0
	s_setprio 1
	v_mfma_f32_16x16x32_bf16 v[134:137], v[162:165], v[188:191], v[134:137]
	v_mfma_f32_16x16x32_bf16 v[126:129], v[180:183], v[188:191], v[126:129]
	v_mfma_f32_16x16x32_bf16 v[102:105], v[162:165], v[196:199], v[102:105]
	v_mfma_f32_16x16x32_bf16 v[98:101], v[180:183], v[196:199], v[98:101]
	v_mfma_f32_16x16x32_bf16 v[86:89], v[162:165], v[204:207], v[86:89]
	v_mfma_f32_16x16x32_bf16 v[82:85], v[180:183], v[204:207], v[82:85]
	v_mfma_f32_16x16x32_bf16 v[70:73], v[162:165], v[212:215], v[70:73]
	v_mfma_f32_16x16x32_bf16 v[66:69], v[180:183], v[212:215], v[66:69]
	v_mfma_f32_16x16x32_bf16 v[134:137], v[176:179], v[192:195], v[134:137]
	v_mfma_f32_16x16x32_bf16 v[126:129], v[184:187], v[192:195], v[126:129]
	s_barrier
	v_mfma_f32_16x16x32_bf16 v[102:105], v[176:179], v[200:203], v[102:105]
	v_mfma_f32_16x16x32_bf16 v[98:101], v[184:187], v[200:203], v[98:101]
	v_mfma_f32_16x16x32_bf16 v[86:89], v[176:179], v[208:211], v[86:89]
	v_mfma_f32_16x16x32_bf16 v[82:85], v[184:187], v[208:211], v[82:85]
	v_mfma_f32_16x16x32_bf16 v[70:73], v[176:179], v[216:219], v[70:73]
	v_mfma_f32_16x16x32_bf16 v[66:69], v[184:187], v[216:219], v[66:69]
	s_setprio 0
	s_nop 0
	s_add_i32 s30, s83, s37
	v_lshl_add_u64 v[220:221], v[220:221], 0, s[20:21]
	s_mov_b32 m0, s30
	ds_read_b128 v[188:191], v173 offset:49152
	ds_read_b128 v[192:195], v173 offset:50176
	ds_read_b128 v[196:199], v173 offset:51200
	ds_read_b128 v[200:203], v173 offset:52224
	ds_read_b128 v[204:207], v173 offset:53248
	ds_read_b128 v[208:211], v173 offset:54272
	ds_read_b128 v[212:215], v173 offset:55296
	ds_read_b128 v[216:219], v173 offset:56320
	global_load_lds_dwordx4 v[220:221], off
	v_lshl_add_u64 v[220:221], v[222:223], 0, s[20:21]
	s_add_i32 m0, s30, 0x2000
	s_add_i32 s30, s84, s37
	global_load_lds_dwordx4 v[220:221], off
	v_lshl_add_u64 v[220:221], v[224:225], 0, s[20:21]
	s_mov_b32 m0, s30
	s_nop 0
	global_load_lds_dwordx4 v[220:221], off
	v_lshl_add_u64 v[220:221], v[226:227], 0, s[20:21]
	s_add_i32 m0, s30, 0x2000
	s_nop 0
	global_load_lds_dwordx4 v[220:221], off
	v_lshl_add_u64 v[220:221], v[228:229], 0, s[20:21]
	s_mov_b32 m0, s55
	s_nop 0
	global_load_lds_dwordx4 v[220:221], off
	v_lshl_add_u64 v[220:221], v[230:231], 0, s[20:21]
	s_mov_b32 m0, s56
	s_nop 0
	global_load_lds_dwordx4 v[220:221], off
	s_waitcnt vmcnt(8)
	s_waitcnt lgkmcnt(0)
	s_barrier
	s_setprio 1
	s_waitcnt lgkmcnt(0)
	v_mfma_f32_16x16x32_bf16 v[62:65], v[114:117], v[188:191], v[62:65]
	v_mfma_f32_16x16x32_bf16 v[58:61], v[122:125], v[188:191], v[58:61]
	v_mfma_f32_16x16x32_bf16 v[46:49], v[114:117], v[196:199], v[46:49]
	v_mfma_f32_16x16x32_bf16 v[42:45], v[122:125], v[196:199], v[42:45]
	v_mfma_f32_16x16x32_bf16 v[30:33], v[114:117], v[204:207], v[30:33]
	v_mfma_f32_16x16x32_bf16 v[26:29], v[122:125], v[204:207], v[26:29]
	v_mfma_f32_16x16x32_bf16 v[14:17], v[114:117], v[212:215], v[14:17]
	v_mfma_f32_16x16x32_bf16 v[10:13], v[122:125], v[212:215], v[10:13]
	v_mfma_f32_16x16x32_bf16 v[62:65], v[118:121], v[192:195], v[62:65]
	v_mfma_f32_16x16x32_bf16 v[58:61], v[130:133], v[192:195], v[58:61]
	v_mfma_f32_16x16x32_bf16 v[46:49], v[118:121], v[200:203], v[46:49]
	v_mfma_f32_16x16x32_bf16 v[42:45], v[130:133], v[200:203], v[42:45]
	v_mfma_f32_16x16x32_bf16 v[30:33], v[118:121], v[208:211], v[30:33]
	v_mfma_f32_16x16x32_bf16 v[26:29], v[130:133], v[208:211], v[26:29]
	v_mfma_f32_16x16x32_bf16 v[14:17], v[118:121], v[216:219], v[14:17]
	v_mfma_f32_16x16x32_bf16 v[10:13], v[130:133], v[216:219], v[10:13]
	s_setprio 0
	s_setprio 1
	v_mfma_f32_16x16x32_bf16 v[54:57], v[162:165], v[188:191], v[54:57]
	v_mfma_f32_16x16x32_bf16 v[50:53], v[180:183], v[188:191], v[50:53]
	v_mfma_f32_16x16x32_bf16 v[38:41], v[162:165], v[196:199], v[38:41]
	v_mfma_f32_16x16x32_bf16 v[34:37], v[180:183], v[196:199], v[34:37]
	v_mfma_f32_16x16x32_bf16 v[22:25], v[162:165], v[204:207], v[22:25]
	v_mfma_f32_16x16x32_bf16 v[18:21], v[180:183], v[204:207], v[18:21]
	v_mfma_f32_16x16x32_bf16 v[6:9], v[162:165], v[212:215], v[6:9]
	v_mfma_f32_16x16x32_bf16 v[2:5], v[180:183], v[212:215], v[2:5]
	v_mfma_f32_16x16x32_bf16 v[54:57], v[176:179], v[192:195], v[54:57]
	v_mfma_f32_16x16x32_bf16 v[50:53], v[184:187], v[192:195], v[50:53]
	s_barrier
	v_mfma_f32_16x16x32_bf16 v[38:41], v[176:179], v[200:203], v[38:41]
	v_mfma_f32_16x16x32_bf16 v[34:37], v[184:187], v[200:203], v[34:37]
	v_mfma_f32_16x16x32_bf16 v[22:25], v[176:179], v[208:211], v[22:25]
	v_mfma_f32_16x16x32_bf16 v[18:21], v[184:187], v[208:211], v[18:21]
	v_mfma_f32_16x16x32_bf16 v[6:9], v[176:179], v[216:219], v[6:9]
	v_mfma_f32_16x16x32_bf16 v[2:5], v[184:187], v[216:219], v[2:5]
	s_setprio 0
	s_nop 0
	s_add_u32 s2, s2, 0x100
	s_addc_u32 s3, s3, 0
	s_add_u32 s34, s34, 0x100
	s_addc_u32 s35, s35, 0
	s_cmp_ge_i32 s82, s57
	s_mov_b32 s30, s82
	s_cbranch_scc0 .LBB0_1276

.LBB0_1461:
	ds_read_b128 v[148:151], v168
	ds_read_b128 v[172:175], v168 offset:1024
	ds_read_b128 v[176:179], v168 offset:2048
	ds_read_b128 v[180:183], v168 offset:3072
	ds_read_b128 v[184:187], v169
	ds_read_b128 v[188:191], v169 offset:1024
	ds_read_b128 v[192:195], v169 offset:2048
	ds_read_b128 v[196:199], v169 offset:3072
	s_add_i32 s67, s26, 2
	s_add_u32 s68, s24, 0x80
	s_addc_u32 s27, s25, 0
	s_cmp_eq_u32 s50, s26
	s_cselect_b32 s26, s2, s68
	s_cselect_b32 s27, s3, s27
	s_cselect_b32 s69, s23, s66
	s_cselect_b32 s68, s22, s65
	v_lshl_add_u64 v[232:233], s[24:25], 0, v[140:141]
	s_add_i32 m0, s37, 0xc000
	ds_read_b128 v[200:203], v170
	ds_read_b128 v[204:207], v170 offset:1024
	ds_read_b128 v[208:211], v170 offset:2048
	ds_read_b128 v[212:215], v170 offset:3072
	ds_read_b128 v[216:219], v170 offset:4096
	ds_read_b128 v[220:223], v170 offset:5120
	ds_read_b128 v[224:227], v170 offset:6144
	ds_read_b128 v[228:231], v170 offset:7168
	global_load_lds_dwordx4 v[232:233], off
	v_lshl_add_u64 v[232:233], s[24:25], 0, v[142:143]
	s_add_i32 m0, s37, 0xe000
	s_nop 0
	global_load_lds_dwordx4 v[232:233], off
	s_waitcnt vmcnt(8)
	s_waitcnt lgkmcnt(0)
	s_barrier
	s_setprio 1
	s_waitcnt lgkmcnt(0)
	v_mfma_f32_16x16x32_bf16 v[128:131], v[148:151], v[200:203], v[128:131]
	v_mfma_f32_16x16x32_bf16 v[124:127], v[176:179], v[200:203], v[124:127]
	v_mfma_f32_16x16x32_bf16 v[120:123], v[148:151], v[208:211], v[120:123]
	v_mfma_f32_16x16x32_bf16 v[116:119], v[176:179], v[208:211], v[116:119]
	v_mfma_f32_16x16x32_bf16 v[112:115], v[148:151], v[216:219], v[112:115]
	v_mfma_f32_16x16x32_bf16 v[108:111], v[176:179], v[216:219], v[108:111]
	v_mfma_f32_16x16x32_bf16 v[104:107], v[148:151], v[224:227], v[104:107]
	v_mfma_f32_16x16x32_bf16 v[100:103], v[176:179], v[224:227], v[100:103]
	v_mfma_f32_16x16x32_bf16 v[128:131], v[172:175], v[204:207], v[128:131]
	v_mfma_f32_16x16x32_bf16 v[124:127], v[180:183], v[204:207], v[124:127]
	v_mfma_f32_16x16x32_bf16 v[120:123], v[172:175], v[212:215], v[120:123]
	v_mfma_f32_16x16x32_bf16 v[116:119], v[180:183], v[212:215], v[116:119]
	v_mfma_f32_16x16x32_bf16 v[112:115], v[172:175], v[220:223], v[112:115]
	v_mfma_f32_16x16x32_bf16 v[108:111], v[180:183], v[220:223], v[108:111]
	v_mfma_f32_16x16x32_bf16 v[104:107], v[172:175], v[228:231], v[104:107]
	v_mfma_f32_16x16x32_bf16 v[100:103], v[180:183], v[228:231], v[100:103]
	s_setprio 0
	s_setprio 1
	v_mfma_f32_16x16x32_bf16 v[64:67], v[184:187], v[200:203], v[64:67]
	v_mfma_f32_16x16x32_bf16 v[60:63], v[192:195], v[200:203], v[60:63]
	v_mfma_f32_16x16x32_bf16 v[56:59], v[184:187], v[208:211], v[56:59]
	v_mfma_f32_16x16x32_bf16 v[52:55], v[192:195], v[208:211], v[52:55]
	v_mfma_f32_16x16x32_bf16 v[48:51], v[184:187], v[216:219], v[48:51]
	v_mfma_f32_16x16x32_bf16 v[44:47], v[192:195], v[216:219], v[44:47]
	v_mfma_f32_16x16x32_bf16 v[40:43], v[184:187], v[224:227], v[40:43]
	v_mfma_f32_16x16x32_bf16 v[36:39], v[192:195], v[224:227], v[36:39]
	v_mfma_f32_16x16x32_bf16 v[64:67], v[188:191], v[204:207], v[64:67]
	v_mfma_f32_16x16x32_bf16 v[60:63], v[196:199], v[204:207], v[60:63]
	s_barrier
	v_mfma_f32_16x16x32_bf16 v[56:59], v[188:191], v[212:215], v[56:59]
	v_mfma_f32_16x16x32_bf16 v[52:55], v[196:199], v[212:215], v[52:55]
	v_mfma_f32_16x16x32_bf16 v[48:51], v[188:191], v[220:223], v[48:51]
	v_mfma_f32_16x16x32_bf16 v[44:47], v[196:199], v[220:223], v[44:47]
	v_mfma_f32_16x16x32_bf16 v[40:43], v[188:191], v[228:231], v[40:43]
	v_mfma_f32_16x16x32_bf16 v[36:39], v[196:199], v[228:231], v[36:39]
	s_setprio 0
	s_nop 0
	s_add_i32 s80, s57, s36
	v_lshl_add_u64 v[232:233], s[68:69], 0, v[134:135]
	s_mov_b32 m0, s80
	ds_read_b128 v[200:203], v170 offset:16384
	ds_read_b128 v[204:207], v170 offset:17408
	ds_read_b128 v[208:211], v170 offset:18432
	ds_read_b128 v[212:215], v170 offset:19456
	ds_read_b128 v[216:219], v170 offset:20480
	ds_read_b128 v[220:223], v170 offset:21504
	ds_read_b128 v[224:227], v170 offset:22528
	ds_read_b128 v[228:231], v170 offset:23552
	global_load_lds_dwordx4 v[232:233], off
	s_add_i32 m0, s80, 0x2000
	v_lshl_add_u64 v[234:235], s[68:69], 0, v[138:139]
	s_add_u32 s68, s68, s6
	s_addc_u32 s69, s69, s7
	s_add_i32 s80, s58, s36
	global_load_lds_dwordx4 v[234:235], off
	v_lshl_add_u64 v[236:237], s[68:69], 0, v[134:135]
	s_mov_b32 m0, s80
	v_lshl_add_u64 v[238:239], s[68:69], 0, v[138:139]
	global_load_lds_dwordx4 v[236:237], off
	s_add_i32 m0, s80, 0x2000
	v_lshl_add_u64 v[240:241], s[26:27], 0, v[132:133]
	global_load_lds_dwordx4 v[238:239], off
	s_mov_b32 m0, s37
	v_lshl_add_u64 v[242:243], s[26:27], 0, v[136:137]
	global_load_lds_dwordx4 v[240:241], off
	s_mov_b32 m0, s38
	s_nop 0
	global_load_lds_dwordx4 v[242:243], off
	s_waitcnt vmcnt(8)
	s_waitcnt lgkmcnt(0)
	s_barrier
	s_setprio 1
	s_waitcnt lgkmcnt(0)
	v_mfma_f32_16x16x32_bf16 v[96:99], v[148:151], v[200:203], v[96:99]
	v_mfma_f32_16x16x32_bf16 v[92:95], v[176:179], v[200:203], v[92:95]
	v_mfma_f32_16x16x32_bf16 v[88:91], v[148:151], v[208:211], v[88:91]
	v_mfma_f32_16x16x32_bf16 v[84:87], v[176:179], v[208:211], v[84:87]
	v_mfma_f32_16x16x32_bf16 v[80:83], v[148:151], v[216:219], v[80:83]
	v_mfma_f32_16x16x32_bf16 v[76:79], v[176:179], v[216:219], v[76:79]
	v_mfma_f32_16x16x32_bf16 v[72:75], v[148:151], v[224:227], v[72:75]
	v_mfma_f32_16x16x32_bf16 v[68:71], v[176:179], v[224:227], v[68:71]
	v_mfma_f32_16x16x32_bf16 v[96:99], v[172:175], v[204:207], v[96:99]
	v_mfma_f32_16x16x32_bf16 v[92:95], v[180:183], v[204:207], v[92:95]
	v_mfma_f32_16x16x32_bf16 v[88:91], v[172:175], v[212:215], v[88:91]
	v_mfma_f32_16x16x32_bf16 v[84:87], v[180:183], v[212:215], v[84:87]
	v_mfma_f32_16x16x32_bf16 v[80:83], v[172:175], v[220:223], v[80:83]
	v_mfma_f32_16x16x32_bf16 v[76:79], v[180:183], v[220:223], v[76:79]
	v_mfma_f32_16x16x32_bf16 v[72:75], v[172:175], v[228:231], v[72:75]
	v_mfma_f32_16x16x32_bf16 v[68:71], v[180:183], v[228:231], v[68:71]
	s_setprio 0
	s_setprio 1
	v_mfma_f32_16x16x32_bf16 v[32:35], v[184:187], v[200:203], v[32:35]
	v_mfma_f32_16x16x32_bf16 v[28:31], v[192:195], v[200:203], v[28:31]
	v_mfma_f32_16x16x32_bf16 v[24:27], v[184:187], v[208:211], v[24:27]
	v_mfma_f32_16x16x32_bf16 v[20:23], v[192:195], v[208:211], v[20:23]
	v_mfma_f32_16x16x32_bf16 v[16:19], v[184:187], v[216:219], v[16:19]
	v_mfma_f32_16x16x32_bf16 v[12:15], v[192:195], v[216:219], v[12:15]
	v_mfma_f32_16x16x32_bf16 v[8:11], v[184:187], v[224:227], v[8:11]
	v_mfma_f32_16x16x32_bf16 v[4:7], v[192:195], v[224:227], v[4:7]
	v_mfma_f32_16x16x32_bf16 v[32:35], v[188:191], v[204:207], v[32:35]
	v_mfma_f32_16x16x32_bf16 v[28:31], v[196:199], v[204:207], v[28:31]
	s_barrier
	v_mfma_f32_16x16x32_bf16 v[24:27], v[188:191], v[212:215], v[24:27]
	v_mfma_f32_16x16x32_bf16 v[20:23], v[196:199], v[212:215], v[20:23]
	v_mfma_f32_16x16x32_bf16 v[16:19], v[188:191], v[220:223], v[16:19]
	v_mfma_f32_16x16x32_bf16 v[12:15], v[196:199], v[220:223], v[12:15]
	v_mfma_f32_16x16x32_bf16 v[8:11], v[188:191], v[228:231], v[8:11]
	v_mfma_f32_16x16x32_bf16 v[4:7], v[196:199], v[228:231], v[4:7]
	s_setprio 0
	s_nop 0
	s_add_i32 s68, 0, 0x18000
	v_add_u32_e32 v3, s68, v166
	s_add_i32 s69, 0, 0x1c000
	ds_read_b128 v[148:151], v3
	ds_read_b128 v[172:175], v3 offset:1024
	ds_read_b128 v[176:179], v3 offset:2048
	ds_read_b128 v[180:183], v3 offset:3072
	v_add_u32_e32 v3, s69, v166
	ds_read_b128 v[184:187], v3
	ds_read_b128 v[188:191], v3 offset:1024
	ds_read_b128 v[192:195], v3 offset:2048
	ds_read_b128 v[196:199], v3 offset:3072
	s_add_u32 s26, s26, s6
	s_addc_u32 s27, s27, s7
	s_mov_b32 m0, s39
	v_lshl_add_u64 v[244:245], s[26:27], 0, v[132:133]
	ds_read_b128 v[200:203], v170 offset:32768
	ds_read_b128 v[204:207], v170 offset:33792
	ds_read_b128 v[208:211], v170 offset:34816
	ds_read_b128 v[212:215], v170 offset:35840
	ds_read_b128 v[216:219], v170 offset:36864
	ds_read_b128 v[220:223], v170 offset:37888
	ds_read_b128 v[224:227], v170 offset:38912
	ds_read_b128 v[228:231], v170 offset:39936
	global_load_lds_dwordx4 v[244:245], off
	v_lshl_add_u64 v[244:245], s[26:27], 0, v[136:137]
	s_mov_b32 m0, s42
	s_nop 0
	global_load_lds_dwordx4 v[244:245], off
	s_waitcnt vmcnt(8)
	s_waitcnt lgkmcnt(0)
	s_barrier
	s_setprio 1
	s_waitcnt lgkmcnt(0)
	v_mfma_f32_16x16x32_bf16 v[128:131], v[148:151], v[200:203], v[128:131]
	v_mfma_f32_16x16x32_bf16 v[124:127], v[176:179], v[200:203], v[124:127]
	v_mfma_f32_16x16x32_bf16 v[120:123], v[148:151], v[208:211], v[120:123]
	v_mfma_f32_16x16x32_bf16 v[116:119], v[176:179], v[208:211], v[116:119]
	v_mfma_f32_16x16x32_bf16 v[112:115], v[148:151], v[216:219], v[112:115]
	v_mfma_f32_16x16x32_bf16 v[108:111], v[176:179], v[216:219], v[108:111]
	v_mfma_f32_16x16x32_bf16 v[104:107], v[148:151], v[224:227], v[104:107]
	v_mfma_f32_16x16x32_bf16 v[100:103], v[176:179], v[224:227], v[100:103]
	v_mfma_f32_16x16x32_bf16 v[128:131], v[172:175], v[204:207], v[128:131]
	v_mfma_f32_16x16x32_bf16 v[124:127], v[180:183], v[204:207], v[124:127]
	v_mfma_f32_16x16x32_bf16 v[120:123], v[172:175], v[212:215], v[120:123]
	v_mfma_f32_16x16x32_bf16 v[116:119], v[180:183], v[212:215], v[116:119]
	v_mfma_f32_16x16x32_bf16 v[112:115], v[172:175], v[220:223], v[112:115]
	v_mfma_f32_16x16x32_bf16 v[108:111], v[180:183], v[220:223], v[108:111]
	v_mfma_f32_16x16x32_bf16 v[104:107], v[172:175], v[228:231], v[104:107]
	v_mfma_f32_16x16x32_bf16 v[100:103], v[180:183], v[228:231], v[100:103]
	s_setprio 0
	s_setprio 1
	v_mfma_f32_16x16x32_bf16 v[64:67], v[184:187], v[200:203], v[64:67]
	v_mfma_f32_16x16x32_bf16 v[60:63], v[192:195], v[200:203], v[60:63]
	v_mfma_f32_16x16x32_bf16 v[56:59], v[184:187], v[208:211], v[56:59]
	v_mfma_f32_16x16x32_bf16 v[52:55], v[192:195], v[208:211], v[52:55]
	v_mfma_f32_16x16x32_bf16 v[48:51], v[184:187], v[216:219], v[48:51]
	v_mfma_f32_16x16x32_bf16 v[44:47], v[192:195], v[216:219], v[44:47]
	v_mfma_f32_16x16x32_bf16 v[40:43], v[184:187], v[224:227], v[40:43]
	v_mfma_f32_16x16x32_bf16 v[36:39], v[192:195], v[224:227], v[36:39]
	v_mfma_f32_16x16x32_bf16 v[64:67], v[188:191], v[204:207], v[64:67]
	v_mfma_f32_16x16x32_bf16 v[60:63], v[196:199], v[204:207], v[60:63]
	s_barrier
	v_mfma_f32_16x16x32_bf16 v[56:59], v[188:191], v[212:215], v[56:59]
	v_mfma_f32_16x16x32_bf16 v[52:55], v[196:199], v[212:215], v[52:55]
	v_mfma_f32_16x16x32_bf16 v[48:51], v[188:191], v[220:223], v[48:51]
	v_mfma_f32_16x16x32_bf16 v[44:47], v[196:199], v[220:223], v[44:47]
	v_mfma_f32_16x16x32_bf16 v[40:43], v[188:191], v[228:231], v[40:43]
	v_mfma_f32_16x16x32_bf16 v[36:39], v[196:199], v[228:231], v[36:39]
	s_setprio 0
	s_nop 0
	s_add_i32 s26, s68, s36
	v_lshl_add_u64 v[232:233], v[232:233], 0, s[16:17]
	s_mov_b32 m0, s26
	ds_read_b128 v[200:203], v170 offset:49152
	ds_read_b128 v[204:207], v170 offset:50176
	ds_read_b128 v[208:211], v170 offset:51200
	ds_read_b128 v[212:215], v170 offset:52224
	ds_read_b128 v[216:219], v170 offset:53248
	ds_read_b128 v[220:223], v170 offset:54272
	ds_read_b128 v[224:227], v170 offset:55296
	ds_read_b128 v[228:231], v170 offset:56320
	global_load_lds_dwordx4 v[232:233], off
	v_lshl_add_u64 v[232:233], v[234:235], 0, s[16:17]
	s_add_i32 m0, s26, 0x2000
	s_add_i32 s26, s69, s36
	global_load_lds_dwordx4 v[232:233], off
	v_lshl_add_u64 v[232:233], v[236:237], 0, s[16:17]
	s_mov_b32 m0, s26
	s_nop 0
	global_load_lds_dwordx4 v[232:233], off
	v_lshl_add_u64 v[232:233], v[238:239], 0, s[16:17]
	s_add_i32 m0, s26, 0x2000
	s_nop 0
	global_load_lds_dwordx4 v[232:233], off
	v_lshl_add_u64 v[232:233], v[240:241], 0, s[16:17]
	s_mov_b32 m0, s44
	s_nop 0
	global_load_lds_dwordx4 v[232:233], off
	v_lshl_add_u64 v[232:233], v[242:243], 0, s[16:17]
	s_mov_b32 m0, s45
	s_nop 0
	global_load_lds_dwordx4 v[232:233], off
	s_waitcnt vmcnt(8)
	s_waitcnt lgkmcnt(0)
	s_barrier
	s_setprio 1
	s_waitcnt lgkmcnt(0)
	v_mfma_f32_16x16x32_bf16 v[96:99], v[148:151], v[200:203], v[96:99]
	v_mfma_f32_16x16x32_bf16 v[92:95], v[176:179], v[200:203], v[92:95]
	v_mfma_f32_16x16x32_bf16 v[88:91], v[148:151], v[208:211], v[88:91]
	v_mfma_f32_16x16x32_bf16 v[84:87], v[176:179], v[208:211], v[84:87]
	v_mfma_f32_16x16x32_bf16 v[80:83], v[148:151], v[216:219], v[80:83]
	v_mfma_f32_16x16x32_bf16 v[76:79], v[176:179], v[216:219], v[76:79]
	v_mfma_f32_16x16x32_bf16 v[72:75], v[148:151], v[224:227], v[72:75]
	v_mfma_f32_16x16x32_bf16 v[68:71], v[176:179], v[224:227], v[68:71]
	v_mfma_f32_16x16x32_bf16 v[96:99], v[172:175], v[204:207], v[96:99]
	v_mfma_f32_16x16x32_bf16 v[92:95], v[180:183], v[204:207], v[92:95]
	v_mfma_f32_16x16x32_bf16 v[88:91], v[172:175], v[212:215], v[88:91]
	v_mfma_f32_16x16x32_bf16 v[84:87], v[180:183], v[212:215], v[84:87]
	v_mfma_f32_16x16x32_bf16 v[80:83], v[172:175], v[220:223], v[80:83]
	v_mfma_f32_16x16x32_bf16 v[76:79], v[180:183], v[220:223], v[76:79]
	v_mfma_f32_16x16x32_bf16 v[72:75], v[172:175], v[228:231], v[72:75]
	v_mfma_f32_16x16x32_bf16 v[68:71], v[180:183], v[228:231], v[68:71]
	s_setprio 0
	s_setprio 1
	v_mfma_f32_16x16x32_bf16 v[32:35], v[184:187], v[200:203], v[32:35]
	v_mfma_f32_16x16x32_bf16 v[28:31], v[192:195], v[200:203], v[28:31]
	v_mfma_f32_16x16x32_bf16 v[24:27], v[184:187], v[208:211], v[24:27]
	v_mfma_f32_16x16x32_bf16 v[20:23], v[192:195], v[208:211], v[20:23]
	v_mfma_f32_16x16x32_bf16 v[16:19], v[184:187], v[216:219], v[16:19]
	v_mfma_f32_16x16x32_bf16 v[12:15], v[192:195], v[216:219], v[12:15]
	v_mfma_f32_16x16x32_bf16 v[8:11], v[184:187], v[224:227], v[8:11]
	v_mfma_f32_16x16x32_bf16 v[4:7], v[192:195], v[224:227], v[4:7]
	v_mfma_f32_16x16x32_bf16 v[32:35], v[188:191], v[204:207], v[32:35]
	v_mfma_f32_16x16x32_bf16 v[28:31], v[196:199], v[204:207], v[28:31]
	s_barrier
	v_mfma_f32_16x16x32_bf16 v[24:27], v[188:191], v[212:215], v[24:27]
	v_mfma_f32_16x16x32_bf16 v[20:23], v[196:199], v[212:215], v[20:23]
	v_mfma_f32_16x16x32_bf16 v[16:19], v[188:191], v[220:223], v[16:19]
	v_mfma_f32_16x16x32_bf16 v[12:15], v[196:199], v[220:223], v[12:15]
	v_mfma_f32_16x16x32_bf16 v[8:11], v[188:191], v[228:231], v[8:11]
	v_mfma_f32_16x16x32_bf16 v[4:7], v[196:199], v[228:231], v[4:7]
	s_setprio 0
	s_nop 0
	s_add_u32 s24, s24, 0x100
	s_addc_u32 s25, s25, 0
	s_add_u32 s65, s65, 0x100
	s_addc_u32 s66, s66, 0
	s_cmp_ge_i32 s67, s46
	s_mov_b32 s26, s67
	s_cbranch_scc0 .LBB0_1461

.LBB0_1514:
	ds_read_b128 v[152:155], v149
	ds_read_b128 v[156:159], v149 offset:1024
	ds_read_b128 v[160:163], v149 offset:2048
	ds_read_b128 v[164:167], v149 offset:3072
	ds_read_b128 v[168:171], v150
	ds_read_b128 v[172:175], v150 offset:1024
	ds_read_b128 v[176:179], v150 offset:2048
	ds_read_b128 v[180:183], v150 offset:3072
	s_add_i32 s69, s36, 2
	s_add_u32 s80, s34, 0x80
	s_addc_u32 s37, s35, 0
	s_cmp_eq_u32 s59, s36
	s_cselect_b32 s36, s2, s80
	s_cselect_b32 s37, s3, s37
	s_cselect_b32 s81, s31, s68
	s_cselect_b32 s80, s30, s67
	v_lshl_add_u64 v[216:217], s[34:35], 0, v[138:139]
	s_add_i32 m0, s47, 0xc000
	ds_read_b128 v[184:187], v151
	ds_read_b128 v[188:191], v151 offset:1024
	ds_read_b128 v[192:195], v151 offset:2048
	ds_read_b128 v[196:199], v151 offset:3072
	ds_read_b128 v[200:203], v151 offset:4096
	ds_read_b128 v[204:207], v151 offset:5120
	ds_read_b128 v[208:211], v151 offset:6144
	ds_read_b128 v[212:215], v151 offset:7168
	global_load_lds_dwordx4 v[216:217], off
	v_lshl_add_u64 v[216:217], s[34:35], 0, v[140:141]
	s_add_i32 m0, s47, 0xe000
	s_nop 0
	global_load_lds_dwordx4 v[216:217], off
	s_waitcnt vmcnt(8)
	s_waitcnt lgkmcnt(0)
	s_barrier
	s_setprio 1
	s_waitcnt lgkmcnt(0)
	v_mfma_f32_16x16x32_bf16 v[122:125], v[152:155], v[184:187], v[122:125]
	v_mfma_f32_16x16x32_bf16 v[126:129], v[160:163], v[184:187], v[126:129]
	v_mfma_f32_16x16x32_bf16 v[110:113], v[152:155], v[192:195], v[110:113]
	v_mfma_f32_16x16x32_bf16 v[106:109], v[160:163], v[192:195], v[106:109]
	v_mfma_f32_16x16x32_bf16 v[94:97], v[152:155], v[200:203], v[94:97]
	v_mfma_f32_16x16x32_bf16 v[90:93], v[160:163], v[200:203], v[90:93]
	v_mfma_f32_16x16x32_bf16 v[78:81], v[152:155], v[208:211], v[78:81]
	v_mfma_f32_16x16x32_bf16 v[74:77], v[160:163], v[208:211], v[74:77]
	v_mfma_f32_16x16x32_bf16 v[122:125], v[156:159], v[188:191], v[122:125]
	v_mfma_f32_16x16x32_bf16 v[126:129], v[164:167], v[188:191], v[126:129]
	v_mfma_f32_16x16x32_bf16 v[110:113], v[156:159], v[196:199], v[110:113]
	v_mfma_f32_16x16x32_bf16 v[106:109], v[164:167], v[196:199], v[106:109]
	v_mfma_f32_16x16x32_bf16 v[94:97], v[156:159], v[204:207], v[94:97]
	v_mfma_f32_16x16x32_bf16 v[90:93], v[164:167], v[204:207], v[90:93]
	v_mfma_f32_16x16x32_bf16 v[78:81], v[156:159], v[212:215], v[78:81]
	v_mfma_f32_16x16x32_bf16 v[74:77], v[164:167], v[212:215], v[74:77]
	s_setprio 0
	s_setprio 1
	v_mfma_f32_16x16x32_bf16 v[118:121], v[168:171], v[184:187], v[118:121]
	v_mfma_f32_16x16x32_bf16 v[114:117], v[176:179], v[184:187], v[114:117]
	v_mfma_f32_16x16x32_bf16 v[102:105], v[168:171], v[192:195], v[102:105]
	v_mfma_f32_16x16x32_bf16 v[98:101], v[176:179], v[192:195], v[98:101]
	v_mfma_f32_16x16x32_bf16 v[86:89], v[168:171], v[200:203], v[86:89]
	v_mfma_f32_16x16x32_bf16 v[82:85], v[176:179], v[200:203], v[82:85]
	v_mfma_f32_16x16x32_bf16 v[70:73], v[168:171], v[208:211], v[70:73]
	v_mfma_f32_16x16x32_bf16 v[66:69], v[176:179], v[208:211], v[66:69]
	v_mfma_f32_16x16x32_bf16 v[118:121], v[172:175], v[188:191], v[118:121]
	v_mfma_f32_16x16x32_bf16 v[114:117], v[180:183], v[188:191], v[114:117]
	s_barrier
	v_mfma_f32_16x16x32_bf16 v[102:105], v[172:175], v[196:199], v[102:105]
	v_mfma_f32_16x16x32_bf16 v[98:101], v[180:183], v[196:199], v[98:101]
	v_mfma_f32_16x16x32_bf16 v[86:89], v[172:175], v[204:207], v[86:89]
	v_mfma_f32_16x16x32_bf16 v[82:85], v[180:183], v[204:207], v[82:85]
	v_mfma_f32_16x16x32_bf16 v[70:73], v[172:175], v[212:215], v[70:73]
	v_mfma_f32_16x16x32_bf16 v[66:69], v[180:183], v[212:215], v[66:69]
	s_setprio 0
	s_nop 0
	s_add_i32 s82, s61, s44
	v_lshl_add_u64 v[216:217], s[80:81], 0, v[134:135]
	s_mov_b32 m0, s82
	ds_read_b128 v[184:187], v151 offset:16384
	ds_read_b128 v[188:191], v151 offset:17408
	ds_read_b128 v[192:195], v151 offset:18432
	ds_read_b128 v[196:199], v151 offset:19456
	ds_read_b128 v[200:203], v151 offset:20480
	ds_read_b128 v[204:207], v151 offset:21504
	ds_read_b128 v[208:211], v151 offset:22528
	ds_read_b128 v[212:215], v151 offset:23552
	global_load_lds_dwordx4 v[216:217], off
	s_add_i32 m0, s82, 0x2000
	v_lshl_add_u64 v[218:219], s[80:81], 0, v[130:131]
	s_add_u32 s80, s80, s6
	s_addc_u32 s81, s81, s7
	s_add_i32 s82, s62, s44
	global_load_lds_dwordx4 v[218:219], off
	v_lshl_add_u64 v[220:221], s[80:81], 0, v[134:135]
	s_mov_b32 m0, s82
	v_lshl_add_u64 v[222:223], s[80:81], 0, v[130:131]
	global_load_lds_dwordx4 v[220:221], off
	s_add_i32 m0, s82, 0x2000
	v_lshl_add_u64 v[224:225], s[36:37], 0, v[136:137]
	global_load_lds_dwordx4 v[222:223], off
	s_mov_b32 m0, s47
	v_lshl_add_u64 v[226:227], s[36:37], 0, v[132:133]
	global_load_lds_dwordx4 v[224:225], off
	s_mov_b32 m0, s50
	s_nop 0
	global_load_lds_dwordx4 v[226:227], off
	s_waitcnt vmcnt(8)
	s_waitcnt lgkmcnt(0)
	s_barrier
	s_setprio 1
	s_waitcnt lgkmcnt(0)
	v_mfma_f32_16x16x32_bf16 v[62:65], v[152:155], v[184:187], v[62:65]
	v_mfma_f32_16x16x32_bf16 v[58:61], v[160:163], v[184:187], v[58:61]
	v_mfma_f32_16x16x32_bf16 v[46:49], v[152:155], v[192:195], v[46:49]
	v_mfma_f32_16x16x32_bf16 v[42:45], v[160:163], v[192:195], v[42:45]
	v_mfma_f32_16x16x32_bf16 v[30:33], v[152:155], v[200:203], v[30:33]
	v_mfma_f32_16x16x32_bf16 v[26:29], v[160:163], v[200:203], v[26:29]
	v_mfma_f32_16x16x32_bf16 v[14:17], v[152:155], v[208:211], v[14:17]
	v_mfma_f32_16x16x32_bf16 v[10:13], v[160:163], v[208:211], v[10:13]
	v_mfma_f32_16x16x32_bf16 v[62:65], v[156:159], v[188:191], v[62:65]
	v_mfma_f32_16x16x32_bf16 v[58:61], v[164:167], v[188:191], v[58:61]
	v_mfma_f32_16x16x32_bf16 v[46:49], v[156:159], v[196:199], v[46:49]
	v_mfma_f32_16x16x32_bf16 v[42:45], v[164:167], v[196:199], v[42:45]
	v_mfma_f32_16x16x32_bf16 v[30:33], v[156:159], v[204:207], v[30:33]
	v_mfma_f32_16x16x32_bf16 v[26:29], v[164:167], v[204:207], v[26:29]
	v_mfma_f32_16x16x32_bf16 v[14:17], v[156:159], v[212:215], v[14:17]
	v_mfma_f32_16x16x32_bf16 v[10:13], v[164:167], v[212:215], v[10:13]
	s_setprio 0
	s_setprio 1
	v_mfma_f32_16x16x32_bf16 v[54:57], v[168:171], v[184:187], v[54:57]
	v_mfma_f32_16x16x32_bf16 v[50:53], v[176:179], v[184:187], v[50:53]
	v_mfma_f32_16x16x32_bf16 v[38:41], v[168:171], v[192:195], v[38:41]
	v_mfma_f32_16x16x32_bf16 v[34:37], v[176:179], v[192:195], v[34:37]
	v_mfma_f32_16x16x32_bf16 v[22:25], v[168:171], v[200:203], v[22:25]
	v_mfma_f32_16x16x32_bf16 v[18:21], v[176:179], v[200:203], v[18:21]
	v_mfma_f32_16x16x32_bf16 v[6:9], v[168:171], v[208:211], v[6:9]
	v_mfma_f32_16x16x32_bf16 v[2:5], v[176:179], v[208:211], v[2:5]
	v_mfma_f32_16x16x32_bf16 v[54:57], v[172:175], v[188:191], v[54:57]
	v_mfma_f32_16x16x32_bf16 v[50:53], v[180:183], v[188:191], v[50:53]
	s_barrier
	v_mfma_f32_16x16x32_bf16 v[38:41], v[172:175], v[196:199], v[38:41]
	v_mfma_f32_16x16x32_bf16 v[34:37], v[180:183], v[196:199], v[34:37]
	v_mfma_f32_16x16x32_bf16 v[22:25], v[172:175], v[204:207], v[22:25]
	v_mfma_f32_16x16x32_bf16 v[18:21], v[180:183], v[204:207], v[18:21]
	v_mfma_f32_16x16x32_bf16 v[6:9], v[172:175], v[212:215], v[6:9]
	v_mfma_f32_16x16x32_bf16 v[2:5], v[180:183], v[212:215], v[2:5]
	s_setprio 0
	s_nop 0
	s_add_i32 s80, 0, 0x18000
	s_add_i32 s81, 0, 0x1c000
	v_add_u32_e32 v164, s80, v147
	v_add_u32_e32 v180, s81, v147
	ds_read_b128 v[152:155], v164
	ds_read_b128 v[156:159], v164 offset:1024
	ds_read_b128 v[160:163], v164 offset:2048
	ds_read_b128 v[164:167], v164 offset:3072
	ds_read_b128 v[168:171], v180
	ds_read_b128 v[172:175], v180 offset:1024
	ds_read_b128 v[176:179], v180 offset:2048
	ds_read_b128 v[180:183], v180 offset:3072
	s_add_u32 s36, s36, s6
	s_addc_u32 s37, s37, s7
	s_mov_b32 m0, s51
	v_lshl_add_u64 v[228:229], s[36:37], 0, v[136:137]
	ds_read_b128 v[184:187], v151 offset:32768
	ds_read_b128 v[188:191], v151 offset:33792
	ds_read_b128 v[192:195], v151 offset:34816
	ds_read_b128 v[196:199], v151 offset:35840
	ds_read_b128 v[200:203], v151 offset:36864
	ds_read_b128 v[204:207], v151 offset:37888
	ds_read_b128 v[208:211], v151 offset:38912
	ds_read_b128 v[212:215], v151 offset:39936
	global_load_lds_dwordx4 v[228:229], off
	v_lshl_add_u64 v[228:229], s[36:37], 0, v[132:133]
	s_mov_b32 m0, s54
	s_nop 0
	global_load_lds_dwordx4 v[228:229], off
	s_waitcnt vmcnt(8)
	s_waitcnt lgkmcnt(0)
	s_barrier
	s_setprio 1
	s_waitcnt lgkmcnt(0)
	v_mfma_f32_16x16x32_bf16 v[122:125], v[152:155], v[184:187], v[122:125]
	v_mfma_f32_16x16x32_bf16 v[126:129], v[160:163], v[184:187], v[126:129]
	v_mfma_f32_16x16x32_bf16 v[110:113], v[152:155], v[192:195], v[110:113]
	v_mfma_f32_16x16x32_bf16 v[106:109], v[160:163], v[192:195], v[106:109]
	v_mfma_f32_16x16x32_bf16 v[94:97], v[152:155], v[200:203], v[94:97]
	v_mfma_f32_16x16x32_bf16 v[90:93], v[160:163], v[200:203], v[90:93]
	v_mfma_f32_16x16x32_bf16 v[78:81], v[152:155], v[208:211], v[78:81]
	v_mfma_f32_16x16x32_bf16 v[74:77], v[160:163], v[208:211], v[74:77]
	v_mfma_f32_16x16x32_bf16 v[122:125], v[156:159], v[188:191], v[122:125]
	v_mfma_f32_16x16x32_bf16 v[126:129], v[164:167], v[188:191], v[126:129]
	v_mfma_f32_16x16x32_bf16 v[110:113], v[156:159], v[196:199], v[110:113]
	v_mfma_f32_16x16x32_bf16 v[106:109], v[164:167], v[196:199], v[106:109]
	v_mfma_f32_16x16x32_bf16 v[94:97], v[156:159], v[204:207], v[94:97]
	v_mfma_f32_16x16x32_bf16 v[90:93], v[164:167], v[204:207], v[90:93]
	v_mfma_f32_16x16x32_bf16 v[78:81], v[156:159], v[212:215], v[78:81]
	v_mfma_f32_16x16x32_bf16 v[74:77], v[164:167], v[212:215], v[74:77]
	s_setprio 0
	s_setprio 1
	v_mfma_f32_16x16x32_bf16 v[118:121], v[168:171], v[184:187], v[118:121]
	v_mfma_f32_16x16x32_bf16 v[114:117], v[176:179], v[184:187], v[114:117]
	v_mfma_f32_16x16x32_bf16 v[102:105], v[168:171], v[192:195], v[102:105]
	v_mfma_f32_16x16x32_bf16 v[98:101], v[176:179], v[192:195], v[98:101]
	v_mfma_f32_16x16x32_bf16 v[86:89], v[168:171], v[200:203], v[86:89]
	v_mfma_f32_16x16x32_bf16 v[82:85], v[176:179], v[200:203], v[82:85]
	v_mfma_f32_16x16x32_bf16 v[70:73], v[168:171], v[208:211], v[70:73]
	v_mfma_f32_16x16x32_bf16 v[66:69], v[176:179], v[208:211], v[66:69]
	v_mfma_f32_16x16x32_bf16 v[118:121], v[172:175], v[188:191], v[118:121]
	v_mfma_f32_16x16x32_bf16 v[114:117], v[180:183], v[188:191], v[114:117]
	s_barrier
	v_mfma_f32_16x16x32_bf16 v[102:105], v[172:175], v[196:199], v[102:105]
	v_mfma_f32_16x16x32_bf16 v[98:101], v[180:183], v[196:199], v[98:101]
	v_mfma_f32_16x16x32_bf16 v[86:89], v[172:175], v[204:207], v[86:89]
	v_mfma_f32_16x16x32_bf16 v[82:85], v[180:183], v[204:207], v[82:85]
	v_mfma_f32_16x16x32_bf16 v[70:73], v[172:175], v[212:215], v[70:73]
	v_mfma_f32_16x16x32_bf16 v[66:69], v[180:183], v[212:215], v[66:69]
	s_setprio 0
	s_nop 0
	s_add_i32 s36, s80, s44
	v_lshl_add_u64 v[216:217], v[216:217], 0, s[16:17]
	s_mov_b32 m0, s36
	ds_read_b128 v[184:187], v151 offset:49152
	ds_read_b128 v[188:191], v151 offset:50176
	ds_read_b128 v[192:195], v151 offset:51200
	ds_read_b128 v[196:199], v151 offset:52224
	ds_read_b128 v[200:203], v151 offset:53248
	ds_read_b128 v[204:207], v151 offset:54272
	ds_read_b128 v[208:211], v151 offset:55296
	ds_read_b128 v[212:215], v151 offset:56320
	global_load_lds_dwordx4 v[216:217], off
	v_lshl_add_u64 v[216:217], v[218:219], 0, s[16:17]
	s_add_i32 m0, s36, 0x2000
	s_add_i32 s36, s81, s44
	global_load_lds_dwordx4 v[216:217], off
	v_lshl_add_u64 v[216:217], v[220:221], 0, s[16:17]
	s_mov_b32 m0, s36
	s_nop 0
	global_load_lds_dwordx4 v[216:217], off
	v_lshl_add_u64 v[216:217], v[222:223], 0, s[16:17]
	s_add_i32 m0, s36, 0x2000
	s_nop 0
	global_load_lds_dwordx4 v[216:217], off
	v_lshl_add_u64 v[216:217], v[224:225], 0, s[16:17]
	s_mov_b32 m0, s56
	s_nop 0
	global_load_lds_dwordx4 v[216:217], off
	v_lshl_add_u64 v[216:217], v[226:227], 0, s[16:17]
	s_mov_b32 m0, s57
	s_nop 0
	global_load_lds_dwordx4 v[216:217], off
	s_waitcnt vmcnt(8)
	s_waitcnt lgkmcnt(0)
	s_barrier
	s_setprio 1
	s_waitcnt lgkmcnt(0)
	v_mfma_f32_16x16x32_bf16 v[62:65], v[152:155], v[184:187], v[62:65]
	v_mfma_f32_16x16x32_bf16 v[58:61], v[160:163], v[184:187], v[58:61]
	v_mfma_f32_16x16x32_bf16 v[46:49], v[152:155], v[192:195], v[46:49]
	v_mfma_f32_16x16x32_bf16 v[42:45], v[160:163], v[192:195], v[42:45]
	v_mfma_f32_16x16x32_bf16 v[30:33], v[152:155], v[200:203], v[30:33]
	v_mfma_f32_16x16x32_bf16 v[26:29], v[160:163], v[200:203], v[26:29]
	v_mfma_f32_16x16x32_bf16 v[14:17], v[152:155], v[208:211], v[14:17]
	v_mfma_f32_16x16x32_bf16 v[10:13], v[160:163], v[208:211], v[10:13]
	v_mfma_f32_16x16x32_bf16 v[62:65], v[156:159], v[188:191], v[62:65]
	v_mfma_f32_16x16x32_bf16 v[58:61], v[164:167], v[188:191], v[58:61]
	v_mfma_f32_16x16x32_bf16 v[46:49], v[156:159], v[196:199], v[46:49]
	v_mfma_f32_16x16x32_bf16 v[42:45], v[164:167], v[196:199], v[42:45]
	v_mfma_f32_16x16x32_bf16 v[30:33], v[156:159], v[204:207], v[30:33]
	v_mfma_f32_16x16x32_bf16 v[26:29], v[164:167], v[204:207], v[26:29]
	v_mfma_f32_16x16x32_bf16 v[14:17], v[156:159], v[212:215], v[14:17]
	v_mfma_f32_16x16x32_bf16 v[10:13], v[164:167], v[212:215], v[10:13]
	s_setprio 0
	s_setprio 1
	v_mfma_f32_16x16x32_bf16 v[54:57], v[168:171], v[184:187], v[54:57]
	v_mfma_f32_16x16x32_bf16 v[50:53], v[176:179], v[184:187], v[50:53]
	v_mfma_f32_16x16x32_bf16 v[38:41], v[168:171], v[192:195], v[38:41]
	v_mfma_f32_16x16x32_bf16 v[34:37], v[176:179], v[192:195], v[34:37]
	v_mfma_f32_16x16x32_bf16 v[22:25], v[168:171], v[200:203], v[22:25]
	v_mfma_f32_16x16x32_bf16 v[18:21], v[176:179], v[200:203], v[18:21]
	v_mfma_f32_16x16x32_bf16 v[6:9], v[168:171], v[208:211], v[6:9]
	v_mfma_f32_16x16x32_bf16 v[2:5], v[176:179], v[208:211], v[2:5]
	v_mfma_f32_16x16x32_bf16 v[54:57], v[172:175], v[188:191], v[54:57]
	v_mfma_f32_16x16x32_bf16 v[50:53], v[180:183], v[188:191], v[50:53]
	s_barrier
	v_mfma_f32_16x16x32_bf16 v[38:41], v[172:175], v[196:199], v[38:41]
	v_mfma_f32_16x16x32_bf16 v[34:37], v[180:183], v[196:199], v[34:37]
	v_mfma_f32_16x16x32_bf16 v[22:25], v[172:175], v[204:207], v[22:25]
	v_mfma_f32_16x16x32_bf16 v[18:21], v[180:183], v[204:207], v[18:21]
	v_mfma_f32_16x16x32_bf16 v[6:9], v[172:175], v[212:215], v[6:9]
	v_mfma_f32_16x16x32_bf16 v[2:5], v[180:183], v[212:215], v[2:5]
	s_setprio 0
	s_nop 0
	s_add_u32 s34, s34, 0x100
	s_addc_u32 s35, s35, 0
	s_add_u32 s67, s67, 0x100
	s_addc_u32 s68, s68, 0
	s_cmp_ge_i32 s69, s58
	s_mov_b32 s36, s69
	s_cbranch_scc0 .LBB0_1514

.LBB0_1754:
	v_add_u32_e32 v158, s80, v229
	v_add_u32_e32 v174, s81, v229
	ds_read_b128 v[146:149], v158
	ds_read_b128 v[150:153], v158 offset:1024
	ds_read_b128 v[154:157], v158 offset:2048
	ds_read_b128 v[158:161], v158 offset:3072
	ds_read_b128 v[162:165], v174
	ds_read_b128 v[166:169], v174 offset:1024
	ds_read_b128 v[170:173], v174 offset:2048
	ds_read_b128 v[174:177], v174 offset:3072
	s_add_i32 s88, s44, 2
	s_add_u32 s89, s42, 0x80
	s_addc_u32 s45, s43, 0
	s_cmp_eq_u32 s67, s44
	s_cselect_b32 s44, s4, s89
	s_cselect_b32 s45, s5, s45
	s_cselect_b32 s91, s39, s87
	s_cselect_b32 s90, s38, s86
	v_lshl_add_u64 v[210:211], s[42:43], 0, v[138:139]
	s_add_i32 m0, s55, 0xc000
	ds_read_b128 v[178:181], v231
	ds_read_b128 v[182:185], v231 offset:1024
	ds_read_b128 v[186:189], v231 offset:2048
	ds_read_b128 v[190:193], v231 offset:3072
	ds_read_b128 v[194:197], v231 offset:4096
	ds_read_b128 v[198:201], v231 offset:5120
	ds_read_b128 v[202:205], v231 offset:6144
	ds_read_b128 v[206:209], v231 offset:7168
	global_load_lds_dwordx4 v[210:211], off
	v_lshl_add_u64 v[210:211], s[42:43], 0, v[140:141]
	s_add_i32 m0, s55, 0xe000
	s_nop 0
	global_load_lds_dwordx4 v[210:211], off
	s_waitcnt vmcnt(8)
	s_waitcnt lgkmcnt(0)
	s_barrier
	s_setprio 1
	s_waitcnt lgkmcnt(0)
	v_mfma_i32_16x16x64_i8 v[126:129], v[146:149], v[178:181], v[126:129]
	v_mfma_i32_16x16x64_i8 v[122:125], v[154:157], v[178:181], v[122:125]
	v_mfma_i32_16x16x64_i8 v[118:121], v[146:149], v[186:189], v[118:121]
	v_mfma_i32_16x16x64_i8 v[114:117], v[154:157], v[186:189], v[114:117]
	v_mfma_i32_16x16x64_i8 v[106:109], v[146:149], v[194:197], v[106:109]
	v_mfma_i32_16x16x64_i8 v[98:101], v[154:157], v[194:197], v[98:101]
	v_mfma_i32_16x16x64_i8 v[90:93], v[146:149], v[202:205], v[90:93]
	v_mfma_i32_16x16x64_i8 v[82:85], v[154:157], v[202:205], v[82:85]
	v_mfma_i32_16x16x64_i8 v[126:129], v[150:153], v[182:185], v[126:129]
	v_mfma_i32_16x16x64_i8 v[122:125], v[158:161], v[182:185], v[122:125]
	v_mfma_i32_16x16x64_i8 v[118:121], v[150:153], v[190:193], v[118:121]
	v_mfma_i32_16x16x64_i8 v[114:117], v[158:161], v[190:193], v[114:117]
	v_mfma_i32_16x16x64_i8 v[106:109], v[150:153], v[198:201], v[106:109]
	v_mfma_i32_16x16x64_i8 v[98:101], v[158:161], v[198:201], v[98:101]
	v_mfma_i32_16x16x64_i8 v[90:93], v[150:153], v[206:209], v[90:93]
	v_mfma_i32_16x16x64_i8 v[82:85], v[158:161], v[206:209], v[82:85]
	s_setprio 0
	s_setprio 1
	v_mfma_i32_16x16x64_i8 v[110:113], v[162:165], v[178:181], v[110:113]
	v_mfma_i32_16x16x64_i8 v[102:105], v[170:173], v[178:181], v[102:105]
	v_mfma_i32_16x16x64_i8 v[94:97], v[162:165], v[186:189], v[94:97]
	v_mfma_i32_16x16x64_i8 v[86:89], v[170:173], v[186:189], v[86:89]
	v_mfma_i32_16x16x64_i8 v[78:81], v[162:165], v[194:197], v[78:81]
	v_mfma_i32_16x16x64_i8 v[74:77], v[170:173], v[194:197], v[74:77]
	v_mfma_i32_16x16x64_i8 v[70:73], v[162:165], v[202:205], v[70:73]
	v_mfma_i32_16x16x64_i8 v[66:69], v[170:173], v[202:205], v[66:69]
	v_mfma_i32_16x16x64_i8 v[110:113], v[166:169], v[182:185], v[110:113]
	v_mfma_i32_16x16x64_i8 v[102:105], v[174:177], v[182:185], v[102:105]
	s_barrier
	v_mfma_i32_16x16x64_i8 v[94:97], v[166:169], v[190:193], v[94:97]
	v_mfma_i32_16x16x64_i8 v[86:89], v[174:177], v[190:193], v[86:89]
	v_mfma_i32_16x16x64_i8 v[78:81], v[166:169], v[198:201], v[78:81]
	v_mfma_i32_16x16x64_i8 v[74:77], v[174:177], v[198:201], v[74:77]
	v_mfma_i32_16x16x64_i8 v[70:73], v[166:169], v[206:209], v[70:73]
	v_mfma_i32_16x16x64_i8 v[66:69], v[174:177], v[206:209], v[66:69]
	s_setprio 0
	s_nop 0
	s_add_i32 s89, s80, s54
	v_lshl_add_u64 v[210:211], s[90:91], 0, v[132:133]
	s_mov_b32 m0, s89
	ds_read_b128 v[178:181], v231 offset:16384
	ds_read_b128 v[182:185], v231 offset:17408
	ds_read_b128 v[186:189], v231 offset:18432
	ds_read_b128 v[190:193], v231 offset:19456
	ds_read_b128 v[194:197], v231 offset:20480
	ds_read_b128 v[198:201], v231 offset:21504
	ds_read_b128 v[202:205], v231 offset:22528
	ds_read_b128 v[206:209], v231 offset:23552
	global_load_lds_dwordx4 v[210:211], off
	s_add_i32 m0, s89, 0x2000
	v_lshl_add_u64 v[212:213], s[90:91], 0, v[136:137]
	s_add_u32 s90, s90, s8
	s_addc_u32 s91, s91, s9
	s_add_i32 s89, s81, s54
	global_load_lds_dwordx4 v[212:213], off
	v_lshl_add_u64 v[214:215], s[90:91], 0, v[132:133]
	s_mov_b32 m0, s89
	v_lshl_add_u64 v[216:217], s[90:91], 0, v[136:137]
	global_load_lds_dwordx4 v[214:215], off
	s_add_i32 m0, s89, 0x2000
	v_lshl_add_u64 v[218:219], s[44:45], 0, v[130:131]
	global_load_lds_dwordx4 v[216:217], off
	s_mov_b32 m0, s55
	v_lshl_add_u64 v[220:221], s[44:45], 0, v[134:135]
	global_load_lds_dwordx4 v[218:219], off
	s_mov_b32 m0, s56
	s_nop 0
	global_load_lds_dwordx4 v[220:221], off
	s_waitcnt vmcnt(8)
	s_waitcnt lgkmcnt(0)
	s_barrier
	s_setprio 1
	s_waitcnt lgkmcnt(0)
	v_mfma_i32_16x16x64_i8 v[62:65], v[146:149], v[178:181], v[62:65]
	v_mfma_i32_16x16x64_i8 v[58:61], v[154:157], v[178:181], v[58:61]
	v_mfma_i32_16x16x64_i8 v[54:57], v[146:149], v[186:189], v[54:57]
	v_mfma_i32_16x16x64_i8 v[50:53], v[154:157], v[186:189], v[50:53]
	v_mfma_i32_16x16x64_i8 v[42:45], v[146:149], v[194:197], v[42:45]
	v_mfma_i32_16x16x64_i8 v[34:37], v[154:157], v[194:197], v[34:37]
	v_mfma_i32_16x16x64_i8 v[26:29], v[146:149], v[202:205], v[26:29]
	v_mfma_i32_16x16x64_i8 v[18:21], v[154:157], v[202:205], v[18:21]
	v_mfma_i32_16x16x64_i8 v[62:65], v[150:153], v[182:185], v[62:65]
	v_mfma_i32_16x16x64_i8 v[58:61], v[158:161], v[182:185], v[58:61]
	v_mfma_i32_16x16x64_i8 v[54:57], v[150:153], v[190:193], v[54:57]
	v_mfma_i32_16x16x64_i8 v[50:53], v[158:161], v[190:193], v[50:53]
	v_mfma_i32_16x16x64_i8 v[42:45], v[150:153], v[198:201], v[42:45]
	v_mfma_i32_16x16x64_i8 v[34:37], v[158:161], v[198:201], v[34:37]
	v_mfma_i32_16x16x64_i8 v[26:29], v[150:153], v[206:209], v[26:29]
	v_mfma_i32_16x16x64_i8 v[18:21], v[158:161], v[206:209], v[18:21]
	s_setprio 0
	s_setprio 1
	v_mfma_i32_16x16x64_i8 v[46:49], v[162:165], v[178:181], v[46:49]
	v_mfma_i32_16x16x64_i8 v[38:41], v[170:173], v[178:181], v[38:41]
	v_mfma_i32_16x16x64_i8 v[30:33], v[162:165], v[186:189], v[30:33]
	v_mfma_i32_16x16x64_i8 v[22:25], v[170:173], v[186:189], v[22:25]
	v_mfma_i32_16x16x64_i8 v[14:17], v[162:165], v[194:197], v[14:17]
	v_mfma_i32_16x16x64_i8 v[10:13], v[170:173], v[194:197], v[10:13]
	v_mfma_i32_16x16x64_i8 v[6:9], v[162:165], v[202:205], v[6:9]
	v_mfma_i32_16x16x64_i8 v[2:5], v[170:173], v[202:205], v[2:5]
	v_mfma_i32_16x16x64_i8 v[46:49], v[166:169], v[182:185], v[46:49]
	v_mfma_i32_16x16x64_i8 v[38:41], v[174:177], v[182:185], v[38:41]
	s_barrier
	v_mfma_i32_16x16x64_i8 v[30:33], v[166:169], v[190:193], v[30:33]
	v_mfma_i32_16x16x64_i8 v[22:25], v[174:177], v[190:193], v[22:25]
	v_mfma_i32_16x16x64_i8 v[14:17], v[166:169], v[198:201], v[14:17]
	v_mfma_i32_16x16x64_i8 v[10:13], v[174:177], v[198:201], v[10:13]
	v_mfma_i32_16x16x64_i8 v[6:9], v[166:169], v[206:209], v[6:9]
	v_mfma_i32_16x16x64_i8 v[2:5], v[174:177], v[206:209], v[2:5]
	s_setprio 0
	s_nop 0
	s_add_i32 s89, 0, 0x18000
	s_add_i32 s90, 0, 0x1c000
	v_add_u32_e32 v158, s89, v229
	v_add_u32_e32 v174, s90, v229
	ds_read_b128 v[146:149], v158
	ds_read_b128 v[150:153], v158 offset:1024
	ds_read_b128 v[154:157], v158 offset:2048
	ds_read_b128 v[158:161], v158 offset:3072
	ds_read_b128 v[162:165], v174
	ds_read_b128 v[166:169], v174 offset:1024
	ds_read_b128 v[170:173], v174 offset:2048
	ds_read_b128 v[174:177], v174 offset:3072
	s_add_u32 s44, s44, s8
	s_addc_u32 s45, s45, s9
	s_mov_b32 m0, s57
	v_lshl_add_u64 v[222:223], s[44:45], 0, v[130:131]
	ds_read_b128 v[178:181], v231 offset:32768
	ds_read_b128 v[182:185], v231 offset:33792
	ds_read_b128 v[186:189], v231 offset:34816
	ds_read_b128 v[190:193], v231 offset:35840
	ds_read_b128 v[194:197], v231 offset:36864
	ds_read_b128 v[198:201], v231 offset:37888
	ds_read_b128 v[202:205], v231 offset:38912
	ds_read_b128 v[206:209], v231 offset:39936
	global_load_lds_dwordx4 v[222:223], off
	v_lshl_add_u64 v[222:223], s[44:45], 0, v[134:135]
	s_mov_b32 m0, s58
	s_nop 0
	global_load_lds_dwordx4 v[222:223], off
	s_waitcnt vmcnt(8)
	s_waitcnt lgkmcnt(0)
	s_barrier
	s_setprio 1
	s_waitcnt lgkmcnt(0)
	v_mfma_i32_16x16x64_i8 v[126:129], v[146:149], v[178:181], v[126:129]
	v_mfma_i32_16x16x64_i8 v[122:125], v[154:157], v[178:181], v[122:125]
	v_mfma_i32_16x16x64_i8 v[118:121], v[146:149], v[186:189], v[118:121]
	v_mfma_i32_16x16x64_i8 v[114:117], v[154:157], v[186:189], v[114:117]
	v_mfma_i32_16x16x64_i8 v[106:109], v[146:149], v[194:197], v[106:109]
	v_mfma_i32_16x16x64_i8 v[98:101], v[154:157], v[194:197], v[98:101]
	v_mfma_i32_16x16x64_i8 v[90:93], v[146:149], v[202:205], v[90:93]
	v_mfma_i32_16x16x64_i8 v[82:85], v[154:157], v[202:205], v[82:85]
	v_mfma_i32_16x16x64_i8 v[126:129], v[150:153], v[182:185], v[126:129]
	v_mfma_i32_16x16x64_i8 v[122:125], v[158:161], v[182:185], v[122:125]
	v_mfma_i32_16x16x64_i8 v[118:121], v[150:153], v[190:193], v[118:121]
	v_mfma_i32_16x16x64_i8 v[114:117], v[158:161], v[190:193], v[114:117]
	v_mfma_i32_16x16x64_i8 v[106:109], v[150:153], v[198:201], v[106:109]
	v_mfma_i32_16x16x64_i8 v[98:101], v[158:161], v[198:201], v[98:101]
	v_mfma_i32_16x16x64_i8 v[90:93], v[150:153], v[206:209], v[90:93]
	v_mfma_i32_16x16x64_i8 v[82:85], v[158:161], v[206:209], v[82:85]
	s_setprio 0
	s_setprio 1
	v_mfma_i32_16x16x64_i8 v[110:113], v[162:165], v[178:181], v[110:113]
	v_mfma_i32_16x16x64_i8 v[102:105], v[170:173], v[178:181], v[102:105]
	v_mfma_i32_16x16x64_i8 v[94:97], v[162:165], v[186:189], v[94:97]
	v_mfma_i32_16x16x64_i8 v[86:89], v[170:173], v[186:189], v[86:89]
	v_mfma_i32_16x16x64_i8 v[78:81], v[162:165], v[194:197], v[78:81]
	v_mfma_i32_16x16x64_i8 v[74:77], v[170:173], v[194:197], v[74:77]
	v_mfma_i32_16x16x64_i8 v[70:73], v[162:165], v[202:205], v[70:73]
	v_mfma_i32_16x16x64_i8 v[66:69], v[170:173], v[202:205], v[66:69]
	v_mfma_i32_16x16x64_i8 v[110:113], v[166:169], v[182:185], v[110:113]
	v_mfma_i32_16x16x64_i8 v[102:105], v[174:177], v[182:185], v[102:105]
	s_barrier
	v_mfma_i32_16x16x64_i8 v[94:97], v[166:169], v[190:193], v[94:97]
	v_mfma_i32_16x16x64_i8 v[86:89], v[174:177], v[190:193], v[86:89]
	v_mfma_i32_16x16x64_i8 v[78:81], v[166:169], v[198:201], v[78:81]
	v_mfma_i32_16x16x64_i8 v[74:77], v[174:177], v[198:201], v[74:77]
	v_mfma_i32_16x16x64_i8 v[70:73], v[166:169], v[206:209], v[70:73]
	v_mfma_i32_16x16x64_i8 v[66:69], v[174:177], v[206:209], v[66:69]
	s_setprio 0
	s_nop 0
	s_add_i32 s44, s89, s54
	v_lshl_add_u64 v[210:211], v[210:211], 0, s[30:31]
	s_mov_b32 m0, s44
	ds_read_b128 v[178:181], v231 offset:49152
	ds_read_b128 v[182:185], v231 offset:50176
	ds_read_b128 v[186:189], v231 offset:51200
	ds_read_b128 v[190:193], v231 offset:52224
	ds_read_b128 v[194:197], v231 offset:53248
	ds_read_b128 v[198:201], v231 offset:54272
	ds_read_b128 v[202:205], v231 offset:55296
	ds_read_b128 v[206:209], v231 offset:56320
	global_load_lds_dwordx4 v[210:211], off
	v_lshl_add_u64 v[210:211], v[212:213], 0, s[30:31]
	s_add_i32 m0, s44, 0x2000
	s_add_i32 s44, s90, s54
	global_load_lds_dwordx4 v[210:211], off
	v_lshl_add_u64 v[210:211], v[214:215], 0, s[30:31]
	s_mov_b32 m0, s44
	s_nop 0
	global_load_lds_dwordx4 v[210:211], off
	v_lshl_add_u64 v[210:211], v[216:217], 0, s[30:31]
	s_add_i32 m0, s44, 0x2000
	s_nop 0
	global_load_lds_dwordx4 v[210:211], off
	v_lshl_add_u64 v[210:211], v[218:219], 0, s[30:31]
	s_mov_b32 m0, s63
	s_nop 0
	global_load_lds_dwordx4 v[210:211], off
	v_lshl_add_u64 v[210:211], v[220:221], 0, s[30:31]
	s_mov_b32 m0, s64
	s_nop 0
	global_load_lds_dwordx4 v[210:211], off
	s_waitcnt vmcnt(8)
	s_waitcnt lgkmcnt(0)
	s_barrier
	s_setprio 1
	s_waitcnt lgkmcnt(0)
	v_mfma_i32_16x16x64_i8 v[62:65], v[146:149], v[178:181], v[62:65]
	v_mfma_i32_16x16x64_i8 v[58:61], v[154:157], v[178:181], v[58:61]
	v_mfma_i32_16x16x64_i8 v[54:57], v[146:149], v[186:189], v[54:57]
	v_mfma_i32_16x16x64_i8 v[50:53], v[154:157], v[186:189], v[50:53]
	v_mfma_i32_16x16x64_i8 v[42:45], v[146:149], v[194:197], v[42:45]
	v_mfma_i32_16x16x64_i8 v[34:37], v[154:157], v[194:197], v[34:37]
	v_mfma_i32_16x16x64_i8 v[26:29], v[146:149], v[202:205], v[26:29]
	v_mfma_i32_16x16x64_i8 v[18:21], v[154:157], v[202:205], v[18:21]
	v_mfma_i32_16x16x64_i8 v[62:65], v[150:153], v[182:185], v[62:65]
	v_mfma_i32_16x16x64_i8 v[58:61], v[158:161], v[182:185], v[58:61]
	v_mfma_i32_16x16x64_i8 v[54:57], v[150:153], v[190:193], v[54:57]
	v_mfma_i32_16x16x64_i8 v[50:53], v[158:161], v[190:193], v[50:53]
	v_mfma_i32_16x16x64_i8 v[42:45], v[150:153], v[198:201], v[42:45]
	v_mfma_i32_16x16x64_i8 v[34:37], v[158:161], v[198:201], v[34:37]
	v_mfma_i32_16x16x64_i8 v[26:29], v[150:153], v[206:209], v[26:29]
	v_mfma_i32_16x16x64_i8 v[18:21], v[158:161], v[206:209], v[18:21]
	s_setprio 0
	s_setprio 1
	v_mfma_i32_16x16x64_i8 v[46:49], v[162:165], v[178:181], v[46:49]
	v_mfma_i32_16x16x64_i8 v[38:41], v[170:173], v[178:181], v[38:41]
	v_mfma_i32_16x16x64_i8 v[30:33], v[162:165], v[186:189], v[30:33]
	v_mfma_i32_16x16x64_i8 v[22:25], v[170:173], v[186:189], v[22:25]
	v_mfma_i32_16x16x64_i8 v[14:17], v[162:165], v[194:197], v[14:17]
	v_mfma_i32_16x16x64_i8 v[10:13], v[170:173], v[194:197], v[10:13]
	v_mfma_i32_16x16x64_i8 v[6:9], v[162:165], v[202:205], v[6:9]
	v_mfma_i32_16x16x64_i8 v[2:5], v[170:173], v[202:205], v[2:5]
	v_mfma_i32_16x16x64_i8 v[46:49], v[166:169], v[182:185], v[46:49]
	v_mfma_i32_16x16x64_i8 v[38:41], v[174:177], v[182:185], v[38:41]
	s_barrier
	v_mfma_i32_16x16x64_i8 v[30:33], v[166:169], v[190:193], v[30:33]
	v_mfma_i32_16x16x64_i8 v[22:25], v[174:177], v[190:193], v[22:25]
	v_mfma_i32_16x16x64_i8 v[14:17], v[166:169], v[198:201], v[14:17]
	v_mfma_i32_16x16x64_i8 v[10:13], v[174:177], v[198:201], v[10:13]
	v_mfma_i32_16x16x64_i8 v[6:9], v[166:169], v[206:209], v[6:9]
	v_mfma_i32_16x16x64_i8 v[2:5], v[174:177], v[206:209], v[2:5]
	s_setprio 0
	s_nop 0
	s_add_u32 s42, s42, 0x100
	s_addc_u32 s43, s43, 0
	s_add_u32 s86, s86, 0x100
	s_addc_u32 s87, s87, 0
	s_cmp_ge_i32 s88, s66
	s_mov_b32 s44, s88
	s_cbranch_scc0 .LBB0_1754
	v_cvt_f32_i32_e32 v214, v126
	v_cvt_f32_i32_e32 v215, v127
	v_cvt_f32_i32_e32 v212, v128
	v_cvt_f32_i32_e32 v213, v129
	v_cvt_f32_i32_e32 v218, v122
	v_cvt_f32_i32_e32 v219, v123
	v_cvt_f32_i32_e32 v216, v124
	v_cvt_f32_i32_e32 v217, v125
	v_cvt_f32_i32_e32 v222, v110
	v_cvt_f32_i32_e32 v223, v111
	v_cvt_f32_i32_e32 v220, v112
	v_cvt_f32_i32_e32 v221, v113
	v_cvt_f32_i32_e32 v226, v102
	v_cvt_f32_i32_e32 v227, v103
	v_cvt_f32_i32_e32 v224, v104
	v_cvt_f32_i32_e32 v225, v105
	v_cvt_f32_i32_e32 v194, v118
	v_cvt_f32_i32_e32 v195, v119
	v_cvt_f32_i32_e32 v192, v120
	v_cvt_f32_i32_e32 v193, v121
	v_cvt_f32_i32_e32 v200, v114
	v_cvt_f32_i32_e32 v201, v115
	v_cvt_f32_i32_e32 v198, v116
	v_cvt_f32_i32_e32 v199, v117
	v_cvt_f32_i32_e32 v206, v94
	v_cvt_f32_i32_e32 v207, v95
	v_cvt_f32_i32_e32 v202, v96
	v_cvt_f32_i32_e32 v203, v97
	v_cvt_f32_i32_e32 v208, v86
	v_cvt_f32_i32_e32 v209, v87
	v_cvt_f32_i32_e32 v204, v88
	v_cvt_f32_i32_e32 v205, v89
	v_cvt_f32_i32_e32 v178, v106
	v_cvt_f32_i32_e32 v179, v107
	v_cvt_f32_i32_e32 v176, v108
	v_cvt_f32_i32_e32 v177, v109
	v_cvt_f32_i32_e32 v182, v98
	v_cvt_f32_i32_e32 v183, v99
	v_cvt_f32_i32_e32 v180, v100
	v_cvt_f32_i32_e32 v181, v101
	v_cvt_f32_i32_e32 v188, v78
	v_cvt_f32_i32_e32 v189, v79
	v_cvt_f32_i32_e32 v184, v80
	v_cvt_f32_i32_e32 v185, v81
	v_cvt_f32_i32_e32 v190, v74
	v_cvt_f32_i32_e32 v191, v75
	v_cvt_f32_i32_e32 v186, v76
	v_cvt_f32_i32_e32 v187, v77
	v_cvt_f32_i32_e32 v162, v90
	v_cvt_f32_i32_e32 v163, v91
	v_cvt_f32_i32_e32 v160, v92
	v_cvt_f32_i32_e32 v161, v93
	v_cvt_f32_i32_e32 v166, v82
	v_cvt_f32_i32_e32 v167, v83
	v_cvt_f32_i32_e32 v164, v84
	v_cvt_f32_i32_e32 v165, v85
	v_cvt_f32_i32_e32 v172, v70
	v_cvt_f32_i32_e32 v173, v71
	v_cvt_f32_i32_e32 v168, v72
	v_cvt_f32_i32_e32 v169, v73
	v_cvt_f32_i32_e32 v174, v66
	v_cvt_f32_i32_e32 v175, v67
	v_cvt_f32_i32_e32 v170, v68
	v_cvt_f32_i32_e32 v171, v69
	v_cvt_f32_i32_e32 v146, v62
	v_cvt_f32_i32_e32 v147, v63
	v_cvt_f32_i32_e32 v128, v64
	v_cvt_f32_i32_e32 v129, v65
	v_cvt_f32_i32_e32 v150, v58
	v_cvt_f32_i32_e32 v151, v59
	v_cvt_f32_i32_e32 v148, v60
	v_cvt_f32_i32_e32 v149, v61
	v_cvt_f32_i32_e32 v156, v46
	v_cvt_f32_i32_e32 v157, v47
	v_cvt_f32_i32_e32 v152, v48
	v_cvt_f32_i32_e32 v153, v49
	v_cvt_f32_i32_e32 v158, v38
	v_cvt_f32_i32_e32 v159, v39
	v_cvt_f32_i32_e32 v154, v40
	v_cvt_f32_i32_e32 v155, v41
	v_cvt_f32_i32_e32 v114, v54
	v_cvt_f32_i32_e32 v115, v55
	v_cvt_f32_i32_e32 v112, v56
	v_cvt_f32_i32_e32 v113, v57
	v_cvt_f32_i32_e32 v118, v50
	v_cvt_f32_i32_e32 v119, v51
	v_cvt_f32_i32_e32 v116, v52
	v_cvt_f32_i32_e32 v117, v53
	v_cvt_f32_i32_e32 v124, v30
	v_cvt_f32_i32_e32 v125, v31
	v_cvt_f32_i32_e32 v120, v32
	v_cvt_f32_i32_e32 v121, v33
	v_cvt_f32_i32_e32 v126, v22
	v_cvt_f32_i32_e32 v127, v23
	v_cvt_f32_i32_e32 v122, v24
	v_cvt_f32_i32_e32 v123, v25
	v_cvt_f32_i32_e32 v64, v42
	v_cvt_f32_i32_e32 v65, v43
	v_cvt_f32_i32_e32 v62, v44
	v_cvt_f32_i32_e32 v63, v45
	v_cvt_f32_i32_e32 v68, v34
	v_cvt_f32_i32_e32 v69, v35
	v_cvt_f32_i32_e32 v66, v36
	v_cvt_f32_i32_e32 v67, v37
	v_cvt_f32_i32_e32 v74, v14
	v_cvt_f32_i32_e32 v75, v15
	v_cvt_f32_i32_e32 v70, v16
	v_cvt_f32_i32_e32 v71, v17
	v_cvt_f32_i32_e32 v76, v10
	v_cvt_f32_i32_e32 v77, v11
	v_cvt_f32_i32_e32 v72, v12
	v_cvt_f32_i32_e32 v73, v13
	v_cvt_f32_i32_e32 v48, v26
	v_cvt_f32_i32_e32 v49, v27
	v_cvt_f32_i32_e32 v46, v28
	v_cvt_f32_i32_e32 v47, v29
	v_cvt_f32_i32_e32 v52, v18
	v_cvt_f32_i32_e32 v53, v19
	v_cvt_f32_i32_e32 v50, v20
	v_cvt_f32_i32_e32 v51, v21
	v_cvt_f32_i32_e32 v58, v6
	v_cvt_f32_i32_e32 v59, v7
	v_cvt_f32_i32_e32 v54, v8
	v_cvt_f32_i32_e32 v55, v9
	v_cvt_f32_i32_e32 v60, v2
	v_cvt_f32_i32_e32 v61, v3
	v_cvt_f32_i32_e32 v56, v4
	v_cvt_f32_i32_e32 v57, v5

.LBB0_1939:
	v_add_u32_e32 v138, s62, v188
	ds_read_b128 v[148:151], v138
	ds_read_b128 v[152:155], v138 offset:1024
	ds_read_b128 v[156:159], v138 offset:2048
	ds_read_b128 v[160:163], v138 offset:3072
	v_add_u32_e32 v138, s63, v188
	ds_read_b128 v[164:167], v138
	ds_read_b128 v[168:171], v138 offset:1024
	ds_read_b128 v[172:175], v138 offset:2048
	ds_read_b128 v[176:179], v138 offset:3072
	s_add_i32 s66, s28, 2
	s_add_u32 s67, s26, 0x80
	s_addc_u32 s29, s27, 0
	s_cmp_eq_u32 s60, s28
	s_cselect_b32 s28, s2, s67
	s_cselect_b32 s29, s3, s29
	s_cselect_b32 s69, s25, s35
	s_cselect_b32 s68, s24, s34
	v_lshl_add_u64 v[184:185], s[26:27], 0, v[140:141]
	s_add_i32 m0, s44, 0xc000
	ds_read_b128 v[180:183], v189
	ds_read_b128 v[190:193], v189 offset:1024
	ds_read_b128 v[194:197], v189 offset:2048
	ds_read_b128 v[198:201], v189 offset:3072
	ds_read_b128 v[202:205], v189 offset:4096
	ds_read_b128 v[206:209], v189 offset:5120
	ds_read_b128 v[210:213], v189 offset:6144
	ds_read_b128 v[214:217], v189 offset:7168
	global_load_lds_dwordx4 v[184:185], off
	v_lshl_add_u64 v[184:185], s[26:27], 0, v[142:143]
	s_add_i32 m0, s44, 0xe000
	s_nop 0
	global_load_lds_dwordx4 v[184:185], off
	s_waitcnt vmcnt(8)
	s_waitcnt lgkmcnt(0)
	s_barrier
	s_setprio 1
	s_waitcnt lgkmcnt(0)
	v_mfma_i32_16x16x64_i8 v[126:129], v[148:151], v[180:183], v[126:129]
	v_mfma_i32_16x16x64_i8 v[122:125], v[156:159], v[180:183], v[122:125]
	v_mfma_i32_16x16x64_i8 v[118:121], v[148:151], v[194:197], v[118:121]
	v_mfma_i32_16x16x64_i8 v[114:117], v[156:159], v[194:197], v[114:117]
	v_mfma_i32_16x16x64_i8 v[106:109], v[148:151], v[202:205], v[106:109]
	v_mfma_i32_16x16x64_i8 v[98:101], v[156:159], v[202:205], v[98:101]
	v_mfma_i32_16x16x64_i8 v[90:93], v[148:151], v[210:213], v[90:93]
	v_mfma_i32_16x16x64_i8 v[82:85], v[156:159], v[210:213], v[82:85]
	v_mfma_i32_16x16x64_i8 v[126:129], v[152:155], v[190:193], v[126:129]
	v_mfma_i32_16x16x64_i8 v[122:125], v[160:163], v[190:193], v[122:125]
	v_mfma_i32_16x16x64_i8 v[118:121], v[152:155], v[198:201], v[118:121]
	v_mfma_i32_16x16x64_i8 v[114:117], v[160:163], v[198:201], v[114:117]
	v_mfma_i32_16x16x64_i8 v[106:109], v[152:155], v[206:209], v[106:109]
	v_mfma_i32_16x16x64_i8 v[98:101], v[160:163], v[206:209], v[98:101]
	v_mfma_i32_16x16x64_i8 v[90:93], v[152:155], v[214:217], v[90:93]
	v_mfma_i32_16x16x64_i8 v[82:85], v[160:163], v[214:217], v[82:85]
	s_setprio 0
	s_setprio 1
	v_mfma_i32_16x16x64_i8 v[110:113], v[164:167], v[180:183], v[110:113]
	v_mfma_i32_16x16x64_i8 v[102:105], v[172:175], v[180:183], v[102:105]
	v_mfma_i32_16x16x64_i8 v[94:97], v[164:167], v[194:197], v[94:97]
	v_mfma_i32_16x16x64_i8 v[86:89], v[172:175], v[194:197], v[86:89]
	v_mfma_i32_16x16x64_i8 v[78:81], v[164:167], v[202:205], v[78:81]
	v_mfma_i32_16x16x64_i8 v[74:77], v[172:175], v[202:205], v[74:77]
	v_mfma_i32_16x16x64_i8 v[70:73], v[164:167], v[210:213], v[70:73]
	v_mfma_i32_16x16x64_i8 v[66:69], v[172:175], v[210:213], v[66:69]
	v_mfma_i32_16x16x64_i8 v[110:113], v[168:171], v[190:193], v[110:113]
	v_mfma_i32_16x16x64_i8 v[102:105], v[176:179], v[190:193], v[102:105]
	s_barrier
	v_mfma_i32_16x16x64_i8 v[94:97], v[168:171], v[198:201], v[94:97]
	v_mfma_i32_16x16x64_i8 v[86:89], v[176:179], v[198:201], v[86:89]
	v_mfma_i32_16x16x64_i8 v[78:81], v[168:171], v[206:209], v[78:81]
	v_mfma_i32_16x16x64_i8 v[74:77], v[176:179], v[206:209], v[74:77]
	v_mfma_i32_16x16x64_i8 v[70:73], v[168:171], v[214:217], v[70:73]
	v_mfma_i32_16x16x64_i8 v[66:69], v[176:179], v[214:217], v[66:69]
	s_setprio 0
	s_nop 0
	s_add_i32 s67, s62, s43
	v_lshl_add_u64 v[184:185], s[68:69], 0, v[132:133]
	s_mov_b32 m0, s67
	ds_read_b128 v[180:183], v189 offset:16384
	ds_read_b128 v[190:193], v189 offset:17408
	ds_read_b128 v[194:197], v189 offset:18432
	ds_read_b128 v[198:201], v189 offset:19456
	ds_read_b128 v[202:205], v189 offset:20480
	ds_read_b128 v[206:209], v189 offset:21504
	ds_read_b128 v[210:213], v189 offset:22528
	ds_read_b128 v[214:217], v189 offset:23552
	global_load_lds_dwordx4 v[184:185], off
	s_add_i32 m0, s67, 0x2000
	v_lshl_add_u64 v[218:219], s[68:69], 0, v[136:137]
	s_add_u32 s68, s68, s6
	s_addc_u32 s69, s69, s7
	s_add_i32 s67, s63, s43
	global_load_lds_dwordx4 v[218:219], off
	v_lshl_add_u64 v[220:221], s[68:69], 0, v[132:133]
	s_mov_b32 m0, s67
	v_lshl_add_u64 v[222:223], s[68:69], 0, v[136:137]
	global_load_lds_dwordx4 v[220:221], off
	s_add_i32 m0, s67, 0x2000
	v_lshl_add_u64 v[224:225], s[28:29], 0, v[130:131]
	global_load_lds_dwordx4 v[222:223], off
	s_mov_b32 m0, s44
	v_lshl_add_u64 v[226:227], s[28:29], 0, v[134:135]
	global_load_lds_dwordx4 v[224:225], off
	s_mov_b32 m0, s45
	s_nop 0
	global_load_lds_dwordx4 v[226:227], off
	s_waitcnt vmcnt(8)
	s_waitcnt lgkmcnt(0)
	s_barrier
	s_setprio 1
	s_waitcnt lgkmcnt(0)
	v_mfma_i32_16x16x64_i8 v[62:65], v[148:151], v[180:183], v[62:65]
	v_mfma_i32_16x16x64_i8 v[58:61], v[156:159], v[180:183], v[58:61]
	v_mfma_i32_16x16x64_i8 v[54:57], v[148:151], v[194:197], v[54:57]
	v_mfma_i32_16x16x64_i8 v[50:53], v[156:159], v[194:197], v[50:53]
	v_mfma_i32_16x16x64_i8 v[42:45], v[148:151], v[202:205], v[42:45]
	v_mfma_i32_16x16x64_i8 v[34:37], v[156:159], v[202:205], v[34:37]
	v_mfma_i32_16x16x64_i8 v[26:29], v[148:151], v[210:213], v[26:29]
	v_mfma_i32_16x16x64_i8 v[18:21], v[156:159], v[210:213], v[18:21]
	v_mfma_i32_16x16x64_i8 v[62:65], v[152:155], v[190:193], v[62:65]
	v_mfma_i32_16x16x64_i8 v[58:61], v[160:163], v[190:193], v[58:61]
	v_mfma_i32_16x16x64_i8 v[54:57], v[152:155], v[198:201], v[54:57]
	v_mfma_i32_16x16x64_i8 v[50:53], v[160:163], v[198:201], v[50:53]
	v_mfma_i32_16x16x64_i8 v[42:45], v[152:155], v[206:209], v[42:45]
	v_mfma_i32_16x16x64_i8 v[34:37], v[160:163], v[206:209], v[34:37]
	v_mfma_i32_16x16x64_i8 v[26:29], v[152:155], v[214:217], v[26:29]
	v_mfma_i32_16x16x64_i8 v[18:21], v[160:163], v[214:217], v[18:21]
	s_setprio 0
	s_setprio 1
	v_mfma_i32_16x16x64_i8 v[46:49], v[164:167], v[180:183], v[46:49]
	v_mfma_i32_16x16x64_i8 v[38:41], v[172:175], v[180:183], v[38:41]
	v_mfma_i32_16x16x64_i8 v[30:33], v[164:167], v[194:197], v[30:33]
	v_mfma_i32_16x16x64_i8 v[22:25], v[172:175], v[194:197], v[22:25]
	v_mfma_i32_16x16x64_i8 v[14:17], v[164:167], v[202:205], v[14:17]
	v_mfma_i32_16x16x64_i8 v[10:13], v[172:175], v[202:205], v[10:13]
	v_mfma_i32_16x16x64_i8 v[6:9], v[164:167], v[210:213], v[6:9]
	v_mfma_i32_16x16x64_i8 v[2:5], v[172:175], v[210:213], v[2:5]
	v_mfma_i32_16x16x64_i8 v[46:49], v[168:171], v[190:193], v[46:49]
	v_mfma_i32_16x16x64_i8 v[38:41], v[176:179], v[190:193], v[38:41]
	s_barrier
	v_mfma_i32_16x16x64_i8 v[30:33], v[168:171], v[198:201], v[30:33]
	v_mfma_i32_16x16x64_i8 v[22:25], v[176:179], v[198:201], v[22:25]
	v_mfma_i32_16x16x64_i8 v[14:17], v[168:171], v[206:209], v[14:17]
	v_mfma_i32_16x16x64_i8 v[10:13], v[176:179], v[206:209], v[10:13]
	v_mfma_i32_16x16x64_i8 v[6:9], v[168:171], v[214:217], v[6:9]
	v_mfma_i32_16x16x64_i8 v[2:5], v[176:179], v[214:217], v[2:5]
	s_setprio 0
	s_nop 0
	s_add_i32 s67, 0, 0x18000
	v_add_u32_e32 v138, s67, v188
	s_add_i32 s68, 0, 0x1c000
	ds_read_b128 v[148:151], v138
	ds_read_b128 v[152:155], v138 offset:1024
	ds_read_b128 v[156:159], v138 offset:2048
	ds_read_b128 v[160:163], v138 offset:3072
	v_add_u32_e32 v138, s68, v188
	ds_read_b128 v[164:167], v138
	ds_read_b128 v[168:171], v138 offset:1024
	ds_read_b128 v[172:175], v138 offset:2048
	ds_read_b128 v[176:179], v138 offset:3072
	s_add_u32 s28, s28, s6
	s_addc_u32 s29, s29, s7
	s_mov_b32 m0, s46
	v_lshl_add_u64 v[228:229], s[28:29], 0, v[130:131]
	ds_read_b128 v[180:183], v189 offset:32768
	ds_read_b128 v[190:193], v189 offset:33792
	ds_read_b128 v[194:197], v189 offset:34816
	ds_read_b128 v[198:201], v189 offset:35840
	ds_read_b128 v[202:205], v189 offset:36864
	ds_read_b128 v[206:209], v189 offset:37888
	ds_read_b128 v[210:213], v189 offset:38912
	ds_read_b128 v[214:217], v189 offset:39936
	global_load_lds_dwordx4 v[228:229], off
	v_lshl_add_u64 v[228:229], s[28:29], 0, v[134:135]
	s_mov_b32 m0, s47
	s_nop 0
	global_load_lds_dwordx4 v[228:229], off
	s_waitcnt vmcnt(8)
	s_waitcnt lgkmcnt(0)
	s_barrier
	s_setprio 1
	s_waitcnt lgkmcnt(0)
	v_mfma_i32_16x16x64_i8 v[126:129], v[148:151], v[180:183], v[126:129]
	v_mfma_i32_16x16x64_i8 v[122:125], v[156:159], v[180:183], v[122:125]
	v_mfma_i32_16x16x64_i8 v[118:121], v[148:151], v[194:197], v[118:121]
	v_mfma_i32_16x16x64_i8 v[114:117], v[156:159], v[194:197], v[114:117]
	v_mfma_i32_16x16x64_i8 v[106:109], v[148:151], v[202:205], v[106:109]
	v_mfma_i32_16x16x64_i8 v[98:101], v[156:159], v[202:205], v[98:101]
	v_mfma_i32_16x16x64_i8 v[90:93], v[148:151], v[210:213], v[90:93]
	v_mfma_i32_16x16x64_i8 v[82:85], v[156:159], v[210:213], v[82:85]
	v_mfma_i32_16x16x64_i8 v[126:129], v[152:155], v[190:193], v[126:129]
	v_mfma_i32_16x16x64_i8 v[122:125], v[160:163], v[190:193], v[122:125]
	v_mfma_i32_16x16x64_i8 v[118:121], v[152:155], v[198:201], v[118:121]
	v_mfma_i32_16x16x64_i8 v[114:117], v[160:163], v[198:201], v[114:117]
	v_mfma_i32_16x16x64_i8 v[106:109], v[152:155], v[206:209], v[106:109]
	v_mfma_i32_16x16x64_i8 v[98:101], v[160:163], v[206:209], v[98:101]
	v_mfma_i32_16x16x64_i8 v[90:93], v[152:155], v[214:217], v[90:93]
	v_mfma_i32_16x16x64_i8 v[82:85], v[160:163], v[214:217], v[82:85]
	s_setprio 0
	s_setprio 1
	v_mfma_i32_16x16x64_i8 v[110:113], v[164:167], v[180:183], v[110:113]
	v_mfma_i32_16x16x64_i8 v[102:105], v[172:175], v[180:183], v[102:105]
	v_mfma_i32_16x16x64_i8 v[94:97], v[164:167], v[194:197], v[94:97]
	v_mfma_i32_16x16x64_i8 v[86:89], v[172:175], v[194:197], v[86:89]
	v_mfma_i32_16x16x64_i8 v[78:81], v[164:167], v[202:205], v[78:81]
	v_mfma_i32_16x16x64_i8 v[74:77], v[172:175], v[202:205], v[74:77]
	v_mfma_i32_16x16x64_i8 v[70:73], v[164:167], v[210:213], v[70:73]
	v_mfma_i32_16x16x64_i8 v[66:69], v[172:175], v[210:213], v[66:69]
	v_mfma_i32_16x16x64_i8 v[110:113], v[168:171], v[190:193], v[110:113]
	v_mfma_i32_16x16x64_i8 v[102:105], v[176:179], v[190:193], v[102:105]
	s_barrier
	v_mfma_i32_16x16x64_i8 v[94:97], v[168:171], v[198:201], v[94:97]
	v_mfma_i32_16x16x64_i8 v[86:89], v[176:179], v[198:201], v[86:89]
	v_mfma_i32_16x16x64_i8 v[78:81], v[168:171], v[206:209], v[78:81]
	v_mfma_i32_16x16x64_i8 v[74:77], v[176:179], v[206:209], v[74:77]
	v_mfma_i32_16x16x64_i8 v[70:73], v[168:171], v[214:217], v[70:73]
	v_mfma_i32_16x16x64_i8 v[66:69], v[176:179], v[214:217], v[66:69]
	s_setprio 0
	s_nop 0
	s_add_i32 s28, s67, s43
	v_lshl_add_u64 v[184:185], v[184:185], 0, s[18:19]
	s_mov_b32 m0, s28
	ds_read_b128 v[180:183], v189 offset:49152
	ds_read_b128 v[190:193], v189 offset:50176
	ds_read_b128 v[194:197], v189 offset:51200
	ds_read_b128 v[198:201], v189 offset:52224
	ds_read_b128 v[202:205], v189 offset:53248
	ds_read_b128 v[206:209], v189 offset:54272
	ds_read_b128 v[210:213], v189 offset:55296
	ds_read_b128 v[214:217], v189 offset:56320
	global_load_lds_dwordx4 v[184:185], off
	v_lshl_add_u64 v[184:185], v[218:219], 0, s[18:19]
	s_add_i32 m0, s28, 0x2000
	s_add_i32 s28, s68, s43
	global_load_lds_dwordx4 v[184:185], off
	v_lshl_add_u64 v[184:185], v[220:221], 0, s[18:19]
	s_mov_b32 m0, s28
	s_nop 0
	global_load_lds_dwordx4 v[184:185], off
	v_lshl_add_u64 v[184:185], v[222:223], 0, s[18:19]
	s_add_i32 m0, s28, 0x2000
	s_nop 0
	global_load_lds_dwordx4 v[184:185], off
	v_lshl_add_u64 v[184:185], v[224:225], 0, s[18:19]
	s_mov_b32 m0, s55
	s_nop 0
	global_load_lds_dwordx4 v[184:185], off
	v_lshl_add_u64 v[184:185], v[226:227], 0, s[18:19]
	s_mov_b32 m0, s56
	s_nop 0
	global_load_lds_dwordx4 v[184:185], off
	s_waitcnt vmcnt(8)
	s_waitcnt lgkmcnt(0)
	s_barrier
	s_setprio 1
	s_waitcnt lgkmcnt(0)
	v_mfma_i32_16x16x64_i8 v[62:65], v[148:151], v[180:183], v[62:65]
	v_mfma_i32_16x16x64_i8 v[58:61], v[156:159], v[180:183], v[58:61]
	v_mfma_i32_16x16x64_i8 v[54:57], v[148:151], v[194:197], v[54:57]
	v_mfma_i32_16x16x64_i8 v[50:53], v[156:159], v[194:197], v[50:53]
	v_mfma_i32_16x16x64_i8 v[42:45], v[148:151], v[202:205], v[42:45]
	v_mfma_i32_16x16x64_i8 v[34:37], v[156:159], v[202:205], v[34:37]
	v_mfma_i32_16x16x64_i8 v[26:29], v[148:151], v[210:213], v[26:29]
	v_mfma_i32_16x16x64_i8 v[18:21], v[156:159], v[210:213], v[18:21]
	v_mfma_i32_16x16x64_i8 v[62:65], v[152:155], v[190:193], v[62:65]
	v_mfma_i32_16x16x64_i8 v[58:61], v[160:163], v[190:193], v[58:61]
	v_mfma_i32_16x16x64_i8 v[54:57], v[152:155], v[198:201], v[54:57]
	v_mfma_i32_16x16x64_i8 v[50:53], v[160:163], v[198:201], v[50:53]
	v_mfma_i32_16x16x64_i8 v[42:45], v[152:155], v[206:209], v[42:45]
	v_mfma_i32_16x16x64_i8 v[34:37], v[160:163], v[206:209], v[34:37]
	v_mfma_i32_16x16x64_i8 v[26:29], v[152:155], v[214:217], v[26:29]
	v_mfma_i32_16x16x64_i8 v[18:21], v[160:163], v[214:217], v[18:21]
	s_setprio 0
	s_setprio 1
	v_mfma_i32_16x16x64_i8 v[46:49], v[164:167], v[180:183], v[46:49]
	v_mfma_i32_16x16x64_i8 v[38:41], v[172:175], v[180:183], v[38:41]
	v_mfma_i32_16x16x64_i8 v[30:33], v[164:167], v[194:197], v[30:33]
	v_mfma_i32_16x16x64_i8 v[22:25], v[172:175], v[194:197], v[22:25]
	v_mfma_i32_16x16x64_i8 v[14:17], v[164:167], v[202:205], v[14:17]
	v_mfma_i32_16x16x64_i8 v[10:13], v[172:175], v[202:205], v[10:13]
	v_mfma_i32_16x16x64_i8 v[6:9], v[164:167], v[210:213], v[6:9]
	v_mfma_i32_16x16x64_i8 v[2:5], v[172:175], v[210:213], v[2:5]
	v_mfma_i32_16x16x64_i8 v[46:49], v[168:171], v[190:193], v[46:49]
	v_mfma_i32_16x16x64_i8 v[38:41], v[176:179], v[190:193], v[38:41]
	s_barrier
	v_mfma_i32_16x16x64_i8 v[30:33], v[168:171], v[198:201], v[30:33]
	v_mfma_i32_16x16x64_i8 v[22:25], v[176:179], v[198:201], v[22:25]
	v_mfma_i32_16x16x64_i8 v[14:17], v[168:171], v[206:209], v[14:17]
	v_mfma_i32_16x16x64_i8 v[10:13], v[176:179], v[206:209], v[10:13]
	v_mfma_i32_16x16x64_i8 v[6:9], v[168:171], v[214:217], v[6:9]
	v_mfma_i32_16x16x64_i8 v[2:5], v[176:179], v[214:217], v[2:5]
	s_setprio 0
	s_nop 0
	s_add_u32 s26, s26, 0x100
	s_addc_u32 s27, s27, 0
	s_add_u32 s34, s34, 0x100
	s_addc_u32 s35, s35, 0
	s_cmp_ge_i32 s66, s57
	s_mov_b32 s28, s66
	s_cbranch_scc0 .LBB0_1939
	v_cvt_f32_i32_e32 v172, v126
	v_cvt_f32_i32_e32 v173, v127
	v_cvt_f32_i32_e32 v170, v128
	v_cvt_f32_i32_e32 v171, v129
	v_cvt_f32_i32_e32 v174, v122
	v_cvt_f32_i32_e32 v175, v123
	v_cvt_f32_i32_e32 v176, v124
	v_cvt_f32_i32_e32 v177, v125
	v_cvt_f32_i32_e32 v180, v110
	v_cvt_f32_i32_e32 v181, v111
	v_cvt_f32_i32_e32 v182, v112
	v_cvt_f32_i32_e32 v183, v113
	v_cvt_f32_i32_e32 v178, v102
	v_cvt_f32_i32_e32 v179, v103
	v_cvt_f32_i32_e32 v184, v104
	v_cvt_f32_i32_e32 v185, v105
	v_cvt_f32_i32_e32 v152, v118
	v_cvt_f32_i32_e32 v153, v119
	v_cvt_f32_i32_e32 v154, v120
	v_cvt_f32_i32_e32 v155, v121
	v_cvt_f32_i32_e32 v156, v114
	v_cvt_f32_i32_e32 v157, v115
	v_cvt_f32_i32_e32 v158, v116
	v_cvt_f32_i32_e32 v159, v117
	v_cvt_f32_i32_e32 v160, v94
	v_cvt_f32_i32_e32 v161, v95
	v_cvt_f32_i32_e32 v162, v96
	v_cvt_f32_i32_e32 v163, v97
	v_cvt_f32_i32_e32 v164, v86
	v_cvt_f32_i32_e32 v165, v87
	v_cvt_f32_i32_e32 v166, v88
	v_cvt_f32_i32_e32 v167, v89
	v_cvt_f32_i32_e32 v118, v106
	v_cvt_f32_i32_e32 v119, v107
	v_cvt_f32_i32_e32 v120, v108
	v_cvt_f32_i32_e32 v121, v109
	v_cvt_f32_i32_e32 v122, v98
	v_cvt_f32_i32_e32 v123, v99
	v_cvt_f32_i32_e32 v124, v100
	v_cvt_f32_i32_e32 v125, v101
	v_cvt_f32_i32_e32 v126, v78
	v_cvt_f32_i32_e32 v127, v79
	v_cvt_f32_i32_e32 v128, v80
	v_cvt_f32_i32_e32 v129, v81
	v_cvt_f32_i32_e32 v148, v74
	v_cvt_f32_i32_e32 v149, v75
	v_cvt_f32_i32_e32 v150, v76
	v_cvt_f32_i32_e32 v151, v77
	v_cvt_f32_i32_e32 v102, v90
	v_cvt_f32_i32_e32 v103, v91
	v_cvt_f32_i32_e32 v104, v92
	v_cvt_f32_i32_e32 v105, v93
	v_cvt_f32_i32_e32 v106, v82
	v_cvt_f32_i32_e32 v107, v83
	v_cvt_f32_i32_e32 v108, v84
	v_cvt_f32_i32_e32 v109, v85
	v_cvt_f32_i32_e32 v110, v70
	v_cvt_f32_i32_e32 v111, v71
	v_cvt_f32_i32_e32 v112, v72
	v_cvt_f32_i32_e32 v113, v73
	v_cvt_f32_i32_e32 v114, v66
	v_cvt_f32_i32_e32 v115, v67
	v_cvt_f32_i32_e32 v116, v68
	v_cvt_f32_i32_e32 v117, v69
	v_cvt_f32_i32_e32 v82, v62
	v_cvt_f32_i32_e32 v83, v63
	v_cvt_f32_i32_e32 v84, v64
	v_cvt_f32_i32_e32 v85, v65
	v_cvt_f32_i32_e32 v86, v58
	v_cvt_f32_i32_e32 v87, v59
	v_cvt_f32_i32_e32 v88, v60
	v_cvt_f32_i32_e32 v89, v61
	v_cvt_f32_i32_e32 v92, v46
	v_cvt_f32_i32_e32 v93, v47
	v_cvt_f32_i32_e32 v94, v48
	v_cvt_f32_i32_e32 v95, v49
	v_cvt_f32_i32_e32 v96, v38
	v_cvt_f32_i32_e32 v97, v39
	v_cvt_f32_i32_e32 v98, v40
	v_cvt_f32_i32_e32 v99, v41
	v_cvt_f32_i32_e32 v66, v54
	v_cvt_f32_i32_e32 v67, v55
	v_cvt_f32_i32_e32 v68, v56
	v_cvt_f32_i32_e32 v69, v57
	v_cvt_f32_i32_e32 v70, v50
	v_cvt_f32_i32_e32 v71, v51
	v_cvt_f32_i32_e32 v72, v52
	v_cvt_f32_i32_e32 v73, v53
	v_cvt_f32_i32_e32 v74, v30
	v_cvt_f32_i32_e32 v75, v31
	v_cvt_f32_i32_e32 v76, v32
	v_cvt_f32_i32_e32 v77, v33
	v_cvt_f32_i32_e32 v78, v22
	v_cvt_f32_i32_e32 v79, v23
	v_cvt_f32_i32_e32 v80, v24
	v_cvt_f32_i32_e32 v81, v25
	v_cvt_f32_i32_e32 v50, v42
	v_cvt_f32_i32_e32 v51, v43
	v_cvt_f32_i32_e32 v52, v44
	v_cvt_f32_i32_e32 v53, v45
	v_cvt_f32_i32_e32 v54, v34
	v_cvt_f32_i32_e32 v55, v35
	v_cvt_f32_i32_e32 v56, v36
	v_cvt_f32_i32_e32 v57, v37
	v_cvt_f32_i32_e32 v58, v14
	v_cvt_f32_i32_e32 v59, v15
	v_cvt_f32_i32_e32 v60, v16
	v_cvt_f32_i32_e32 v61, v17
	v_cvt_f32_i32_e32 v62, v10
	v_cvt_f32_i32_e32 v63, v11
	v_cvt_f32_i32_e32 v64, v12
	v_cvt_f32_i32_e32 v65, v13
	v_cvt_f32_i32_e32 v34, v26
	v_cvt_f32_i32_e32 v35, v27
	v_cvt_f32_i32_e32 v36, v28
	v_cvt_f32_i32_e32 v37, v29
	v_cvt_f32_i32_e32 v38, v18
	v_cvt_f32_i32_e32 v39, v19
	v_cvt_f32_i32_e32 v40, v20
	v_cvt_f32_i32_e32 v41, v21
	v_cvt_f32_i32_e32 v42, v6
	v_cvt_f32_i32_e32 v43, v7
	v_cvt_f32_i32_e32 v44, v8
	v_cvt_f32_i32_e32 v45, v9
	v_cvt_f32_i32_e32 v46, v2
	v_cvt_f32_i32_e32 v47, v3
	v_cvt_f32_i32_e32 v48, v4
	v_cvt_f32_i32_e32 v49, v5

.LBB0_2022:
	ds_read_b128 v[114:117], v209
	ds_read_b128 v[118:121], v209 offset:1024
	ds_read_b128 v[122:125], v209 offset:2048
	ds_read_b128 v[126:129], v209 offset:3072
	ds_read_b128 v[146:149], v210
	ds_read_b128 v[150:153], v210 offset:1024
	ds_read_b128 v[154:157], v210 offset:2048
	ds_read_b128 v[158:161], v210 offset:3072
	s_add_i32 s84, s36, 2
	s_add_u32 s37, s34, 0x4000
	s_addc_u32 s38, s35, 0
	s_cmp_eq_u32 s63, s36
	s_cselect_b32 s39, s5, s38
	s_cselect_b32 s38, s4, s37
	s_cselect_b32 s86, s30, s82
	s_cselect_b32 s87, s31, s83
	s_add_u32 s36, s38, 0x8000
	s_addc_u32 s37, s39, 0
	v_lshl_add_u64 v[218:219], s[34:35], 0, v[170:171]
	s_add_i32 m0, s47, 0xc000
	ds_read_b128 v[178:181], v211
	ds_read_b128 v[182:185], v211 offset:1024
	ds_read_b128 v[186:189], v211 offset:2048
	ds_read_b128 v[190:193], v211 offset:3072
	ds_read_b128 v[194:197], v211 offset:4096
	ds_read_b128 v[198:201], v211 offset:5120
	ds_read_b128 v[202:205], v211 offset:6144
	ds_read_b128 v[214:217], v211 offset:7168
	global_load_lds_dwordx4 v[218:219], off
	v_lshl_add_u64 v[218:219], s[34:35], 0, v[172:173]
	s_add_i32 m0, s47, 0xe000
	s_nop 0
	global_load_lds_dwordx4 v[218:219], off
	s_waitcnt vmcnt(8)
	s_waitcnt lgkmcnt(0)
	s_barrier
	s_setprio 1
	s_waitcnt lgkmcnt(0)
	v_mfma_f32_16x16x32_bf16 v[142:145], v[114:117], v[178:181], v[142:145]
	v_mfma_f32_16x16x32_bf16 v[138:141], v[122:125], v[178:181], v[138:141]
	v_mfma_f32_16x16x32_bf16 v[110:113], v[114:117], v[186:189], v[110:113]
	v_mfma_f32_16x16x32_bf16 v[106:109], v[122:125], v[186:189], v[106:109]
	v_mfma_f32_16x16x32_bf16 v[94:97], v[114:117], v[194:197], v[94:97]
	v_mfma_f32_16x16x32_bf16 v[90:93], v[122:125], v[194:197], v[90:93]
	v_mfma_f32_16x16x32_bf16 v[78:81], v[114:117], v[202:205], v[78:81]
	v_mfma_f32_16x16x32_bf16 v[74:77], v[122:125], v[202:205], v[74:77]
	v_mfma_f32_16x16x32_bf16 v[142:145], v[118:121], v[182:185], v[142:145]
	v_mfma_f32_16x16x32_bf16 v[138:141], v[126:129], v[182:185], v[138:141]
	v_mfma_f32_16x16x32_bf16 v[110:113], v[118:121], v[190:193], v[110:113]
	v_mfma_f32_16x16x32_bf16 v[106:109], v[126:129], v[190:193], v[106:109]
	v_mfma_f32_16x16x32_bf16 v[94:97], v[118:121], v[198:201], v[94:97]
	v_mfma_f32_16x16x32_bf16 v[90:93], v[126:129], v[198:201], v[90:93]
	v_mfma_f32_16x16x32_bf16 v[78:81], v[118:121], v[214:217], v[78:81]
	v_mfma_f32_16x16x32_bf16 v[74:77], v[126:129], v[214:217], v[74:77]
	s_setprio 0
	s_setprio 1
	v_mfma_f32_16x16x32_bf16 v[134:137], v[146:149], v[178:181], v[134:137]
	v_mfma_f32_16x16x32_bf16 v[130:133], v[154:157], v[178:181], v[130:133]
	v_mfma_f32_16x16x32_bf16 v[102:105], v[146:149], v[186:189], v[102:105]
	v_mfma_f32_16x16x32_bf16 v[98:101], v[154:157], v[186:189], v[98:101]
	v_mfma_f32_16x16x32_bf16 v[86:89], v[146:149], v[194:197], v[86:89]
	v_mfma_f32_16x16x32_bf16 v[82:85], v[154:157], v[194:197], v[82:85]
	v_mfma_f32_16x16x32_bf16 v[70:73], v[146:149], v[202:205], v[70:73]
	v_mfma_f32_16x16x32_bf16 v[66:69], v[154:157], v[202:205], v[66:69]
	v_mfma_f32_16x16x32_bf16 v[134:137], v[150:153], v[182:185], v[134:137]
	v_mfma_f32_16x16x32_bf16 v[130:133], v[158:161], v[182:185], v[130:133]
	s_barrier
	v_mfma_f32_16x16x32_bf16 v[102:105], v[150:153], v[190:193], v[102:105]
	v_mfma_f32_16x16x32_bf16 v[98:101], v[158:161], v[190:193], v[98:101]
	v_mfma_f32_16x16x32_bf16 v[86:89], v[150:153], v[198:201], v[86:89]
	v_mfma_f32_16x16x32_bf16 v[82:85], v[158:161], v[198:201], v[82:85]
	v_mfma_f32_16x16x32_bf16 v[70:73], v[150:153], v[214:217], v[70:73]
	v_mfma_f32_16x16x32_bf16 v[66:69], v[158:161], v[214:217], v[66:69]
	s_setprio 0
	s_nop 0
	s_add_i32 s85, s66, s46
	v_lshl_add_u64 v[218:219], s[86:87], 0, v[164:165]
	s_mov_b32 m0, s85
	ds_read_b128 v[178:181], v211 offset:16384
	ds_read_b128 v[182:185], v211 offset:17408
	ds_read_b128 v[186:189], v211 offset:18432
	ds_read_b128 v[190:193], v211 offset:19456
	ds_read_b128 v[194:197], v211 offset:20480
	ds_read_b128 v[198:201], v211 offset:21504
	ds_read_b128 v[202:205], v211 offset:22528
	ds_read_b128 v[214:217], v211 offset:23552
	global_load_lds_dwordx4 v[218:219], off
	s_add_i32 m0, s85, 0x2000
	v_lshl_add_u64 v[220:221], s[86:87], 0, v[168:169]
	s_add_u32 s86, s86, s8
	s_addc_u32 s87, s87, s9
	s_add_i32 s85, s67, s46
	global_load_lds_dwordx4 v[220:221], off
	v_lshl_add_u64 v[222:223], s[86:87], 0, v[164:165]
	s_mov_b32 m0, s85
	v_lshl_add_u64 v[224:225], s[86:87], 0, v[168:169]
	global_load_lds_dwordx4 v[222:223], off
	s_add_i32 m0, s85, 0x2000
	v_lshl_add_u64 v[226:227], s[38:39], 0, v[162:163]
	global_load_lds_dwordx4 v[224:225], off
	s_mov_b32 m0, s47
	s_nop 0
	global_load_lds_dwordx4 v[226:227], off
	v_lshl_add_u64 v[226:227], s[38:39], 0, v[166:167]
	s_mov_b32 m0, s50
	s_nop 0
	global_load_lds_dwordx4 v[226:227], off
	s_waitcnt vmcnt(8)
	s_waitcnt lgkmcnt(0)
	s_barrier
	s_setprio 1
	s_waitcnt lgkmcnt(0)
	v_mfma_f32_16x16x32_bf16 v[62:65], v[114:117], v[178:181], v[62:65]
	v_mfma_f32_16x16x32_bf16 v[58:61], v[122:125], v[178:181], v[58:61]
	v_mfma_f32_16x16x32_bf16 v[46:49], v[114:117], v[186:189], v[46:49]
	v_mfma_f32_16x16x32_bf16 v[42:45], v[122:125], v[186:189], v[42:45]
	v_mfma_f32_16x16x32_bf16 v[30:33], v[114:117], v[194:197], v[30:33]
	v_mfma_f32_16x16x32_bf16 v[26:29], v[122:125], v[194:197], v[26:29]
	v_mfma_f32_16x16x32_bf16 v[14:17], v[114:117], v[202:205], v[14:17]
	v_mfma_f32_16x16x32_bf16 v[10:13], v[122:125], v[202:205], v[10:13]
	v_mfma_f32_16x16x32_bf16 v[62:65], v[118:121], v[182:185], v[62:65]
	v_mfma_f32_16x16x32_bf16 v[58:61], v[126:129], v[182:185], v[58:61]
	v_mfma_f32_16x16x32_bf16 v[46:49], v[118:121], v[190:193], v[46:49]
	v_mfma_f32_16x16x32_bf16 v[42:45], v[126:129], v[190:193], v[42:45]
	v_mfma_f32_16x16x32_bf16 v[30:33], v[118:121], v[198:201], v[30:33]
	v_mfma_f32_16x16x32_bf16 v[26:29], v[126:129], v[198:201], v[26:29]
	v_mfma_f32_16x16x32_bf16 v[14:17], v[118:121], v[214:217], v[14:17]
	v_mfma_f32_16x16x32_bf16 v[10:13], v[126:129], v[214:217], v[10:13]
	s_setprio 0
	s_setprio 1
	v_mfma_f32_16x16x32_bf16 v[54:57], v[146:149], v[178:181], v[54:57]
	v_mfma_f32_16x16x32_bf16 v[50:53], v[154:157], v[178:181], v[50:53]
	v_mfma_f32_16x16x32_bf16 v[38:41], v[146:149], v[186:189], v[38:41]
	v_mfma_f32_16x16x32_bf16 v[34:37], v[154:157], v[186:189], v[34:37]
	v_mfma_f32_16x16x32_bf16 v[22:25], v[146:149], v[194:197], v[22:25]
	v_mfma_f32_16x16x32_bf16 v[18:21], v[154:157], v[194:197], v[18:21]
	v_mfma_f32_16x16x32_bf16 v[6:9], v[146:149], v[202:205], v[6:9]
	v_mfma_f32_16x16x32_bf16 v[2:5], v[154:157], v[202:205], v[2:5]
	v_mfma_f32_16x16x32_bf16 v[54:57], v[150:153], v[182:185], v[54:57]
	v_mfma_f32_16x16x32_bf16 v[50:53], v[158:161], v[182:185], v[50:53]
	s_barrier
	v_mfma_f32_16x16x32_bf16 v[38:41], v[150:153], v[190:193], v[38:41]
	v_mfma_f32_16x16x32_bf16 v[34:37], v[158:161], v[190:193], v[34:37]
	v_mfma_f32_16x16x32_bf16 v[22:25], v[150:153], v[198:201], v[22:25]
	v_mfma_f32_16x16x32_bf16 v[18:21], v[158:161], v[198:201], v[18:21]
	v_mfma_f32_16x16x32_bf16 v[6:9], v[150:153], v[214:217], v[6:9]
	v_mfma_f32_16x16x32_bf16 v[2:5], v[158:161], v[214:217], v[2:5]
	s_setprio 0
	s_nop 0
	s_add_i32 s85, 0, 0x18000
	s_add_i32 s86, 0, 0x1c000
	v_add_u32_e32 v126, s85, v207
	v_add_u32_e32 v158, s86, v207
	ds_read_b128 v[114:117], v126
	ds_read_b128 v[118:121], v126 offset:1024
	ds_read_b128 v[122:125], v126 offset:2048
	ds_read_b128 v[126:129], v126 offset:3072
	ds_read_b128 v[146:149], v158
	ds_read_b128 v[150:153], v158 offset:1024
	ds_read_b128 v[154:157], v158 offset:2048
	ds_read_b128 v[158:161], v158 offset:3072
	s_add_u32 s38, s38, 0x4000
	s_addc_u32 s39, s39, 0
	s_mov_b32 m0, s51
	v_lshl_add_u64 v[226:227], s[38:39], 0, v[162:163]
	ds_read_b128 v[178:181], v211 offset:32768
	ds_read_b128 v[182:185], v211 offset:33792
	ds_read_b128 v[186:189], v211 offset:34816
	ds_read_b128 v[190:193], v211 offset:35840
	ds_read_b128 v[194:197], v211 offset:36864
	ds_read_b128 v[198:201], v211 offset:37888
	ds_read_b128 v[202:205], v211 offset:38912
	ds_read_b128 v[214:217], v211 offset:39936
	global_load_lds_dwordx4 v[226:227], off
	v_lshl_add_u64 v[226:227], s[38:39], 0, v[166:167]
	s_mov_b32 m0, s54
	s_nop 0
	global_load_lds_dwordx4 v[226:227], off
	s_waitcnt vmcnt(8)
	s_waitcnt lgkmcnt(0)
	s_barrier
	s_setprio 1
	s_waitcnt lgkmcnt(0)
	v_mfma_f32_16x16x32_bf16 v[142:145], v[114:117], v[178:181], v[142:145]
	v_mfma_f32_16x16x32_bf16 v[138:141], v[122:125], v[178:181], v[138:141]
	v_mfma_f32_16x16x32_bf16 v[110:113], v[114:117], v[186:189], v[110:113]
	v_mfma_f32_16x16x32_bf16 v[106:109], v[122:125], v[186:189], v[106:109]
	v_mfma_f32_16x16x32_bf16 v[94:97], v[114:117], v[194:197], v[94:97]
	v_mfma_f32_16x16x32_bf16 v[90:93], v[122:125], v[194:197], v[90:93]
	v_mfma_f32_16x16x32_bf16 v[78:81], v[114:117], v[202:205], v[78:81]
	v_mfma_f32_16x16x32_bf16 v[74:77], v[122:125], v[202:205], v[74:77]
	v_mfma_f32_16x16x32_bf16 v[142:145], v[118:121], v[182:185], v[142:145]
	v_mfma_f32_16x16x32_bf16 v[138:141], v[126:129], v[182:185], v[138:141]
	v_mfma_f32_16x16x32_bf16 v[110:113], v[118:121], v[190:193], v[110:113]
	v_mfma_f32_16x16x32_bf16 v[106:109], v[126:129], v[190:193], v[106:109]
	v_mfma_f32_16x16x32_bf16 v[94:97], v[118:121], v[198:201], v[94:97]
	v_mfma_f32_16x16x32_bf16 v[90:93], v[126:129], v[198:201], v[90:93]
	v_mfma_f32_16x16x32_bf16 v[78:81], v[118:121], v[214:217], v[78:81]
	v_mfma_f32_16x16x32_bf16 v[74:77], v[126:129], v[214:217], v[74:77]
	s_setprio 0
	s_setprio 1
	v_mfma_f32_16x16x32_bf16 v[134:137], v[146:149], v[178:181], v[134:137]
	v_mfma_f32_16x16x32_bf16 v[130:133], v[154:157], v[178:181], v[130:133]
	v_mfma_f32_16x16x32_bf16 v[102:105], v[146:149], v[186:189], v[102:105]
	v_mfma_f32_16x16x32_bf16 v[98:101], v[154:157], v[186:189], v[98:101]
	v_mfma_f32_16x16x32_bf16 v[86:89], v[146:149], v[194:197], v[86:89]
	v_mfma_f32_16x16x32_bf16 v[82:85], v[154:157], v[194:197], v[82:85]
	v_mfma_f32_16x16x32_bf16 v[70:73], v[146:149], v[202:205], v[70:73]
	v_mfma_f32_16x16x32_bf16 v[66:69], v[154:157], v[202:205], v[66:69]
	v_mfma_f32_16x16x32_bf16 v[134:137], v[150:153], v[182:185], v[134:137]
	v_mfma_f32_16x16x32_bf16 v[130:133], v[158:161], v[182:185], v[130:133]
	s_barrier
	v_mfma_f32_16x16x32_bf16 v[102:105], v[150:153], v[190:193], v[102:105]
	v_mfma_f32_16x16x32_bf16 v[98:101], v[158:161], v[190:193], v[98:101]
	v_mfma_f32_16x16x32_bf16 v[86:89], v[150:153], v[198:201], v[86:89]
	v_mfma_f32_16x16x32_bf16 v[82:85], v[158:161], v[198:201], v[82:85]
	v_mfma_f32_16x16x32_bf16 v[70:73], v[150:153], v[214:217], v[70:73]
	v_mfma_f32_16x16x32_bf16 v[66:69], v[158:161], v[214:217], v[66:69]
	s_setprio 0
	s_nop 0
	s_add_i32 s38, s85, s46
	v_lshl_add_u64 v[218:219], v[218:219], 0, s[24:25]
	s_mov_b32 m0, s38
	ds_read_b128 v[178:181], v211 offset:49152
	ds_read_b128 v[182:185], v211 offset:50176
	ds_read_b128 v[186:189], v211 offset:51200
	ds_read_b128 v[190:193], v211 offset:52224
	ds_read_b128 v[194:197], v211 offset:53248
	ds_read_b128 v[198:201], v211 offset:54272
	ds_read_b128 v[202:205], v211 offset:55296
	ds_read_b128 v[214:217], v211 offset:56320
	global_load_lds_dwordx4 v[218:219], off
	v_lshl_add_u64 v[218:219], v[220:221], 0, s[24:25]
	s_add_i32 m0, s38, 0x2000
	s_add_i32 s38, s86, s46
	global_load_lds_dwordx4 v[218:219], off
	v_lshl_add_u64 v[218:219], v[222:223], 0, s[24:25]
	s_mov_b32 m0, s38
	s_nop 0
	global_load_lds_dwordx4 v[218:219], off
	v_lshl_add_u64 v[218:219], v[224:225], 0, s[24:25]
	s_add_i32 m0, s38, 0x2000
	s_nop 0
	global_load_lds_dwordx4 v[218:219], off
	v_lshl_add_u64 v[218:219], s[36:37], 0, v[162:163]
	s_mov_b32 m0, s61
	s_nop 0
	global_load_lds_dwordx4 v[218:219], off
	v_lshl_add_u64 v[218:219], s[36:37], 0, v[166:167]
	s_mov_b32 m0, s62
	s_nop 0
	global_load_lds_dwordx4 v[218:219], off
	s_waitcnt vmcnt(8)
	s_waitcnt lgkmcnt(0)
	s_barrier
	s_setprio 1
	s_waitcnt lgkmcnt(0)
	v_mfma_f32_16x16x32_bf16 v[62:65], v[114:117], v[178:181], v[62:65]
	v_mfma_f32_16x16x32_bf16 v[58:61], v[122:125], v[178:181], v[58:61]
	v_mfma_f32_16x16x32_bf16 v[46:49], v[114:117], v[186:189], v[46:49]
	v_mfma_f32_16x16x32_bf16 v[42:45], v[122:125], v[186:189], v[42:45]
	v_mfma_f32_16x16x32_bf16 v[30:33], v[114:117], v[194:197], v[30:33]
	v_mfma_f32_16x16x32_bf16 v[26:29], v[122:125], v[194:197], v[26:29]
	v_mfma_f32_16x16x32_bf16 v[14:17], v[114:117], v[202:205], v[14:17]
	v_mfma_f32_16x16x32_bf16 v[10:13], v[122:125], v[202:205], v[10:13]
	v_mfma_f32_16x16x32_bf16 v[62:65], v[118:121], v[182:185], v[62:65]
	v_mfma_f32_16x16x32_bf16 v[58:61], v[126:129], v[182:185], v[58:61]
	v_mfma_f32_16x16x32_bf16 v[46:49], v[118:121], v[190:193], v[46:49]
	v_mfma_f32_16x16x32_bf16 v[42:45], v[126:129], v[190:193], v[42:45]
	v_mfma_f32_16x16x32_bf16 v[30:33], v[118:121], v[198:201], v[30:33]
	v_mfma_f32_16x16x32_bf16 v[26:29], v[126:129], v[198:201], v[26:29]
	v_mfma_f32_16x16x32_bf16 v[14:17], v[118:121], v[214:217], v[14:17]
	v_mfma_f32_16x16x32_bf16 v[10:13], v[126:129], v[214:217], v[10:13]
	s_setprio 0
	s_setprio 1
	v_mfma_f32_16x16x32_bf16 v[54:57], v[146:149], v[178:181], v[54:57]
	v_mfma_f32_16x16x32_bf16 v[50:53], v[154:157], v[178:181], v[50:53]
	v_mfma_f32_16x16x32_bf16 v[38:41], v[146:149], v[186:189], v[38:41]
	v_mfma_f32_16x16x32_bf16 v[34:37], v[154:157], v[186:189], v[34:37]
	v_mfma_f32_16x16x32_bf16 v[22:25], v[146:149], v[194:197], v[22:25]
	v_mfma_f32_16x16x32_bf16 v[18:21], v[154:157], v[194:197], v[18:21]
	v_mfma_f32_16x16x32_bf16 v[6:9], v[146:149], v[202:205], v[6:9]
	v_mfma_f32_16x16x32_bf16 v[2:5], v[154:157], v[202:205], v[2:5]
	v_mfma_f32_16x16x32_bf16 v[54:57], v[150:153], v[182:185], v[54:57]
	v_mfma_f32_16x16x32_bf16 v[50:53], v[158:161], v[182:185], v[50:53]
	s_barrier
	v_mfma_f32_16x16x32_bf16 v[38:41], v[150:153], v[190:193], v[38:41]
	v_mfma_f32_16x16x32_bf16 v[34:37], v[158:161], v[190:193], v[34:37]
	v_mfma_f32_16x16x32_bf16 v[22:25], v[150:153], v[198:201], v[22:25]
	v_mfma_f32_16x16x32_bf16 v[18:21], v[158:161], v[198:201], v[18:21]
	v_mfma_f32_16x16x32_bf16 v[6:9], v[150:153], v[214:217], v[6:9]
	v_mfma_f32_16x16x32_bf16 v[2:5], v[158:161], v[214:217], v[2:5]
	s_setprio 0
	s_nop 0
	s_add_u32 s82, s82, 0x100
	s_addc_u32 s83, s83, 0
	s_add_u32 s34, s34, 0x10000
	s_addc_u32 s35, s35, 0
	s_cmp_ge_i32 s84, s60
	s_mov_b32 s36, s84
	s_cbranch_scc0 .LBB0_2022

.LBB0_2116:
	ds_read_b128 v[34:37], v186
	ds_read_b128 v[38:41], v186 offset:1024
	ds_read_b128 v[50:53], v186 offset:2048
	ds_read_b128 v[54:57], v186 offset:3072
	ds_read_b128 v[168:171], v187
	ds_read_b128 v[172:175], v187 offset:1024
	ds_read_b128 v[176:179], v187 offset:2048
	ds_read_b128 v[192:195], v187 offset:3072
	s_add_i32 s47, s4, 2
	s_add_u32 s50, s2, 0x80
	s_addc_u32 s5, s3, 0
	s_cmp_eq_u32 s85, s4
	s_cselect_b32 s4, s42, s50
	s_cselect_b32 s5, s43, s5
	s_cselect_b32 s51, s45, s7
	s_cselect_b32 s50, s44, s6
	v_lshl_add_u64 v[228:229], s[2:3], 0, v[160:161]
	s_add_i32 m0, s65, 0xc000
	ds_read_b128 v[196:199], v188
	ds_read_b128 v[200:203], v188 offset:1024
	ds_read_b128 v[204:207], v188 offset:2048
	ds_read_b128 v[208:211], v188 offset:3072
	ds_read_b128 v[212:215], v188 offset:4096
	ds_read_b128 v[216:219], v188 offset:5120
	ds_read_b128 v[220:223], v188 offset:6144
	ds_read_b128 v[224:227], v188 offset:7168
	global_load_lds_dwordx4 v[228:229], off
	v_lshl_add_u64 v[228:229], s[2:3], 0, v[162:163]
	s_add_i32 m0, s65, 0xe000
	s_nop 0
	global_load_lds_dwordx4 v[228:229], off
	s_waitcnt vmcnt(8)
	s_waitcnt lgkmcnt(0)
	s_barrier
	s_setprio 1
	s_waitcnt lgkmcnt(0)
	v_mfma_f32_16x16x32_bf16 v[142:145], v[34:37], v[196:199], v[142:145]
	v_mfma_f32_16x16x32_bf16 v[138:141], v[50:53], v[196:199], v[138:141]
	v_mfma_f32_16x16x32_bf16 v[126:129], v[34:37], v[204:207], v[126:129]
	v_mfma_f32_16x16x32_bf16 v[122:125], v[50:53], v[204:207], v[122:125]
	v_mfma_f32_16x16x32_bf16 v[110:113], v[34:37], v[212:215], v[110:113]
	v_mfma_f32_16x16x32_bf16 v[106:109], v[50:53], v[212:215], v[106:109]
	v_mfma_f32_16x16x32_bf16 v[94:97], v[34:37], v[220:223], v[94:97]
	v_mfma_f32_16x16x32_bf16 v[90:93], v[50:53], v[220:223], v[90:93]
	v_mfma_f32_16x16x32_bf16 v[142:145], v[38:41], v[200:203], v[142:145]
	v_mfma_f32_16x16x32_bf16 v[138:141], v[54:57], v[200:203], v[138:141]
	v_mfma_f32_16x16x32_bf16 v[126:129], v[38:41], v[208:211], v[126:129]
	v_mfma_f32_16x16x32_bf16 v[122:125], v[54:57], v[208:211], v[122:125]
	v_mfma_f32_16x16x32_bf16 v[110:113], v[38:41], v[216:219], v[110:113]
	v_mfma_f32_16x16x32_bf16 v[106:109], v[54:57], v[216:219], v[106:109]
	v_mfma_f32_16x16x32_bf16 v[94:97], v[38:41], v[224:227], v[94:97]
	v_mfma_f32_16x16x32_bf16 v[90:93], v[54:57], v[224:227], v[90:93]
	s_setprio 0
	s_setprio 1
	v_mfma_f32_16x16x32_bf16 v[134:137], v[168:171], v[196:199], v[134:137]
	v_mfma_f32_16x16x32_bf16 v[130:133], v[176:179], v[196:199], v[130:133]
	v_mfma_f32_16x16x32_bf16 v[118:121], v[168:171], v[204:207], v[118:121]
	v_mfma_f32_16x16x32_bf16 v[114:117], v[176:179], v[204:207], v[114:117]
	v_mfma_f32_16x16x32_bf16 v[102:105], v[168:171], v[212:215], v[102:105]
	v_mfma_f32_16x16x32_bf16 v[98:101], v[176:179], v[212:215], v[98:101]
	v_mfma_f32_16x16x32_bf16 v[86:89], v[168:171], v[220:223], v[86:89]
	v_mfma_f32_16x16x32_bf16 v[82:85], v[176:179], v[220:223], v[82:85]
	v_mfma_f32_16x16x32_bf16 v[134:137], v[172:175], v[200:203], v[134:137]
	v_mfma_f32_16x16x32_bf16 v[130:133], v[192:195], v[200:203], v[130:133]
	s_barrier
	v_mfma_f32_16x16x32_bf16 v[118:121], v[172:175], v[208:211], v[118:121]
	v_mfma_f32_16x16x32_bf16 v[114:117], v[192:195], v[208:211], v[114:117]
	v_mfma_f32_16x16x32_bf16 v[102:105], v[172:175], v[216:219], v[102:105]
	v_mfma_f32_16x16x32_bf16 v[98:101], v[192:195], v[216:219], v[98:101]
	v_mfma_f32_16x16x32_bf16 v[86:89], v[172:175], v[224:227], v[86:89]
	v_mfma_f32_16x16x32_bf16 v[82:85], v[192:195], v[224:227], v[82:85]
	s_setprio 0
	s_nop 0
	s_add_i32 s55, s88, s62
	v_lshl_add_u64 v[228:229], s[50:51], 0, v[148:149]
	s_mov_b32 m0, s55
	ds_read_b128 v[196:199], v188 offset:16384
	ds_read_b128 v[200:203], v188 offset:17408
	ds_read_b128 v[204:207], v188 offset:18432
	ds_read_b128 v[208:211], v188 offset:19456
	ds_read_b128 v[212:215], v188 offset:20480
	ds_read_b128 v[216:219], v188 offset:21504
	ds_read_b128 v[220:223], v188 offset:22528
	ds_read_b128 v[224:227], v188 offset:23552
	global_load_lds_dwordx4 v[228:229], off
	s_add_i32 m0, s55, 0x2000
	v_lshl_add_u64 v[230:231], s[50:51], 0, v[152:153]
	s_add_u32 s50, s50, s14
	s_addc_u32 s51, s51, s15
	s_add_i32 s55, s89, s62
	global_load_lds_dwordx4 v[230:231], off
	v_lshl_add_u64 v[232:233], s[50:51], 0, v[148:149]
	s_mov_b32 m0, s55
	v_lshl_add_u64 v[234:235], s[50:51], 0, v[152:153]
	global_load_lds_dwordx4 v[232:233], off
	s_add_i32 m0, s55, 0x2000
	v_lshl_add_u64 v[236:237], s[4:5], 0, v[146:147]
	global_load_lds_dwordx4 v[234:235], off
	s_mov_b32 m0, s65
	v_lshl_add_u64 v[238:239], s[4:5], 0, v[150:151]
	global_load_lds_dwordx4 v[236:237], off
	s_mov_b32 m0, s66
	s_nop 0
	global_load_lds_dwordx4 v[238:239], off
	s_waitcnt vmcnt(8)
	s_waitcnt lgkmcnt(0)
	s_barrier
	s_setprio 1
	s_waitcnt lgkmcnt(0)
	v_mfma_f32_16x16x32_bf16 v[78:81], v[34:37], v[196:199], v[78:81]
	v_mfma_f32_16x16x32_bf16 v[74:77], v[50:53], v[196:199], v[74:77]
	v_mfma_f32_16x16x32_bf16 v[62:65], v[34:37], v[204:207], v[62:65]
	v_mfma_f32_16x16x32_bf16 v[58:61], v[50:53], v[204:207], v[58:61]
	v_mfma_f32_16x16x32_bf16 v[30:33], v[34:37], v[212:215], v[30:33]
	v_mfma_f32_16x16x32_bf16 v[26:29], v[50:53], v[212:215], v[26:29]
	v_mfma_f32_16x16x32_bf16 v[14:17], v[34:37], v[220:223], v[14:17]
	v_mfma_f32_16x16x32_bf16 v[10:13], v[50:53], v[220:223], v[10:13]
	v_mfma_f32_16x16x32_bf16 v[78:81], v[38:41], v[200:203], v[78:81]
	v_mfma_f32_16x16x32_bf16 v[74:77], v[54:57], v[200:203], v[74:77]
	v_mfma_f32_16x16x32_bf16 v[62:65], v[38:41], v[208:211], v[62:65]
	v_mfma_f32_16x16x32_bf16 v[58:61], v[54:57], v[208:211], v[58:61]
	v_mfma_f32_16x16x32_bf16 v[30:33], v[38:41], v[216:219], v[30:33]
	v_mfma_f32_16x16x32_bf16 v[26:29], v[54:57], v[216:219], v[26:29]
	v_mfma_f32_16x16x32_bf16 v[14:17], v[38:41], v[224:227], v[14:17]
	v_mfma_f32_16x16x32_bf16 v[10:13], v[54:57], v[224:227], v[10:13]
	s_setprio 0
	s_setprio 1
	v_mfma_f32_16x16x32_bf16 v[46:49], v[168:171], v[204:207], v[46:49]
	v_mfma_f32_16x16x32_bf16 v[42:45], v[176:179], v[204:207], v[42:45]
	v_mfma_f32_16x16x32_bf16 v[22:25], v[168:171], v[212:215], v[22:25]
	v_mfma_f32_16x16x32_bf16 v[18:21], v[176:179], v[212:215], v[18:21]
	v_mfma_f32_16x16x32_bf16 v[6:9], v[168:171], v[220:223], v[6:9]
	v_mfma_f32_16x16x32_bf16 v[2:5], v[176:179], v[220:223], v[2:5]
	v_mfma_f32_16x16x32_bf16 v[34:37], v[168:171], v[196:199], v[70:73]
	v_mfma_f32_16x16x32_bf16 v[38:41], v[176:179], v[196:199], v[66:69]
	v_mfma_f32_16x16x32_bf16 v[46:49], v[172:175], v[208:211], v[46:49]
	v_mfma_f32_16x16x32_bf16 v[42:45], v[192:195], v[208:211], v[42:45]
	s_barrier
	v_mfma_f32_16x16x32_bf16 v[22:25], v[172:175], v[216:219], v[22:25]
	v_mfma_f32_16x16x32_bf16 v[18:21], v[192:195], v[216:219], v[18:21]
	v_mfma_f32_16x16x32_bf16 v[6:9], v[172:175], v[224:227], v[6:9]
	v_mfma_f32_16x16x32_bf16 v[2:5], v[192:195], v[224:227], v[2:5]
	v_mfma_f32_16x16x32_bf16 v[34:37], v[172:175], v[200:203], v[34:37]
	v_mfma_f32_16x16x32_bf16 v[38:41], v[192:195], v[200:203], v[38:41]
	s_setprio 0
	s_nop 0
	s_add_i32 s50, 0, 0x18000
	s_add_i32 s51, 0, 0x1c000
	v_add_u32_e32 v70, s50, v184
	v_add_u32_e32 v154, s51, v184
	ds_read_b128 v[50:53], v70
	ds_read_b128 v[54:57], v70 offset:1024
	ds_read_b128 v[66:69], v70 offset:2048
	ds_read_b128 v[70:73], v70 offset:3072
	ds_read_b128 v[168:171], v154
	ds_read_b128 v[172:175], v154 offset:1024
	ds_read_b128 v[176:179], v154 offset:2048
	ds_read_b128 v[192:195], v154 offset:3072
	s_add_u32 s4, s4, s14
	s_addc_u32 s5, s5, s15
	s_mov_b32 m0, s67
	v_lshl_add_u64 v[240:241], s[4:5], 0, v[146:147]
	ds_read_b128 v[196:199], v188 offset:32768
	ds_read_b128 v[200:203], v188 offset:33792
	ds_read_b128 v[204:207], v188 offset:34816
	ds_read_b128 v[208:211], v188 offset:35840
	ds_read_b128 v[212:215], v188 offset:36864
	ds_read_b128 v[216:219], v188 offset:37888
	ds_read_b128 v[220:223], v188 offset:38912
	ds_read_b128 v[224:227], v188 offset:39936
	global_load_lds_dwordx4 v[240:241], off
	v_lshl_add_u64 v[240:241], s[4:5], 0, v[150:151]
	s_mov_b32 m0, s68
	s_nop 0
	global_load_lds_dwordx4 v[240:241], off
	s_waitcnt vmcnt(8)
	s_waitcnt lgkmcnt(0)
	s_barrier
	s_setprio 1
	s_waitcnt lgkmcnt(0)
	v_mfma_f32_16x16x32_bf16 v[142:145], v[50:53], v[196:199], v[142:145]
	v_mfma_f32_16x16x32_bf16 v[138:141], v[66:69], v[196:199], v[138:141]
	v_mfma_f32_16x16x32_bf16 v[126:129], v[50:53], v[204:207], v[126:129]
	v_mfma_f32_16x16x32_bf16 v[122:125], v[66:69], v[204:207], v[122:125]
	v_mfma_f32_16x16x32_bf16 v[110:113], v[50:53], v[212:215], v[110:113]
	v_mfma_f32_16x16x32_bf16 v[106:109], v[66:69], v[212:215], v[106:109]
	v_mfma_f32_16x16x32_bf16 v[94:97], v[50:53], v[220:223], v[94:97]
	v_mfma_f32_16x16x32_bf16 v[90:93], v[66:69], v[220:223], v[90:93]
	v_mfma_f32_16x16x32_bf16 v[142:145], v[54:57], v[200:203], v[142:145]
	v_mfma_f32_16x16x32_bf16 v[138:141], v[70:73], v[200:203], v[138:141]
	v_mfma_f32_16x16x32_bf16 v[126:129], v[54:57], v[208:211], v[126:129]
	v_mfma_f32_16x16x32_bf16 v[122:125], v[70:73], v[208:211], v[122:125]
	v_mfma_f32_16x16x32_bf16 v[110:113], v[54:57], v[216:219], v[110:113]
	v_mfma_f32_16x16x32_bf16 v[106:109], v[70:73], v[216:219], v[106:109]
	v_mfma_f32_16x16x32_bf16 v[94:97], v[54:57], v[224:227], v[94:97]
	v_mfma_f32_16x16x32_bf16 v[90:93], v[70:73], v[224:227], v[90:93]
	s_setprio 0
	s_setprio 1
	v_mfma_f32_16x16x32_bf16 v[134:137], v[168:171], v[196:199], v[134:137]
	v_mfma_f32_16x16x32_bf16 v[130:133], v[176:179], v[196:199], v[130:133]
	v_mfma_f32_16x16x32_bf16 v[118:121], v[168:171], v[204:207], v[118:121]
	v_mfma_f32_16x16x32_bf16 v[114:117], v[176:179], v[204:207], v[114:117]
	v_mfma_f32_16x16x32_bf16 v[102:105], v[168:171], v[212:215], v[102:105]
	v_mfma_f32_16x16x32_bf16 v[98:101], v[176:179], v[212:215], v[98:101]
	v_mfma_f32_16x16x32_bf16 v[86:89], v[168:171], v[220:223], v[86:89]
	v_mfma_f32_16x16x32_bf16 v[82:85], v[176:179], v[220:223], v[82:85]
	v_mfma_f32_16x16x32_bf16 v[134:137], v[172:175], v[200:203], v[134:137]
	v_mfma_f32_16x16x32_bf16 v[130:133], v[192:195], v[200:203], v[130:133]
	s_barrier
	v_mfma_f32_16x16x32_bf16 v[118:121], v[172:175], v[208:211], v[118:121]
	v_mfma_f32_16x16x32_bf16 v[114:117], v[192:195], v[208:211], v[114:117]
	v_mfma_f32_16x16x32_bf16 v[102:105], v[172:175], v[216:219], v[102:105]
	v_mfma_f32_16x16x32_bf16 v[98:101], v[192:195], v[216:219], v[98:101]
	v_mfma_f32_16x16x32_bf16 v[86:89], v[172:175], v[224:227], v[86:89]
	v_mfma_f32_16x16x32_bf16 v[82:85], v[192:195], v[224:227], v[82:85]
	s_setprio 0
	s_nop 0
	s_add_i32 s4, s50, s62
	v_lshl_add_u64 v[228:229], v[228:229], 0, s[28:29]
	s_mov_b32 m0, s4
	ds_read_b128 v[196:199], v188 offset:49152
	ds_read_b128 v[200:203], v188 offset:50176
	ds_read_b128 v[204:207], v188 offset:51200
	ds_read_b128 v[208:211], v188 offset:52224
	ds_read_b128 v[212:215], v188 offset:53248
	ds_read_b128 v[216:219], v188 offset:54272
	ds_read_b128 v[220:223], v188 offset:55296
	ds_read_b128 v[224:227], v188 offset:56320
	global_load_lds_dwordx4 v[228:229], off
	v_lshl_add_u64 v[228:229], v[230:231], 0, s[28:29]
	s_add_i32 m0, s4, 0x2000
	s_add_i32 s4, s51, s62
	global_load_lds_dwordx4 v[228:229], off
	v_lshl_add_u64 v[228:229], v[232:233], 0, s[28:29]
	s_mov_b32 m0, s4
	s_nop 0
	global_load_lds_dwordx4 v[228:229], off
	v_lshl_add_u64 v[228:229], v[234:235], 0, s[28:29]
	s_add_i32 m0, s4, 0x2000
	s_nop 0
	global_load_lds_dwordx4 v[228:229], off
	v_lshl_add_u64 v[228:229], v[236:237], 0, s[28:29]
	s_mov_b32 m0, s82
	s_nop 0
	global_load_lds_dwordx4 v[228:229], off
	v_lshl_add_u64 v[228:229], v[238:239], 0, s[28:29]
	s_mov_b32 m0, s83
	s_nop 0
	global_load_lds_dwordx4 v[228:229], off
	s_waitcnt vmcnt(8)
	s_waitcnt lgkmcnt(0)
	s_barrier
	s_setprio 1
	s_waitcnt lgkmcnt(0)
	v_mfma_f32_16x16x32_bf16 v[78:81], v[50:53], v[196:199], v[78:81]
	v_mfma_f32_16x16x32_bf16 v[74:77], v[66:69], v[196:199], v[74:77]
	v_mfma_f32_16x16x32_bf16 v[62:65], v[50:53], v[204:207], v[62:65]
	v_mfma_f32_16x16x32_bf16 v[58:61], v[66:69], v[204:207], v[58:61]
	v_mfma_f32_16x16x32_bf16 v[30:33], v[50:53], v[212:215], v[30:33]
	v_mfma_f32_16x16x32_bf16 v[26:29], v[66:69], v[212:215], v[26:29]
	v_mfma_f32_16x16x32_bf16 v[14:17], v[50:53], v[220:223], v[14:17]
	v_mfma_f32_16x16x32_bf16 v[10:13], v[66:69], v[220:223], v[10:13]
	v_mfma_f32_16x16x32_bf16 v[78:81], v[54:57], v[200:203], v[78:81]
	v_mfma_f32_16x16x32_bf16 v[74:77], v[70:73], v[200:203], v[74:77]
	v_mfma_f32_16x16x32_bf16 v[62:65], v[54:57], v[208:211], v[62:65]
	v_mfma_f32_16x16x32_bf16 v[58:61], v[70:73], v[208:211], v[58:61]
	v_mfma_f32_16x16x32_bf16 v[30:33], v[54:57], v[216:219], v[30:33]
	v_mfma_f32_16x16x32_bf16 v[26:29], v[70:73], v[216:219], v[26:29]
	v_mfma_f32_16x16x32_bf16 v[14:17], v[54:57], v[224:227], v[14:17]
	v_mfma_f32_16x16x32_bf16 v[10:13], v[70:73], v[224:227], v[10:13]
	s_setprio 0
	s_setprio 1
	v_mfma_f32_16x16x32_bf16 v[34:37], v[168:171], v[196:199], v[34:37]
	v_mfma_f32_16x16x32_bf16 v[70:73], v[172:175], v[200:203], v[34:37]
	v_mfma_f32_16x16x32_bf16 v[34:37], v[176:179], v[196:199], v[38:41]
	v_mfma_f32_16x16x32_bf16 v[66:69], v[192:195], v[200:203], v[34:37]
	v_mfma_f32_16x16x32_bf16 v[34:37], v[168:171], v[204:207], v[46:49]
	v_mfma_f32_16x16x32_bf16 v[46:49], v[172:175], v[208:211], v[34:37]
	v_mfma_f32_16x16x32_bf16 v[34:37], v[176:179], v[204:207], v[42:45]
	v_mfma_f32_16x16x32_bf16 v[22:25], v[168:171], v[212:215], v[22:25]
	v_mfma_f32_16x16x32_bf16 v[18:21], v[176:179], v[212:215], v[18:21]
	v_mfma_f32_16x16x32_bf16 v[6:9], v[168:171], v[220:223], v[6:9]
	s_barrier
	v_mfma_f32_16x16x32_bf16 v[2:5], v[176:179], v[220:223], v[2:5]
	v_mfma_f32_16x16x32_bf16 v[42:45], v[192:195], v[208:211], v[34:37]
	v_mfma_f32_16x16x32_bf16 v[22:25], v[172:175], v[216:219], v[22:25]
	v_mfma_f32_16x16x32_bf16 v[18:21], v[192:195], v[216:219], v[18:21]
	v_mfma_f32_16x16x32_bf16 v[6:9], v[172:175], v[224:227], v[6:9]
	v_mfma_f32_16x16x32_bf16 v[2:5], v[192:195], v[224:227], v[2:5]
	s_setprio 0
	s_nop 0
	s_add_u32 s2, s2, 0x100
	s_addc_u32 s3, s3, 0
	s_add_u32 s6, s6, 0x100
	s_addc_u32 s7, s7, 0
	s_cmp_ge_i32 s47, s84
	s_mov_b32 s4, s47
	s_cbranch_scc0 .LBB0_2116

.LBB0_2764:
	v_add_u32_e32 v158, s68, v229
	v_add_u32_e32 v174, s69, v229
	ds_read_b128 v[146:149], v158
	ds_read_b128 v[150:153], v158 offset:1024
	ds_read_b128 v[154:157], v158 offset:2048
	ds_read_b128 v[158:161], v158 offset:3072
	ds_read_b128 v[162:165], v174
	ds_read_b128 v[166:169], v174 offset:1024
	ds_read_b128 v[170:173], v174 offset:2048
	ds_read_b128 v[174:177], v174 offset:3072
	s_add_i32 s84, s42, 2
	s_add_u32 s85, s40, 0x80
	s_addc_u32 s43, s41, 0
	s_cmp_eq_u32 s65, s42
	s_cselect_b32 s42, s4, s85
	s_cselect_b32 s43, s5, s43
	s_cselect_b32 s87, s39, s83
	s_cselect_b32 s86, s38, s82
	v_lshl_add_u64 v[210:211], s[40:41], 0, v[138:139]
	s_add_i32 m0, s51, 0xc000
	ds_read_b128 v[178:181], v231
	ds_read_b128 v[182:185], v231 offset:1024
	ds_read_b128 v[186:189], v231 offset:2048
	ds_read_b128 v[190:193], v231 offset:3072
	ds_read_b128 v[194:197], v231 offset:4096
	ds_read_b128 v[198:201], v231 offset:5120
	ds_read_b128 v[202:205], v231 offset:6144
	ds_read_b128 v[206:209], v231 offset:7168
	global_load_lds_dwordx4 v[210:211], off
	v_lshl_add_u64 v[210:211], s[40:41], 0, v[140:141]
	s_add_i32 m0, s51, 0xe000
	s_nop 0
	global_load_lds_dwordx4 v[210:211], off
	s_waitcnt vmcnt(8)
	s_waitcnt lgkmcnt(0)
	s_barrier
	s_setprio 1
	s_waitcnt lgkmcnt(0)
	v_mfma_i32_16x16x64_i8 v[126:129], v[146:149], v[178:181], v[126:129]
	v_mfma_i32_16x16x64_i8 v[122:125], v[154:157], v[178:181], v[122:125]
	v_mfma_i32_16x16x64_i8 v[118:121], v[146:149], v[186:189], v[118:121]
	v_mfma_i32_16x16x64_i8 v[114:117], v[154:157], v[186:189], v[114:117]
	v_mfma_i32_16x16x64_i8 v[106:109], v[146:149], v[194:197], v[106:109]
	v_mfma_i32_16x16x64_i8 v[98:101], v[154:157], v[194:197], v[98:101]
	v_mfma_i32_16x16x64_i8 v[90:93], v[146:149], v[202:205], v[90:93]
	v_mfma_i32_16x16x64_i8 v[82:85], v[154:157], v[202:205], v[82:85]
	v_mfma_i32_16x16x64_i8 v[126:129], v[150:153], v[182:185], v[126:129]
	v_mfma_i32_16x16x64_i8 v[122:125], v[158:161], v[182:185], v[122:125]
	v_mfma_i32_16x16x64_i8 v[118:121], v[150:153], v[190:193], v[118:121]
	v_mfma_i32_16x16x64_i8 v[114:117], v[158:161], v[190:193], v[114:117]
	v_mfma_i32_16x16x64_i8 v[106:109], v[150:153], v[198:201], v[106:109]
	v_mfma_i32_16x16x64_i8 v[98:101], v[158:161], v[198:201], v[98:101]
	v_mfma_i32_16x16x64_i8 v[90:93], v[150:153], v[206:209], v[90:93]
	v_mfma_i32_16x16x64_i8 v[82:85], v[158:161], v[206:209], v[82:85]
	s_setprio 0
	s_setprio 1
	v_mfma_i32_16x16x64_i8 v[110:113], v[162:165], v[178:181], v[110:113]
	v_mfma_i32_16x16x64_i8 v[102:105], v[170:173], v[178:181], v[102:105]
	v_mfma_i32_16x16x64_i8 v[94:97], v[162:165], v[186:189], v[94:97]
	v_mfma_i32_16x16x64_i8 v[86:89], v[170:173], v[186:189], v[86:89]
	v_mfma_i32_16x16x64_i8 v[78:81], v[162:165], v[194:197], v[78:81]
	v_mfma_i32_16x16x64_i8 v[74:77], v[170:173], v[194:197], v[74:77]
	v_mfma_i32_16x16x64_i8 v[70:73], v[162:165], v[202:205], v[70:73]
	v_mfma_i32_16x16x64_i8 v[66:69], v[170:173], v[202:205], v[66:69]
	v_mfma_i32_16x16x64_i8 v[110:113], v[166:169], v[182:185], v[110:113]
	v_mfma_i32_16x16x64_i8 v[102:105], v[174:177], v[182:185], v[102:105]
	s_barrier
	v_mfma_i32_16x16x64_i8 v[94:97], v[166:169], v[190:193], v[94:97]
	v_mfma_i32_16x16x64_i8 v[86:89], v[174:177], v[190:193], v[86:89]
	v_mfma_i32_16x16x64_i8 v[78:81], v[166:169], v[198:201], v[78:81]
	v_mfma_i32_16x16x64_i8 v[74:77], v[174:177], v[198:201], v[74:77]
	v_mfma_i32_16x16x64_i8 v[70:73], v[166:169], v[206:209], v[70:73]
	v_mfma_i32_16x16x64_i8 v[66:69], v[174:177], v[206:209], v[66:69]
	s_setprio 0
	s_nop 0
	s_add_i32 s85, s68, s50
	v_lshl_add_u64 v[210:211], s[86:87], 0, v[132:133]
	s_mov_b32 m0, s85
	ds_read_b128 v[178:181], v231 offset:16384
	ds_read_b128 v[182:185], v231 offset:17408
	ds_read_b128 v[186:189], v231 offset:18432
	ds_read_b128 v[190:193], v231 offset:19456
	ds_read_b128 v[194:197], v231 offset:20480
	ds_read_b128 v[198:201], v231 offset:21504
	ds_read_b128 v[202:205], v231 offset:22528
	ds_read_b128 v[206:209], v231 offset:23552
	global_load_lds_dwordx4 v[210:211], off
	s_add_i32 m0, s85, 0x2000
	v_lshl_add_u64 v[212:213], s[86:87], 0, v[136:137]
	s_add_u32 s86, s86, s8
	s_addc_u32 s87, s87, s9
	s_add_i32 s85, s69, s50
	global_load_lds_dwordx4 v[212:213], off
	v_lshl_add_u64 v[214:215], s[86:87], 0, v[132:133]
	s_mov_b32 m0, s85
	v_lshl_add_u64 v[216:217], s[86:87], 0, v[136:137]
	global_load_lds_dwordx4 v[214:215], off
	s_add_i32 m0, s85, 0x2000
	v_lshl_add_u64 v[218:219], s[42:43], 0, v[130:131]
	global_load_lds_dwordx4 v[216:217], off
	s_mov_b32 m0, s51
	v_lshl_add_u64 v[220:221], s[42:43], 0, v[134:135]
	global_load_lds_dwordx4 v[218:219], off
	s_mov_b32 m0, s54
	s_nop 0
	global_load_lds_dwordx4 v[220:221], off
	s_waitcnt vmcnt(8)
	s_waitcnt lgkmcnt(0)
	s_barrier
	s_setprio 1
	s_waitcnt lgkmcnt(0)
	v_mfma_i32_16x16x64_i8 v[62:65], v[146:149], v[178:181], v[62:65]
	v_mfma_i32_16x16x64_i8 v[58:61], v[154:157], v[178:181], v[58:61]
	v_mfma_i32_16x16x64_i8 v[54:57], v[146:149], v[186:189], v[54:57]
	v_mfma_i32_16x16x64_i8 v[50:53], v[154:157], v[186:189], v[50:53]
	v_mfma_i32_16x16x64_i8 v[42:45], v[146:149], v[194:197], v[42:45]
	v_mfma_i32_16x16x64_i8 v[34:37], v[154:157], v[194:197], v[34:37]
	v_mfma_i32_16x16x64_i8 v[26:29], v[146:149], v[202:205], v[26:29]
	v_mfma_i32_16x16x64_i8 v[18:21], v[154:157], v[202:205], v[18:21]
	v_mfma_i32_16x16x64_i8 v[62:65], v[150:153], v[182:185], v[62:65]
	v_mfma_i32_16x16x64_i8 v[58:61], v[158:161], v[182:185], v[58:61]
	v_mfma_i32_16x16x64_i8 v[54:57], v[150:153], v[190:193], v[54:57]
	v_mfma_i32_16x16x64_i8 v[50:53], v[158:161], v[190:193], v[50:53]
	v_mfma_i32_16x16x64_i8 v[42:45], v[150:153], v[198:201], v[42:45]
	v_mfma_i32_16x16x64_i8 v[34:37], v[158:161], v[198:201], v[34:37]
	v_mfma_i32_16x16x64_i8 v[26:29], v[150:153], v[206:209], v[26:29]
	v_mfma_i32_16x16x64_i8 v[18:21], v[158:161], v[206:209], v[18:21]
	s_setprio 0
	s_setprio 1
	v_mfma_i32_16x16x64_i8 v[46:49], v[162:165], v[178:181], v[46:49]
	v_mfma_i32_16x16x64_i8 v[38:41], v[170:173], v[178:181], v[38:41]
	v_mfma_i32_16x16x64_i8 v[30:33], v[162:165], v[186:189], v[30:33]
	v_mfma_i32_16x16x64_i8 v[22:25], v[170:173], v[186:189], v[22:25]
	v_mfma_i32_16x16x64_i8 v[14:17], v[162:165], v[194:197], v[14:17]
	v_mfma_i32_16x16x64_i8 v[10:13], v[170:173], v[194:197], v[10:13]
	v_mfma_i32_16x16x64_i8 v[6:9], v[162:165], v[202:205], v[6:9]
	v_mfma_i32_16x16x64_i8 v[2:5], v[170:173], v[202:205], v[2:5]
	v_mfma_i32_16x16x64_i8 v[46:49], v[166:169], v[182:185], v[46:49]
	v_mfma_i32_16x16x64_i8 v[38:41], v[174:177], v[182:185], v[38:41]
	s_barrier
	v_mfma_i32_16x16x64_i8 v[30:33], v[166:169], v[190:193], v[30:33]
	v_mfma_i32_16x16x64_i8 v[22:25], v[174:177], v[190:193], v[22:25]
	v_mfma_i32_16x16x64_i8 v[14:17], v[166:169], v[198:201], v[14:17]
	v_mfma_i32_16x16x64_i8 v[10:13], v[174:177], v[198:201], v[10:13]
	v_mfma_i32_16x16x64_i8 v[6:9], v[166:169], v[206:209], v[6:9]
	v_mfma_i32_16x16x64_i8 v[2:5], v[174:177], v[206:209], v[2:5]
	s_setprio 0
	s_nop 0
	s_add_i32 s85, 0, 0x18000
	s_add_i32 s86, 0, 0x1c000
	v_add_u32_e32 v158, s85, v229
	v_add_u32_e32 v174, s86, v229
	ds_read_b128 v[146:149], v158
	ds_read_b128 v[150:153], v158 offset:1024
	ds_read_b128 v[154:157], v158 offset:2048
	ds_read_b128 v[158:161], v158 offset:3072
	ds_read_b128 v[162:165], v174
	ds_read_b128 v[166:169], v174 offset:1024
	ds_read_b128 v[170:173], v174 offset:2048
	ds_read_b128 v[174:177], v174 offset:3072
	s_add_u32 s42, s42, s8
	s_addc_u32 s43, s43, s9
	s_mov_b32 m0, s55
	v_lshl_add_u64 v[222:223], s[42:43], 0, v[130:131]
	ds_read_b128 v[178:181], v231 offset:32768
	ds_read_b128 v[182:185], v231 offset:33792
	ds_read_b128 v[186:189], v231 offset:34816
	ds_read_b128 v[190:193], v231 offset:35840
	ds_read_b128 v[194:197], v231 offset:36864
	ds_read_b128 v[198:201], v231 offset:37888
	ds_read_b128 v[202:205], v231 offset:38912
	ds_read_b128 v[206:209], v231 offset:39936
	global_load_lds_dwordx4 v[222:223], off
	v_lshl_add_u64 v[222:223], s[42:43], 0, v[134:135]
	s_mov_b32 m0, s56
	s_nop 0
	global_load_lds_dwordx4 v[222:223], off
	s_waitcnt vmcnt(8)
	s_waitcnt lgkmcnt(0)
	s_barrier
	s_setprio 1
	s_waitcnt lgkmcnt(0)
	v_mfma_i32_16x16x64_i8 v[126:129], v[146:149], v[178:181], v[126:129]
	v_mfma_i32_16x16x64_i8 v[122:125], v[154:157], v[178:181], v[122:125]
	v_mfma_i32_16x16x64_i8 v[118:121], v[146:149], v[186:189], v[118:121]
	v_mfma_i32_16x16x64_i8 v[114:117], v[154:157], v[186:189], v[114:117]
	v_mfma_i32_16x16x64_i8 v[106:109], v[146:149], v[194:197], v[106:109]
	v_mfma_i32_16x16x64_i8 v[98:101], v[154:157], v[194:197], v[98:101]
	v_mfma_i32_16x16x64_i8 v[90:93], v[146:149], v[202:205], v[90:93]
	v_mfma_i32_16x16x64_i8 v[82:85], v[154:157], v[202:205], v[82:85]
	v_mfma_i32_16x16x64_i8 v[126:129], v[150:153], v[182:185], v[126:129]
	v_mfma_i32_16x16x64_i8 v[122:125], v[158:161], v[182:185], v[122:125]
	v_mfma_i32_16x16x64_i8 v[118:121], v[150:153], v[190:193], v[118:121]
	v_mfma_i32_16x16x64_i8 v[114:117], v[158:161], v[190:193], v[114:117]
	v_mfma_i32_16x16x64_i8 v[106:109], v[150:153], v[198:201], v[106:109]
	v_mfma_i32_16x16x64_i8 v[98:101], v[158:161], v[198:201], v[98:101]
	v_mfma_i32_16x16x64_i8 v[90:93], v[150:153], v[206:209], v[90:93]
	v_mfma_i32_16x16x64_i8 v[82:85], v[158:161], v[206:209], v[82:85]
	s_setprio 0
	s_setprio 1
	v_mfma_i32_16x16x64_i8 v[110:113], v[162:165], v[178:181], v[110:113]
	v_mfma_i32_16x16x64_i8 v[102:105], v[170:173], v[178:181], v[102:105]
	v_mfma_i32_16x16x64_i8 v[94:97], v[162:165], v[186:189], v[94:97]
	v_mfma_i32_16x16x64_i8 v[86:89], v[170:173], v[186:189], v[86:89]
	v_mfma_i32_16x16x64_i8 v[78:81], v[162:165], v[194:197], v[78:81]
	v_mfma_i32_16x16x64_i8 v[74:77], v[170:173], v[194:197], v[74:77]
	v_mfma_i32_16x16x64_i8 v[70:73], v[162:165], v[202:205], v[70:73]
	v_mfma_i32_16x16x64_i8 v[66:69], v[170:173], v[202:205], v[66:69]
	v_mfma_i32_16x16x64_i8 v[110:113], v[166:169], v[182:185], v[110:113]
	v_mfma_i32_16x16x64_i8 v[102:105], v[174:177], v[182:185], v[102:105]
	s_barrier
	v_mfma_i32_16x16x64_i8 v[94:97], v[166:169], v[190:193], v[94:97]
	v_mfma_i32_16x16x64_i8 v[86:89], v[174:177], v[190:193], v[86:89]
	v_mfma_i32_16x16x64_i8 v[78:81], v[166:169], v[198:201], v[78:81]
	v_mfma_i32_16x16x64_i8 v[74:77], v[174:177], v[198:201], v[74:77]
	v_mfma_i32_16x16x64_i8 v[70:73], v[166:169], v[206:209], v[70:73]
	v_mfma_i32_16x16x64_i8 v[66:69], v[174:177], v[206:209], v[66:69]
	s_setprio 0
	s_nop 0
	s_add_i32 s42, s85, s50
	v_lshl_add_u64 v[210:211], v[210:211], 0, s[30:31]
	s_mov_b32 m0, s42
	ds_read_b128 v[178:181], v231 offset:49152
	ds_read_b128 v[182:185], v231 offset:50176
	ds_read_b128 v[186:189], v231 offset:51200
	ds_read_b128 v[190:193], v231 offset:52224
	ds_read_b128 v[194:197], v231 offset:53248
	ds_read_b128 v[198:201], v231 offset:54272
	ds_read_b128 v[202:205], v231 offset:55296
	ds_read_b128 v[206:209], v231 offset:56320
	global_load_lds_dwordx4 v[210:211], off
	v_lshl_add_u64 v[210:211], v[212:213], 0, s[30:31]
	s_add_i32 m0, s42, 0x2000
	s_add_i32 s42, s86, s50
	global_load_lds_dwordx4 v[210:211], off
	v_lshl_add_u64 v[210:211], v[214:215], 0, s[30:31]
	s_mov_b32 m0, s42
	s_nop 0
	global_load_lds_dwordx4 v[210:211], off
	v_lshl_add_u64 v[210:211], v[216:217], 0, s[30:31]
	s_add_i32 m0, s42, 0x2000
	s_nop 0
	global_load_lds_dwordx4 v[210:211], off
	v_lshl_add_u64 v[210:211], v[218:219], 0, s[30:31]
	s_mov_b32 m0, s61
	s_nop 0
	global_load_lds_dwordx4 v[210:211], off
	v_lshl_add_u64 v[210:211], v[220:221], 0, s[30:31]
	s_mov_b32 m0, s62
	s_nop 0
	global_load_lds_dwordx4 v[210:211], off
	s_waitcnt vmcnt(8)
	s_waitcnt lgkmcnt(0)
	s_barrier
	s_setprio 1
	s_waitcnt lgkmcnt(0)
	v_mfma_i32_16x16x64_i8 v[62:65], v[146:149], v[178:181], v[62:65]
	v_mfma_i32_16x16x64_i8 v[58:61], v[154:157], v[178:181], v[58:61]
	v_mfma_i32_16x16x64_i8 v[54:57], v[146:149], v[186:189], v[54:57]
	v_mfma_i32_16x16x64_i8 v[50:53], v[154:157], v[186:189], v[50:53]
	v_mfma_i32_16x16x64_i8 v[42:45], v[146:149], v[194:197], v[42:45]
	v_mfma_i32_16x16x64_i8 v[34:37], v[154:157], v[194:197], v[34:37]
	v_mfma_i32_16x16x64_i8 v[26:29], v[146:149], v[202:205], v[26:29]
	v_mfma_i32_16x16x64_i8 v[18:21], v[154:157], v[202:205], v[18:21]
	v_mfma_i32_16x16x64_i8 v[62:65], v[150:153], v[182:185], v[62:65]
	v_mfma_i32_16x16x64_i8 v[58:61], v[158:161], v[182:185], v[58:61]
	v_mfma_i32_16x16x64_i8 v[54:57], v[150:153], v[190:193], v[54:57]
	v_mfma_i32_16x16x64_i8 v[50:53], v[158:161], v[190:193], v[50:53]
	v_mfma_i32_16x16x64_i8 v[42:45], v[150:153], v[198:201], v[42:45]
	v_mfma_i32_16x16x64_i8 v[34:37], v[158:161], v[198:201], v[34:37]
	v_mfma_i32_16x16x64_i8 v[26:29], v[150:153], v[206:209], v[26:29]
	v_mfma_i32_16x16x64_i8 v[18:21], v[158:161], v[206:209], v[18:21]
	s_setprio 0
	s_setprio 1
	v_mfma_i32_16x16x64_i8 v[46:49], v[162:165], v[178:181], v[46:49]
	v_mfma_i32_16x16x64_i8 v[38:41], v[170:173], v[178:181], v[38:41]
	v_mfma_i32_16x16x64_i8 v[30:33], v[162:165], v[186:189], v[30:33]
	v_mfma_i32_16x16x64_i8 v[22:25], v[170:173], v[186:189], v[22:25]
	v_mfma_i32_16x16x64_i8 v[14:17], v[162:165], v[194:197], v[14:17]
	v_mfma_i32_16x16x64_i8 v[10:13], v[170:173], v[194:197], v[10:13]
	v_mfma_i32_16x16x64_i8 v[6:9], v[162:165], v[202:205], v[6:9]
	v_mfma_i32_16x16x64_i8 v[2:5], v[170:173], v[202:205], v[2:5]
	v_mfma_i32_16x16x64_i8 v[46:49], v[166:169], v[182:185], v[46:49]
	v_mfma_i32_16x16x64_i8 v[38:41], v[174:177], v[182:185], v[38:41]
	s_barrier
	v_mfma_i32_16x16x64_i8 v[30:33], v[166:169], v[190:193], v[30:33]
	v_mfma_i32_16x16x64_i8 v[22:25], v[174:177], v[190:193], v[22:25]
	v_mfma_i32_16x16x64_i8 v[14:17], v[166:169], v[198:201], v[14:17]
	v_mfma_i32_16x16x64_i8 v[10:13], v[174:177], v[198:201], v[10:13]
	v_mfma_i32_16x16x64_i8 v[6:9], v[166:169], v[206:209], v[6:9]
	v_mfma_i32_16x16x64_i8 v[2:5], v[174:177], v[206:209], v[2:5]
	s_setprio 0
	s_nop 0
	s_add_u32 s40, s40, 0x100
	s_addc_u32 s41, s41, 0
	s_add_u32 s82, s82, 0x100
	s_addc_u32 s83, s83, 0
	s_cmp_ge_i32 s84, s64
	s_mov_b32 s42, s84
	s_cbranch_scc0 .LBB0_2764
	v_cvt_f32_i32_e32 v214, v126
	v_cvt_f32_i32_e32 v215, v127
	v_cvt_f32_i32_e32 v212, v128
	v_cvt_f32_i32_e32 v213, v129
	v_cvt_f32_i32_e32 v218, v122
	v_cvt_f32_i32_e32 v219, v123
	v_cvt_f32_i32_e32 v216, v124
	v_cvt_f32_i32_e32 v217, v125
	v_cvt_f32_i32_e32 v222, v110
	v_cvt_f32_i32_e32 v223, v111
	v_cvt_f32_i32_e32 v220, v112
	v_cvt_f32_i32_e32 v221, v113
	v_cvt_f32_i32_e32 v226, v102
	v_cvt_f32_i32_e32 v227, v103
	v_cvt_f32_i32_e32 v224, v104
	v_cvt_f32_i32_e32 v225, v105
	v_cvt_f32_i32_e32 v194, v118
	v_cvt_f32_i32_e32 v195, v119
	v_cvt_f32_i32_e32 v192, v120
	v_cvt_f32_i32_e32 v193, v121
	v_cvt_f32_i32_e32 v200, v114
	v_cvt_f32_i32_e32 v201, v115
	v_cvt_f32_i32_e32 v198, v116
	v_cvt_f32_i32_e32 v199, v117
	v_cvt_f32_i32_e32 v206, v94
	v_cvt_f32_i32_e32 v207, v95
	v_cvt_f32_i32_e32 v202, v96
	v_cvt_f32_i32_e32 v203, v97
	v_cvt_f32_i32_e32 v208, v86
	v_cvt_f32_i32_e32 v209, v87
	v_cvt_f32_i32_e32 v204, v88
	v_cvt_f32_i32_e32 v205, v89
	v_cvt_f32_i32_e32 v178, v106
	v_cvt_f32_i32_e32 v179, v107
	v_cvt_f32_i32_e32 v176, v108
	v_cvt_f32_i32_e32 v177, v109
	v_cvt_f32_i32_e32 v182, v98
	v_cvt_f32_i32_e32 v183, v99
	v_cvt_f32_i32_e32 v180, v100
	v_cvt_f32_i32_e32 v181, v101
	v_cvt_f32_i32_e32 v188, v78
	v_cvt_f32_i32_e32 v189, v79
	v_cvt_f32_i32_e32 v184, v80
	v_cvt_f32_i32_e32 v185, v81
	v_cvt_f32_i32_e32 v190, v74
	v_cvt_f32_i32_e32 v191, v75
	v_cvt_f32_i32_e32 v186, v76
	v_cvt_f32_i32_e32 v187, v77
	v_cvt_f32_i32_e32 v162, v90
	v_cvt_f32_i32_e32 v163, v91
	v_cvt_f32_i32_e32 v160, v92
	v_cvt_f32_i32_e32 v161, v93
	v_cvt_f32_i32_e32 v166, v82
	v_cvt_f32_i32_e32 v167, v83
	v_cvt_f32_i32_e32 v164, v84
	v_cvt_f32_i32_e32 v165, v85
	v_cvt_f32_i32_e32 v172, v70
	v_cvt_f32_i32_e32 v173, v71
	v_cvt_f32_i32_e32 v168, v72
	v_cvt_f32_i32_e32 v169, v73
	v_cvt_f32_i32_e32 v174, v66
	v_cvt_f32_i32_e32 v175, v67
	v_cvt_f32_i32_e32 v170, v68
	v_cvt_f32_i32_e32 v171, v69
	v_cvt_f32_i32_e32 v146, v62
	v_cvt_f32_i32_e32 v147, v63
	v_cvt_f32_i32_e32 v128, v64
	v_cvt_f32_i32_e32 v129, v65
	v_cvt_f32_i32_e32 v150, v58
	v_cvt_f32_i32_e32 v151, v59
	v_cvt_f32_i32_e32 v148, v60
	v_cvt_f32_i32_e32 v149, v61
	v_cvt_f32_i32_e32 v156, v46
	v_cvt_f32_i32_e32 v157, v47
	v_cvt_f32_i32_e32 v152, v48
	v_cvt_f32_i32_e32 v153, v49
	v_cvt_f32_i32_e32 v158, v38
	v_cvt_f32_i32_e32 v159, v39
	v_cvt_f32_i32_e32 v154, v40
	v_cvt_f32_i32_e32 v155, v41
	v_cvt_f32_i32_e32 v114, v54
	v_cvt_f32_i32_e32 v115, v55
	v_cvt_f32_i32_e32 v112, v56
	v_cvt_f32_i32_e32 v113, v57
	v_cvt_f32_i32_e32 v118, v50
	v_cvt_f32_i32_e32 v119, v51
	v_cvt_f32_i32_e32 v116, v52
	v_cvt_f32_i32_e32 v117, v53
	v_cvt_f32_i32_e32 v124, v30
	v_cvt_f32_i32_e32 v125, v31
	v_cvt_f32_i32_e32 v120, v32
	v_cvt_f32_i32_e32 v121, v33
	v_cvt_f32_i32_e32 v126, v22
	v_cvt_f32_i32_e32 v127, v23
	v_cvt_f32_i32_e32 v122, v24
	v_cvt_f32_i32_e32 v123, v25
	v_cvt_f32_i32_e32 v64, v42
	v_cvt_f32_i32_e32 v65, v43
	v_cvt_f32_i32_e32 v62, v44
	v_cvt_f32_i32_e32 v63, v45
	v_cvt_f32_i32_e32 v68, v34
	v_cvt_f32_i32_e32 v69, v35
	v_cvt_f32_i32_e32 v66, v36
	v_cvt_f32_i32_e32 v67, v37
	v_cvt_f32_i32_e32 v74, v14
	v_cvt_f32_i32_e32 v75, v15
	v_cvt_f32_i32_e32 v70, v16
	v_cvt_f32_i32_e32 v71, v17
	v_cvt_f32_i32_e32 v76, v10
	v_cvt_f32_i32_e32 v77, v11
	v_cvt_f32_i32_e32 v72, v12
	v_cvt_f32_i32_e32 v73, v13
	v_cvt_f32_i32_e32 v48, v26
	v_cvt_f32_i32_e32 v49, v27
	v_cvt_f32_i32_e32 v46, v28
	v_cvt_f32_i32_e32 v47, v29
	v_cvt_f32_i32_e32 v52, v18
	v_cvt_f32_i32_e32 v53, v19
	v_cvt_f32_i32_e32 v50, v20
	v_cvt_f32_i32_e32 v51, v21
	v_cvt_f32_i32_e32 v58, v6
	v_cvt_f32_i32_e32 v59, v7
	v_cvt_f32_i32_e32 v54, v8
	v_cvt_f32_i32_e32 v55, v9
	v_cvt_f32_i32_e32 v60, v2
	v_cvt_f32_i32_e32 v61, v3
	v_cvt_f32_i32_e32 v56, v4
	v_cvt_f32_i32_e32 v57, v5

.LBB0_2949:
	v_add_u32_e32 v138, s60, v188
	ds_read_b128 v[148:151], v138
	ds_read_b128 v[152:155], v138 offset:1024
	ds_read_b128 v[156:159], v138 offset:2048
	ds_read_b128 v[160:163], v138 offset:3072
	v_add_u32_e32 v138, s61, v188
	ds_read_b128 v[164:167], v138
	ds_read_b128 v[168:171], v138 offset:1024
	ds_read_b128 v[172:175], v138 offset:2048
	ds_read_b128 v[176:179], v138 offset:3072
	s_add_i32 s64, s28, 2
	s_add_u32 s65, s26, 0x80
	s_addc_u32 s29, s27, 0
	s_cmp_eq_u32 s58, s28
	s_cselect_b32 s28, s2, s65
	s_cselect_b32 s29, s3, s29
	s_cselect_b32 s67, s25, s35
	s_cselect_b32 s66, s24, s34
	v_lshl_add_u64 v[184:185], s[26:27], 0, v[140:141]
	s_add_i32 m0, s42, 0xc000
	ds_read_b128 v[180:183], v189
	ds_read_b128 v[190:193], v189 offset:1024
	ds_read_b128 v[194:197], v189 offset:2048
	ds_read_b128 v[198:201], v189 offset:3072
	ds_read_b128 v[202:205], v189 offset:4096
	ds_read_b128 v[206:209], v189 offset:5120
	ds_read_b128 v[210:213], v189 offset:6144
	ds_read_b128 v[214:217], v189 offset:7168
	global_load_lds_dwordx4 v[184:185], off
	v_lshl_add_u64 v[184:185], s[26:27], 0, v[142:143]
	s_add_i32 m0, s42, 0xe000
	s_nop 0
	global_load_lds_dwordx4 v[184:185], off
	s_waitcnt vmcnt(8)
	s_waitcnt lgkmcnt(0)
	s_barrier
	s_setprio 1
	s_waitcnt lgkmcnt(0)
	v_mfma_i32_16x16x64_i8 v[126:129], v[148:151], v[180:183], v[126:129]
	v_mfma_i32_16x16x64_i8 v[122:125], v[156:159], v[180:183], v[122:125]
	v_mfma_i32_16x16x64_i8 v[118:121], v[148:151], v[194:197], v[118:121]
	v_mfma_i32_16x16x64_i8 v[114:117], v[156:159], v[194:197], v[114:117]
	v_mfma_i32_16x16x64_i8 v[106:109], v[148:151], v[202:205], v[106:109]
	v_mfma_i32_16x16x64_i8 v[98:101], v[156:159], v[202:205], v[98:101]
	v_mfma_i32_16x16x64_i8 v[90:93], v[148:151], v[210:213], v[90:93]
	v_mfma_i32_16x16x64_i8 v[82:85], v[156:159], v[210:213], v[82:85]
	v_mfma_i32_16x16x64_i8 v[126:129], v[152:155], v[190:193], v[126:129]
	v_mfma_i32_16x16x64_i8 v[122:125], v[160:163], v[190:193], v[122:125]
	v_mfma_i32_16x16x64_i8 v[118:121], v[152:155], v[198:201], v[118:121]
	v_mfma_i32_16x16x64_i8 v[114:117], v[160:163], v[198:201], v[114:117]
	v_mfma_i32_16x16x64_i8 v[106:109], v[152:155], v[206:209], v[106:109]
	v_mfma_i32_16x16x64_i8 v[98:101], v[160:163], v[206:209], v[98:101]
	v_mfma_i32_16x16x64_i8 v[90:93], v[152:155], v[214:217], v[90:93]
	v_mfma_i32_16x16x64_i8 v[82:85], v[160:163], v[214:217], v[82:85]
	s_setprio 0
	s_setprio 1
	v_mfma_i32_16x16x64_i8 v[110:113], v[164:167], v[180:183], v[110:113]
	v_mfma_i32_16x16x64_i8 v[102:105], v[172:175], v[180:183], v[102:105]
	v_mfma_i32_16x16x64_i8 v[94:97], v[164:167], v[194:197], v[94:97]
	v_mfma_i32_16x16x64_i8 v[86:89], v[172:175], v[194:197], v[86:89]
	v_mfma_i32_16x16x64_i8 v[78:81], v[164:167], v[202:205], v[78:81]
	v_mfma_i32_16x16x64_i8 v[74:77], v[172:175], v[202:205], v[74:77]
	v_mfma_i32_16x16x64_i8 v[70:73], v[164:167], v[210:213], v[70:73]
	v_mfma_i32_16x16x64_i8 v[66:69], v[172:175], v[210:213], v[66:69]
	v_mfma_i32_16x16x64_i8 v[110:113], v[168:171], v[190:193], v[110:113]
	v_mfma_i32_16x16x64_i8 v[102:105], v[176:179], v[190:193], v[102:105]
	s_barrier
	v_mfma_i32_16x16x64_i8 v[94:97], v[168:171], v[198:201], v[94:97]
	v_mfma_i32_16x16x64_i8 v[86:89], v[176:179], v[198:201], v[86:89]
	v_mfma_i32_16x16x64_i8 v[78:81], v[168:171], v[206:209], v[78:81]
	v_mfma_i32_16x16x64_i8 v[74:77], v[176:179], v[206:209], v[74:77]
	v_mfma_i32_16x16x64_i8 v[70:73], v[168:171], v[214:217], v[70:73]
	v_mfma_i32_16x16x64_i8 v[66:69], v[176:179], v[214:217], v[66:69]
	s_setprio 0
	s_nop 0
	s_add_i32 s65, s60, s41
	v_lshl_add_u64 v[184:185], s[66:67], 0, v[132:133]
	s_mov_b32 m0, s65
	ds_read_b128 v[180:183], v189 offset:16384
	ds_read_b128 v[190:193], v189 offset:17408
	ds_read_b128 v[194:197], v189 offset:18432
	ds_read_b128 v[198:201], v189 offset:19456
	ds_read_b128 v[202:205], v189 offset:20480
	ds_read_b128 v[206:209], v189 offset:21504
	ds_read_b128 v[210:213], v189 offset:22528
	ds_read_b128 v[214:217], v189 offset:23552
	global_load_lds_dwordx4 v[184:185], off
	s_add_i32 m0, s65, 0x2000
	v_lshl_add_u64 v[218:219], s[66:67], 0, v[136:137]
	s_add_u32 s66, s66, s6
	s_addc_u32 s67, s67, s7
	s_add_i32 s65, s61, s41
	global_load_lds_dwordx4 v[218:219], off
	v_lshl_add_u64 v[220:221], s[66:67], 0, v[132:133]
	s_mov_b32 m0, s65
	v_lshl_add_u64 v[222:223], s[66:67], 0, v[136:137]
	global_load_lds_dwordx4 v[220:221], off
	s_add_i32 m0, s65, 0x2000
	v_lshl_add_u64 v[224:225], s[28:29], 0, v[130:131]
	global_load_lds_dwordx4 v[222:223], off
	s_mov_b32 m0, s42
	v_lshl_add_u64 v[226:227], s[28:29], 0, v[134:135]
	global_load_lds_dwordx4 v[224:225], off
	s_mov_b32 m0, s43
	s_nop 0
	global_load_lds_dwordx4 v[226:227], off
	s_waitcnt vmcnt(8)
	s_waitcnt lgkmcnt(0)
	s_barrier
	s_setprio 1
	s_waitcnt lgkmcnt(0)
	v_mfma_i32_16x16x64_i8 v[62:65], v[148:151], v[180:183], v[62:65]
	v_mfma_i32_16x16x64_i8 v[58:61], v[156:159], v[180:183], v[58:61]
	v_mfma_i32_16x16x64_i8 v[54:57], v[148:151], v[194:197], v[54:57]
	v_mfma_i32_16x16x64_i8 v[50:53], v[156:159], v[194:197], v[50:53]
	v_mfma_i32_16x16x64_i8 v[42:45], v[148:151], v[202:205], v[42:45]
	v_mfma_i32_16x16x64_i8 v[34:37], v[156:159], v[202:205], v[34:37]
	v_mfma_i32_16x16x64_i8 v[26:29], v[148:151], v[210:213], v[26:29]
	v_mfma_i32_16x16x64_i8 v[18:21], v[156:159], v[210:213], v[18:21]
	v_mfma_i32_16x16x64_i8 v[62:65], v[152:155], v[190:193], v[62:65]
	v_mfma_i32_16x16x64_i8 v[58:61], v[160:163], v[190:193], v[58:61]
	v_mfma_i32_16x16x64_i8 v[54:57], v[152:155], v[198:201], v[54:57]
	v_mfma_i32_16x16x64_i8 v[50:53], v[160:163], v[198:201], v[50:53]
	v_mfma_i32_16x16x64_i8 v[42:45], v[152:155], v[206:209], v[42:45]
	v_mfma_i32_16x16x64_i8 v[34:37], v[160:163], v[206:209], v[34:37]
	v_mfma_i32_16x16x64_i8 v[26:29], v[152:155], v[214:217], v[26:29]
	v_mfma_i32_16x16x64_i8 v[18:21], v[160:163], v[214:217], v[18:21]
	s_setprio 0
	s_setprio 1
	v_mfma_i32_16x16x64_i8 v[46:49], v[164:167], v[180:183], v[46:49]
	v_mfma_i32_16x16x64_i8 v[38:41], v[172:175], v[180:183], v[38:41]
	v_mfma_i32_16x16x64_i8 v[30:33], v[164:167], v[194:197], v[30:33]
	v_mfma_i32_16x16x64_i8 v[22:25], v[172:175], v[194:197], v[22:25]
	v_mfma_i32_16x16x64_i8 v[14:17], v[164:167], v[202:205], v[14:17]
	v_mfma_i32_16x16x64_i8 v[10:13], v[172:175], v[202:205], v[10:13]
	v_mfma_i32_16x16x64_i8 v[6:9], v[164:167], v[210:213], v[6:9]
	v_mfma_i32_16x16x64_i8 v[2:5], v[172:175], v[210:213], v[2:5]
	v_mfma_i32_16x16x64_i8 v[46:49], v[168:171], v[190:193], v[46:49]
	v_mfma_i32_16x16x64_i8 v[38:41], v[176:179], v[190:193], v[38:41]
	s_barrier
	v_mfma_i32_16x16x64_i8 v[30:33], v[168:171], v[198:201], v[30:33]
	v_mfma_i32_16x16x64_i8 v[22:25], v[176:179], v[198:201], v[22:25]
	v_mfma_i32_16x16x64_i8 v[14:17], v[168:171], v[206:209], v[14:17]
	v_mfma_i32_16x16x64_i8 v[10:13], v[176:179], v[206:209], v[10:13]
	v_mfma_i32_16x16x64_i8 v[6:9], v[168:171], v[214:217], v[6:9]
	v_mfma_i32_16x16x64_i8 v[2:5], v[176:179], v[214:217], v[2:5]
	s_setprio 0
	s_nop 0
	s_add_i32 s65, 0, 0x18000
	v_add_u32_e32 v138, s65, v188
	s_add_i32 s66, 0, 0x1c000
	ds_read_b128 v[148:151], v138
	ds_read_b128 v[152:155], v138 offset:1024
	ds_read_b128 v[156:159], v138 offset:2048
	ds_read_b128 v[160:163], v138 offset:3072
	v_add_u32_e32 v138, s66, v188
	ds_read_b128 v[164:167], v138
	ds_read_b128 v[168:171], v138 offset:1024
	ds_read_b128 v[172:175], v138 offset:2048
	ds_read_b128 v[176:179], v138 offset:3072
	s_add_u32 s28, s28, s6
	s_addc_u32 s29, s29, s7
	s_mov_b32 m0, s44
	v_lshl_add_u64 v[228:229], s[28:29], 0, v[130:131]
	ds_read_b128 v[180:183], v189 offset:32768
	ds_read_b128 v[190:193], v189 offset:33792
	ds_read_b128 v[194:197], v189 offset:34816
	ds_read_b128 v[198:201], v189 offset:35840
	ds_read_b128 v[202:205], v189 offset:36864
	ds_read_b128 v[206:209], v189 offset:37888
	ds_read_b128 v[210:213], v189 offset:38912
	ds_read_b128 v[214:217], v189 offset:39936
	global_load_lds_dwordx4 v[228:229], off
	v_lshl_add_u64 v[228:229], s[28:29], 0, v[134:135]
	s_mov_b32 m0, s45
	s_nop 0
	global_load_lds_dwordx4 v[228:229], off
	s_waitcnt vmcnt(8)
	s_waitcnt lgkmcnt(0)
	s_barrier
	s_setprio 1
	s_waitcnt lgkmcnt(0)
	v_mfma_i32_16x16x64_i8 v[126:129], v[148:151], v[180:183], v[126:129]
	v_mfma_i32_16x16x64_i8 v[122:125], v[156:159], v[180:183], v[122:125]
	v_mfma_i32_16x16x64_i8 v[118:121], v[148:151], v[194:197], v[118:121]
	v_mfma_i32_16x16x64_i8 v[114:117], v[156:159], v[194:197], v[114:117]
	v_mfma_i32_16x16x64_i8 v[106:109], v[148:151], v[202:205], v[106:109]
	v_mfma_i32_16x16x64_i8 v[98:101], v[156:159], v[202:205], v[98:101]
	v_mfma_i32_16x16x64_i8 v[90:93], v[148:151], v[210:213], v[90:93]
	v_mfma_i32_16x16x64_i8 v[82:85], v[156:159], v[210:213], v[82:85]
	v_mfma_i32_16x16x64_i8 v[126:129], v[152:155], v[190:193], v[126:129]
	v_mfma_i32_16x16x64_i8 v[122:125], v[160:163], v[190:193], v[122:125]
	v_mfma_i32_16x16x64_i8 v[118:121], v[152:155], v[198:201], v[118:121]
	v_mfma_i32_16x16x64_i8 v[114:117], v[160:163], v[198:201], v[114:117]
	v_mfma_i32_16x16x64_i8 v[106:109], v[152:155], v[206:209], v[106:109]
	v_mfma_i32_16x16x64_i8 v[98:101], v[160:163], v[206:209], v[98:101]
	v_mfma_i32_16x16x64_i8 v[90:93], v[152:155], v[214:217], v[90:93]
	v_mfma_i32_16x16x64_i8 v[82:85], v[160:163], v[214:217], v[82:85]
	s_setprio 0
	s_setprio 1
	v_mfma_i32_16x16x64_i8 v[110:113], v[164:167], v[180:183], v[110:113]
	v_mfma_i32_16x16x64_i8 v[102:105], v[172:175], v[180:183], v[102:105]
	v_mfma_i32_16x16x64_i8 v[94:97], v[164:167], v[194:197], v[94:97]
	v_mfma_i32_16x16x64_i8 v[86:89], v[172:175], v[194:197], v[86:89]
	v_mfma_i32_16x16x64_i8 v[78:81], v[164:167], v[202:205], v[78:81]
	v_mfma_i32_16x16x64_i8 v[74:77], v[172:175], v[202:205], v[74:77]
	v_mfma_i32_16x16x64_i8 v[70:73], v[164:167], v[210:213], v[70:73]
	v_mfma_i32_16x16x64_i8 v[66:69], v[172:175], v[210:213], v[66:69]
	v_mfma_i32_16x16x64_i8 v[110:113], v[168:171], v[190:193], v[110:113]
	v_mfma_i32_16x16x64_i8 v[102:105], v[176:179], v[190:193], v[102:105]
	s_barrier
	v_mfma_i32_16x16x64_i8 v[94:97], v[168:171], v[198:201], v[94:97]
	v_mfma_i32_16x16x64_i8 v[86:89], v[176:179], v[198:201], v[86:89]
	v_mfma_i32_16x16x64_i8 v[78:81], v[168:171], v[206:209], v[78:81]
	v_mfma_i32_16x16x64_i8 v[74:77], v[176:179], v[206:209], v[74:77]
	v_mfma_i32_16x16x64_i8 v[70:73], v[168:171], v[214:217], v[70:73]
	v_mfma_i32_16x16x64_i8 v[66:69], v[176:179], v[214:217], v[66:69]
	s_setprio 0
	s_nop 0
	s_add_i32 s28, s65, s41
	v_lshl_add_u64 v[184:185], v[184:185], 0, s[18:19]
	s_mov_b32 m0, s28
	ds_read_b128 v[180:183], v189 offset:49152
	ds_read_b128 v[190:193], v189 offset:50176
	ds_read_b128 v[194:197], v189 offset:51200
	ds_read_b128 v[198:201], v189 offset:52224
	ds_read_b128 v[202:205], v189 offset:53248
	ds_read_b128 v[206:209], v189 offset:54272
	ds_read_b128 v[210:213], v189 offset:55296
	ds_read_b128 v[214:217], v189 offset:56320
	global_load_lds_dwordx4 v[184:185], off
	v_lshl_add_u64 v[184:185], v[218:219], 0, s[18:19]
	s_add_i32 m0, s28, 0x2000
	s_add_i32 s28, s66, s41
	global_load_lds_dwordx4 v[184:185], off
	v_lshl_add_u64 v[184:185], v[220:221], 0, s[18:19]
	s_mov_b32 m0, s28
	s_nop 0
	global_load_lds_dwordx4 v[184:185], off
	v_lshl_add_u64 v[184:185], v[222:223], 0, s[18:19]
	s_add_i32 m0, s28, 0x2000
	s_nop 0
	global_load_lds_dwordx4 v[184:185], off
	v_lshl_add_u64 v[184:185], v[224:225], 0, s[18:19]
	s_mov_b32 m0, s51
	s_nop 0
	global_load_lds_dwordx4 v[184:185], off
	v_lshl_add_u64 v[184:185], v[226:227], 0, s[18:19]
	s_mov_b32 m0, s54
	s_nop 0
	global_load_lds_dwordx4 v[184:185], off
	s_waitcnt vmcnt(8)
	s_waitcnt lgkmcnt(0)
	s_barrier
	s_setprio 1
	s_waitcnt lgkmcnt(0)
	v_mfma_i32_16x16x64_i8 v[62:65], v[148:151], v[180:183], v[62:65]
	v_mfma_i32_16x16x64_i8 v[58:61], v[156:159], v[180:183], v[58:61]
	v_mfma_i32_16x16x64_i8 v[54:57], v[148:151], v[194:197], v[54:57]
	v_mfma_i32_16x16x64_i8 v[50:53], v[156:159], v[194:197], v[50:53]
	v_mfma_i32_16x16x64_i8 v[42:45], v[148:151], v[202:205], v[42:45]
	v_mfma_i32_16x16x64_i8 v[34:37], v[156:159], v[202:205], v[34:37]
	v_mfma_i32_16x16x64_i8 v[26:29], v[148:151], v[210:213], v[26:29]
	v_mfma_i32_16x16x64_i8 v[18:21], v[156:159], v[210:213], v[18:21]
	v_mfma_i32_16x16x64_i8 v[62:65], v[152:155], v[190:193], v[62:65]
	v_mfma_i32_16x16x64_i8 v[58:61], v[160:163], v[190:193], v[58:61]
	v_mfma_i32_16x16x64_i8 v[54:57], v[152:155], v[198:201], v[54:57]
	v_mfma_i32_16x16x64_i8 v[50:53], v[160:163], v[198:201], v[50:53]
	v_mfma_i32_16x16x64_i8 v[42:45], v[152:155], v[206:209], v[42:45]
	v_mfma_i32_16x16x64_i8 v[34:37], v[160:163], v[206:209], v[34:37]
	v_mfma_i32_16x16x64_i8 v[26:29], v[152:155], v[214:217], v[26:29]
	v_mfma_i32_16x16x64_i8 v[18:21], v[160:163], v[214:217], v[18:21]
	s_setprio 0
	s_setprio 1
	v_mfma_i32_16x16x64_i8 v[46:49], v[164:167], v[180:183], v[46:49]
	v_mfma_i32_16x16x64_i8 v[38:41], v[172:175], v[180:183], v[38:41]
	v_mfma_i32_16x16x64_i8 v[30:33], v[164:167], v[194:197], v[30:33]
	v_mfma_i32_16x16x64_i8 v[22:25], v[172:175], v[194:197], v[22:25]
	v_mfma_i32_16x16x64_i8 v[14:17], v[164:167], v[202:205], v[14:17]
	v_mfma_i32_16x16x64_i8 v[10:13], v[172:175], v[202:205], v[10:13]
	v_mfma_i32_16x16x64_i8 v[6:9], v[164:167], v[210:213], v[6:9]
	v_mfma_i32_16x16x64_i8 v[2:5], v[172:175], v[210:213], v[2:5]
	v_mfma_i32_16x16x64_i8 v[46:49], v[168:171], v[190:193], v[46:49]
	v_mfma_i32_16x16x64_i8 v[38:41], v[176:179], v[190:193], v[38:41]
	s_barrier
	v_mfma_i32_16x16x64_i8 v[30:33], v[168:171], v[198:201], v[30:33]
	v_mfma_i32_16x16x64_i8 v[22:25], v[176:179], v[198:201], v[22:25]
	v_mfma_i32_16x16x64_i8 v[14:17], v[168:171], v[206:209], v[14:17]
	v_mfma_i32_16x16x64_i8 v[10:13], v[176:179], v[206:209], v[10:13]
	v_mfma_i32_16x16x64_i8 v[6:9], v[168:171], v[214:217], v[6:9]
	v_mfma_i32_16x16x64_i8 v[2:5], v[176:179], v[214:217], v[2:5]
	s_setprio 0
	s_nop 0
	s_add_u32 s26, s26, 0x100
	s_addc_u32 s27, s27, 0
	s_add_u32 s34, s34, 0x100
	s_addc_u32 s35, s35, 0
	s_cmp_ge_i32 s64, s55
	s_mov_b32 s28, s64
	s_cbranch_scc0 .LBB0_2949
	v_cvt_f32_i32_e32 v172, v126
	v_cvt_f32_i32_e32 v173, v127
	v_cvt_f32_i32_e32 v170, v128
	v_cvt_f32_i32_e32 v171, v129
	v_cvt_f32_i32_e32 v174, v122
	v_cvt_f32_i32_e32 v175, v123
	v_cvt_f32_i32_e32 v176, v124
	v_cvt_f32_i32_e32 v177, v125
	v_cvt_f32_i32_e32 v180, v110
	v_cvt_f32_i32_e32 v181, v111
	v_cvt_f32_i32_e32 v182, v112
	v_cvt_f32_i32_e32 v183, v113
	v_cvt_f32_i32_e32 v178, v102
	v_cvt_f32_i32_e32 v179, v103
	v_cvt_f32_i32_e32 v184, v104
	v_cvt_f32_i32_e32 v185, v105
	v_cvt_f32_i32_e32 v152, v118
	v_cvt_f32_i32_e32 v153, v119
	v_cvt_f32_i32_e32 v154, v120
	v_cvt_f32_i32_e32 v155, v121
	v_cvt_f32_i32_e32 v156, v114
	v_cvt_f32_i32_e32 v157, v115
	v_cvt_f32_i32_e32 v158, v116
	v_cvt_f32_i32_e32 v159, v117
	v_cvt_f32_i32_e32 v160, v94
	v_cvt_f32_i32_e32 v161, v95
	v_cvt_f32_i32_e32 v162, v96
	v_cvt_f32_i32_e32 v163, v97
	v_cvt_f32_i32_e32 v164, v86
	v_cvt_f32_i32_e32 v165, v87
	v_cvt_f32_i32_e32 v166, v88
	v_cvt_f32_i32_e32 v167, v89
	v_cvt_f32_i32_e32 v118, v106
	v_cvt_f32_i32_e32 v119, v107
	v_cvt_f32_i32_e32 v120, v108
	v_cvt_f32_i32_e32 v121, v109
	v_cvt_f32_i32_e32 v122, v98
	v_cvt_f32_i32_e32 v123, v99
	v_cvt_f32_i32_e32 v124, v100
	v_cvt_f32_i32_e32 v125, v101
	v_cvt_f32_i32_e32 v126, v78
	v_cvt_f32_i32_e32 v127, v79
	v_cvt_f32_i32_e32 v128, v80
	v_cvt_f32_i32_e32 v129, v81
	v_cvt_f32_i32_e32 v148, v74
	v_cvt_f32_i32_e32 v149, v75
	v_cvt_f32_i32_e32 v150, v76
	v_cvt_f32_i32_e32 v151, v77
	v_cvt_f32_i32_e32 v102, v90
	v_cvt_f32_i32_e32 v103, v91
	v_cvt_f32_i32_e32 v104, v92
	v_cvt_f32_i32_e32 v105, v93
	v_cvt_f32_i32_e32 v106, v82
	v_cvt_f32_i32_e32 v107, v83
	v_cvt_f32_i32_e32 v108, v84
	v_cvt_f32_i32_e32 v109, v85
	v_cvt_f32_i32_e32 v110, v70
	v_cvt_f32_i32_e32 v111, v71
	v_cvt_f32_i32_e32 v112, v72
	v_cvt_f32_i32_e32 v113, v73
	v_cvt_f32_i32_e32 v114, v66
	v_cvt_f32_i32_e32 v115, v67
	v_cvt_f32_i32_e32 v116, v68
	v_cvt_f32_i32_e32 v117, v69
	v_cvt_f32_i32_e32 v82, v62
	v_cvt_f32_i32_e32 v83, v63
	v_cvt_f32_i32_e32 v84, v64
	v_cvt_f32_i32_e32 v85, v65
	v_cvt_f32_i32_e32 v86, v58
	v_cvt_f32_i32_e32 v87, v59
	v_cvt_f32_i32_e32 v88, v60
	v_cvt_f32_i32_e32 v89, v61
	v_cvt_f32_i32_e32 v92, v46
	v_cvt_f32_i32_e32 v93, v47
	v_cvt_f32_i32_e32 v94, v48
	v_cvt_f32_i32_e32 v95, v49
	v_cvt_f32_i32_e32 v96, v38
	v_cvt_f32_i32_e32 v97, v39
	v_cvt_f32_i32_e32 v98, v40
	v_cvt_f32_i32_e32 v99, v41
	v_cvt_f32_i32_e32 v66, v54
	v_cvt_f32_i32_e32 v67, v55
	v_cvt_f32_i32_e32 v68, v56
	v_cvt_f32_i32_e32 v69, v57
	v_cvt_f32_i32_e32 v70, v50
	v_cvt_f32_i32_e32 v71, v51
	v_cvt_f32_i32_e32 v72, v52
	v_cvt_f32_i32_e32 v73, v53
	v_cvt_f32_i32_e32 v74, v30
	v_cvt_f32_i32_e32 v75, v31
	v_cvt_f32_i32_e32 v76, v32
	v_cvt_f32_i32_e32 v77, v33
	v_cvt_f32_i32_e32 v78, v22
	v_cvt_f32_i32_e32 v79, v23
	v_cvt_f32_i32_e32 v80, v24
	v_cvt_f32_i32_e32 v81, v25
	v_cvt_f32_i32_e32 v50, v42
	v_cvt_f32_i32_e32 v51, v43
	v_cvt_f32_i32_e32 v52, v44
	v_cvt_f32_i32_e32 v53, v45
	v_cvt_f32_i32_e32 v54, v34
	v_cvt_f32_i32_e32 v55, v35
	v_cvt_f32_i32_e32 v56, v36
	v_cvt_f32_i32_e32 v57, v37
	v_cvt_f32_i32_e32 v58, v14
	v_cvt_f32_i32_e32 v59, v15
	v_cvt_f32_i32_e32 v60, v16
	v_cvt_f32_i32_e32 v61, v17
	v_cvt_f32_i32_e32 v62, v10
	v_cvt_f32_i32_e32 v63, v11
	v_cvt_f32_i32_e32 v64, v12
	v_cvt_f32_i32_e32 v65, v13
	v_cvt_f32_i32_e32 v34, v26
	v_cvt_f32_i32_e32 v35, v27
	v_cvt_f32_i32_e32 v36, v28
	v_cvt_f32_i32_e32 v37, v29
	v_cvt_f32_i32_e32 v38, v18
	v_cvt_f32_i32_e32 v39, v19
	v_cvt_f32_i32_e32 v40, v20
	v_cvt_f32_i32_e32 v41, v21
	v_cvt_f32_i32_e32 v42, v6
	v_cvt_f32_i32_e32 v43, v7
	v_cvt_f32_i32_e32 v44, v8
	v_cvt_f32_i32_e32 v45, v9
	v_cvt_f32_i32_e32 v46, v2
	v_cvt_f32_i32_e32 v47, v3
	v_cvt_f32_i32_e32 v48, v4
	v_cvt_f32_i32_e32 v49, v5

.LBB0_3032:
	ds_read_b128 v[114:117], v209
	ds_read_b128 v[118:121], v209 offset:1024
	ds_read_b128 v[122:125], v209 offset:2048
	ds_read_b128 v[126:129], v209 offset:3072
	ds_read_b128 v[146:149], v210
	ds_read_b128 v[150:153], v210 offset:1024
	ds_read_b128 v[154:157], v210 offset:2048
	ds_read_b128 v[158:161], v210 offset:3072
	s_add_i32 s80, s36, 2
	s_add_u32 s37, s34, 0x4000
	s_addc_u32 s38, s35, 0
	s_cmp_eq_u32 s61, s36
	s_cselect_b32 s39, s5, s38
	s_cselect_b32 s38, s4, s37
	s_cselect_b32 s82, s30, s70
	s_cselect_b32 s83, s31, s71
	s_add_u32 s36, s38, 0x8000
	s_addc_u32 s37, s39, 0
	v_lshl_add_u64 v[218:219], s[34:35], 0, v[170:171]
	s_add_i32 m0, s45, 0xc000
	ds_read_b128 v[178:181], v211
	ds_read_b128 v[182:185], v211 offset:1024
	ds_read_b128 v[186:189], v211 offset:2048
	ds_read_b128 v[190:193], v211 offset:3072
	ds_read_b128 v[194:197], v211 offset:4096
	ds_read_b128 v[198:201], v211 offset:5120
	ds_read_b128 v[202:205], v211 offset:6144
	ds_read_b128 v[214:217], v211 offset:7168
	global_load_lds_dwordx4 v[218:219], off
	v_lshl_add_u64 v[218:219], s[34:35], 0, v[172:173]
	s_add_i32 m0, s45, 0xe000
	s_nop 0
	global_load_lds_dwordx4 v[218:219], off
	s_waitcnt vmcnt(8)
	s_waitcnt lgkmcnt(0)
	s_barrier
	s_setprio 1
	s_waitcnt lgkmcnt(0)
	v_mfma_f32_16x16x32_bf16 v[142:145], v[114:117], v[178:181], v[142:145]
	v_mfma_f32_16x16x32_bf16 v[138:141], v[122:125], v[178:181], v[138:141]
	v_mfma_f32_16x16x32_bf16 v[110:113], v[114:117], v[186:189], v[110:113]
	v_mfma_f32_16x16x32_bf16 v[106:109], v[122:125], v[186:189], v[106:109]
	v_mfma_f32_16x16x32_bf16 v[94:97], v[114:117], v[194:197], v[94:97]
	v_mfma_f32_16x16x32_bf16 v[90:93], v[122:125], v[194:197], v[90:93]
	v_mfma_f32_16x16x32_bf16 v[78:81], v[114:117], v[202:205], v[78:81]
	v_mfma_f32_16x16x32_bf16 v[74:77], v[122:125], v[202:205], v[74:77]
	v_mfma_f32_16x16x32_bf16 v[142:145], v[118:121], v[182:185], v[142:145]
	v_mfma_f32_16x16x32_bf16 v[138:141], v[126:129], v[182:185], v[138:141]
	v_mfma_f32_16x16x32_bf16 v[110:113], v[118:121], v[190:193], v[110:113]
	v_mfma_f32_16x16x32_bf16 v[106:109], v[126:129], v[190:193], v[106:109]
	v_mfma_f32_16x16x32_bf16 v[94:97], v[118:121], v[198:201], v[94:97]
	v_mfma_f32_16x16x32_bf16 v[90:93], v[126:129], v[198:201], v[90:93]
	v_mfma_f32_16x16x32_bf16 v[78:81], v[118:121], v[214:217], v[78:81]
	v_mfma_f32_16x16x32_bf16 v[74:77], v[126:129], v[214:217], v[74:77]
	s_setprio 0
	s_setprio 1
	v_mfma_f32_16x16x32_bf16 v[134:137], v[146:149], v[178:181], v[134:137]
	v_mfma_f32_16x16x32_bf16 v[130:133], v[154:157], v[178:181], v[130:133]
	v_mfma_f32_16x16x32_bf16 v[102:105], v[146:149], v[186:189], v[102:105]
	v_mfma_f32_16x16x32_bf16 v[98:101], v[154:157], v[186:189], v[98:101]
	v_mfma_f32_16x16x32_bf16 v[86:89], v[146:149], v[194:197], v[86:89]
	v_mfma_f32_16x16x32_bf16 v[82:85], v[154:157], v[194:197], v[82:85]
	v_mfma_f32_16x16x32_bf16 v[70:73], v[146:149], v[202:205], v[70:73]
	v_mfma_f32_16x16x32_bf16 v[66:69], v[154:157], v[202:205], v[66:69]
	v_mfma_f32_16x16x32_bf16 v[134:137], v[150:153], v[182:185], v[134:137]
	v_mfma_f32_16x16x32_bf16 v[130:133], v[158:161], v[182:185], v[130:133]
	s_barrier
	v_mfma_f32_16x16x32_bf16 v[102:105], v[150:153], v[190:193], v[102:105]
	v_mfma_f32_16x16x32_bf16 v[98:101], v[158:161], v[190:193], v[98:101]
	v_mfma_f32_16x16x32_bf16 v[86:89], v[150:153], v[198:201], v[86:89]
	v_mfma_f32_16x16x32_bf16 v[82:85], v[158:161], v[198:201], v[82:85]
	v_mfma_f32_16x16x32_bf16 v[70:73], v[150:153], v[214:217], v[70:73]
	v_mfma_f32_16x16x32_bf16 v[66:69], v[158:161], v[214:217], v[66:69]
	s_setprio 0
	s_nop 0
	s_add_i32 s81, s64, s44
	v_lshl_add_u64 v[218:219], s[82:83], 0, v[164:165]
	s_mov_b32 m0, s81
	ds_read_b128 v[178:181], v211 offset:16384
	ds_read_b128 v[182:185], v211 offset:17408
	ds_read_b128 v[186:189], v211 offset:18432
	ds_read_b128 v[190:193], v211 offset:19456
	ds_read_b128 v[194:197], v211 offset:20480
	ds_read_b128 v[198:201], v211 offset:21504
	ds_read_b128 v[202:205], v211 offset:22528
	ds_read_b128 v[214:217], v211 offset:23552
	global_load_lds_dwordx4 v[218:219], off
	s_add_i32 m0, s81, 0x2000
	v_lshl_add_u64 v[220:221], s[82:83], 0, v[168:169]
	s_add_u32 s82, s82, s8
	s_addc_u32 s83, s83, s9
	s_add_i32 s81, s65, s44
	global_load_lds_dwordx4 v[220:221], off
	v_lshl_add_u64 v[222:223], s[82:83], 0, v[164:165]
	s_mov_b32 m0, s81
	v_lshl_add_u64 v[224:225], s[82:83], 0, v[168:169]
	global_load_lds_dwordx4 v[222:223], off
	s_add_i32 m0, s81, 0x2000
	v_lshl_add_u64 v[226:227], s[38:39], 0, v[162:163]
	global_load_lds_dwordx4 v[224:225], off
	s_mov_b32 m0, s45
	s_nop 0
	global_load_lds_dwordx4 v[226:227], off
	v_lshl_add_u64 v[226:227], s[38:39], 0, v[166:167]
	s_mov_b32 m0, s46
	s_nop 0
	global_load_lds_dwordx4 v[226:227], off
	s_waitcnt vmcnt(8)
	s_waitcnt lgkmcnt(0)
	s_barrier
	s_setprio 1
	s_waitcnt lgkmcnt(0)
	v_mfma_f32_16x16x32_bf16 v[62:65], v[114:117], v[178:181], v[62:65]
	v_mfma_f32_16x16x32_bf16 v[58:61], v[122:125], v[178:181], v[58:61]
	v_mfma_f32_16x16x32_bf16 v[46:49], v[114:117], v[186:189], v[46:49]
	v_mfma_f32_16x16x32_bf16 v[42:45], v[122:125], v[186:189], v[42:45]
	v_mfma_f32_16x16x32_bf16 v[30:33], v[114:117], v[194:197], v[30:33]
	v_mfma_f32_16x16x32_bf16 v[26:29], v[122:125], v[194:197], v[26:29]
	v_mfma_f32_16x16x32_bf16 v[14:17], v[114:117], v[202:205], v[14:17]
	v_mfma_f32_16x16x32_bf16 v[10:13], v[122:125], v[202:205], v[10:13]
	v_mfma_f32_16x16x32_bf16 v[62:65], v[118:121], v[182:185], v[62:65]
	v_mfma_f32_16x16x32_bf16 v[58:61], v[126:129], v[182:185], v[58:61]
	v_mfma_f32_16x16x32_bf16 v[46:49], v[118:121], v[190:193], v[46:49]
	v_mfma_f32_16x16x32_bf16 v[42:45], v[126:129], v[190:193], v[42:45]
	v_mfma_f32_16x16x32_bf16 v[30:33], v[118:121], v[198:201], v[30:33]
	v_mfma_f32_16x16x32_bf16 v[26:29], v[126:129], v[198:201], v[26:29]
	v_mfma_f32_16x16x32_bf16 v[14:17], v[118:121], v[214:217], v[14:17]
	v_mfma_f32_16x16x32_bf16 v[10:13], v[126:129], v[214:217], v[10:13]
	s_setprio 0
	s_setprio 1
	v_mfma_f32_16x16x32_bf16 v[54:57], v[146:149], v[178:181], v[54:57]
	v_mfma_f32_16x16x32_bf16 v[50:53], v[154:157], v[178:181], v[50:53]
	v_mfma_f32_16x16x32_bf16 v[38:41], v[146:149], v[186:189], v[38:41]
	v_mfma_f32_16x16x32_bf16 v[34:37], v[154:157], v[186:189], v[34:37]
	v_mfma_f32_16x16x32_bf16 v[22:25], v[146:149], v[194:197], v[22:25]
	v_mfma_f32_16x16x32_bf16 v[18:21], v[154:157], v[194:197], v[18:21]
	v_mfma_f32_16x16x32_bf16 v[6:9], v[146:149], v[202:205], v[6:9]
	v_mfma_f32_16x16x32_bf16 v[2:5], v[154:157], v[202:205], v[2:5]
	v_mfma_f32_16x16x32_bf16 v[54:57], v[150:153], v[182:185], v[54:57]
	v_mfma_f32_16x16x32_bf16 v[50:53], v[158:161], v[182:185], v[50:53]
	s_barrier
	v_mfma_f32_16x16x32_bf16 v[38:41], v[150:153], v[190:193], v[38:41]
	v_mfma_f32_16x16x32_bf16 v[34:37], v[158:161], v[190:193], v[34:37]
	v_mfma_f32_16x16x32_bf16 v[22:25], v[150:153], v[198:201], v[22:25]
	v_mfma_f32_16x16x32_bf16 v[18:21], v[158:161], v[198:201], v[18:21]
	v_mfma_f32_16x16x32_bf16 v[6:9], v[150:153], v[214:217], v[6:9]
	v_mfma_f32_16x16x32_bf16 v[2:5], v[158:161], v[214:217], v[2:5]
	s_setprio 0
	s_nop 0
	s_add_i32 s81, 0, 0x18000
	s_add_i32 s82, 0, 0x1c000
	v_add_u32_e32 v126, s81, v207
	v_add_u32_e32 v158, s82, v207
	ds_read_b128 v[114:117], v126
	ds_read_b128 v[118:121], v126 offset:1024
	ds_read_b128 v[122:125], v126 offset:2048
	ds_read_b128 v[126:129], v126 offset:3072
	ds_read_b128 v[146:149], v158
	ds_read_b128 v[150:153], v158 offset:1024
	ds_read_b128 v[154:157], v158 offset:2048
	ds_read_b128 v[158:161], v158 offset:3072
	s_add_u32 s38, s38, 0x4000
	s_addc_u32 s39, s39, 0
	s_mov_b32 m0, s47
	v_lshl_add_u64 v[226:227], s[38:39], 0, v[162:163]
	ds_read_b128 v[178:181], v211 offset:32768
	ds_read_b128 v[182:185], v211 offset:33792
	ds_read_b128 v[186:189], v211 offset:34816
	ds_read_b128 v[190:193], v211 offset:35840
	ds_read_b128 v[194:197], v211 offset:36864
	ds_read_b128 v[198:201], v211 offset:37888
	ds_read_b128 v[202:205], v211 offset:38912
	ds_read_b128 v[214:217], v211 offset:39936
	global_load_lds_dwordx4 v[226:227], off
	v_lshl_add_u64 v[226:227], s[38:39], 0, v[166:167]
	s_mov_b32 m0, s50
	s_nop 0
	global_load_lds_dwordx4 v[226:227], off
	s_waitcnt vmcnt(8)
	s_waitcnt lgkmcnt(0)
	s_barrier
	s_setprio 1
	s_waitcnt lgkmcnt(0)
	v_mfma_f32_16x16x32_bf16 v[142:145], v[114:117], v[178:181], v[142:145]
	v_mfma_f32_16x16x32_bf16 v[138:141], v[122:125], v[178:181], v[138:141]
	v_mfma_f32_16x16x32_bf16 v[110:113], v[114:117], v[186:189], v[110:113]
	v_mfma_f32_16x16x32_bf16 v[106:109], v[122:125], v[186:189], v[106:109]
	v_mfma_f32_16x16x32_bf16 v[94:97], v[114:117], v[194:197], v[94:97]
	v_mfma_f32_16x16x32_bf16 v[90:93], v[122:125], v[194:197], v[90:93]
	v_mfma_f32_16x16x32_bf16 v[78:81], v[114:117], v[202:205], v[78:81]
	v_mfma_f32_16x16x32_bf16 v[74:77], v[122:125], v[202:205], v[74:77]
	v_mfma_f32_16x16x32_bf16 v[142:145], v[118:121], v[182:185], v[142:145]
	v_mfma_f32_16x16x32_bf16 v[138:141], v[126:129], v[182:185], v[138:141]
	v_mfma_f32_16x16x32_bf16 v[110:113], v[118:121], v[190:193], v[110:113]
	v_mfma_f32_16x16x32_bf16 v[106:109], v[126:129], v[190:193], v[106:109]
	v_mfma_f32_16x16x32_bf16 v[94:97], v[118:121], v[198:201], v[94:97]
	v_mfma_f32_16x16x32_bf16 v[90:93], v[126:129], v[198:201], v[90:93]
	v_mfma_f32_16x16x32_bf16 v[78:81], v[118:121], v[214:217], v[78:81]
	v_mfma_f32_16x16x32_bf16 v[74:77], v[126:129], v[214:217], v[74:77]
	s_setprio 0
	s_setprio 1
	v_mfma_f32_16x16x32_bf16 v[134:137], v[146:149], v[178:181], v[134:137]
	v_mfma_f32_16x16x32_bf16 v[130:133], v[154:157], v[178:181], v[130:133]
	v_mfma_f32_16x16x32_bf16 v[102:105], v[146:149], v[186:189], v[102:105]
	v_mfma_f32_16x16x32_bf16 v[98:101], v[154:157], v[186:189], v[98:101]
	v_mfma_f32_16x16x32_bf16 v[86:89], v[146:149], v[194:197], v[86:89]
	v_mfma_f32_16x16x32_bf16 v[82:85], v[154:157], v[194:197], v[82:85]
	v_mfma_f32_16x16x32_bf16 v[70:73], v[146:149], v[202:205], v[70:73]
	v_mfma_f32_16x16x32_bf16 v[66:69], v[154:157], v[202:205], v[66:69]
	v_mfma_f32_16x16x32_bf16 v[134:137], v[150:153], v[182:185], v[134:137]
	v_mfma_f32_16x16x32_bf16 v[130:133], v[158:161], v[182:185], v[130:133]
	s_barrier
	v_mfma_f32_16x16x32_bf16 v[102:105], v[150:153], v[190:193], v[102:105]
	v_mfma_f32_16x16x32_bf16 v[98:101], v[158:161], v[190:193], v[98:101]
	v_mfma_f32_16x16x32_bf16 v[86:89], v[150:153], v[198:201], v[86:89]
	v_mfma_f32_16x16x32_bf16 v[82:85], v[158:161], v[198:201], v[82:85]
	v_mfma_f32_16x16x32_bf16 v[70:73], v[150:153], v[214:217], v[70:73]
	v_mfma_f32_16x16x32_bf16 v[66:69], v[158:161], v[214:217], v[66:69]
	s_setprio 0
	s_nop 0
	s_add_i32 s38, s81, s44
	v_lshl_add_u64 v[218:219], v[218:219], 0, s[24:25]
	s_mov_b32 m0, s38
	ds_read_b128 v[178:181], v211 offset:49152
	ds_read_b128 v[182:185], v211 offset:50176
	ds_read_b128 v[186:189], v211 offset:51200
	ds_read_b128 v[190:193], v211 offset:52224
	ds_read_b128 v[194:197], v211 offset:53248
	ds_read_b128 v[198:201], v211 offset:54272
	ds_read_b128 v[202:205], v211 offset:55296
	ds_read_b128 v[214:217], v211 offset:56320
	global_load_lds_dwordx4 v[218:219], off
	v_lshl_add_u64 v[218:219], v[220:221], 0, s[24:25]
	s_add_i32 m0, s38, 0x2000
	s_add_i32 s38, s82, s44
	global_load_lds_dwordx4 v[218:219], off
	v_lshl_add_u64 v[218:219], v[222:223], 0, s[24:25]
	s_mov_b32 m0, s38
	s_nop 0
	global_load_lds_dwordx4 v[218:219], off
	v_lshl_add_u64 v[218:219], v[224:225], 0, s[24:25]
	s_add_i32 m0, s38, 0x2000
	s_nop 0
	global_load_lds_dwordx4 v[218:219], off
	v_lshl_add_u64 v[218:219], s[36:37], 0, v[162:163]
	s_mov_b32 m0, s59
	s_nop 0
	global_load_lds_dwordx4 v[218:219], off
	v_lshl_add_u64 v[218:219], s[36:37], 0, v[166:167]
	s_mov_b32 m0, s60
	s_nop 0
	global_load_lds_dwordx4 v[218:219], off
	s_waitcnt vmcnt(8)
	s_waitcnt lgkmcnt(0)
	s_barrier
	s_setprio 1
	s_waitcnt lgkmcnt(0)
	v_mfma_f32_16x16x32_bf16 v[62:65], v[114:117], v[178:181], v[62:65]
	v_mfma_f32_16x16x32_bf16 v[58:61], v[122:125], v[178:181], v[58:61]
	v_mfma_f32_16x16x32_bf16 v[46:49], v[114:117], v[186:189], v[46:49]
	v_mfma_f32_16x16x32_bf16 v[42:45], v[122:125], v[186:189], v[42:45]
	v_mfma_f32_16x16x32_bf16 v[30:33], v[114:117], v[194:197], v[30:33]
	v_mfma_f32_16x16x32_bf16 v[26:29], v[122:125], v[194:197], v[26:29]
	v_mfma_f32_16x16x32_bf16 v[14:17], v[114:117], v[202:205], v[14:17]
	v_mfma_f32_16x16x32_bf16 v[10:13], v[122:125], v[202:205], v[10:13]
	v_mfma_f32_16x16x32_bf16 v[62:65], v[118:121], v[182:185], v[62:65]
	v_mfma_f32_16x16x32_bf16 v[58:61], v[126:129], v[182:185], v[58:61]
	v_mfma_f32_16x16x32_bf16 v[46:49], v[118:121], v[190:193], v[46:49]
	v_mfma_f32_16x16x32_bf16 v[42:45], v[126:129], v[190:193], v[42:45]
	v_mfma_f32_16x16x32_bf16 v[30:33], v[118:121], v[198:201], v[30:33]
	v_mfma_f32_16x16x32_bf16 v[26:29], v[126:129], v[198:201], v[26:29]
	v_mfma_f32_16x16x32_bf16 v[14:17], v[118:121], v[214:217], v[14:17]
	v_mfma_f32_16x16x32_bf16 v[10:13], v[126:129], v[214:217], v[10:13]
	s_setprio 0
	s_setprio 1
	v_mfma_f32_16x16x32_bf16 v[54:57], v[146:149], v[178:181], v[54:57]
	v_mfma_f32_16x16x32_bf16 v[50:53], v[154:157], v[178:181], v[50:53]
	v_mfma_f32_16x16x32_bf16 v[38:41], v[146:149], v[186:189], v[38:41]
	v_mfma_f32_16x16x32_bf16 v[34:37], v[154:157], v[186:189], v[34:37]
	v_mfma_f32_16x16x32_bf16 v[22:25], v[146:149], v[194:197], v[22:25]
	v_mfma_f32_16x16x32_bf16 v[18:21], v[154:157], v[194:197], v[18:21]
	v_mfma_f32_16x16x32_bf16 v[6:9], v[146:149], v[202:205], v[6:9]
	v_mfma_f32_16x16x32_bf16 v[2:5], v[154:157], v[202:205], v[2:5]
	v_mfma_f32_16x16x32_bf16 v[54:57], v[150:153], v[182:185], v[54:57]
	v_mfma_f32_16x16x32_bf16 v[50:53], v[158:161], v[182:185], v[50:53]
	s_barrier
	v_mfma_f32_16x16x32_bf16 v[38:41], v[150:153], v[190:193], v[38:41]
	v_mfma_f32_16x16x32_bf16 v[34:37], v[158:161], v[190:193], v[34:37]
	v_mfma_f32_16x16x32_bf16 v[22:25], v[150:153], v[198:201], v[22:25]
	v_mfma_f32_16x16x32_bf16 v[18:21], v[158:161], v[198:201], v[18:21]
	v_mfma_f32_16x16x32_bf16 v[6:9], v[150:153], v[214:217], v[6:9]
	v_mfma_f32_16x16x32_bf16 v[2:5], v[158:161], v[214:217], v[2:5]
	s_setprio 0
	s_nop 0
	s_add_u32 s70, s70, 0x100
	s_addc_u32 s71, s71, 0
	s_add_u32 s34, s34, 0x10000
	s_addc_u32 s35, s35, 0
	s_cmp_ge_i32 s80, s58
	s_mov_b32 s36, s80
	s_cbranch_scc0 .LBB0_3032

.LBB0_3126:
	ds_read_b128 v[34:37], v196
	ds_read_b128 v[38:41], v196 offset:1024
	ds_read_b128 v[50:53], v196 offset:2048
	ds_read_b128 v[54:57], v196 offset:3072
	ds_read_b128 v[146:149], v197
	ds_read_b128 v[150:153], v197 offset:1024
	ds_read_b128 v[184:187], v197 offset:2048
	ds_read_b128 v[188:191], v197 offset:3072
	s_add_i32 s11, s6, 2
	s_add_u32 s12, s4, 0x80
	s_addc_u32 s7, s5, 0
	s_cmp_eq_u32 s84, s6
	s_cselect_b32 s6, s44, s12
	s_cselect_b32 s7, s45, s7
	s_cselect_b32 s13, s47, s9
	s_cselect_b32 s12, s46, s8
	v_lshl_add_u64 v[192:193], s[4:5], 0, v[174:175]
	s_add_i32 m0, s66, 0xc000
	ds_read_b128 v[200:203], v198
	ds_read_b128 v[204:207], v198 offset:1024
	ds_read_b128 v[208:211], v198 offset:2048
	ds_read_b128 v[212:215], v198 offset:3072
	ds_read_b128 v[216:219], v198 offset:4096
	ds_read_b128 v[220:223], v198 offset:5120
	ds_read_b128 v[224:227], v198 offset:6144
	ds_read_b128 v[228:231], v198 offset:7168
	global_load_lds_dwordx4 v[192:193], off
	v_lshl_add_u64 v[192:193], s[4:5], 0, v[176:177]
	s_add_i32 m0, s66, 0xe000
	s_nop 0
	global_load_lds_dwordx4 v[192:193], off
	s_waitcnt vmcnt(8)
	s_waitcnt lgkmcnt(0)
	s_barrier
	s_setprio 1
	s_waitcnt lgkmcnt(0)
	v_mfma_f32_16x16x32_bf16 v[142:145], v[34:37], v[200:203], v[142:145]
	v_mfma_f32_16x16x32_bf16 v[138:141], v[50:53], v[200:203], v[138:141]
	v_mfma_f32_16x16x32_bf16 v[126:129], v[34:37], v[208:211], v[126:129]
	v_mfma_f32_16x16x32_bf16 v[122:125], v[50:53], v[208:211], v[122:125]
	v_mfma_f32_16x16x32_bf16 v[110:113], v[34:37], v[216:219], v[110:113]
	v_mfma_f32_16x16x32_bf16 v[106:109], v[50:53], v[216:219], v[106:109]
	v_mfma_f32_16x16x32_bf16 v[94:97], v[34:37], v[224:227], v[94:97]
	v_mfma_f32_16x16x32_bf16 v[90:93], v[50:53], v[224:227], v[90:93]
	v_mfma_f32_16x16x32_bf16 v[142:145], v[38:41], v[204:207], v[142:145]
	v_mfma_f32_16x16x32_bf16 v[138:141], v[54:57], v[204:207], v[138:141]
	v_mfma_f32_16x16x32_bf16 v[126:129], v[38:41], v[212:215], v[126:129]
	v_mfma_f32_16x16x32_bf16 v[122:125], v[54:57], v[212:215], v[122:125]
	v_mfma_f32_16x16x32_bf16 v[110:113], v[38:41], v[220:223], v[110:113]
	v_mfma_f32_16x16x32_bf16 v[106:109], v[54:57], v[220:223], v[106:109]
	v_mfma_f32_16x16x32_bf16 v[94:97], v[38:41], v[228:231], v[94:97]
	v_mfma_f32_16x16x32_bf16 v[90:93], v[54:57], v[228:231], v[90:93]
	s_setprio 0
	s_setprio 1
	v_mfma_f32_16x16x32_bf16 v[134:137], v[146:149], v[200:203], v[134:137]
	v_mfma_f32_16x16x32_bf16 v[130:133], v[184:187], v[200:203], v[130:133]
	v_mfma_f32_16x16x32_bf16 v[118:121], v[146:149], v[208:211], v[118:121]
	v_mfma_f32_16x16x32_bf16 v[114:117], v[184:187], v[208:211], v[114:117]
	v_mfma_f32_16x16x32_bf16 v[102:105], v[146:149], v[216:219], v[102:105]
	v_mfma_f32_16x16x32_bf16 v[98:101], v[184:187], v[216:219], v[98:101]
	v_mfma_f32_16x16x32_bf16 v[86:89], v[146:149], v[224:227], v[86:89]
	v_mfma_f32_16x16x32_bf16 v[82:85], v[184:187], v[224:227], v[82:85]
	v_mfma_f32_16x16x32_bf16 v[134:137], v[150:153], v[204:207], v[134:137]
	v_mfma_f32_16x16x32_bf16 v[130:133], v[188:191], v[204:207], v[130:133]
	s_barrier
	v_mfma_f32_16x16x32_bf16 v[118:121], v[150:153], v[212:215], v[118:121]
	v_mfma_f32_16x16x32_bf16 v[114:117], v[188:191], v[212:215], v[114:117]
	v_mfma_f32_16x16x32_bf16 v[102:105], v[150:153], v[220:223], v[102:105]
	v_mfma_f32_16x16x32_bf16 v[98:101], v[188:191], v[220:223], v[98:101]
	v_mfma_f32_16x16x32_bf16 v[86:89], v[150:153], v[228:231], v[86:89]
	v_mfma_f32_16x16x32_bf16 v[82:85], v[188:191], v[228:231], v[82:85]
	s_setprio 0
	s_nop 0
	s_add_i32 s20, s88, s61
	v_lshl_add_u64 v[192:193], s[12:13], 0, v[156:157]
	s_mov_b32 m0, s20
	ds_read_b128 v[200:203], v198 offset:16384
	ds_read_b128 v[204:207], v198 offset:17408
	ds_read_b128 v[208:211], v198 offset:18432
	ds_read_b128 v[212:215], v198 offset:19456
	ds_read_b128 v[216:219], v198 offset:20480
	ds_read_b128 v[220:223], v198 offset:21504
	ds_read_b128 v[224:227], v198 offset:22528
	ds_read_b128 v[228:231], v198 offset:23552
	global_load_lds_dwordx4 v[192:193], off
	s_add_i32 m0, s20, 0x2000
	v_lshl_add_u64 v[232:233], s[12:13], 0, v[160:161]
	s_add_u32 s12, s12, s16
	s_addc_u32 s13, s13, s17
	s_add_i32 s20, s89, s61
	global_load_lds_dwordx4 v[232:233], off
	v_lshl_add_u64 v[234:235], s[12:13], 0, v[156:157]
	s_mov_b32 m0, s20
	v_lshl_add_u64 v[236:237], s[12:13], 0, v[160:161]
	global_load_lds_dwordx4 v[234:235], off
	s_add_i32 m0, s20, 0x2000
	v_lshl_add_u64 v[238:239], s[6:7], 0, v[154:155]
	global_load_lds_dwordx4 v[236:237], off
	s_mov_b32 m0, s66
	v_lshl_add_u64 v[240:241], s[6:7], 0, v[158:159]
	global_load_lds_dwordx4 v[238:239], off
	s_mov_b32 m0, s68
	s_nop 0
	global_load_lds_dwordx4 v[240:241], off
	s_waitcnt vmcnt(8)
	s_waitcnt lgkmcnt(0)
	s_barrier
	s_setprio 1
	s_waitcnt lgkmcnt(0)
	v_mfma_f32_16x16x32_bf16 v[78:81], v[34:37], v[200:203], v[78:81]
	v_mfma_f32_16x16x32_bf16 v[74:77], v[50:53], v[200:203], v[74:77]
	v_mfma_f32_16x16x32_bf16 v[62:65], v[34:37], v[208:211], v[62:65]
	v_mfma_f32_16x16x32_bf16 v[58:61], v[50:53], v[208:211], v[58:61]
	v_mfma_f32_16x16x32_bf16 v[30:33], v[34:37], v[216:219], v[30:33]
	v_mfma_f32_16x16x32_bf16 v[26:29], v[50:53], v[216:219], v[26:29]
	v_mfma_f32_16x16x32_bf16 v[14:17], v[34:37], v[224:227], v[14:17]
	v_mfma_f32_16x16x32_bf16 v[10:13], v[50:53], v[224:227], v[10:13]
	v_mfma_f32_16x16x32_bf16 v[78:81], v[38:41], v[204:207], v[78:81]
	v_mfma_f32_16x16x32_bf16 v[74:77], v[54:57], v[204:207], v[74:77]
	v_mfma_f32_16x16x32_bf16 v[62:65], v[38:41], v[212:215], v[62:65]
	v_mfma_f32_16x16x32_bf16 v[58:61], v[54:57], v[212:215], v[58:61]
	v_mfma_f32_16x16x32_bf16 v[30:33], v[38:41], v[220:223], v[30:33]
	v_mfma_f32_16x16x32_bf16 v[26:29], v[54:57], v[220:223], v[26:29]
	v_mfma_f32_16x16x32_bf16 v[14:17], v[38:41], v[228:231], v[14:17]
	v_mfma_f32_16x16x32_bf16 v[10:13], v[54:57], v[228:231], v[10:13]
	s_setprio 0
	s_setprio 1
	v_mfma_f32_16x16x32_bf16 v[46:49], v[146:149], v[208:211], v[46:49]
	v_mfma_f32_16x16x32_bf16 v[42:45], v[184:187], v[208:211], v[42:45]
	v_mfma_f32_16x16x32_bf16 v[22:25], v[146:149], v[216:219], v[22:25]
	v_mfma_f32_16x16x32_bf16 v[18:21], v[184:187], v[216:219], v[18:21]
	v_mfma_f32_16x16x32_bf16 v[6:9], v[146:149], v[224:227], v[6:9]
	v_mfma_f32_16x16x32_bf16 v[2:5], v[184:187], v[224:227], v[2:5]
	v_mfma_f32_16x16x32_bf16 v[34:37], v[146:149], v[200:203], v[70:73]
	v_mfma_f32_16x16x32_bf16 v[38:41], v[184:187], v[200:203], v[66:69]
	v_mfma_f32_16x16x32_bf16 v[46:49], v[150:153], v[212:215], v[46:49]
	v_mfma_f32_16x16x32_bf16 v[42:45], v[188:191], v[212:215], v[42:45]
	s_barrier
	v_mfma_f32_16x16x32_bf16 v[22:25], v[150:153], v[220:223], v[22:25]
	v_mfma_f32_16x16x32_bf16 v[18:21], v[188:191], v[220:223], v[18:21]
	v_mfma_f32_16x16x32_bf16 v[6:9], v[150:153], v[228:231], v[6:9]
	v_mfma_f32_16x16x32_bf16 v[2:5], v[188:191], v[228:231], v[2:5]
	v_mfma_f32_16x16x32_bf16 v[34:37], v[150:153], v[204:207], v[34:37]
	v_mfma_f32_16x16x32_bf16 v[38:41], v[188:191], v[204:207], v[38:41]
	s_setprio 0
	s_nop 0
	s_add_i32 s12, 0, 0x18000
	s_add_i32 s13, 0, 0x1c000
	v_add_u32_e32 v70, s12, v194
	v_add_u32_e32 v162, s13, v194
	ds_read_b128 v[50:53], v70
	ds_read_b128 v[54:57], v70 offset:1024
	ds_read_b128 v[66:69], v70 offset:2048
	ds_read_b128 v[70:73], v70 offset:3072
	ds_read_b128 v[146:149], v162
	ds_read_b128 v[150:153], v162 offset:1024
	ds_read_b128 v[184:187], v162 offset:2048
	ds_read_b128 v[188:191], v162 offset:3072
	s_add_u32 s6, s6, s16
	s_addc_u32 s7, s7, s17
	s_mov_b32 m0, s69
	v_lshl_add_u64 v[242:243], s[6:7], 0, v[154:155]
	ds_read_b128 v[200:203], v198 offset:32768
	ds_read_b128 v[204:207], v198 offset:33792
	ds_read_b128 v[208:211], v198 offset:34816
	ds_read_b128 v[212:215], v198 offset:35840
	ds_read_b128 v[216:219], v198 offset:36864
	ds_read_b128 v[220:223], v198 offset:37888
	ds_read_b128 v[224:227], v198 offset:38912
	ds_read_b128 v[228:231], v198 offset:39936
	global_load_lds_dwordx4 v[242:243], off
	v_lshl_add_u64 v[242:243], s[6:7], 0, v[158:159]
	s_mov_b32 m0, s70
	s_nop 0
	global_load_lds_dwordx4 v[242:243], off
	s_waitcnt vmcnt(8)
	s_waitcnt lgkmcnt(0)
	s_barrier
	s_setprio 1
	s_waitcnt lgkmcnt(0)
	v_mfma_f32_16x16x32_bf16 v[142:145], v[50:53], v[200:203], v[142:145]
	v_mfma_f32_16x16x32_bf16 v[138:141], v[66:69], v[200:203], v[138:141]
	v_mfma_f32_16x16x32_bf16 v[126:129], v[50:53], v[208:211], v[126:129]
	v_mfma_f32_16x16x32_bf16 v[122:125], v[66:69], v[208:211], v[122:125]
	v_mfma_f32_16x16x32_bf16 v[110:113], v[50:53], v[216:219], v[110:113]
	v_mfma_f32_16x16x32_bf16 v[106:109], v[66:69], v[216:219], v[106:109]
	v_mfma_f32_16x16x32_bf16 v[94:97], v[50:53], v[224:227], v[94:97]
	v_mfma_f32_16x16x32_bf16 v[90:93], v[66:69], v[224:227], v[90:93]
	v_mfma_f32_16x16x32_bf16 v[142:145], v[54:57], v[204:207], v[142:145]
	v_mfma_f32_16x16x32_bf16 v[138:141], v[70:73], v[204:207], v[138:141]
	v_mfma_f32_16x16x32_bf16 v[126:129], v[54:57], v[212:215], v[126:129]
	v_mfma_f32_16x16x32_bf16 v[122:125], v[70:73], v[212:215], v[122:125]
	v_mfma_f32_16x16x32_bf16 v[110:113], v[54:57], v[220:223], v[110:113]
	v_mfma_f32_16x16x32_bf16 v[106:109], v[70:73], v[220:223], v[106:109]
	v_mfma_f32_16x16x32_bf16 v[94:97], v[54:57], v[228:231], v[94:97]
	v_mfma_f32_16x16x32_bf16 v[90:93], v[70:73], v[228:231], v[90:93]
	s_setprio 0
	s_setprio 1
	v_mfma_f32_16x16x32_bf16 v[134:137], v[146:149], v[200:203], v[134:137]
	v_mfma_f32_16x16x32_bf16 v[130:133], v[184:187], v[200:203], v[130:133]
	v_mfma_f32_16x16x32_bf16 v[118:121], v[146:149], v[208:211], v[118:121]
	v_mfma_f32_16x16x32_bf16 v[114:117], v[184:187], v[208:211], v[114:117]
	v_mfma_f32_16x16x32_bf16 v[102:105], v[146:149], v[216:219], v[102:105]
	v_mfma_f32_16x16x32_bf16 v[98:101], v[184:187], v[216:219], v[98:101]
	v_mfma_f32_16x16x32_bf16 v[86:89], v[146:149], v[224:227], v[86:89]
	v_mfma_f32_16x16x32_bf16 v[82:85], v[184:187], v[224:227], v[82:85]
	v_mfma_f32_16x16x32_bf16 v[134:137], v[150:153], v[204:207], v[134:137]
	v_mfma_f32_16x16x32_bf16 v[130:133], v[188:191], v[204:207], v[130:133]
	s_barrier
	v_mfma_f32_16x16x32_bf16 v[118:121], v[150:153], v[212:215], v[118:121]
	v_mfma_f32_16x16x32_bf16 v[114:117], v[188:191], v[212:215], v[114:117]
	v_mfma_f32_16x16x32_bf16 v[102:105], v[150:153], v[220:223], v[102:105]
	v_mfma_f32_16x16x32_bf16 v[98:101], v[188:191], v[220:223], v[98:101]
	v_mfma_f32_16x16x32_bf16 v[86:89], v[150:153], v[228:231], v[86:89]
	v_mfma_f32_16x16x32_bf16 v[82:85], v[188:191], v[228:231], v[82:85]
	s_setprio 0
	s_nop 0
	s_add_i32 s6, s12, s61
	v_lshl_add_u64 v[192:193], v[192:193], 0, s[38:39]
	s_mov_b32 m0, s6
	ds_read_b128 v[200:203], v198 offset:49152
	ds_read_b128 v[204:207], v198 offset:50176
	ds_read_b128 v[208:211], v198 offset:51200
	ds_read_b128 v[212:215], v198 offset:52224
	ds_read_b128 v[216:219], v198 offset:53248
	ds_read_b128 v[220:223], v198 offset:54272
	ds_read_b128 v[224:227], v198 offset:55296
	ds_read_b128 v[228:231], v198 offset:56320
	global_load_lds_dwordx4 v[192:193], off
	v_lshl_add_u64 v[192:193], v[232:233], 0, s[38:39]
	s_add_i32 m0, s6, 0x2000
	s_add_i32 s6, s13, s61
	global_load_lds_dwordx4 v[192:193], off
	v_lshl_add_u64 v[192:193], v[234:235], 0, s[38:39]
	s_mov_b32 m0, s6
	s_nop 0
	global_load_lds_dwordx4 v[192:193], off
	v_lshl_add_u64 v[192:193], v[236:237], 0, s[38:39]
	s_add_i32 m0, s6, 0x2000
	s_nop 0
	global_load_lds_dwordx4 v[192:193], off
	v_lshl_add_u64 v[192:193], v[238:239], 0, s[38:39]
	s_mov_b32 m0, s81
	s_nop 0
	global_load_lds_dwordx4 v[192:193], off
	v_lshl_add_u64 v[192:193], v[240:241], 0, s[38:39]
	s_mov_b32 m0, s82
	s_nop 0
	global_load_lds_dwordx4 v[192:193], off
	s_waitcnt vmcnt(8)
	s_waitcnt lgkmcnt(0)
	s_barrier
	s_setprio 1
	s_waitcnt lgkmcnt(0)
	v_mfma_f32_16x16x32_bf16 v[78:81], v[50:53], v[200:203], v[78:81]
	v_mfma_f32_16x16x32_bf16 v[74:77], v[66:69], v[200:203], v[74:77]
	v_mfma_f32_16x16x32_bf16 v[62:65], v[50:53], v[208:211], v[62:65]
	v_mfma_f32_16x16x32_bf16 v[58:61], v[66:69], v[208:211], v[58:61]
	v_mfma_f32_16x16x32_bf16 v[30:33], v[50:53], v[216:219], v[30:33]
	v_mfma_f32_16x16x32_bf16 v[26:29], v[66:69], v[216:219], v[26:29]
	v_mfma_f32_16x16x32_bf16 v[14:17], v[50:53], v[224:227], v[14:17]
	v_mfma_f32_16x16x32_bf16 v[10:13], v[66:69], v[224:227], v[10:13]
	v_mfma_f32_16x16x32_bf16 v[78:81], v[54:57], v[204:207], v[78:81]
	v_mfma_f32_16x16x32_bf16 v[74:77], v[70:73], v[204:207], v[74:77]
	v_mfma_f32_16x16x32_bf16 v[62:65], v[54:57], v[212:215], v[62:65]
	v_mfma_f32_16x16x32_bf16 v[58:61], v[70:73], v[212:215], v[58:61]
	v_mfma_f32_16x16x32_bf16 v[30:33], v[54:57], v[220:223], v[30:33]
	v_mfma_f32_16x16x32_bf16 v[26:29], v[70:73], v[220:223], v[26:29]
	v_mfma_f32_16x16x32_bf16 v[14:17], v[54:57], v[228:231], v[14:17]
	v_mfma_f32_16x16x32_bf16 v[10:13], v[70:73], v[228:231], v[10:13]
	s_setprio 0
	s_setprio 1
	v_mfma_f32_16x16x32_bf16 v[34:37], v[146:149], v[200:203], v[34:37]
	v_mfma_f32_16x16x32_bf16 v[70:73], v[150:153], v[204:207], v[34:37]
	v_mfma_f32_16x16x32_bf16 v[34:37], v[184:187], v[200:203], v[38:41]
	v_mfma_f32_16x16x32_bf16 v[66:69], v[188:191], v[204:207], v[34:37]
	v_mfma_f32_16x16x32_bf16 v[34:37], v[146:149], v[208:211], v[46:49]
	v_mfma_f32_16x16x32_bf16 v[46:49], v[150:153], v[212:215], v[34:37]
	v_mfma_f32_16x16x32_bf16 v[34:37], v[184:187], v[208:211], v[42:45]
	v_mfma_f32_16x16x32_bf16 v[22:25], v[146:149], v[216:219], v[22:25]
	v_mfma_f32_16x16x32_bf16 v[18:21], v[184:187], v[216:219], v[18:21]
	v_mfma_f32_16x16x32_bf16 v[6:9], v[146:149], v[224:227], v[6:9]
	s_barrier
	v_mfma_f32_16x16x32_bf16 v[2:5], v[184:187], v[224:227], v[2:5]
	v_mfma_f32_16x16x32_bf16 v[42:45], v[188:191], v[212:215], v[34:37]
	v_mfma_f32_16x16x32_bf16 v[22:25], v[150:153], v[220:223], v[22:25]
	v_mfma_f32_16x16x32_bf16 v[18:21], v[188:191], v[220:223], v[18:21]
	v_mfma_f32_16x16x32_bf16 v[6:9], v[150:153], v[228:231], v[6:9]
	v_mfma_f32_16x16x32_bf16 v[2:5], v[188:191], v[228:231], v[2:5]
	s_setprio 0
	s_nop 0
	s_add_u32 s4, s4, 0x100
	s_addc_u32 s5, s5, 0
	s_add_u32 s8, s8, 0x100
	s_addc_u32 s9, s9, 0
	s_cmp_ge_i32 s11, s83
	s_mov_b32 s6, s11
	s_cbranch_scc0 .LBB0_3126

.LBB0_3613:
	v_add_u32_e32 v158, s64, v229
	v_add_u32_e32 v174, s65, v229
	ds_read_b128 v[146:149], v158
	ds_read_b128 v[150:153], v158 offset:1024
	ds_read_b128 v[154:157], v158 offset:2048
	ds_read_b128 v[158:161], v158 offset:3072
	ds_read_b128 v[162:165], v174
	ds_read_b128 v[166:169], v174 offset:1024
	ds_read_b128 v[170:173], v174 offset:2048
	ds_read_b128 v[174:177], v174 offset:3072
	s_add_i32 s80, s42, 2
	s_add_u32 s81, s40, 0x80
	s_addc_u32 s43, s41, 0
	s_cmp_eq_u32 s61, s42
	s_cselect_b32 s42, s4, s81
	s_cselect_b32 s43, s5, s43
	s_cselect_b32 s83, s39, s71
	s_cselect_b32 s82, s38, s70
	v_lshl_add_u64 v[210:211], s[40:41], 0, v[138:139]
	s_add_i32 m0, s51, 0xc000
	ds_read_b128 v[178:181], v231
	ds_read_b128 v[182:185], v231 offset:1024
	ds_read_b128 v[186:189], v231 offset:2048
	ds_read_b128 v[190:193], v231 offset:3072
	ds_read_b128 v[194:197], v231 offset:4096
	ds_read_b128 v[198:201], v231 offset:5120
	ds_read_b128 v[202:205], v231 offset:6144
	ds_read_b128 v[206:209], v231 offset:7168
	global_load_lds_dwordx4 v[210:211], off
	v_lshl_add_u64 v[210:211], s[40:41], 0, v[140:141]
	s_add_i32 m0, s51, 0xe000
	s_nop 0
	global_load_lds_dwordx4 v[210:211], off
	s_waitcnt vmcnt(8)
	s_waitcnt lgkmcnt(0)
	s_barrier
	s_setprio 1
	s_waitcnt lgkmcnt(0)
	v_mfma_i32_16x16x64_i8 v[126:129], v[146:149], v[178:181], v[126:129]
	v_mfma_i32_16x16x64_i8 v[122:125], v[154:157], v[178:181], v[122:125]
	v_mfma_i32_16x16x64_i8 v[118:121], v[146:149], v[186:189], v[118:121]
	v_mfma_i32_16x16x64_i8 v[114:117], v[154:157], v[186:189], v[114:117]
	v_mfma_i32_16x16x64_i8 v[106:109], v[146:149], v[194:197], v[106:109]
	v_mfma_i32_16x16x64_i8 v[98:101], v[154:157], v[194:197], v[98:101]
	v_mfma_i32_16x16x64_i8 v[90:93], v[146:149], v[202:205], v[90:93]
	v_mfma_i32_16x16x64_i8 v[82:85], v[154:157], v[202:205], v[82:85]
	v_mfma_i32_16x16x64_i8 v[126:129], v[150:153], v[182:185], v[126:129]
	v_mfma_i32_16x16x64_i8 v[122:125], v[158:161], v[182:185], v[122:125]
	v_mfma_i32_16x16x64_i8 v[118:121], v[150:153], v[190:193], v[118:121]
	v_mfma_i32_16x16x64_i8 v[114:117], v[158:161], v[190:193], v[114:117]
	v_mfma_i32_16x16x64_i8 v[106:109], v[150:153], v[198:201], v[106:109]
	v_mfma_i32_16x16x64_i8 v[98:101], v[158:161], v[198:201], v[98:101]
	v_mfma_i32_16x16x64_i8 v[90:93], v[150:153], v[206:209], v[90:93]
	v_mfma_i32_16x16x64_i8 v[82:85], v[158:161], v[206:209], v[82:85]
	s_setprio 0
	s_setprio 1
	v_mfma_i32_16x16x64_i8 v[110:113], v[162:165], v[178:181], v[110:113]
	v_mfma_i32_16x16x64_i8 v[102:105], v[170:173], v[178:181], v[102:105]
	v_mfma_i32_16x16x64_i8 v[94:97], v[162:165], v[186:189], v[94:97]
	v_mfma_i32_16x16x64_i8 v[86:89], v[170:173], v[186:189], v[86:89]
	v_mfma_i32_16x16x64_i8 v[78:81], v[162:165], v[194:197], v[78:81]
	v_mfma_i32_16x16x64_i8 v[74:77], v[170:173], v[194:197], v[74:77]
	v_mfma_i32_16x16x64_i8 v[70:73], v[162:165], v[202:205], v[70:73]
	v_mfma_i32_16x16x64_i8 v[66:69], v[170:173], v[202:205], v[66:69]
	v_mfma_i32_16x16x64_i8 v[110:113], v[166:169], v[182:185], v[110:113]
	v_mfma_i32_16x16x64_i8 v[102:105], v[174:177], v[182:185], v[102:105]
	s_barrier
	v_mfma_i32_16x16x64_i8 v[94:97], v[166:169], v[190:193], v[94:97]
	v_mfma_i32_16x16x64_i8 v[86:89], v[174:177], v[190:193], v[86:89]
	v_mfma_i32_16x16x64_i8 v[78:81], v[166:169], v[198:201], v[78:81]
	v_mfma_i32_16x16x64_i8 v[74:77], v[174:177], v[198:201], v[74:77]
	v_mfma_i32_16x16x64_i8 v[70:73], v[166:169], v[206:209], v[70:73]
	v_mfma_i32_16x16x64_i8 v[66:69], v[174:177], v[206:209], v[66:69]
	s_setprio 0
	s_nop 0
	s_add_i32 s81, s64, s50
	v_lshl_add_u64 v[210:211], s[82:83], 0, v[132:133]
	s_mov_b32 m0, s81
	ds_read_b128 v[178:181], v231 offset:16384
	ds_read_b128 v[182:185], v231 offset:17408
	ds_read_b128 v[186:189], v231 offset:18432
	ds_read_b128 v[190:193], v231 offset:19456
	ds_read_b128 v[194:197], v231 offset:20480
	ds_read_b128 v[198:201], v231 offset:21504
	ds_read_b128 v[202:205], v231 offset:22528
	ds_read_b128 v[206:209], v231 offset:23552
	global_load_lds_dwordx4 v[210:211], off
	s_add_i32 m0, s81, 0x2000
	v_lshl_add_u64 v[212:213], s[82:83], 0, v[136:137]
	s_add_u32 s82, s82, s8
	s_addc_u32 s83, s83, s9
	s_add_i32 s81, s65, s50
	global_load_lds_dwordx4 v[212:213], off
	v_lshl_add_u64 v[214:215], s[82:83], 0, v[132:133]
	s_mov_b32 m0, s81
	v_lshl_add_u64 v[216:217], s[82:83], 0, v[136:137]
	global_load_lds_dwordx4 v[214:215], off
	s_add_i32 m0, s81, 0x2000
	v_lshl_add_u64 v[218:219], s[42:43], 0, v[130:131]
	global_load_lds_dwordx4 v[216:217], off
	s_mov_b32 m0, s51
	v_lshl_add_u64 v[220:221], s[42:43], 0, v[134:135]
	global_load_lds_dwordx4 v[218:219], off
	s_mov_b32 m0, s52
	s_nop 0
	global_load_lds_dwordx4 v[220:221], off
	s_waitcnt vmcnt(8)
	s_waitcnt lgkmcnt(0)
	s_barrier
	s_setprio 1
	s_waitcnt lgkmcnt(0)
	v_mfma_i32_16x16x64_i8 v[62:65], v[146:149], v[178:181], v[62:65]
	v_mfma_i32_16x16x64_i8 v[58:61], v[154:157], v[178:181], v[58:61]
	v_mfma_i32_16x16x64_i8 v[54:57], v[146:149], v[186:189], v[54:57]
	v_mfma_i32_16x16x64_i8 v[50:53], v[154:157], v[186:189], v[50:53]
	v_mfma_i32_16x16x64_i8 v[42:45], v[146:149], v[194:197], v[42:45]
	v_mfma_i32_16x16x64_i8 v[34:37], v[154:157], v[194:197], v[34:37]
	v_mfma_i32_16x16x64_i8 v[26:29], v[146:149], v[202:205], v[26:29]
	v_mfma_i32_16x16x64_i8 v[18:21], v[154:157], v[202:205], v[18:21]
	v_mfma_i32_16x16x64_i8 v[62:65], v[150:153], v[182:185], v[62:65]
	v_mfma_i32_16x16x64_i8 v[58:61], v[158:161], v[182:185], v[58:61]
	v_mfma_i32_16x16x64_i8 v[54:57], v[150:153], v[190:193], v[54:57]
	v_mfma_i32_16x16x64_i8 v[50:53], v[158:161], v[190:193], v[50:53]
	v_mfma_i32_16x16x64_i8 v[42:45], v[150:153], v[198:201], v[42:45]
	v_mfma_i32_16x16x64_i8 v[34:37], v[158:161], v[198:201], v[34:37]
	v_mfma_i32_16x16x64_i8 v[26:29], v[150:153], v[206:209], v[26:29]
	v_mfma_i32_16x16x64_i8 v[18:21], v[158:161], v[206:209], v[18:21]
	s_setprio 0
	s_setprio 1
	v_mfma_i32_16x16x64_i8 v[46:49], v[162:165], v[178:181], v[46:49]
	v_mfma_i32_16x16x64_i8 v[38:41], v[170:173], v[178:181], v[38:41]
	v_mfma_i32_16x16x64_i8 v[30:33], v[162:165], v[186:189], v[30:33]
	v_mfma_i32_16x16x64_i8 v[22:25], v[170:173], v[186:189], v[22:25]
	v_mfma_i32_16x16x64_i8 v[14:17], v[162:165], v[194:197], v[14:17]
	v_mfma_i32_16x16x64_i8 v[10:13], v[170:173], v[194:197], v[10:13]
	v_mfma_i32_16x16x64_i8 v[6:9], v[162:165], v[202:205], v[6:9]
	v_mfma_i32_16x16x64_i8 v[2:5], v[170:173], v[202:205], v[2:5]
	v_mfma_i32_16x16x64_i8 v[46:49], v[166:169], v[182:185], v[46:49]
	v_mfma_i32_16x16x64_i8 v[38:41], v[174:177], v[182:185], v[38:41]
	s_barrier
	v_mfma_i32_16x16x64_i8 v[30:33], v[166:169], v[190:193], v[30:33]
	v_mfma_i32_16x16x64_i8 v[22:25], v[174:177], v[190:193], v[22:25]
	v_mfma_i32_16x16x64_i8 v[14:17], v[166:169], v[198:201], v[14:17]
	v_mfma_i32_16x16x64_i8 v[10:13], v[174:177], v[198:201], v[10:13]
	v_mfma_i32_16x16x64_i8 v[6:9], v[166:169], v[206:209], v[6:9]
	v_mfma_i32_16x16x64_i8 v[2:5], v[174:177], v[206:209], v[2:5]
	s_setprio 0
	s_nop 0
	s_add_i32 s81, 0, 0x18000
	s_add_i32 s82, 0, 0x1c000
	v_add_u32_e32 v158, s81, v229
	v_add_u32_e32 v174, s82, v229
	ds_read_b128 v[146:149], v158
	ds_read_b128 v[150:153], v158 offset:1024
	ds_read_b128 v[154:157], v158 offset:2048
	ds_read_b128 v[158:161], v158 offset:3072
	ds_read_b128 v[162:165], v174
	ds_read_b128 v[166:169], v174 offset:1024
	ds_read_b128 v[170:173], v174 offset:2048
	ds_read_b128 v[174:177], v174 offset:3072
	s_add_u32 s42, s42, s8
	s_addc_u32 s43, s43, s9
	s_mov_b32 m0, s53
	v_lshl_add_u64 v[222:223], s[42:43], 0, v[130:131]
	ds_read_b128 v[178:181], v231 offset:32768
	ds_read_b128 v[182:185], v231 offset:33792
	ds_read_b128 v[186:189], v231 offset:34816
	ds_read_b128 v[190:193], v231 offset:35840
	ds_read_b128 v[194:197], v231 offset:36864
	ds_read_b128 v[198:201], v231 offset:37888
	ds_read_b128 v[202:205], v231 offset:38912
	ds_read_b128 v[206:209], v231 offset:39936
	global_load_lds_dwordx4 v[222:223], off
	v_lshl_add_u64 v[222:223], s[42:43], 0, v[134:135]
	s_mov_b32 m0, s54
	s_nop 0
	global_load_lds_dwordx4 v[222:223], off
	s_waitcnt vmcnt(8)
	s_waitcnt lgkmcnt(0)
	s_barrier
	s_setprio 1
	s_waitcnt lgkmcnt(0)
	v_mfma_i32_16x16x64_i8 v[126:129], v[146:149], v[178:181], v[126:129]
	v_mfma_i32_16x16x64_i8 v[122:125], v[154:157], v[178:181], v[122:125]
	v_mfma_i32_16x16x64_i8 v[118:121], v[146:149], v[186:189], v[118:121]
	v_mfma_i32_16x16x64_i8 v[114:117], v[154:157], v[186:189], v[114:117]
	v_mfma_i32_16x16x64_i8 v[106:109], v[146:149], v[194:197], v[106:109]
	v_mfma_i32_16x16x64_i8 v[98:101], v[154:157], v[194:197], v[98:101]
	v_mfma_i32_16x16x64_i8 v[90:93], v[146:149], v[202:205], v[90:93]
	v_mfma_i32_16x16x64_i8 v[82:85], v[154:157], v[202:205], v[82:85]
	v_mfma_i32_16x16x64_i8 v[126:129], v[150:153], v[182:185], v[126:129]
	v_mfma_i32_16x16x64_i8 v[122:125], v[158:161], v[182:185], v[122:125]
	v_mfma_i32_16x16x64_i8 v[118:121], v[150:153], v[190:193], v[118:121]
	v_mfma_i32_16x16x64_i8 v[114:117], v[158:161], v[190:193], v[114:117]
	v_mfma_i32_16x16x64_i8 v[106:109], v[150:153], v[198:201], v[106:109]
	v_mfma_i32_16x16x64_i8 v[98:101], v[158:161], v[198:201], v[98:101]
	v_mfma_i32_16x16x64_i8 v[90:93], v[150:153], v[206:209], v[90:93]
	v_mfma_i32_16x16x64_i8 v[82:85], v[158:161], v[206:209], v[82:85]
	s_setprio 0
	s_setprio 1
	v_mfma_i32_16x16x64_i8 v[110:113], v[162:165], v[178:181], v[110:113]
	v_mfma_i32_16x16x64_i8 v[102:105], v[170:173], v[178:181], v[102:105]
	v_mfma_i32_16x16x64_i8 v[94:97], v[162:165], v[186:189], v[94:97]
	v_mfma_i32_16x16x64_i8 v[86:89], v[170:173], v[186:189], v[86:89]
	v_mfma_i32_16x16x64_i8 v[78:81], v[162:165], v[194:197], v[78:81]
	v_mfma_i32_16x16x64_i8 v[74:77], v[170:173], v[194:197], v[74:77]
	v_mfma_i32_16x16x64_i8 v[70:73], v[162:165], v[202:205], v[70:73]
	v_mfma_i32_16x16x64_i8 v[66:69], v[170:173], v[202:205], v[66:69]
	v_mfma_i32_16x16x64_i8 v[110:113], v[166:169], v[182:185], v[110:113]
	v_mfma_i32_16x16x64_i8 v[102:105], v[174:177], v[182:185], v[102:105]
	s_barrier
	v_mfma_i32_16x16x64_i8 v[94:97], v[166:169], v[190:193], v[94:97]
	v_mfma_i32_16x16x64_i8 v[86:89], v[174:177], v[190:193], v[86:89]
	v_mfma_i32_16x16x64_i8 v[78:81], v[166:169], v[198:201], v[78:81]
	v_mfma_i32_16x16x64_i8 v[74:77], v[174:177], v[198:201], v[74:77]
	v_mfma_i32_16x16x64_i8 v[70:73], v[166:169], v[206:209], v[70:73]
	v_mfma_i32_16x16x64_i8 v[66:69], v[174:177], v[206:209], v[66:69]
	s_setprio 0
	s_nop 0
	s_add_i32 s42, s81, s50
	v_lshl_add_u64 v[210:211], v[210:211], 0, s[30:31]
	s_mov_b32 m0, s42
	ds_read_b128 v[178:181], v231 offset:49152
	ds_read_b128 v[182:185], v231 offset:50176
	ds_read_b128 v[186:189], v231 offset:51200
	ds_read_b128 v[190:193], v231 offset:52224
	ds_read_b128 v[194:197], v231 offset:53248
	ds_read_b128 v[198:201], v231 offset:54272
	ds_read_b128 v[202:205], v231 offset:55296
	ds_read_b128 v[206:209], v231 offset:56320
	global_load_lds_dwordx4 v[210:211], off
	v_lshl_add_u64 v[210:211], v[212:213], 0, s[30:31]
	s_add_i32 m0, s42, 0x2000
	s_add_i32 s42, s82, s50
	global_load_lds_dwordx4 v[210:211], off
	v_lshl_add_u64 v[210:211], v[214:215], 0, s[30:31]
	s_mov_b32 m0, s42
	s_nop 0
	global_load_lds_dwordx4 v[210:211], off
	v_lshl_add_u64 v[210:211], v[216:217], 0, s[30:31]
	s_add_i32 m0, s42, 0x2000
	s_nop 0
	global_load_lds_dwordx4 v[210:211], off
	v_lshl_add_u64 v[210:211], v[218:219], 0, s[30:31]
	s_mov_b32 m0, s57
	s_nop 0
	global_load_lds_dwordx4 v[210:211], off
	v_lshl_add_u64 v[210:211], v[220:221], 0, s[30:31]
	s_mov_b32 m0, s58
	s_nop 0
	global_load_lds_dwordx4 v[210:211], off
	s_waitcnt vmcnt(8)
	s_waitcnt lgkmcnt(0)
	s_barrier
	s_setprio 1
	s_waitcnt lgkmcnt(0)
	v_mfma_i32_16x16x64_i8 v[62:65], v[146:149], v[178:181], v[62:65]
	v_mfma_i32_16x16x64_i8 v[58:61], v[154:157], v[178:181], v[58:61]
	v_mfma_i32_16x16x64_i8 v[54:57], v[146:149], v[186:189], v[54:57]
	v_mfma_i32_16x16x64_i8 v[50:53], v[154:157], v[186:189], v[50:53]
	v_mfma_i32_16x16x64_i8 v[42:45], v[146:149], v[194:197], v[42:45]
	v_mfma_i32_16x16x64_i8 v[34:37], v[154:157], v[194:197], v[34:37]
	v_mfma_i32_16x16x64_i8 v[26:29], v[146:149], v[202:205], v[26:29]
	v_mfma_i32_16x16x64_i8 v[18:21], v[154:157], v[202:205], v[18:21]
	v_mfma_i32_16x16x64_i8 v[62:65], v[150:153], v[182:185], v[62:65]
	v_mfma_i32_16x16x64_i8 v[58:61], v[158:161], v[182:185], v[58:61]
	v_mfma_i32_16x16x64_i8 v[54:57], v[150:153], v[190:193], v[54:57]
	v_mfma_i32_16x16x64_i8 v[50:53], v[158:161], v[190:193], v[50:53]
	v_mfma_i32_16x16x64_i8 v[42:45], v[150:153], v[198:201], v[42:45]
	v_mfma_i32_16x16x64_i8 v[34:37], v[158:161], v[198:201], v[34:37]
	v_mfma_i32_16x16x64_i8 v[26:29], v[150:153], v[206:209], v[26:29]
	v_mfma_i32_16x16x64_i8 v[18:21], v[158:161], v[206:209], v[18:21]
	s_setprio 0
	s_setprio 1
	v_mfma_i32_16x16x64_i8 v[46:49], v[162:165], v[178:181], v[46:49]
	v_mfma_i32_16x16x64_i8 v[38:41], v[170:173], v[178:181], v[38:41]
	v_mfma_i32_16x16x64_i8 v[30:33], v[162:165], v[186:189], v[30:33]
	v_mfma_i32_16x16x64_i8 v[22:25], v[170:173], v[186:189], v[22:25]
	v_mfma_i32_16x16x64_i8 v[14:17], v[162:165], v[194:197], v[14:17]
	v_mfma_i32_16x16x64_i8 v[10:13], v[170:173], v[194:197], v[10:13]
	v_mfma_i32_16x16x64_i8 v[6:9], v[162:165], v[202:205], v[6:9]
	v_mfma_i32_16x16x64_i8 v[2:5], v[170:173], v[202:205], v[2:5]
	v_mfma_i32_16x16x64_i8 v[46:49], v[166:169], v[182:185], v[46:49]
	v_mfma_i32_16x16x64_i8 v[38:41], v[174:177], v[182:185], v[38:41]
	s_barrier
	v_mfma_i32_16x16x64_i8 v[30:33], v[166:169], v[190:193], v[30:33]
	v_mfma_i32_16x16x64_i8 v[22:25], v[174:177], v[190:193], v[22:25]
	v_mfma_i32_16x16x64_i8 v[14:17], v[166:169], v[198:201], v[14:17]
	v_mfma_i32_16x16x64_i8 v[10:13], v[174:177], v[198:201], v[10:13]
	v_mfma_i32_16x16x64_i8 v[6:9], v[166:169], v[206:209], v[6:9]
	v_mfma_i32_16x16x64_i8 v[2:5], v[174:177], v[206:209], v[2:5]
	s_setprio 0
	s_nop 0
	s_add_u32 s40, s40, 0x100
	s_addc_u32 s41, s41, 0
	s_add_u32 s70, s70, 0x100
	s_addc_u32 s71, s71, 0
	s_cmp_ge_i32 s80, s60
	s_mov_b32 s42, s80
	s_cbranch_scc0 .LBB0_3613
	v_cvt_f32_i32_e32 v214, v126
	v_cvt_f32_i32_e32 v215, v127
	v_cvt_f32_i32_e32 v212, v128
	v_cvt_f32_i32_e32 v213, v129
	v_cvt_f32_i32_e32 v218, v122
	v_cvt_f32_i32_e32 v219, v123
	v_cvt_f32_i32_e32 v216, v124
	v_cvt_f32_i32_e32 v217, v125
	v_cvt_f32_i32_e32 v222, v110
	v_cvt_f32_i32_e32 v223, v111
	v_cvt_f32_i32_e32 v220, v112
	v_cvt_f32_i32_e32 v221, v113
	v_cvt_f32_i32_e32 v226, v102
	v_cvt_f32_i32_e32 v227, v103
	v_cvt_f32_i32_e32 v224, v104
	v_cvt_f32_i32_e32 v225, v105
	v_cvt_f32_i32_e32 v194, v118
	v_cvt_f32_i32_e32 v195, v119
	v_cvt_f32_i32_e32 v192, v120
	v_cvt_f32_i32_e32 v193, v121
	v_cvt_f32_i32_e32 v200, v114
	v_cvt_f32_i32_e32 v201, v115
	v_cvt_f32_i32_e32 v198, v116
	v_cvt_f32_i32_e32 v199, v117
	v_cvt_f32_i32_e32 v206, v94
	v_cvt_f32_i32_e32 v207, v95
	v_cvt_f32_i32_e32 v202, v96
	v_cvt_f32_i32_e32 v203, v97
	v_cvt_f32_i32_e32 v208, v86
	v_cvt_f32_i32_e32 v209, v87
	v_cvt_f32_i32_e32 v204, v88
	v_cvt_f32_i32_e32 v205, v89
	v_cvt_f32_i32_e32 v178, v106
	v_cvt_f32_i32_e32 v179, v107
	v_cvt_f32_i32_e32 v176, v108
	v_cvt_f32_i32_e32 v177, v109
	v_cvt_f32_i32_e32 v182, v98
	v_cvt_f32_i32_e32 v183, v99
	v_cvt_f32_i32_e32 v180, v100
	v_cvt_f32_i32_e32 v181, v101
	v_cvt_f32_i32_e32 v188, v78
	v_cvt_f32_i32_e32 v189, v79
	v_cvt_f32_i32_e32 v184, v80
	v_cvt_f32_i32_e32 v185, v81
	v_cvt_f32_i32_e32 v190, v74
	v_cvt_f32_i32_e32 v191, v75
	v_cvt_f32_i32_e32 v186, v76
	v_cvt_f32_i32_e32 v187, v77
	v_cvt_f32_i32_e32 v162, v90
	v_cvt_f32_i32_e32 v163, v91
	v_cvt_f32_i32_e32 v160, v92
	v_cvt_f32_i32_e32 v161, v93
	v_cvt_f32_i32_e32 v166, v82
	v_cvt_f32_i32_e32 v167, v83
	v_cvt_f32_i32_e32 v164, v84
	v_cvt_f32_i32_e32 v165, v85
	v_cvt_f32_i32_e32 v172, v70
	v_cvt_f32_i32_e32 v173, v71
	v_cvt_f32_i32_e32 v168, v72
	v_cvt_f32_i32_e32 v169, v73
	v_cvt_f32_i32_e32 v174, v66
	v_cvt_f32_i32_e32 v175, v67
	v_cvt_f32_i32_e32 v170, v68
	v_cvt_f32_i32_e32 v171, v69
	v_cvt_f32_i32_e32 v146, v62
	v_cvt_f32_i32_e32 v147, v63
	v_cvt_f32_i32_e32 v128, v64
	v_cvt_f32_i32_e32 v129, v65
	v_cvt_f32_i32_e32 v150, v58
	v_cvt_f32_i32_e32 v151, v59
	v_cvt_f32_i32_e32 v148, v60
	v_cvt_f32_i32_e32 v149, v61
	v_cvt_f32_i32_e32 v156, v46
	v_cvt_f32_i32_e32 v157, v47
	v_cvt_f32_i32_e32 v152, v48
	v_cvt_f32_i32_e32 v153, v49
	v_cvt_f32_i32_e32 v158, v38
	v_cvt_f32_i32_e32 v159, v39
	v_cvt_f32_i32_e32 v154, v40
	v_cvt_f32_i32_e32 v155, v41
	v_cvt_f32_i32_e32 v114, v54
	v_cvt_f32_i32_e32 v115, v55
	v_cvt_f32_i32_e32 v112, v56
	v_cvt_f32_i32_e32 v113, v57
	v_cvt_f32_i32_e32 v118, v50
	v_cvt_f32_i32_e32 v119, v51
	v_cvt_f32_i32_e32 v116, v52
	v_cvt_f32_i32_e32 v117, v53
	v_cvt_f32_i32_e32 v124, v30
	v_cvt_f32_i32_e32 v125, v31
	v_cvt_f32_i32_e32 v120, v32
	v_cvt_f32_i32_e32 v121, v33
	v_cvt_f32_i32_e32 v126, v22
	v_cvt_f32_i32_e32 v127, v23
	v_cvt_f32_i32_e32 v122, v24
	v_cvt_f32_i32_e32 v123, v25
	v_cvt_f32_i32_e32 v64, v42
	v_cvt_f32_i32_e32 v65, v43
	v_cvt_f32_i32_e32 v62, v44
	v_cvt_f32_i32_e32 v63, v45
	v_cvt_f32_i32_e32 v68, v34
	v_cvt_f32_i32_e32 v69, v35
	v_cvt_f32_i32_e32 v66, v36
	v_cvt_f32_i32_e32 v67, v37
	v_cvt_f32_i32_e32 v74, v14
	v_cvt_f32_i32_e32 v75, v15
	v_cvt_f32_i32_e32 v70, v16
	v_cvt_f32_i32_e32 v71, v17
	v_cvt_f32_i32_e32 v76, v10
	v_cvt_f32_i32_e32 v77, v11
	v_cvt_f32_i32_e32 v72, v12
	v_cvt_f32_i32_e32 v73, v13
	v_cvt_f32_i32_e32 v48, v26
	v_cvt_f32_i32_e32 v49, v27
	v_cvt_f32_i32_e32 v46, v28
	v_cvt_f32_i32_e32 v47, v29
	v_cvt_f32_i32_e32 v52, v18
	v_cvt_f32_i32_e32 v53, v19
	v_cvt_f32_i32_e32 v50, v20
	v_cvt_f32_i32_e32 v51, v21
	v_cvt_f32_i32_e32 v58, v6
	v_cvt_f32_i32_e32 v59, v7
	v_cvt_f32_i32_e32 v54, v8
	v_cvt_f32_i32_e32 v55, v9
	v_cvt_f32_i32_e32 v60, v2
	v_cvt_f32_i32_e32 v61, v3
	v_cvt_f32_i32_e32 v56, v4
	v_cvt_f32_i32_e32 v57, v5

.LBB0_3798:
	v_add_u32_e32 v138, s56, v188
	ds_read_b128 v[148:151], v138
	ds_read_b128 v[152:155], v138 offset:1024
	ds_read_b128 v[156:159], v138 offset:2048
	ds_read_b128 v[160:163], v138 offset:3072
	v_add_u32_e32 v138, s57, v188
	ds_read_b128 v[164:167], v138
	ds_read_b128 v[168:171], v138 offset:1024
	ds_read_b128 v[172:175], v138 offset:2048
	ds_read_b128 v[176:179], v138 offset:3072
	s_add_i32 s60, s28, 2
	s_add_u32 s61, s26, 0x80
	s_addc_u32 s29, s27, 0
	s_cmp_eq_u32 s54, s28
	s_cselect_b32 s28, s2, s61
	s_cselect_b32 s29, s3, s29
	s_cselect_b32 s63, s25, s35
	s_cselect_b32 s62, s24, s34
	v_lshl_add_u64 v[184:185], s[26:27], 0, v[140:141]
	s_add_i32 m0, s42, 0xc000
	ds_read_b128 v[180:183], v189
	ds_read_b128 v[190:193], v189 offset:1024
	ds_read_b128 v[194:197], v189 offset:2048
	ds_read_b128 v[198:201], v189 offset:3072
	ds_read_b128 v[202:205], v189 offset:4096
	ds_read_b128 v[206:209], v189 offset:5120
	ds_read_b128 v[210:213], v189 offset:6144
	ds_read_b128 v[214:217], v189 offset:7168
	global_load_lds_dwordx4 v[184:185], off
	v_lshl_add_u64 v[184:185], s[26:27], 0, v[142:143]
	s_add_i32 m0, s42, 0xe000
	s_nop 0
	global_load_lds_dwordx4 v[184:185], off
	s_waitcnt vmcnt(8)
	s_waitcnt lgkmcnt(0)
	s_barrier
	s_setprio 1
	s_waitcnt lgkmcnt(0)
	v_mfma_i32_16x16x64_i8 v[126:129], v[148:151], v[180:183], v[126:129]
	v_mfma_i32_16x16x64_i8 v[122:125], v[156:159], v[180:183], v[122:125]
	v_mfma_i32_16x16x64_i8 v[118:121], v[148:151], v[194:197], v[118:121]
	v_mfma_i32_16x16x64_i8 v[114:117], v[156:159], v[194:197], v[114:117]
	v_mfma_i32_16x16x64_i8 v[106:109], v[148:151], v[202:205], v[106:109]
	v_mfma_i32_16x16x64_i8 v[98:101], v[156:159], v[202:205], v[98:101]
	v_mfma_i32_16x16x64_i8 v[90:93], v[148:151], v[210:213], v[90:93]
	v_mfma_i32_16x16x64_i8 v[82:85], v[156:159], v[210:213], v[82:85]
	v_mfma_i32_16x16x64_i8 v[126:129], v[152:155], v[190:193], v[126:129]
	v_mfma_i32_16x16x64_i8 v[122:125], v[160:163], v[190:193], v[122:125]
	v_mfma_i32_16x16x64_i8 v[118:121], v[152:155], v[198:201], v[118:121]
	v_mfma_i32_16x16x64_i8 v[114:117], v[160:163], v[198:201], v[114:117]
	v_mfma_i32_16x16x64_i8 v[106:109], v[152:155], v[206:209], v[106:109]
	v_mfma_i32_16x16x64_i8 v[98:101], v[160:163], v[206:209], v[98:101]
	v_mfma_i32_16x16x64_i8 v[90:93], v[152:155], v[214:217], v[90:93]
	v_mfma_i32_16x16x64_i8 v[82:85], v[160:163], v[214:217], v[82:85]
	s_setprio 0
	s_setprio 1
	v_mfma_i32_16x16x64_i8 v[110:113], v[164:167], v[180:183], v[110:113]
	v_mfma_i32_16x16x64_i8 v[102:105], v[172:175], v[180:183], v[102:105]
	v_mfma_i32_16x16x64_i8 v[94:97], v[164:167], v[194:197], v[94:97]
	v_mfma_i32_16x16x64_i8 v[86:89], v[172:175], v[194:197], v[86:89]
	v_mfma_i32_16x16x64_i8 v[78:81], v[164:167], v[202:205], v[78:81]
	v_mfma_i32_16x16x64_i8 v[74:77], v[172:175], v[202:205], v[74:77]
	v_mfma_i32_16x16x64_i8 v[70:73], v[164:167], v[210:213], v[70:73]
	v_mfma_i32_16x16x64_i8 v[66:69], v[172:175], v[210:213], v[66:69]
	v_mfma_i32_16x16x64_i8 v[110:113], v[168:171], v[190:193], v[110:113]
	v_mfma_i32_16x16x64_i8 v[102:105], v[176:179], v[190:193], v[102:105]
	s_barrier
	v_mfma_i32_16x16x64_i8 v[94:97], v[168:171], v[198:201], v[94:97]
	v_mfma_i32_16x16x64_i8 v[86:89], v[176:179], v[198:201], v[86:89]
	v_mfma_i32_16x16x64_i8 v[78:81], v[168:171], v[206:209], v[78:81]
	v_mfma_i32_16x16x64_i8 v[74:77], v[176:179], v[206:209], v[74:77]
	v_mfma_i32_16x16x64_i8 v[70:73], v[168:171], v[214:217], v[70:73]
	v_mfma_i32_16x16x64_i8 v[66:69], v[176:179], v[214:217], v[66:69]
	s_setprio 0
	s_nop 0
	s_add_i32 s61, s56, s41
	v_lshl_add_u64 v[184:185], s[62:63], 0, v[132:133]
	s_mov_b32 m0, s61
	ds_read_b128 v[180:183], v189 offset:16384
	ds_read_b128 v[190:193], v189 offset:17408
	ds_read_b128 v[194:197], v189 offset:18432
	ds_read_b128 v[198:201], v189 offset:19456
	ds_read_b128 v[202:205], v189 offset:20480
	ds_read_b128 v[206:209], v189 offset:21504
	ds_read_b128 v[210:213], v189 offset:22528
	ds_read_b128 v[214:217], v189 offset:23552
	global_load_lds_dwordx4 v[184:185], off
	s_add_i32 m0, s61, 0x2000
	v_lshl_add_u64 v[218:219], s[62:63], 0, v[136:137]
	s_add_u32 s62, s62, s6
	s_addc_u32 s63, s63, s7
	s_add_i32 s61, s57, s41
	global_load_lds_dwordx4 v[218:219], off
	v_lshl_add_u64 v[220:221], s[62:63], 0, v[132:133]
	s_mov_b32 m0, s61
	v_lshl_add_u64 v[222:223], s[62:63], 0, v[136:137]
	global_load_lds_dwordx4 v[220:221], off
	s_add_i32 m0, s61, 0x2000
	v_lshl_add_u64 v[224:225], s[28:29], 0, v[130:131]
	global_load_lds_dwordx4 v[222:223], off
	s_mov_b32 m0, s42
	v_lshl_add_u64 v[226:227], s[28:29], 0, v[134:135]
	global_load_lds_dwordx4 v[224:225], off
	s_mov_b32 m0, s43
	s_nop 0
	global_load_lds_dwordx4 v[226:227], off
	s_waitcnt vmcnt(8)
	s_waitcnt lgkmcnt(0)
	s_barrier
	s_setprio 1
	s_waitcnt lgkmcnt(0)
	v_mfma_i32_16x16x64_i8 v[62:65], v[148:151], v[180:183], v[62:65]
	v_mfma_i32_16x16x64_i8 v[58:61], v[156:159], v[180:183], v[58:61]
	v_mfma_i32_16x16x64_i8 v[54:57], v[148:151], v[194:197], v[54:57]
	v_mfma_i32_16x16x64_i8 v[50:53], v[156:159], v[194:197], v[50:53]
	v_mfma_i32_16x16x64_i8 v[42:45], v[148:151], v[202:205], v[42:45]
	v_mfma_i32_16x16x64_i8 v[34:37], v[156:159], v[202:205], v[34:37]
	v_mfma_i32_16x16x64_i8 v[26:29], v[148:151], v[210:213], v[26:29]
	v_mfma_i32_16x16x64_i8 v[18:21], v[156:159], v[210:213], v[18:21]
	v_mfma_i32_16x16x64_i8 v[62:65], v[152:155], v[190:193], v[62:65]
	v_mfma_i32_16x16x64_i8 v[58:61], v[160:163], v[190:193], v[58:61]
	v_mfma_i32_16x16x64_i8 v[54:57], v[152:155], v[198:201], v[54:57]
	v_mfma_i32_16x16x64_i8 v[50:53], v[160:163], v[198:201], v[50:53]
	v_mfma_i32_16x16x64_i8 v[42:45], v[152:155], v[206:209], v[42:45]
	v_mfma_i32_16x16x64_i8 v[34:37], v[160:163], v[206:209], v[34:37]
	v_mfma_i32_16x16x64_i8 v[26:29], v[152:155], v[214:217], v[26:29]
	v_mfma_i32_16x16x64_i8 v[18:21], v[160:163], v[214:217], v[18:21]
	s_setprio 0
	s_setprio 1
	v_mfma_i32_16x16x64_i8 v[46:49], v[164:167], v[180:183], v[46:49]
	v_mfma_i32_16x16x64_i8 v[38:41], v[172:175], v[180:183], v[38:41]
	v_mfma_i32_16x16x64_i8 v[30:33], v[164:167], v[194:197], v[30:33]
	v_mfma_i32_16x16x64_i8 v[22:25], v[172:175], v[194:197], v[22:25]
	v_mfma_i32_16x16x64_i8 v[14:17], v[164:167], v[202:205], v[14:17]
	v_mfma_i32_16x16x64_i8 v[10:13], v[172:175], v[202:205], v[10:13]
	v_mfma_i32_16x16x64_i8 v[6:9], v[164:167], v[210:213], v[6:9]
	v_mfma_i32_16x16x64_i8 v[2:5], v[172:175], v[210:213], v[2:5]
	v_mfma_i32_16x16x64_i8 v[46:49], v[168:171], v[190:193], v[46:49]
	v_mfma_i32_16x16x64_i8 v[38:41], v[176:179], v[190:193], v[38:41]
	s_barrier
	v_mfma_i32_16x16x64_i8 v[30:33], v[168:171], v[198:201], v[30:33]
	v_mfma_i32_16x16x64_i8 v[22:25], v[176:179], v[198:201], v[22:25]
	v_mfma_i32_16x16x64_i8 v[14:17], v[168:171], v[206:209], v[14:17]
	v_mfma_i32_16x16x64_i8 v[10:13], v[176:179], v[206:209], v[10:13]
	v_mfma_i32_16x16x64_i8 v[6:9], v[168:171], v[214:217], v[6:9]
	v_mfma_i32_16x16x64_i8 v[2:5], v[176:179], v[214:217], v[2:5]
	s_setprio 0
	s_nop 0
	s_add_i32 s61, 0, 0x18000
	v_add_u32_e32 v138, s61, v188
	s_add_i32 s62, 0, 0x1c000
	ds_read_b128 v[148:151], v138
	ds_read_b128 v[152:155], v138 offset:1024
	ds_read_b128 v[156:159], v138 offset:2048
	ds_read_b128 v[160:163], v138 offset:3072
	v_add_u32_e32 v138, s62, v188
	ds_read_b128 v[164:167], v138
	ds_read_b128 v[168:171], v138 offset:1024
	ds_read_b128 v[172:175], v138 offset:2048
	ds_read_b128 v[176:179], v138 offset:3072
	s_add_u32 s28, s28, s6
	s_addc_u32 s29, s29, s7
	s_mov_b32 m0, s44
	v_lshl_add_u64 v[228:229], s[28:29], 0, v[130:131]
	ds_read_b128 v[180:183], v189 offset:32768
	ds_read_b128 v[190:193], v189 offset:33792
	ds_read_b128 v[194:197], v189 offset:34816
	ds_read_b128 v[198:201], v189 offset:35840
	ds_read_b128 v[202:205], v189 offset:36864
	ds_read_b128 v[206:209], v189 offset:37888
	ds_read_b128 v[210:213], v189 offset:38912
	ds_read_b128 v[214:217], v189 offset:39936
	global_load_lds_dwordx4 v[228:229], off
	v_lshl_add_u64 v[228:229], s[28:29], 0, v[134:135]
	s_mov_b32 m0, s45
	s_nop 0
	global_load_lds_dwordx4 v[228:229], off
	s_waitcnt vmcnt(8)
	s_waitcnt lgkmcnt(0)
	s_barrier
	s_setprio 1
	s_waitcnt lgkmcnt(0)
	v_mfma_i32_16x16x64_i8 v[126:129], v[148:151], v[180:183], v[126:129]
	v_mfma_i32_16x16x64_i8 v[122:125], v[156:159], v[180:183], v[122:125]
	v_mfma_i32_16x16x64_i8 v[118:121], v[148:151], v[194:197], v[118:121]
	v_mfma_i32_16x16x64_i8 v[114:117], v[156:159], v[194:197], v[114:117]
	v_mfma_i32_16x16x64_i8 v[106:109], v[148:151], v[202:205], v[106:109]
	v_mfma_i32_16x16x64_i8 v[98:101], v[156:159], v[202:205], v[98:101]
	v_mfma_i32_16x16x64_i8 v[90:93], v[148:151], v[210:213], v[90:93]
	v_mfma_i32_16x16x64_i8 v[82:85], v[156:159], v[210:213], v[82:85]
	v_mfma_i32_16x16x64_i8 v[126:129], v[152:155], v[190:193], v[126:129]
	v_mfma_i32_16x16x64_i8 v[122:125], v[160:163], v[190:193], v[122:125]
	v_mfma_i32_16x16x64_i8 v[118:121], v[152:155], v[198:201], v[118:121]
	v_mfma_i32_16x16x64_i8 v[114:117], v[160:163], v[198:201], v[114:117]
	v_mfma_i32_16x16x64_i8 v[106:109], v[152:155], v[206:209], v[106:109]
	v_mfma_i32_16x16x64_i8 v[98:101], v[160:163], v[206:209], v[98:101]
	v_mfma_i32_16x16x64_i8 v[90:93], v[152:155], v[214:217], v[90:93]
	v_mfma_i32_16x16x64_i8 v[82:85], v[160:163], v[214:217], v[82:85]
	s_setprio 0
	s_setprio 1
	v_mfma_i32_16x16x64_i8 v[110:113], v[164:167], v[180:183], v[110:113]
	v_mfma_i32_16x16x64_i8 v[102:105], v[172:175], v[180:183], v[102:105]
	v_mfma_i32_16x16x64_i8 v[94:97], v[164:167], v[194:197], v[94:97]
	v_mfma_i32_16x16x64_i8 v[86:89], v[172:175], v[194:197], v[86:89]
	v_mfma_i32_16x16x64_i8 v[78:81], v[164:167], v[202:205], v[78:81]
	v_mfma_i32_16x16x64_i8 v[74:77], v[172:175], v[202:205], v[74:77]
	v_mfma_i32_16x16x64_i8 v[70:73], v[164:167], v[210:213], v[70:73]
	v_mfma_i32_16x16x64_i8 v[66:69], v[172:175], v[210:213], v[66:69]
	v_mfma_i32_16x16x64_i8 v[110:113], v[168:171], v[190:193], v[110:113]
	v_mfma_i32_16x16x64_i8 v[102:105], v[176:179], v[190:193], v[102:105]
	s_barrier
	v_mfma_i32_16x16x64_i8 v[94:97], v[168:171], v[198:201], v[94:97]
	v_mfma_i32_16x16x64_i8 v[86:89], v[176:179], v[198:201], v[86:89]
	v_mfma_i32_16x16x64_i8 v[78:81], v[168:171], v[206:209], v[78:81]
	v_mfma_i32_16x16x64_i8 v[74:77], v[176:179], v[206:209], v[74:77]
	v_mfma_i32_16x16x64_i8 v[70:73], v[168:171], v[214:217], v[70:73]
	v_mfma_i32_16x16x64_i8 v[66:69], v[176:179], v[214:217], v[66:69]
	s_setprio 0
	s_nop 0
	s_add_i32 s28, s61, s41
	v_lshl_add_u64 v[184:185], v[184:185], 0, s[18:19]
	s_mov_b32 m0, s28
	ds_read_b128 v[180:183], v189 offset:49152
	ds_read_b128 v[190:193], v189 offset:50176
	ds_read_b128 v[194:197], v189 offset:51200
	ds_read_b128 v[198:201], v189 offset:52224
	ds_read_b128 v[202:205], v189 offset:53248
	ds_read_b128 v[206:209], v189 offset:54272
	ds_read_b128 v[210:213], v189 offset:55296
	ds_read_b128 v[214:217], v189 offset:56320
	global_load_lds_dwordx4 v[184:185], off
	v_lshl_add_u64 v[184:185], v[218:219], 0, s[18:19]
	s_add_i32 m0, s28, 0x2000
	s_add_i32 s28, s62, s41
	global_load_lds_dwordx4 v[184:185], off
	v_lshl_add_u64 v[184:185], v[220:221], 0, s[18:19]
	s_mov_b32 m0, s28
	s_nop 0
	global_load_lds_dwordx4 v[184:185], off
	v_lshl_add_u64 v[184:185], v[222:223], 0, s[18:19]
	s_add_i32 m0, s28, 0x2000
	s_nop 0
	global_load_lds_dwordx4 v[184:185], off
	v_lshl_add_u64 v[184:185], v[224:225], 0, s[18:19]
	s_mov_b32 m0, s49
	s_nop 0
	global_load_lds_dwordx4 v[184:185], off
	v_lshl_add_u64 v[184:185], v[226:227], 0, s[18:19]
	s_mov_b32 m0, s50
	s_nop 0
	global_load_lds_dwordx4 v[184:185], off
	s_waitcnt vmcnt(8)
	s_waitcnt lgkmcnt(0)
	s_barrier
	s_setprio 1
	s_waitcnt lgkmcnt(0)
	v_mfma_i32_16x16x64_i8 v[62:65], v[148:151], v[180:183], v[62:65]
	v_mfma_i32_16x16x64_i8 v[58:61], v[156:159], v[180:183], v[58:61]
	v_mfma_i32_16x16x64_i8 v[54:57], v[148:151], v[194:197], v[54:57]
	v_mfma_i32_16x16x64_i8 v[50:53], v[156:159], v[194:197], v[50:53]
	v_mfma_i32_16x16x64_i8 v[42:45], v[148:151], v[202:205], v[42:45]
	v_mfma_i32_16x16x64_i8 v[34:37], v[156:159], v[202:205], v[34:37]
	v_mfma_i32_16x16x64_i8 v[26:29], v[148:151], v[210:213], v[26:29]
	v_mfma_i32_16x16x64_i8 v[18:21], v[156:159], v[210:213], v[18:21]
	v_mfma_i32_16x16x64_i8 v[62:65], v[152:155], v[190:193], v[62:65]
	v_mfma_i32_16x16x64_i8 v[58:61], v[160:163], v[190:193], v[58:61]
	v_mfma_i32_16x16x64_i8 v[54:57], v[152:155], v[198:201], v[54:57]
	v_mfma_i32_16x16x64_i8 v[50:53], v[160:163], v[198:201], v[50:53]
	v_mfma_i32_16x16x64_i8 v[42:45], v[152:155], v[206:209], v[42:45]
	v_mfma_i32_16x16x64_i8 v[34:37], v[160:163], v[206:209], v[34:37]
	v_mfma_i32_16x16x64_i8 v[26:29], v[152:155], v[214:217], v[26:29]
	v_mfma_i32_16x16x64_i8 v[18:21], v[160:163], v[214:217], v[18:21]
	s_setprio 0
	s_setprio 1
	v_mfma_i32_16x16x64_i8 v[46:49], v[164:167], v[180:183], v[46:49]
	v_mfma_i32_16x16x64_i8 v[38:41], v[172:175], v[180:183], v[38:41]
	v_mfma_i32_16x16x64_i8 v[30:33], v[164:167], v[194:197], v[30:33]
	v_mfma_i32_16x16x64_i8 v[22:25], v[172:175], v[194:197], v[22:25]
	v_mfma_i32_16x16x64_i8 v[14:17], v[164:167], v[202:205], v[14:17]
	v_mfma_i32_16x16x64_i8 v[10:13], v[172:175], v[202:205], v[10:13]
	v_mfma_i32_16x16x64_i8 v[6:9], v[164:167], v[210:213], v[6:9]
	v_mfma_i32_16x16x64_i8 v[2:5], v[172:175], v[210:213], v[2:5]
	v_mfma_i32_16x16x64_i8 v[46:49], v[168:171], v[190:193], v[46:49]
	v_mfma_i32_16x16x64_i8 v[38:41], v[176:179], v[190:193], v[38:41]
	s_barrier
	v_mfma_i32_16x16x64_i8 v[30:33], v[168:171], v[198:201], v[30:33]
	v_mfma_i32_16x16x64_i8 v[22:25], v[176:179], v[198:201], v[22:25]
	v_mfma_i32_16x16x64_i8 v[14:17], v[168:171], v[206:209], v[14:17]
	v_mfma_i32_16x16x64_i8 v[10:13], v[176:179], v[206:209], v[10:13]
	v_mfma_i32_16x16x64_i8 v[6:9], v[168:171], v[214:217], v[6:9]
	v_mfma_i32_16x16x64_i8 v[2:5], v[176:179], v[214:217], v[2:5]
	s_setprio 0
	s_nop 0
	s_add_u32 s26, s26, 0x100
	s_addc_u32 s27, s27, 0
	s_add_u32 s34, s34, 0x100
	s_addc_u32 s35, s35, 0
	s_cmp_ge_i32 s60, s51
	s_mov_b32 s28, s60
	s_cbranch_scc0 .LBB0_3798
	v_cvt_f32_i32_e32 v172, v126
	v_cvt_f32_i32_e32 v173, v127
	v_cvt_f32_i32_e32 v170, v128
	v_cvt_f32_i32_e32 v171, v129
	v_cvt_f32_i32_e32 v174, v122
	v_cvt_f32_i32_e32 v175, v123
	v_cvt_f32_i32_e32 v176, v124
	v_cvt_f32_i32_e32 v177, v125
	v_cvt_f32_i32_e32 v180, v110
	v_cvt_f32_i32_e32 v181, v111
	v_cvt_f32_i32_e32 v182, v112
	v_cvt_f32_i32_e32 v183, v113
	v_cvt_f32_i32_e32 v178, v102
	v_cvt_f32_i32_e32 v179, v103
	v_cvt_f32_i32_e32 v184, v104
	v_cvt_f32_i32_e32 v185, v105
	v_cvt_f32_i32_e32 v152, v118
	v_cvt_f32_i32_e32 v153, v119
	v_cvt_f32_i32_e32 v154, v120
	v_cvt_f32_i32_e32 v155, v121
	v_cvt_f32_i32_e32 v156, v114
	v_cvt_f32_i32_e32 v157, v115
	v_cvt_f32_i32_e32 v158, v116
	v_cvt_f32_i32_e32 v159, v117
	v_cvt_f32_i32_e32 v160, v94
	v_cvt_f32_i32_e32 v161, v95
	v_cvt_f32_i32_e32 v162, v96
	v_cvt_f32_i32_e32 v163, v97
	v_cvt_f32_i32_e32 v164, v86
	v_cvt_f32_i32_e32 v165, v87
	v_cvt_f32_i32_e32 v166, v88
	v_cvt_f32_i32_e32 v167, v89
	v_cvt_f32_i32_e32 v118, v106
	v_cvt_f32_i32_e32 v119, v107
	v_cvt_f32_i32_e32 v120, v108
	v_cvt_f32_i32_e32 v121, v109
	v_cvt_f32_i32_e32 v122, v98
	v_cvt_f32_i32_e32 v123, v99
	v_cvt_f32_i32_e32 v124, v100
	v_cvt_f32_i32_e32 v125, v101
	v_cvt_f32_i32_e32 v126, v78
	v_cvt_f32_i32_e32 v127, v79
	v_cvt_f32_i32_e32 v128, v80
	v_cvt_f32_i32_e32 v129, v81
	v_cvt_f32_i32_e32 v148, v74
	v_cvt_f32_i32_e32 v149, v75
	v_cvt_f32_i32_e32 v150, v76
	v_cvt_f32_i32_e32 v151, v77
	v_cvt_f32_i32_e32 v102, v90
	v_cvt_f32_i32_e32 v103, v91
	v_cvt_f32_i32_e32 v104, v92
	v_cvt_f32_i32_e32 v105, v93
	v_cvt_f32_i32_e32 v106, v82
	v_cvt_f32_i32_e32 v107, v83
	v_cvt_f32_i32_e32 v108, v84
	v_cvt_f32_i32_e32 v109, v85
	v_cvt_f32_i32_e32 v110, v70
	v_cvt_f32_i32_e32 v111, v71
	v_cvt_f32_i32_e32 v112, v72
	v_cvt_f32_i32_e32 v113, v73
	v_cvt_f32_i32_e32 v114, v66
	v_cvt_f32_i32_e32 v115, v67
	v_cvt_f32_i32_e32 v116, v68
	v_cvt_f32_i32_e32 v117, v69
	v_cvt_f32_i32_e32 v82, v62
	v_cvt_f32_i32_e32 v83, v63
	v_cvt_f32_i32_e32 v84, v64
	v_cvt_f32_i32_e32 v85, v65
	v_cvt_f32_i32_e32 v86, v58
	v_cvt_f32_i32_e32 v87, v59
	v_cvt_f32_i32_e32 v88, v60
	v_cvt_f32_i32_e32 v89, v61
	v_cvt_f32_i32_e32 v92, v46
	v_cvt_f32_i32_e32 v93, v47
	v_cvt_f32_i32_e32 v94, v48
	v_cvt_f32_i32_e32 v95, v49
	v_cvt_f32_i32_e32 v96, v38
	v_cvt_f32_i32_e32 v97, v39
	v_cvt_f32_i32_e32 v98, v40
	v_cvt_f32_i32_e32 v99, v41
	v_cvt_f32_i32_e32 v66, v54
	v_cvt_f32_i32_e32 v67, v55
	v_cvt_f32_i32_e32 v68, v56
	v_cvt_f32_i32_e32 v69, v57
	v_cvt_f32_i32_e32 v70, v50
	v_cvt_f32_i32_e32 v71, v51
	v_cvt_f32_i32_e32 v72, v52
	v_cvt_f32_i32_e32 v73, v53
	v_cvt_f32_i32_e32 v74, v30
	v_cvt_f32_i32_e32 v75, v31
	v_cvt_f32_i32_e32 v76, v32
	v_cvt_f32_i32_e32 v77, v33
	v_cvt_f32_i32_e32 v78, v22
	v_cvt_f32_i32_e32 v79, v23
	v_cvt_f32_i32_e32 v80, v24
	v_cvt_f32_i32_e32 v81, v25
	v_cvt_f32_i32_e32 v50, v42
	v_cvt_f32_i32_e32 v51, v43
	v_cvt_f32_i32_e32 v52, v44
	v_cvt_f32_i32_e32 v53, v45
	v_cvt_f32_i32_e32 v54, v34
	v_cvt_f32_i32_e32 v55, v35
	v_cvt_f32_i32_e32 v56, v36
	v_cvt_f32_i32_e32 v57, v37
	v_cvt_f32_i32_e32 v58, v14
	v_cvt_f32_i32_e32 v59, v15
	v_cvt_f32_i32_e32 v60, v16
	v_cvt_f32_i32_e32 v61, v17
	v_cvt_f32_i32_e32 v62, v10
	v_cvt_f32_i32_e32 v63, v11
	v_cvt_f32_i32_e32 v64, v12
	v_cvt_f32_i32_e32 v65, v13
	v_cvt_f32_i32_e32 v34, v26
	v_cvt_f32_i32_e32 v35, v27
	v_cvt_f32_i32_e32 v36, v28
	v_cvt_f32_i32_e32 v37, v29
	v_cvt_f32_i32_e32 v38, v18
	v_cvt_f32_i32_e32 v39, v19
	v_cvt_f32_i32_e32 v40, v20
	v_cvt_f32_i32_e32 v41, v21
	v_cvt_f32_i32_e32 v42, v6
	v_cvt_f32_i32_e32 v43, v7
	v_cvt_f32_i32_e32 v44, v8
	v_cvt_f32_i32_e32 v45, v9
	v_cvt_f32_i32_e32 v46, v2
	v_cvt_f32_i32_e32 v47, v3
	v_cvt_f32_i32_e32 v48, v4
	v_cvt_f32_i32_e32 v49, v5

.LBB0_3879:
	ds_read_b128 v[130:133], v169
	ds_read_b128 v[134:137], v169 offset:1024
	ds_read_b128 v[138:141], v169 offset:2048
	ds_read_b128 v[142:145], v169 offset:3072
	ds_read_b128 v[162:165], v170
	ds_read_b128 v[172:175], v170 offset:1024
	ds_read_b128 v[176:179], v170 offset:2048
	ds_read_b128 v[180:183], v170 offset:3072
	s_add_i32 s59, s26, 2
	s_add_u32 s27, s24, 0x4000
	s_addc_u32 s28, s25, 0
	s_cmp_eq_u32 s48, s26
	s_cselect_b32 s29, s3, s28
	s_cselect_b32 s28, s2, s27
	s_cselect_b32 s60, s22, s57
	s_cselect_b32 s61, s23, s58
	s_add_u32 s26, s28, 0x8000
	s_addc_u32 s27, s29, 0
	v_lshl_add_u64 v[216:217], s[24:25], 0, v[154:155]
	s_add_i32 m0, s38, 0xc000
	ds_read_b128 v[184:187], v171
	ds_read_b128 v[188:191], v171 offset:1024
	ds_read_b128 v[192:195], v171 offset:2048
	ds_read_b128 v[196:199], v171 offset:3072
	ds_read_b128 v[200:203], v171 offset:4096
	ds_read_b128 v[204:207], v171 offset:5120
	ds_read_b128 v[208:211], v171 offset:6144
	ds_read_b128 v[212:215], v171 offset:7168
	global_load_lds_dwordx4 v[216:217], off
	v_lshl_add_u64 v[216:217], s[24:25], 0, v[156:157]
	s_add_i32 m0, s38, 0xe000
	s_nop 0
	global_load_lds_dwordx4 v[216:217], off
	s_waitcnt vmcnt(8)
	s_waitcnt lgkmcnt(0)
	s_barrier
	s_setprio 1
	s_waitcnt lgkmcnt(0)
	v_mfma_f32_16x16x32_bf16 v[126:129], v[130:133], v[184:187], v[126:129]
	v_mfma_f32_16x16x32_bf16 v[122:125], v[138:141], v[184:187], v[122:125]
	v_mfma_f32_16x16x32_bf16 v[110:113], v[130:133], v[192:195], v[110:113]
	v_mfma_f32_16x16x32_bf16 v[106:109], v[138:141], v[192:195], v[106:109]
	v_mfma_f32_16x16x32_bf16 v[94:97], v[130:133], v[200:203], v[94:97]
	v_mfma_f32_16x16x32_bf16 v[90:93], v[138:141], v[200:203], v[90:93]
	v_mfma_f32_16x16x32_bf16 v[78:81], v[130:133], v[208:211], v[78:81]
	v_mfma_f32_16x16x32_bf16 v[74:77], v[138:141], v[208:211], v[74:77]
	v_mfma_f32_16x16x32_bf16 v[126:129], v[134:137], v[188:191], v[126:129]
	v_mfma_f32_16x16x32_bf16 v[122:125], v[142:145], v[188:191], v[122:125]
	v_mfma_f32_16x16x32_bf16 v[110:113], v[134:137], v[196:199], v[110:113]
	v_mfma_f32_16x16x32_bf16 v[106:109], v[142:145], v[196:199], v[106:109]
	v_mfma_f32_16x16x32_bf16 v[94:97], v[134:137], v[204:207], v[94:97]
	v_mfma_f32_16x16x32_bf16 v[90:93], v[142:145], v[204:207], v[90:93]
	v_mfma_f32_16x16x32_bf16 v[78:81], v[134:137], v[212:215], v[78:81]
	v_mfma_f32_16x16x32_bf16 v[74:77], v[142:145], v[212:215], v[74:77]
	s_setprio 0
	s_setprio 1
	v_mfma_f32_16x16x32_bf16 v[118:121], v[162:165], v[184:187], v[118:121]
	v_mfma_f32_16x16x32_bf16 v[114:117], v[176:179], v[184:187], v[114:117]
	v_mfma_f32_16x16x32_bf16 v[102:105], v[162:165], v[192:195], v[102:105]
	v_mfma_f32_16x16x32_bf16 v[98:101], v[176:179], v[192:195], v[98:101]
	v_mfma_f32_16x16x32_bf16 v[86:89], v[162:165], v[200:203], v[86:89]
	v_mfma_f32_16x16x32_bf16 v[82:85], v[176:179], v[200:203], v[82:85]
	v_mfma_f32_16x16x32_bf16 v[70:73], v[162:165], v[208:211], v[70:73]
	v_mfma_f32_16x16x32_bf16 v[66:69], v[176:179], v[208:211], v[66:69]
	v_mfma_f32_16x16x32_bf16 v[118:121], v[172:175], v[188:191], v[118:121]
	v_mfma_f32_16x16x32_bf16 v[114:117], v[180:183], v[188:191], v[114:117]
	s_barrier
	v_mfma_f32_16x16x32_bf16 v[102:105], v[172:175], v[196:199], v[102:105]
	v_mfma_f32_16x16x32_bf16 v[98:101], v[180:183], v[196:199], v[98:101]
	v_mfma_f32_16x16x32_bf16 v[86:89], v[172:175], v[204:207], v[86:89]
	v_mfma_f32_16x16x32_bf16 v[82:85], v[180:183], v[204:207], v[82:85]
	v_mfma_f32_16x16x32_bf16 v[70:73], v[172:175], v[212:215], v[70:73]
	v_mfma_f32_16x16x32_bf16 v[66:69], v[180:183], v[212:215], v[66:69]
	s_setprio 0
	s_nop 0
	s_add_i32 s62, s50, s37
	v_lshl_add_u64 v[216:217], s[60:61], 0, v[148:149]
	s_mov_b32 m0, s62
	ds_read_b128 v[184:187], v171 offset:16384
	ds_read_b128 v[188:191], v171 offset:17408
	ds_read_b128 v[192:195], v171 offset:18432
	ds_read_b128 v[196:199], v171 offset:19456
	ds_read_b128 v[200:203], v171 offset:20480
	ds_read_b128 v[204:207], v171 offset:21504
	ds_read_b128 v[208:211], v171 offset:22528
	ds_read_b128 v[212:215], v171 offset:23552
	global_load_lds_dwordx4 v[216:217], off
	s_add_i32 m0, s62, 0x2000
	v_lshl_add_u64 v[218:219], s[60:61], 0, v[152:153]
	s_add_u32 s60, s60, s6
	s_addc_u32 s61, s61, s7
	s_add_i32 s62, s51, s37
	global_load_lds_dwordx4 v[218:219], off
	v_lshl_add_u64 v[220:221], s[60:61], 0, v[148:149]
	s_mov_b32 m0, s62
	v_lshl_add_u64 v[222:223], s[60:61], 0, v[152:153]
	global_load_lds_dwordx4 v[220:221], off
	s_add_i32 m0, s62, 0x2000
	v_lshl_add_u64 v[224:225], s[28:29], 0, v[146:147]
	global_load_lds_dwordx4 v[222:223], off
	s_mov_b32 m0, s38
	s_nop 0
	global_load_lds_dwordx4 v[224:225], off
	v_lshl_add_u64 v[224:225], s[28:29], 0, v[150:151]
	s_mov_b32 m0, s39
	s_nop 0
	global_load_lds_dwordx4 v[224:225], off
	s_waitcnt vmcnt(8)
	s_waitcnt lgkmcnt(0)
	s_barrier
	s_setprio 1
	s_waitcnt lgkmcnt(0)
	v_mfma_f32_16x16x32_bf16 v[62:65], v[130:133], v[184:187], v[62:65]
	v_mfma_f32_16x16x32_bf16 v[58:61], v[138:141], v[184:187], v[58:61]
	v_mfma_f32_16x16x32_bf16 v[46:49], v[130:133], v[192:195], v[46:49]
	v_mfma_f32_16x16x32_bf16 v[42:45], v[138:141], v[192:195], v[42:45]
	v_mfma_f32_16x16x32_bf16 v[30:33], v[130:133], v[200:203], v[30:33]
	v_mfma_f32_16x16x32_bf16 v[26:29], v[138:141], v[200:203], v[26:29]
	v_mfma_f32_16x16x32_bf16 v[14:17], v[130:133], v[208:211], v[14:17]
	v_mfma_f32_16x16x32_bf16 v[10:13], v[138:141], v[208:211], v[10:13]
	v_mfma_f32_16x16x32_bf16 v[62:65], v[134:137], v[188:191], v[62:65]
	v_mfma_f32_16x16x32_bf16 v[58:61], v[142:145], v[188:191], v[58:61]
	v_mfma_f32_16x16x32_bf16 v[46:49], v[134:137], v[196:199], v[46:49]
	v_mfma_f32_16x16x32_bf16 v[42:45], v[142:145], v[196:199], v[42:45]
	v_mfma_f32_16x16x32_bf16 v[30:33], v[134:137], v[204:207], v[30:33]
	v_mfma_f32_16x16x32_bf16 v[26:29], v[142:145], v[204:207], v[26:29]
	v_mfma_f32_16x16x32_bf16 v[14:17], v[134:137], v[212:215], v[14:17]
	v_mfma_f32_16x16x32_bf16 v[10:13], v[142:145], v[212:215], v[10:13]
	s_setprio 0
	s_setprio 1
	v_mfma_f32_16x16x32_bf16 v[54:57], v[162:165], v[184:187], v[54:57]
	v_mfma_f32_16x16x32_bf16 v[50:53], v[176:179], v[184:187], v[50:53]
	v_mfma_f32_16x16x32_bf16 v[38:41], v[162:165], v[192:195], v[38:41]
	v_mfma_f32_16x16x32_bf16 v[34:37], v[176:179], v[192:195], v[34:37]
	v_mfma_f32_16x16x32_bf16 v[22:25], v[162:165], v[200:203], v[22:25]
	v_mfma_f32_16x16x32_bf16 v[18:21], v[176:179], v[200:203], v[18:21]
	v_mfma_f32_16x16x32_bf16 v[6:9], v[162:165], v[208:211], v[6:9]
	v_mfma_f32_16x16x32_bf16 v[2:5], v[176:179], v[208:211], v[2:5]
	v_mfma_f32_16x16x32_bf16 v[54:57], v[172:175], v[188:191], v[54:57]
	v_mfma_f32_16x16x32_bf16 v[50:53], v[180:183], v[188:191], v[50:53]
	s_barrier
	v_mfma_f32_16x16x32_bf16 v[38:41], v[172:175], v[196:199], v[38:41]
	v_mfma_f32_16x16x32_bf16 v[34:37], v[180:183], v[196:199], v[34:37]
	v_mfma_f32_16x16x32_bf16 v[22:25], v[172:175], v[204:207], v[22:25]
	v_mfma_f32_16x16x32_bf16 v[18:21], v[180:183], v[204:207], v[18:21]
	v_mfma_f32_16x16x32_bf16 v[6:9], v[172:175], v[212:215], v[6:9]
	v_mfma_f32_16x16x32_bf16 v[2:5], v[180:183], v[212:215], v[2:5]
	s_setprio 0
	s_nop 0
	s_add_i32 s60, 0, 0x18000
	s_add_i32 s61, 0, 0x1c000
	v_add_u32_e32 v142, s60, v167
	v_add_u32_e32 v180, s61, v167
	ds_read_b128 v[130:133], v142
	ds_read_b128 v[134:137], v142 offset:1024
	ds_read_b128 v[138:141], v142 offset:2048
	ds_read_b128 v[142:145], v142 offset:3072
	ds_read_b128 v[162:165], v180
	ds_read_b128 v[172:175], v180 offset:1024
	ds_read_b128 v[176:179], v180 offset:2048
	ds_read_b128 v[180:183], v180 offset:3072
	s_add_u32 s28, s28, 0x4000
	s_addc_u32 s29, s29, 0
	s_mov_b32 m0, s40
	v_lshl_add_u64 v[224:225], s[28:29], 0, v[146:147]
	ds_read_b128 v[184:187], v171 offset:32768
	ds_read_b128 v[188:191], v171 offset:33792
	ds_read_b128 v[192:195], v171 offset:34816
	ds_read_b128 v[196:199], v171 offset:35840
	ds_read_b128 v[200:203], v171 offset:36864
	ds_read_b128 v[204:207], v171 offset:37888
	ds_read_b128 v[208:211], v171 offset:38912
	ds_read_b128 v[212:215], v171 offset:39936
	global_load_lds_dwordx4 v[224:225], off
	v_lshl_add_u64 v[224:225], s[28:29], 0, v[150:151]
	s_mov_b32 m0, s41
	s_nop 0
	global_load_lds_dwordx4 v[224:225], off
	s_waitcnt vmcnt(8)
	s_waitcnt lgkmcnt(0)
	s_barrier
	s_setprio 1
	s_waitcnt lgkmcnt(0)
	v_mfma_f32_16x16x32_bf16 v[126:129], v[130:133], v[184:187], v[126:129]
	v_mfma_f32_16x16x32_bf16 v[122:125], v[138:141], v[184:187], v[122:125]
	v_mfma_f32_16x16x32_bf16 v[110:113], v[130:133], v[192:195], v[110:113]
	v_mfma_f32_16x16x32_bf16 v[106:109], v[138:141], v[192:195], v[106:109]
	v_mfma_f32_16x16x32_bf16 v[94:97], v[130:133], v[200:203], v[94:97]
	v_mfma_f32_16x16x32_bf16 v[90:93], v[138:141], v[200:203], v[90:93]
	v_mfma_f32_16x16x32_bf16 v[78:81], v[130:133], v[208:211], v[78:81]
	v_mfma_f32_16x16x32_bf16 v[74:77], v[138:141], v[208:211], v[74:77]
	v_mfma_f32_16x16x32_bf16 v[126:129], v[134:137], v[188:191], v[126:129]
	v_mfma_f32_16x16x32_bf16 v[122:125], v[142:145], v[188:191], v[122:125]
	v_mfma_f32_16x16x32_bf16 v[110:113], v[134:137], v[196:199], v[110:113]
	v_mfma_f32_16x16x32_bf16 v[106:109], v[142:145], v[196:199], v[106:109]
	v_mfma_f32_16x16x32_bf16 v[94:97], v[134:137], v[204:207], v[94:97]
	v_mfma_f32_16x16x32_bf16 v[90:93], v[142:145], v[204:207], v[90:93]
	v_mfma_f32_16x16x32_bf16 v[78:81], v[134:137], v[212:215], v[78:81]
	v_mfma_f32_16x16x32_bf16 v[74:77], v[142:145], v[212:215], v[74:77]
	s_setprio 0
	s_setprio 1
	v_mfma_f32_16x16x32_bf16 v[118:121], v[162:165], v[184:187], v[118:121]
	v_mfma_f32_16x16x32_bf16 v[114:117], v[176:179], v[184:187], v[114:117]
	v_mfma_f32_16x16x32_bf16 v[102:105], v[162:165], v[192:195], v[102:105]
	v_mfma_f32_16x16x32_bf16 v[98:101], v[176:179], v[192:195], v[98:101]
	v_mfma_f32_16x16x32_bf16 v[86:89], v[162:165], v[200:203], v[86:89]
	v_mfma_f32_16x16x32_bf16 v[82:85], v[176:179], v[200:203], v[82:85]
	v_mfma_f32_16x16x32_bf16 v[70:73], v[162:165], v[208:211], v[70:73]
	v_mfma_f32_16x16x32_bf16 v[66:69], v[176:179], v[208:211], v[66:69]
	v_mfma_f32_16x16x32_bf16 v[118:121], v[172:175], v[188:191], v[118:121]
	v_mfma_f32_16x16x32_bf16 v[114:117], v[180:183], v[188:191], v[114:117]
	s_barrier
	v_mfma_f32_16x16x32_bf16 v[102:105], v[172:175], v[196:199], v[102:105]
	v_mfma_f32_16x16x32_bf16 v[98:101], v[180:183], v[196:199], v[98:101]
	v_mfma_f32_16x16x32_bf16 v[86:89], v[172:175], v[204:207], v[86:89]
	v_mfma_f32_16x16x32_bf16 v[82:85], v[180:183], v[204:207], v[82:85]
	v_mfma_f32_16x16x32_bf16 v[70:73], v[172:175], v[212:215], v[70:73]
	v_mfma_f32_16x16x32_bf16 v[66:69], v[180:183], v[212:215], v[66:69]
	s_setprio 0
	s_nop 0
	s_add_i32 s28, s60, s37
	v_lshl_add_u64 v[216:217], v[216:217], 0, s[14:15]
	s_mov_b32 m0, s28
	ds_read_b128 v[184:187], v171 offset:49152
	ds_read_b128 v[188:191], v171 offset:50176
	ds_read_b128 v[192:195], v171 offset:51200
	ds_read_b128 v[196:199], v171 offset:52224
	ds_read_b128 v[200:203], v171 offset:53248
	ds_read_b128 v[204:207], v171 offset:54272
	ds_read_b128 v[208:211], v171 offset:55296
	ds_read_b128 v[212:215], v171 offset:56320
	global_load_lds_dwordx4 v[216:217], off
	v_lshl_add_u64 v[216:217], v[218:219], 0, s[14:15]
	s_add_i32 m0, s28, 0x2000
	s_add_i32 s28, s61, s37
	global_load_lds_dwordx4 v[216:217], off
	v_lshl_add_u64 v[216:217], v[220:221], 0, s[14:15]
	s_mov_b32 m0, s28
	s_nop 0
	global_load_lds_dwordx4 v[216:217], off
	v_lshl_add_u64 v[216:217], v[222:223], 0, s[14:15]
	s_add_i32 m0, s28, 0x2000
	s_nop 0
	global_load_lds_dwordx4 v[216:217], off
	v_lshl_add_u64 v[216:217], s[26:27], 0, v[146:147]
	s_mov_b32 m0, s46
	s_nop 0
	global_load_lds_dwordx4 v[216:217], off
	v_lshl_add_u64 v[216:217], s[26:27], 0, v[150:151]
	s_mov_b32 m0, s47
	s_nop 0
	global_load_lds_dwordx4 v[216:217], off
	s_waitcnt vmcnt(8)
	s_waitcnt lgkmcnt(0)
	s_barrier
	s_setprio 1
	s_waitcnt lgkmcnt(0)
	v_mfma_f32_16x16x32_bf16 v[62:65], v[130:133], v[184:187], v[62:65]
	v_mfma_f32_16x16x32_bf16 v[58:61], v[138:141], v[184:187], v[58:61]
	v_mfma_f32_16x16x32_bf16 v[46:49], v[130:133], v[192:195], v[46:49]
	v_mfma_f32_16x16x32_bf16 v[42:45], v[138:141], v[192:195], v[42:45]
	v_mfma_f32_16x16x32_bf16 v[30:33], v[130:133], v[200:203], v[30:33]
	v_mfma_f32_16x16x32_bf16 v[26:29], v[138:141], v[200:203], v[26:29]
	v_mfma_f32_16x16x32_bf16 v[14:17], v[130:133], v[208:211], v[14:17]
	v_mfma_f32_16x16x32_bf16 v[10:13], v[138:141], v[208:211], v[10:13]
	v_mfma_f32_16x16x32_bf16 v[62:65], v[134:137], v[188:191], v[62:65]
	v_mfma_f32_16x16x32_bf16 v[58:61], v[142:145], v[188:191], v[58:61]
	v_mfma_f32_16x16x32_bf16 v[46:49], v[134:137], v[196:199], v[46:49]
	v_mfma_f32_16x16x32_bf16 v[42:45], v[142:145], v[196:199], v[42:45]
	v_mfma_f32_16x16x32_bf16 v[30:33], v[134:137], v[204:207], v[30:33]
	v_mfma_f32_16x16x32_bf16 v[26:29], v[142:145], v[204:207], v[26:29]
	v_mfma_f32_16x16x32_bf16 v[14:17], v[134:137], v[212:215], v[14:17]
	v_mfma_f32_16x16x32_bf16 v[10:13], v[142:145], v[212:215], v[10:13]
	s_setprio 0
	s_setprio 1
	v_mfma_f32_16x16x32_bf16 v[54:57], v[162:165], v[184:187], v[54:57]
	v_mfma_f32_16x16x32_bf16 v[50:53], v[176:179], v[184:187], v[50:53]
	v_mfma_f32_16x16x32_bf16 v[38:41], v[162:165], v[192:195], v[38:41]
	v_mfma_f32_16x16x32_bf16 v[34:37], v[176:179], v[192:195], v[34:37]
	v_mfma_f32_16x16x32_bf16 v[22:25], v[162:165], v[200:203], v[22:25]
	v_mfma_f32_16x16x32_bf16 v[18:21], v[176:179], v[200:203], v[18:21]
	v_mfma_f32_16x16x32_bf16 v[6:9], v[162:165], v[208:211], v[6:9]
	v_mfma_f32_16x16x32_bf16 v[2:5], v[176:179], v[208:211], v[2:5]
	v_mfma_f32_16x16x32_bf16 v[54:57], v[172:175], v[188:191], v[54:57]
	v_mfma_f32_16x16x32_bf16 v[50:53], v[180:183], v[188:191], v[50:53]
	s_barrier
	v_mfma_f32_16x16x32_bf16 v[38:41], v[172:175], v[196:199], v[38:41]
	v_mfma_f32_16x16x32_bf16 v[34:37], v[180:183], v[196:199], v[34:37]
	v_mfma_f32_16x16x32_bf16 v[22:25], v[172:175], v[204:207], v[22:25]
	v_mfma_f32_16x16x32_bf16 v[18:21], v[180:183], v[204:207], v[18:21]
	v_mfma_f32_16x16x32_bf16 v[6:9], v[172:175], v[212:215], v[6:9]
	v_mfma_f32_16x16x32_bf16 v[2:5], v[180:183], v[212:215], v[2:5]
	s_setprio 0
	s_nop 0
	s_add_u32 s57, s57, 0x100
	s_addc_u32 s58, s58, 0
	s_add_u32 s24, s24, 0x10000
	s_addc_u32 s25, s25, 0
	s_cmp_ge_i32 s59, s45
	s_mov_b32 s26, s59
	s_cbranch_scc0 .LBB0_3879
